# streaming cache policy for once-touched data: conversion items' f32 weight loads and the prologue's x loads nt, converted bf16 weights stored write-through, final f32 output stored nt
# speedup vs baseline: 1.0230x; 1.0230x over previous
; #define LAS __attribute__((address_space(3)))
; __device__ __forceinline__ unsigned pk2(float lo, float hi) { return pg8::cvt_pk_bf16(lo, hi); }
; __device__ __forceinline__ void lds_wait() { asm volatile("s_waitcnt lgkmcnt(0)" ::: "memory"); }
; __device__ __forceinline__ void transpose_item(const float* W, int N, bf16* WT, int K, int k0, int n0, int drow0, const float* gk, LAS float* scr, int lane) {
;     ...
; #pragma unroll
;     for (int j = 0; j < 4; ++j) { const int n = (lane >> 3) + 8 * j; const LAS float* s = scr + (8 * c) * 33 + n;
;         u32x4 o; o.x = pk2(s[0 * 33], s[1 * 33]); o.y = pk2(s[2 * 33], s[3 * 33]); o.z = pk2(s[4 * 33], s[5 * 33]); o.w = pk2(s[6 * 33], s[7 * 33]);
;         *(u32x4*)(WT + (size_t)(drow0 + n) * K + k0 + 8 * c) = o; }
;     lds_wait();
; __device__ __forceinline__ void p0_weight_item(const Args& a, int l, int r, LAS float* scr, int lane) {
;     ...
;         if (r < 2 * IT_BIG) { const int up = r >= IT_BIG; const int it = r - up * IT_BIG; const int kb = it / 88, nb = it % 88, k0 = 64 * kb, n0 = 32 * nb;
;             const float* W = a.in[(f ? 29 : 2) + up] + (size_t)l * DM * FF;
;             transpose_item(W, FF, gu, DM, k0, n0, (n0 >> 7) * 256 + up * 128 + (n0 & 127), nrm + k0, scr, lane); return; }
.LBB0_8:
	s_lshl_b32 s4, s22, 6
	s_and_b32 s22, s4, 0xffffff00
	s_and_b64 s[4:5], s[24:25], exec
	s_cselect_b32 s24, 0x80, 0
	s_and_b32 s25, s28, 0x60
	s_or_b32 s22, s22, s24
	ds_write2_b32 v16, v14, v15 offset0:140 offset1:206
	s_lshl_b64 s[4:5], s[26:27], 1
	s_or_b32 s22, s22, s25
	s_waitcnt lgkmcnt(0)
	s_add_u32 s4, s84, s4
	v_or_b32_e32 v18, s22, v30
	s_waitcnt vmcnt(0)
	ds_read2_b32 v[12:13], v31 offset1:33
	v_mov_b32_e32 v11, v7
	s_addc_u32 s5, s83, s5
	v_ashrrev_i32_e32 v19, 31, v18
	s_waitcnt lgkmcnt(0)
	v_cvt_pk_bf16_f32 v12, v12, v13
	ds_read2_b32 v[14:15], v31 offset0:66 offset1:99
	v_lshl_add_u64 v[20:21], s[4:5], 0, v[10:11]
	v_lshlrev_b64 v[18:19], 11, v[18:19]
	s_waitcnt lgkmcnt(0)
	v_cvt_pk_bf16_f32 v13, v14, v15
	ds_read2_b32 v[14:15], v31 offset0:132 offset1:165
	v_lshl_add_u64 v[18:19], v[20:21], 0, v[18:19]
	s_waitcnt lgkmcnt(0)
	v_cvt_pk_bf16_f32 v14, v14, v15
	ds_read2_b32 v[16:17], v31 offset0:198 offset1:231
	s_waitcnt lgkmcnt(0)
	v_cvt_pk_bf16_f32 v15, v16, v17
	global_store_dwordx4 v[18:19], v[12:15], off sc1
	v_or_b32_e32 v18, s22, v32
	v_ashrrev_i32_e32 v19, 31, v18
	ds_read2_b32 v[16:17], v31 offset0:8 offset1:41
	s_waitcnt lgkmcnt(0)
	v_cvt_pk_bf16_f32 v12, v16, v17
	ds_read2_b32 v[14:15], v31 offset0:74 offset1:107
	v_lshlrev_b64 v[18:19], 11, v[18:19]
	s_waitcnt lgkmcnt(0)
	v_cvt_pk_bf16_f32 v13, v14, v15
	ds_read2_b32 v[14:15], v31 offset0:140 offset1:173
	v_lshl_add_u64 v[18:19], v[20:21], 0, v[18:19]
	s_waitcnt lgkmcnt(0)
	v_cvt_pk_bf16_f32 v14, v14, v15
	ds_read2_b32 v[16:17], v31 offset0:206 offset1:239
	s_waitcnt lgkmcnt(0)
	v_cvt_pk_bf16_f32 v15, v16, v17
	global_store_dwordx4 v[18:19], v[12:15], off sc1
	v_or_b32_e32 v18, s22, v33
	ds_read2_b32 v[16:17], v31 offset0:16 offset1:49
	s_waitcnt lgkmcnt(0)
	v_cvt_pk_bf16_f32 v12, v16, v17
	ds_read2_b32 v[14:15], v31 offset0:82 offset1:115
	v_ashrrev_i32_e32 v19, 31, v18
	s_waitcnt lgkmcnt(0)
	v_cvt_pk_bf16_f32 v13, v14, v15
	ds_read2_b32 v[14:15], v31 offset0:148 offset1:181
	v_lshlrev_b64 v[18:19], 11, v[18:19]
	s_waitcnt lgkmcnt(0)
	v_cvt_pk_bf16_f32 v14, v14, v15
	ds_read2_b32 v[16:17], v31 offset0:214 offset1:247
	s_waitcnt lgkmcnt(0)
	v_cvt_pk_bf16_f32 v15, v16, v17
	v_lshl_add_u64 v[18:19], v[20:21], 0, v[18:19]
	ds_read2_b32 v[16:17], v31 offset0:24 offset1:57
	global_store_dwordx4 v[18:19], v[12:15], off sc1
	v_or_b32_e32 v18, s22, v34
	v_ashrrev_i32_e32 v19, 31, v18
	s_waitcnt lgkmcnt(0)
	v_cvt_pk_bf16_f32 v12, v16, v17
	ds_read2_b32 v[14:15], v31 offset0:90 offset1:123
	s_waitcnt lgkmcnt(0)
	v_cvt_pk_bf16_f32 v13, v14, v15
	ds_read2_b32 v[14:15], v31 offset0:156 offset1:189
	s_waitcnt lgkmcnt(0)
	v_cvt_pk_bf16_f32 v14, v14, v15
	ds_read2_b32 v[16:17], v31 offset0:222 offset1:255
	v_lshlrev_b64 v[18:19], 11, v[18:19]
	s_waitcnt lgkmcnt(0)
	v_cvt_pk_bf16_f32 v15, v16, v17
	v_lshl_add_u64 v[16:17], v[20:21], 0, v[18:19]
	global_store_dwordx4 v[16:17], v[12:15], off sc1
	s_waitcnt lgkmcnt(0)

; __device__ __forceinline__ void p0_weight_item(const Args& a, int l, int r, LAS float* scr, int lane) {
;     unsigned char* wl = a.ws + WS_W + (size_t)l * WL_STRIDE;
; #pragma unroll
;     for (int f = 0; f < 2; ++f) {
;         const float* nrm = a.in[f ? 28 : 1] + (size_t)l * DM;
;         bf16* gu = (bf16*)(wl + (f ? WL_GU2 : WL_GU1)); bf16* dn = (bf16*)(wl + (f ? WL_D2 : WL_D1));
;         if (r < 2 * IT_BIG) { const int up = r >= IT_BIG; const int it = r - up * IT_BIG; const int kb = it / 88, nb = it % 88, k0 = 64 * kb, n0 = 32 * nb;
;             const float* W = a.in[(f ? 29 : 2) + up] + (size_t)l * DM * FF;
;             transpose_item(W, FF, gu, DM, k0, n0, (n0 >> 7) * 256 + up * 128 + (n0 & 127), nrm + k0, scr, lane); return; }
;         r -= 2 * IT_BIG;
;         if (r < IT_BIG) { const int kb = r / 32, nb = r % 32; const float* W = a.in[f ? 31 : 4] + (size_t)l * FF * DM;
;             transpose_item(W, DM, dn, FF, 64 * kb, 32 * nb, 32 * nb, nullptr, scr, lane); return; }
;         r -= IT_BIG;
;     }
;     if (r < IT_BIG) {
;         const int kb = r / 88, nb = r % 88, k0 = 64 * kb, n0 = 32 * nb; const int tile = n0 >> 8, c0 = n0 & 255;
;         int drow = n0;
;         if (tile >= 1 && tile <= 4) { const int hh = c0 >> 7, d0 = c0 & 127, bj = d0 >> 6, dd0 = d0 & 63; drow = tile * 256 + bj * 128 + hh * 64 + dd0; }
;         transpose_item(a.in[6] + (size_t)l * DM * IW, IW, (bf16*)(wl + WL_WIN), DM, k0, n0, drow, a.in[5] + (size_t)l * DM + k0, scr, lane); return; }
;     r -= IT_BIG;
;     if (r < IT_OUT) {
;         const int kb = r / 32, nb = r % 32, k0 = 64 * kb;
;         const float* gk = (k0 < 256) ? a.in[17] + (size_t)l * 256 + k0 : (k0 < 768 ? a.in[18] + (size_t)l * 512 + (k0 - 256) : a.in[26] + (size_t)l * 256 + (k0 - 768));
;         transpose_item(a.in[27] + (size_t)l * DM * DM, DM, (bf16*)(wl + WL_WOUT), DM, k0, 32 * nb, 32 * nb, gk, scr, lane); return; }
;     r -= IT_OUT;
;     if (r < IT_GLU) { const int kb = r / 8, nb = r % 8; transpose_item(a.in[15] + (size_t)l * 65536, 256, (bf16*)(wl + WL_GLU), 256, 64 * kb, 32 * nb, 32 * nb, nullptr, scr, lane); return; }
;     r -= IT_GLU;
;     if (r < IT_LW) { const int blk = r >> 1, nb = r & 1; transpose_item(a.in[21] + (size_t)l * 16384 + blk * 4096, 64, (bf16*)(wl + WL_WA) + blk * 4096, 64, 0, 32 * nb, 32 * nb, nullptr, scr, lane); return; }
;     r -= IT_LW;
.LBB0_10:
	s_mul_hi_i32 s4, s82, 0x3255ba01
	s_lshr_b32 s5, s4, 31
	s_ashr_i32 s4, s4, 11
	s_add_i32 s26, s4, s5
	s_mul_i32 s4, s26, 0xffffd750
	s_add_i32 s88, s82, s4
	s_ashr_i32 s27, s26, 31
	s_mul_i32 s5, s26, 0x2b00000
	s_mul_hi_i32 s4, s26, 0x2b00000
	s_add_u32 s84, s33, s5
	s_addc_u32 s83, s42, s4
	s_lshl_b64 s[24:25], s[26:27], 12
	s_mul_i32 s87, s26, 0x28b0
	s_mul_hi_i32 s85, s26, 0xb00000
	s_mul_i32 s86, s26, 0xb00000
	s_cmpk_gt_i32 s88, 0xaff
	s_mov_b64 s[4:5], -1
	s_cbranch_scc0 .LBB0_122
	s_cmpk_gt_u32 s88, 0x107f
	s_cbranch_scc0 .LBB0_119
	s_cmpk_gt_u32 s88, 0x1b7f
	s_cbranch_scc0 .LBB0_92
	s_add_i32 s4, s88, 0xffffef80
	s_cmpk_lt_u32 s4, 0x1080
	s_mov_b64 s[4:5], -1
	s_cbranch_scc1 .LBB0_89
	s_add_i32 s34, s88, 0xffffdf00
	s_cmpk_gt_u32 s88, 0x267f
	s_cbranch_scc0 .LBB0_60
	s_cmpk_gt_u32 s34, 0x77f
	s_cbranch_scc0 .LBB0_25
	s_cmpk_gt_u32 s34, 0x79f
	s_cbranch_scc0 .LBB0_22
	s_mul_i32 s22, s26, 0xfeba8000
	s_add_i32 s31, s47, s22
	s_add_i32 s22, s43, 0xfffbe000
	s_lshl_b64 s[4:5], s[26:27], 16
	s_and_b32 s30, s22, 32
	s_cmpk_gt_u32 s34, 0x7a7
	s_mov_b64 s[28:29], -1
	v_or_b32_e32 v15, s30, v30
	v_or_b32_e32 v14, s30, v32
	v_or_b32_e32 v13, s30, v33
	v_or_b32_e32 v12, s30, v34
	s_cbranch_scc0 .LBB0_19
	v_readlane_b32 s52, v250, 43
	v_readlane_b32 s66, v250, 57
	v_readlane_b32 s67, v250, 58
	s_add_u32 s35, s66, s4
	s_addc_u32 s38, s67, s5
	s_and_b32 s22, s31, 0x7ffff000
	s_add_i32 s16, s22, 0xffc2c000
	s_lshl_b64 s[28:29], s[16:17], 2
	s_add_u32 s35, s35, s28
	s_addc_u32 s39, s38, s29
	s_lshl_b64 s[28:29], s[16:17], 1
	s_add_u32 s28, s84, s28
	s_addc_u32 s29, s83, s29
	s_lshl_b32 s22, s30, 2
	s_add_u32 s38, s35, s22
	s_addc_u32 s39, s39, 0
	v_lshl_add_u64 v[16:17], s[38:39], 0, v[6:7]
	v_mov_b32_e32 v9, v7
	v_lshl_add_u64 v[16:17], v[16:17], 0, v[8:9]
	v_add_co_u32_e32 v18, vcc, s14, v16
	global_load_dword v9, v[16:17], off nt
	global_load_dword v11, v[16:17], off offset:512 nt
	global_load_dword v22, v[16:17], off offset:1024 nt
	global_load_dword v23, v[16:17], off offset:1536 nt
	global_load_dword v24, v[16:17], off offset:2048 nt
	global_load_dword v25, v[16:17], off offset:2560 nt
	global_load_dword v26, v[16:17], off offset:3072 nt
	global_load_dword v27, v[16:17], off offset:3584 nt
	v_addc_co_u32_e32 v19, vcc, 0, v17, vcc
	v_add_co_u32_e32 v20, vcc, s91, v16
	v_readlane_b32 s53, v250, 44
	s_nop 0
	v_addc_co_u32_e32 v21, vcc, 0, v17, vcc
	v_add_co_u32_e32 v16, vcc, s92, v16
	global_load_dword v28, v[20:21], off offset:-4096 nt
	global_load_dword v29, v[20:21], off nt
	global_load_dword v55, v[20:21], off offset:512 nt
	global_load_dword v56, v[20:21], off offset:1024 nt
	global_load_dword v57, v[20:21], off offset:1536 nt
	global_load_dword v58, v[20:21], off offset:2048 nt
	global_load_dword v59, v[20:21], off offset:2560 nt
	global_load_dword v60, v[20:21], off offset:3072 nt
	s_nop 0
	global_load_dword v20, v[20:21], off offset:3584 nt
	v_addc_co_u32_e32 v17, vcc, 0, v17, vcc
	global_load_dword v21, v[18:19], off offset:512 nt
	global_load_dword v61, v[18:19], off offset:1024 nt
	global_load_dword v62, v[18:19], off offset:1536 nt
	global_load_dword v63, v[18:19], off offset:2048 nt
	global_load_dword v64, v[18:19], off offset:2560 nt
	global_load_dword v65, v[18:19], off offset:3072 nt
	s_nop 0
	global_load_dword v18, v[18:19], off offset:3584 nt
	s_nop 0
	global_load_dword v19, v[16:17], off nt
	global_load_dword v66, v[16:17], off offset:512 nt
	global_load_dword v67, v[16:17], off offset:1024 nt
	global_load_dword v68, v[16:17], off offset:1536 nt
	global_load_dword v69, v[16:17], off offset:2048 nt
	global_load_dword v70, v[16:17], off offset:2560 nt
	global_load_dword v71, v[16:17], off offset:3072 nt
	s_nop 0
	global_load_dword v16, v[16:17], off offset:3584 nt
	v_readlane_b32 s54, v250, 45
	v_readlane_b32 s55, v250, 46
	v_readlane_b32 s56, v250, 47
	v_readlane_b32 s57, v250, 48
	v_readlane_b32 s58, v250, 49
	v_readlane_b32 s59, v250, 50
	v_readlane_b32 s60, v250, 51
	v_readlane_b32 s61, v250, 52
	v_readlane_b32 s62, v250, 53
	v_readlane_b32 s63, v250, 54
	v_readlane_b32 s64, v250, 55
	v_readlane_b32 s65, v250, 56
	s_waitcnt vmcnt(30)
	ds_write2_b32 v5, v9, v11 offset1:66
	s_waitcnt vmcnt(28)
	ds_write2_b32 v5, v22, v23 offset0:132 offset1:198
	s_waitcnt vmcnt(26)
	ds_write2_b32 v48, v24, v25 offset0:8 offset1:74
	s_waitcnt vmcnt(24)
	ds_write2_b32 v48, v26, v27 offset0:140 offset1:206
	s_waitcnt vmcnt(14)
	ds_write2_b32 v49, v28, v21 offset0:16 offset1:82
	s_waitcnt vmcnt(12)
	ds_write2_b32 v49, v61, v62 offset0:148 offset1:214
	s_waitcnt vmcnt(10)
	ds_write2_b32 v50, v63, v64 offset0:24 offset1:90
	s_waitcnt vmcnt(8)
	ds_write2_b32 v50, v65, v18 offset0:156 offset1:222
	ds_write2_b32 v51, v29, v55 offset0:32 offset1:98
	ds_write2_b32 v51, v56, v57 offset0:164 offset1:230
	ds_write2_b32 v52, v58, v59 offset0:40 offset1:106
	ds_write2_b32 v52, v60, v20 offset0:172 offset1:238
	s_waitcnt vmcnt(6)
	ds_write2_b32 v53, v19, v66 offset0:48 offset1:114
	s_waitcnt vmcnt(4)
	ds_write2_b32 v53, v67, v68 offset0:180 offset1:246
	s_waitcnt vmcnt(2)
	ds_write2_b32 v54, v69, v70 offset0:56 offset1:122
	s_waitcnt vmcnt(0)
	ds_write2_b32 v54, v71, v16 offset0:188 offset1:254
	s_waitcnt lgkmcnt(0)
	ds_read2_b32 v[16:17], v31 offset1:33
	v_mov_b32_e32 v11, v7
	s_waitcnt lgkmcnt(0)
	v_cvt_pk_bf16_f32 v16, v16, v17
	ds_read2_b32 v[18:19], v31 offset0:66 offset1:99
	v_lshl_add_u64 v[24:25], s[28:29], 0, v[10:11]
	s_mov_b64 s[28:29], 0x28a8000
	s_waitcnt lgkmcnt(0)
	v_cvt_pk_bf16_f32 v17, v18, v19
	ds_read2_b32 v[18:19], v31 offset0:132 offset1:165
	v_lshlrev_b32_e32 v22, 7, v15
	v_mov_b32_e32 v23, v7
	v_lshl_add_u64 v[24:25], v[24:25], 0, s[28:29]
	s_waitcnt lgkmcnt(0)
; #define LAS __attribute__((address_space(3)))
; __device__ __forceinline__ unsigned pk2(float lo, float hi) { return pg8::cvt_pk_bf16(lo, hi); }
; __device__ __forceinline__ void lds_wait() { asm volatile("s_waitcnt lgkmcnt(0)" ::: "memory"); }
; __device__ __forceinline__ void transpose_item(const float* W, int N, bf16* WT, int K, int k0, int n0, int drow0, const float* gk, LAS float* scr, int lane) {
;     ...
;     for (int j = 0; j < 4; ++j) { const int n = (lane >> 3) + 8 * j; const LAS float* s = scr + (8 * c) * 33 + n;
;         u32x4 o; o.x = pk2(s[0 * 33], s[1 * 33]); o.y = pk2(s[2 * 33], s[3 * 33]); o.z = pk2(s[4 * 33], s[5 * 33]); o.w = pk2(s[6 * 33], s[7 * 33]);
;         *(u32x4*)(WT + (size_t)(drow0 + n) * K + k0 + 8 * c) = o; }
;     lds_wait();
	v_cvt_pk_bf16_f32 v18, v18, v19
	ds_read2_b32 v[20:21], v31 offset0:198 offset1:231
	s_waitcnt lgkmcnt(0)
	v_cvt_pk_bf16_f32 v19, v20, v21
	v_lshl_add_u64 v[22:23], v[24:25], 0, v[22:23]
	ds_read2_b32 v[20:21], v31 offset0:8 offset1:41
	global_store_dwordx4 v[22:23], v[16:19], off sc1
	v_lshlrev_b32_e32 v22, 7, v14
	v_mov_b32_e32 v23, v7
	s_waitcnt lgkmcnt(0)
	v_cvt_pk_bf16_f32 v16, v20, v21
	ds_read2_b32 v[18:19], v31 offset0:74 offset1:107
	s_waitcnt lgkmcnt(0)
	v_cvt_pk_bf16_f32 v17, v18, v19
	ds_read2_b32 v[18:19], v31 offset0:140 offset1:173
	s_waitcnt lgkmcnt(0)
	v_cvt_pk_bf16_f32 v18, v18, v19
	ds_read2_b32 v[20:21], v31 offset0:206 offset1:239
	s_waitcnt lgkmcnt(0)
	v_cvt_pk_bf16_f32 v19, v20, v21
	v_lshl_add_u64 v[22:23], v[24:25], 0, v[22:23]
	ds_read2_b32 v[20:21], v31 offset0:16 offset1:49
	global_store_dwordx4 v[22:23], v[16:19], off sc1
	v_lshlrev_b32_e32 v22, 7, v13
	v_mov_b32_e32 v23, v7
	s_waitcnt lgkmcnt(0)
	v_cvt_pk_bf16_f32 v16, v20, v21
	ds_read2_b32 v[18:19], v31 offset0:82 offset1:115
	s_waitcnt lgkmcnt(0)
	v_cvt_pk_bf16_f32 v17, v18, v19
	ds_read2_b32 v[18:19], v31 offset0:148 offset1:181
	s_waitcnt lgkmcnt(0)
	v_cvt_pk_bf16_f32 v18, v18, v19
	ds_read2_b32 v[20:21], v31 offset0:214 offset1:247
	s_waitcnt lgkmcnt(0)
	v_cvt_pk_bf16_f32 v19, v20, v21
	v_lshl_add_u64 v[22:23], v[24:25], 0, v[22:23]
	ds_read2_b32 v[20:21], v31 offset0:24 offset1:57
	global_store_dwordx4 v[22:23], v[16:19], off sc1
	v_lshlrev_b32_e32 v22, 7, v12
	v_mov_b32_e32 v23, v7
	s_waitcnt lgkmcnt(0)
	v_cvt_pk_bf16_f32 v16, v20, v21
	ds_read2_b32 v[18:19], v31 offset0:90 offset1:123
	s_waitcnt lgkmcnt(0)
	v_cvt_pk_bf16_f32 v17, v18, v19
	ds_read2_b32 v[18:19], v31 offset0:156 offset1:189
	s_waitcnt lgkmcnt(0)
	v_cvt_pk_bf16_f32 v18, v18, v19
	ds_read2_b32 v[20:21], v31 offset0:222 offset1:255
	s_waitcnt lgkmcnt(0)
	v_cvt_pk_bf16_f32 v19, v20, v21
	v_lshl_add_u64 v[20:21], v[24:25], 0, v[22:23]
	global_store_dwordx4 v[20:21], v[16:19], off sc1
	s_waitcnt lgkmcnt(0)
	s_mov_b64 s[28:29], 0
; #define LAS __attribute__((address_space(3)))
; __device__ __forceinline__ unsigned pk2(float lo, float hi) { return pg8::cvt_pk_bf16(lo, hi); }
; __device__ __forceinline__ void lds_wait() { asm volatile("s_waitcnt lgkmcnt(0)" ::: "memory"); }
; __device__ __forceinline__ void transpose_item(const float* W, int N, bf16* WT, int K, int k0, int n0, int drow0, const float* gk, LAS float* scr, int lane) {
;     float wv[32];
; #pragma unroll
;     for (int i = 0; i < 32; ++i) wv[i] = W[(size_t)(k0 + 2 * i + (lane >> 5)) * N + n0 + (lane & 31)];
; #pragma unroll
;     for (int i = 0; i < 32; ++i) { const int kk = 2 * i + (lane >> 5); float v = wv[i]; if (gk) v *= gk[kk]; scr[kk * 33 + (lane & 31)] = v; }
;     lds_wait();
;     const int c = lane & 7;
; #pragma unroll
;     for (int j = 0; j < 4; ++j) { const int n = (lane >> 3) + 8 * j; const LAS float* s = scr + (8 * c) * 33 + n;
;         u32x4 o; o.x = pk2(s[0 * 33], s[1 * 33]); o.y = pk2(s[2 * 33], s[3 * 33]); o.z = pk2(s[4 * 33], s[5 * 33]); o.w = pk2(s[6 * 33], s[7 * 33]);
;         *(u32x4*)(WT + (size_t)(drow0 + n) * K + k0 + 8 * c) = o; }
; __device__ __forceinline__ void p0_weight_item(const Args& a, int l, int r, LAS float* scr, int lane) {
;     ...
;     if (r < IT_LW) { const int blk = r >> 1, nb = r & 1; transpose_item(a.in[21] + (size_t)l * 16384 + blk * 4096, 64, (bf16*)(wl + WL_WA) + blk * 4096, 64, 0, 32 * nb, 32 * nb, nullptr, scr, lane); return; }
.LBB0_19:
	s_andn2_b64 vcc, exec, s[28:29]
	s_cbranch_vccnz .LBB0_21
	v_readlane_b32 s52, v250, 43
	v_readlane_b32 s62, v250, 53
	v_readlane_b32 s63, v250, 54
	s_add_u32 s28, s62, s4
	s_addc_u32 s29, s63, s5
	s_and_b32 s4, s31, 0x3ff000
	s_add_i32 s16, s4, 0xffc30000
	s_lshl_b64 s[4:5], s[16:17], 2
	s_add_u32 s28, s28, s4
	s_addc_u32 s29, s29, s5
	s_lshl_b64 s[4:5], s[16:17], 1
	s_add_u32 s4, s84, s4
	s_addc_u32 s5, s83, s5
	s_lshl_b32 s22, s30, 2
	s_add_u32 s28, s28, s22
	s_addc_u32 s29, s29, 0
	v_lshl_add_u64 v[16:17], s[28:29], 0, v[6:7]
	v_mov_b32_e32 v9, v7
	v_lshl_add_u64 v[16:17], v[16:17], 0, v[8:9]
	v_add_co_u32_e32 v18, vcc, s14, v16
	global_load_dword v9, v[16:17], off nt
	global_load_dword v11, v[16:17], off offset:512 nt
	global_load_dword v22, v[16:17], off offset:1024 nt
	global_load_dword v23, v[16:17], off offset:1536 nt
	global_load_dword v24, v[16:17], off offset:2048 nt
	global_load_dword v25, v[16:17], off offset:2560 nt
	global_load_dword v26, v[16:17], off offset:3072 nt
	global_load_dword v27, v[16:17], off offset:3584 nt
	v_addc_co_u32_e32 v19, vcc, 0, v17, vcc
	v_add_co_u32_e32 v20, vcc, s91, v16
	v_lshlrev_b32_e32 v14, 7, v14
	s_nop 0
	v_addc_co_u32_e32 v21, vcc, 0, v17, vcc
	v_add_co_u32_e32 v16, vcc, s92, v16
	global_load_dword v28, v[20:21], off offset:-4096 nt
	global_load_dword v29, v[20:21], off nt
	global_load_dword v55, v[20:21], off offset:512 nt
	global_load_dword v56, v[20:21], off offset:1024 nt
	global_load_dword v57, v[20:21], off offset:1536 nt
	global_load_dword v58, v[20:21], off offset:2048 nt
	global_load_dword v59, v[20:21], off offset:2560 nt
	global_load_dword v60, v[20:21], off offset:3072 nt
	s_nop 0
	global_load_dword v20, v[20:21], off offset:3584 nt
	v_addc_co_u32_e32 v17, vcc, 0, v17, vcc
	global_load_dword v21, v[18:19], off offset:512 nt
	global_load_dword v61, v[18:19], off offset:1024 nt
	global_load_dword v62, v[18:19], off offset:1536 nt
	global_load_dword v63, v[18:19], off offset:2048 nt
	global_load_dword v64, v[18:19], off offset:2560 nt
	global_load_dword v65, v[18:19], off offset:3072 nt
	s_nop 0
	global_load_dword v18, v[18:19], off offset:3584 nt
	s_nop 0
	global_load_dword v19, v[16:17], off nt
	global_load_dword v66, v[16:17], off offset:512 nt
	global_load_dword v67, v[16:17], off offset:1024 nt
	global_load_dword v68, v[16:17], off offset:1536 nt
	global_load_dword v69, v[16:17], off offset:2048 nt
	global_load_dword v70, v[16:17], off offset:2560 nt
	global_load_dword v71, v[16:17], off offset:3072 nt
	s_nop 0
	global_load_dword v16, v[16:17], off offset:3584 nt
	v_lshlrev_b32_e32 v12, 7, v12
	v_readlane_b32 s53, v250, 44
	v_readlane_b32 s54, v250, 45
	v_readlane_b32 s55, v250, 46
	v_readlane_b32 s56, v250, 47
	v_readlane_b32 s57, v250, 48
	v_readlane_b32 s58, v250, 49
	v_readlane_b32 s59, v250, 50
	v_readlane_b32 s60, v250, 51
	v_readlane_b32 s61, v250, 52
	v_readlane_b32 s64, v250, 55
	v_readlane_b32 s65, v250, 56
	v_readlane_b32 s66, v250, 57
	v_readlane_b32 s67, v250, 58
	s_waitcnt vmcnt(30)
	ds_write2_b32 v5, v9, v11 offset1:66
	s_waitcnt vmcnt(28)
	ds_write2_b32 v5, v22, v23 offset0:132 offset1:198
	s_waitcnt vmcnt(26)
	ds_write2_b32 v48, v24, v25 offset0:8 offset1:74
	s_waitcnt vmcnt(24)
	ds_write2_b32 v48, v26, v27 offset0:140 offset1:206
	s_waitcnt vmcnt(14)
	ds_write2_b32 v49, v28, v21 offset0:16 offset1:82
	s_waitcnt vmcnt(12)
	ds_write2_b32 v49, v61, v62 offset0:148 offset1:214
	s_waitcnt vmcnt(10)
	ds_write2_b32 v50, v63, v64 offset0:24 offset1:90
	s_waitcnt vmcnt(8)
	ds_write2_b32 v50, v65, v18 offset0:156 offset1:222
	ds_write2_b32 v51, v29, v55 offset0:32 offset1:98
	ds_write2_b32 v51, v56, v57 offset0:164 offset1:230
	ds_write2_b32 v52, v58, v59 offset0:40 offset1:106
	ds_write2_b32 v52, v60, v20 offset0:172 offset1:238
	s_waitcnt vmcnt(6)
	ds_write2_b32 v53, v19, v66 offset0:48 offset1:114
	s_waitcnt vmcnt(4)
	ds_write2_b32 v53, v67, v68 offset0:180 offset1:246
	s_waitcnt vmcnt(2)
	ds_write2_b32 v54, v69, v70 offset0:56 offset1:122
	s_waitcnt vmcnt(0)
	ds_write2_b32 v54, v71, v16 offset0:188 offset1:254
	s_waitcnt lgkmcnt(0)
	ds_read2_b32 v[16:17], v31 offset1:33
	v_mov_b32_e32 v11, v7
	s_waitcnt lgkmcnt(0)
	v_cvt_pk_bf16_f32 v16, v16, v17
	ds_read2_b32 v[18:19], v31 offset0:66 offset1:99
	v_lshl_add_u64 v[24:25], s[4:5], 0, v[10:11]
	s_mov_b64 s[4:5], 0x28a0000
	s_waitcnt lgkmcnt(0)
	v_cvt_pk_bf16_f32 v17, v18, v19
	ds_read2_b32 v[18:19], v31 offset0:132 offset1:165
	v_lshlrev_b32_e32 v22, 7, v15
	v_mov_b32_e32 v23, v7
	v_lshl_add_u64 v[24:25], v[24:25], 0, s[4:5]
	s_waitcnt lgkmcnt(0)
	v_cvt_pk_bf16_f32 v18, v18, v19
	ds_read2_b32 v[20:21], v31 offset0:198 offset1:231
	s_waitcnt lgkmcnt(0)
	v_cvt_pk_bf16_f32 v19, v20, v21
	v_lshl_add_u64 v[22:23], v[24:25], 0, v[22:23]
	ds_read2_b32 v[20:21], v31 offset0:8 offset1:41
	global_store_dwordx4 v[22:23], v[16:19], off sc1
	v_mov_b32_e32 v15, v7
	v_lshl_add_u64 v[14:15], v[24:25], 0, v[14:15]
	s_waitcnt lgkmcnt(0)
	v_cvt_pk_bf16_f32 v16, v20, v21
	ds_read2_b32 v[18:19], v31 offset0:74 offset1:107
	s_waitcnt lgkmcnt(0)
	v_cvt_pk_bf16_f32 v17, v18, v19
	ds_read2_b32 v[18:19], v31 offset0:140 offset1:173
	s_waitcnt lgkmcnt(0)
	v_cvt_pk_bf16_f32 v18, v18, v19
	ds_read2_b32 v[20:21], v31 offset0:206 offset1:239
	s_waitcnt lgkmcnt(0)
	v_cvt_pk_bf16_f32 v19, v20, v21
	ds_read2_b32 v[20:21], v31 offset0:16 offset1:49
	global_store_dwordx4 v[14:15], v[16:19], off sc1
	s_waitcnt lgkmcnt(0)
	v_cvt_pk_bf16_f32 v14, v20, v21
	ds_read2_b32 v[16:17], v31 offset0:82 offset1:115
	s_waitcnt lgkmcnt(0)
	v_cvt_pk_bf16_f32 v15, v16, v17
	ds_read2_b32 v[16:17], v31 offset0:148 offset1:181
	v_lshlrev_b32_e32 v20, 7, v13
	v_mov_b32_e32 v21, v7
	s_waitcnt lgkmcnt(0)
	v_cvt_pk_bf16_f32 v16, v16, v17
	ds_read2_b32 v[18:19], v31 offset0:214 offset1:247
	s_waitcnt lgkmcnt(0)
	v_cvt_pk_bf16_f32 v17, v18, v19
	v_lshl_add_u64 v[20:21], v[24:25], 0, v[20:21]
	ds_read2_b32 v[18:19], v31 offset0:24 offset1:57
	global_store_dwordx4 v[20:21], v[14:17], off sc1
	v_mov_b32_e32 v13, v7
	v_lshl_add_u64 v[12:13], v[24:25], 0, v[12:13]
	s_waitcnt lgkmcnt(0)
	v_cvt_pk_bf16_f32 v14, v18, v19
	ds_read2_b32 v[16:17], v31 offset0:90 offset1:123
	s_waitcnt lgkmcnt(0)
	v_cvt_pk_bf16_f32 v15, v16, v17
	ds_read2_b32 v[16:17], v31 offset0:156 offset1:189
	s_waitcnt lgkmcnt(0)
	v_cvt_pk_bf16_f32 v16, v16, v17
	ds_read2_b32 v[18:19], v31 offset0:222 offset1:255
	s_waitcnt lgkmcnt(0)
	v_cvt_pk_bf16_f32 v17, v18, v19
	global_store_dwordx4 v[12:13], v[14:17], off sc1
	s_waitcnt lgkmcnt(0)

; __device__ __forceinline__ void transpose_item(const float* W, int N, bf16* WT, int K, int k0, int n0, int drow0, const float* gk, LAS float* scr, int lane) {
;     float wv[32];
; #pragma unroll
;     for (int i = 0; i < 32; ++i) wv[i] = W[(size_t)(k0 + 2 * i + (lane >> 5)) * N + n0 + (lane & 31)];
; __device__ __forceinline__ void p0_weight_item(const Args& a, int l, int r, LAS float* scr, int lane) {
;     ...
;     if (r < IT_GLU) { const int kb = r / 8, nb = r % 8; transpose_item(a.in[15] + (size_t)l * 65536, 256, (bf16*)(wl + WL_GLU), 256, 64 * kb, 32 * nb, 32 * nb, nullptr, scr, lane); return; }
.LBB0_22:
	s_andn2_b64 vcc, exec, s[4:5]
	s_cbranch_vccnz .LBB0_24
	v_readlane_b32 s52, v250, 27
	s_lshl_b64 s[4:5], s[26:27], 18
	v_readlane_b32 s66, v250, 41
	v_readlane_b32 s67, v250, 42
	s_add_u32 s28, s66, s4
	s_mul_i32 s4, s26, 0xfffeba80
	s_addc_u32 s5, s67, s5
	s_add_i32 s4, s49, s4
	s_and_b32 s4, s4, 0x3fc0
	s_add_i32 s16, s4, 0xffffc400
	s_add_i32 s4, s43, 0xfffbe000
	s_and_b32 s4, s4, 0xe0
	s_lshl_b32 s29, s4, 2
	v_or_b32_e32 v12, s16, v4
	s_add_u32 s28, s28, s29
	s_addc_u32 s29, s5, 0
	v_mov_b32_e32 v13, v7
	v_or_b32_e32 v18, 2, v12
	v_mov_b32_e32 v19, v7
	v_or_b32_e32 v20, 4, v12
	v_mov_b32_e32 v21, v7
	v_or_b32_e32 v22, 6, v12
	v_mov_b32_e32 v23, v7
	v_or_b32_e32 v24, 8, v12
	v_mov_b32_e32 v25, v7
	v_or_b32_e32 v26, 10, v12
	v_mov_b32_e32 v27, v7
	v_or_b32_e32 v28, 12, v12
	v_mov_b32_e32 v29, v7
	v_or_b32_e32 v56, 14, v12
	v_mov_b32_e32 v57, v7
	v_lshl_add_u64 v[14:15], s[28:29], 0, v[6:7]
	v_lshlrev_b64 v[16:17], 10, v[12:13]
	v_lshlrev_b64 v[18:19], 10, v[18:19]
	v_lshlrev_b64 v[20:21], 10, v[20:21]
	v_lshlrev_b64 v[22:23], 10, v[22:23]
	v_lshlrev_b64 v[24:25], 10, v[24:25]
	v_lshlrev_b64 v[26:27], 10, v[26:27]
	v_lshlrev_b64 v[28:29], 10, v[28:29]
	v_lshlrev_b64 v[56:57], 10, v[56:57]
	v_lshl_add_u64 v[16:17], v[14:15], 0, v[16:17]
	v_lshl_add_u64 v[18:19], v[14:15], 0, v[18:19]
	v_lshl_add_u64 v[20:21], v[14:15], 0, v[20:21]
	v_lshl_add_u64 v[22:23], v[14:15], 0, v[22:23]
	v_lshl_add_u64 v[24:25], v[14:15], 0, v[24:25]
	v_lshl_add_u64 v[26:27], v[14:15], 0, v[26:27]
	v_lshl_add_u64 v[28:29], v[14:15], 0, v[28:29]
	v_lshl_add_u64 v[56:57], v[14:15], 0, v[56:57]
	global_load_dword v9, v[16:17], off nt
	global_load_dword v11, v[18:19], off nt
	global_load_dword v55, v[20:21], off nt
	global_load_dword v58, v[22:23], off nt
	global_load_dword v59, v[24:25], off nt
	global_load_dword v60, v[26:27], off nt
	global_load_dword v61, v[28:29], off nt
	global_load_dword v62, v[56:57], off nt
	v_or_b32_e32 v16, 16, v12
	v_mov_b32_e32 v17, v7
	v_or_b32_e32 v18, 18, v12
	v_mov_b32_e32 v19, v7
	v_or_b32_e32 v20, 20, v12
	v_mov_b32_e32 v21, v7
	v_or_b32_e32 v22, 22, v12
	v_mov_b32_e32 v23, v7
	v_or_b32_e32 v24, 24, v12
	v_mov_b32_e32 v25, v7
	v_or_b32_e32 v26, 26, v12
	v_mov_b32_e32 v27, v7
	v_or_b32_e32 v28, 28, v12
	v_mov_b32_e32 v29, v7
	v_or_b32_e32 v56, 30, v12
	v_mov_b32_e32 v57, v7
	v_lshlrev_b64 v[16:17], 10, v[16:17]
	v_lshlrev_b64 v[18:19], 10, v[18:19]
	v_lshlrev_b64 v[20:21], 10, v[20:21]
	v_lshlrev_b64 v[22:23], 10, v[22:23]
	v_lshlrev_b64 v[24:25], 10, v[24:25]
	v_lshlrev_b64 v[26:27], 10, v[26:27]
	v_lshlrev_b64 v[28:29], 10, v[28:29]
	v_lshlrev_b64 v[56:57], 10, v[56:57]
	v_lshl_add_u64 v[16:17], v[14:15], 0, v[16:17]
	v_lshl_add_u64 v[18:19], v[14:15], 0, v[18:19]
	v_lshl_add_u64 v[20:21], v[14:15], 0, v[20:21]
	v_lshl_add_u64 v[22:23], v[14:15], 0, v[22:23]
	v_lshl_add_u64 v[24:25], v[14:15], 0, v[24:25]
	v_lshl_add_u64 v[26:27], v[14:15], 0, v[26:27]
	v_lshl_add_u64 v[28:29], v[14:15], 0, v[28:29]
	v_lshl_add_u64 v[56:57], v[14:15], 0, v[56:57]
	global_load_dword v63, v[16:17], off nt
	global_load_dword v64, v[18:19], off nt
	global_load_dword v65, v[20:21], off nt
	global_load_dword v66, v[22:23], off nt
	global_load_dword v67, v[24:25], off nt
	global_load_dword v68, v[26:27], off nt
	global_load_dword v69, v[28:29], off nt
	global_load_dword v70, v[56:57], off nt
	v_or_b32_e32 v16, 32, v12
	v_mov_b32_e32 v17, v7
	v_or_b32_e32 v18, 34, v12
	v_mov_b32_e32 v19, v7
	v_or_b32_e32 v20, 36, v12
	v_mov_b32_e32 v21, v7
	v_or_b32_e32 v22, 38, v12
	v_mov_b32_e32 v23, v7
	v_or_b32_e32 v24, 40, v12
	v_mov_b32_e32 v25, v7
	v_or_b32_e32 v26, 42, v12
	v_mov_b32_e32 v27, v7
	v_or_b32_e32 v28, 44, v12
	v_mov_b32_e32 v29, v7
	v_or_b32_e32 v56, 46, v12
	v_mov_b32_e32 v57, v7
	v_lshlrev_b64 v[16:17], 10, v[16:17]
	v_lshlrev_b64 v[18:19], 10, v[18:19]
	v_lshlrev_b64 v[20:21], 10, v[20:21]
	v_lshlrev_b64 v[22:23], 10, v[22:23]
	v_lshlrev_b64 v[24:25], 10, v[24:25]
	v_lshlrev_b64 v[26:27], 10, v[26:27]
	v_lshlrev_b64 v[28:29], 10, v[28:29]
	v_lshlrev_b64 v[56:57], 10, v[56:57]
	v_lshl_add_u64 v[16:17], v[14:15], 0, v[16:17]
	v_lshl_add_u64 v[18:19], v[14:15], 0, v[18:19]
	v_lshl_add_u64 v[20:21], v[14:15], 0, v[20:21]
	v_lshl_add_u64 v[22:23], v[14:15], 0, v[22:23]
	v_lshl_add_u64 v[24:25], v[14:15], 0, v[24:25]
	v_lshl_add_u64 v[26:27], v[14:15], 0, v[26:27]
	v_lshl_add_u64 v[28:29], v[14:15], 0, v[28:29]
	v_lshl_add_u64 v[56:57], v[14:15], 0, v[56:57]
	global_load_dword v71, v[16:17], off nt
	global_load_dword v72, v[18:19], off nt
	global_load_dword v73, v[20:21], off nt
	global_load_dword v74, v[22:23], off nt
	global_load_dword v75, v[24:25], off nt
	global_load_dword v76, v[26:27], off nt
	global_load_dword v77, v[28:29], off nt
	s_nop 0
	global_load_dword v56, v[56:57], off nt
	v_or_b32_e32 v16, 48, v12
	v_mov_b32_e32 v17, v7
	v_or_b32_e32 v18, 50, v12
	v_mov_b32_e32 v19, v7
	v_or_b32_e32 v20, 52, v12
	v_mov_b32_e32 v21, v7
	v_or_b32_e32 v22, 54, v12
	v_or_b32_e32 v24, 56, v12
	v_or_b32_e32 v26, 58, v12
	v_or_b32_e32 v28, 60, v12
	v_or_b32_e32 v12, 62, v12
	v_lshlrev_b64 v[16:17], 10, v[16:17]
	v_lshlrev_b64 v[18:19], 10, v[18:19]
	v_lshlrev_b64 v[20:21], 10, v[20:21]
	v_mov_b32_e32 v23, v7
	v_mov_b32_e32 v25, v7
	v_mov_b32_e32 v27, v7
	v_mov_b32_e32 v29, v7
	v_lshlrev_b64 v[12:13], 10, v[12:13]
	v_lshl_add_u64 v[16:17], v[14:15], 0, v[16:17]
	v_lshl_add_u64 v[18:19], v[14:15], 0, v[18:19]
	v_lshl_add_u64 v[20:21], v[14:15], 0, v[20:21]
	v_lshlrev_b64 v[22:23], 10, v[22:23]
	v_lshlrev_b64 v[24:25], 10, v[24:25]
	v_lshlrev_b64 v[26:27], 10, v[26:27]
	v_lshlrev_b64 v[28:29], 10, v[28:29]
	v_lshl_add_u64 v[12:13], v[14:15], 0, v[12:13]
	v_lshl_add_u64 v[22:23], v[14:15], 0, v[22:23]
	v_lshl_add_u64 v[24:25], v[14:15], 0, v[24:25]
	v_lshl_add_u64 v[26:27], v[14:15], 0, v[26:27]
	v_lshl_add_u64 v[28:29], v[14:15], 0, v[28:29]
	global_load_dword v14, v[16:17], off nt
	global_load_dword v15, v[18:19], off nt
	s_nop 0
	global_load_dword v16, v[20:21], off nt
	global_load_dword v17, v[22:23], off nt
	global_load_dword v18, v[24:25], off nt
	global_load_dword v19, v[26:27], off nt
	s_nop 0
	global_load_dword v20, v[28:29], off nt
	s_nop 0
	global_load_dword v12, v[12:13], off nt
	s_waitcnt vmcnt(30)
; #define LAS __attribute__((address_space(3)))
; __device__ __forceinline__ unsigned pk2(float lo, float hi) { return pg8::cvt_pk_bf16(lo, hi); }
; __device__ __forceinline__ void lds_wait() { asm volatile("s_waitcnt lgkmcnt(0)" ::: "memory"); }
; __device__ __forceinline__ void transpose_item(const float* W, int N, bf16* WT, int K, int k0, int n0, int drow0, const float* gk, LAS float* scr, int lane) {
;     ...
; #pragma unroll
;     for (int i = 0; i < 32; ++i) { const int kk = 2 * i + (lane >> 5); float v = wv[i]; if (gk) v *= gk[kk]; scr[kk * 33 + (lane & 31)] = v; }
;     lds_wait();
;     const int c = lane & 7;
; #pragma unroll
;     for (int j = 0; j < 4; ++j) { const int n = (lane >> 3) + 8 * j; const LAS float* s = scr + (8 * c) * 33 + n;
;         u32x4 o; o.x = pk2(s[0 * 33], s[1 * 33]); o.y = pk2(s[2 * 33], s[3 * 33]); o.z = pk2(s[4 * 33], s[5 * 33]); o.w = pk2(s[6 * 33], s[7 * 33]);
;         *(u32x4*)(WT + (size_t)(drow0 + n) * K + k0 + 8 * c) = o; }
;     lds_wait();
; __device__ __forceinline__ void p0_weight_item(const Args& a, int l, int r, LAS float* scr, int lane) {
;     ...
;     if (r < IT_GLU) { const int kb = r / 8, nb = r % 8; transpose_item(a.in[15] + (size_t)l * 65536, 256, (bf16*)(wl + WL_GLU), 256, 64 * kb, 32 * nb, 32 * nb, nullptr, scr, lane); return; }
	ds_write2_b32 v5, v9, v11 offset1:66
	s_waitcnt vmcnt(28)
	ds_write2_b32 v5, v55, v58 offset0:132 offset1:198
	s_waitcnt vmcnt(26)
	ds_write2_b32 v48, v59, v60 offset0:8 offset1:74
	s_waitcnt vmcnt(24)
	ds_write2_b32 v48, v61, v62 offset0:140 offset1:206
	s_waitcnt vmcnt(22)
	ds_write2_b32 v49, v63, v64 offset0:16 offset1:82
	s_waitcnt vmcnt(20)
	ds_write2_b32 v49, v65, v66 offset0:148 offset1:214
	s_waitcnt vmcnt(18)
	ds_write2_b32 v50, v67, v68 offset0:24 offset1:90
	s_waitcnt vmcnt(16)
	ds_write2_b32 v50, v69, v70 offset0:156 offset1:222
	s_waitcnt vmcnt(14)
	ds_write2_b32 v51, v71, v72 offset0:32 offset1:98
	s_waitcnt vmcnt(12)
	ds_write2_b32 v51, v73, v74 offset0:164 offset1:230
	s_waitcnt vmcnt(10)
	ds_write2_b32 v52, v75, v76 offset0:40 offset1:106
	s_waitcnt vmcnt(8)
	ds_write2_b32 v52, v77, v56 offset0:172 offset1:238
	s_waitcnt vmcnt(6)
	ds_write2_b32 v53, v14, v15 offset0:48 offset1:114
	s_waitcnt vmcnt(4)
	ds_write2_b32 v53, v16, v17 offset0:180 offset1:246
	s_waitcnt vmcnt(2)
	ds_write2_b32 v54, v18, v19 offset0:56 offset1:122
	s_waitcnt vmcnt(0)
	ds_write2_b32 v54, v20, v12 offset0:188 offset1:254
	s_lshl_b64 s[28:29], s[16:17], 1
	s_waitcnt lgkmcnt(0)
	s_add_u32 s28, s84, s28
	ds_read2_b32 v[12:13], v31 offset1:33
	s_addc_u32 s29, s83, s29
	v_mov_b32_e32 v11, v7
	s_waitcnt lgkmcnt(0)
	v_cvt_pk_bf16_f32 v12, v12, v13
	ds_read2_b32 v[14:15], v31 offset0:66 offset1:99
	v_lshl_add_u64 v[18:19], s[28:29], 0, v[10:11]
	s_mov_b64 s[28:29], 0x2880000
	v_or_b32_e32 v9, s4, v30
	s_waitcnt lgkmcnt(0)
	v_cvt_pk_bf16_f32 v13, v14, v15
	ds_read2_b32 v[14:15], v31 offset0:132 offset1:165
	v_lshl_add_u64 v[18:19], v[18:19], 0, s[28:29]
	v_lshlrev_b32_e32 v20, 9, v9
	v_mov_b32_e32 v21, v7
	s_waitcnt lgkmcnt(0)
	v_cvt_pk_bf16_f32 v14, v14, v15
	ds_read2_b32 v[16:17], v31 offset0:198 offset1:231
	s_waitcnt lgkmcnt(0)
	v_cvt_pk_bf16_f32 v15, v16, v17
	v_lshl_add_u64 v[20:21], v[18:19], 0, v[20:21]
	ds_read2_b32 v[16:17], v31 offset0:8 offset1:41
	global_store_dwordx4 v[20:21], v[12:15], off sc1
	v_or_b32_e32 v9, s4, v32
	v_lshlrev_b32_e32 v20, 9, v9
	s_waitcnt lgkmcnt(0)
	v_cvt_pk_bf16_f32 v12, v16, v17
	ds_read2_b32 v[14:15], v31 offset0:74 offset1:107
	s_waitcnt lgkmcnt(0)
	v_cvt_pk_bf16_f32 v13, v14, v15
	ds_read2_b32 v[14:15], v31 offset0:140 offset1:173
	v_mov_b32_e32 v21, v7
	s_waitcnt lgkmcnt(0)
	v_cvt_pk_bf16_f32 v14, v14, v15
	ds_read2_b32 v[16:17], v31 offset0:206 offset1:239
	s_waitcnt lgkmcnt(0)
	v_cvt_pk_bf16_f32 v15, v16, v17
	v_lshl_add_u64 v[20:21], v[18:19], 0, v[20:21]
	ds_read2_b32 v[16:17], v31 offset0:16 offset1:49
	global_store_dwordx4 v[20:21], v[12:15], off sc1
	v_or_b32_e32 v9, s4, v33
	v_lshlrev_b32_e32 v20, 9, v9
	s_waitcnt lgkmcnt(0)
	v_cvt_pk_bf16_f32 v12, v16, v17
	ds_read2_b32 v[14:15], v31 offset0:82 offset1:115
	s_waitcnt lgkmcnt(0)
	v_cvt_pk_bf16_f32 v13, v14, v15
	ds_read2_b32 v[14:15], v31 offset0:148 offset1:181
	v_mov_b32_e32 v21, v7
	s_waitcnt lgkmcnt(0)
	v_cvt_pk_bf16_f32 v14, v14, v15
	ds_read2_b32 v[16:17], v31 offset0:214 offset1:247
	s_waitcnt lgkmcnt(0)
	v_cvt_pk_bf16_f32 v15, v16, v17
	v_lshl_add_u64 v[20:21], v[18:19], 0, v[20:21]
	ds_read2_b32 v[16:17], v31 offset0:24 offset1:57
	global_store_dwordx4 v[20:21], v[12:15], off sc1
	v_or_b32_e32 v9, s4, v34
	v_readlane_b32 s53, v250, 28
	s_waitcnt lgkmcnt(0)
	v_cvt_pk_bf16_f32 v12, v16, v17
	ds_read2_b32 v[14:15], v31 offset0:90 offset1:123
	s_waitcnt lgkmcnt(0)
	v_cvt_pk_bf16_f32 v13, v14, v15
	ds_read2_b32 v[14:15], v31 offset0:156 offset1:189
	s_waitcnt lgkmcnt(0)
	v_cvt_pk_bf16_f32 v14, v14, v15
	ds_read2_b32 v[16:17], v31 offset0:222 offset1:255
	s_waitcnt lgkmcnt(0)
	v_cvt_pk_bf16_f32 v15, v16, v17
	v_lshlrev_b32_e32 v16, 9, v9
	v_mov_b32_e32 v17, v7
	v_lshl_add_u64 v[16:17], v[18:19], 0, v[16:17]
	global_store_dwordx4 v[16:17], v[12:15], off sc1
	s_waitcnt lgkmcnt(0)
	v_readlane_b32 s54, v250, 29
	v_readlane_b32 s55, v250, 30
	v_readlane_b32 s56, v250, 31
	v_readlane_b32 s57, v250, 32
	v_readlane_b32 s58, v250, 33
	v_readlane_b32 s59, v250, 34
	v_readlane_b32 s60, v250, 35
	v_readlane_b32 s61, v250, 36
	v_readlane_b32 s62, v250, 37
	v_readlane_b32 s63, v250, 38
	v_readlane_b32 s64, v250, 39
	v_readlane_b32 s65, v250, 40

; __device__ __forceinline__ void transpose_item(const float* W, int N, bf16* WT, int K, int k0, int n0, int drow0, const float* gk, LAS float* scr, int lane) {
;     float wv[32];
; #pragma unroll
;     for (int i = 0; i < 32; ++i) wv[i] = W[(size_t)(k0 + 2 * i + (lane >> 5)) * N + n0 + (lane & 31)];
; __device__ __forceinline__ void p0_weight_item(const Args& a, int l, int r, LAS float* scr, int lane) {
;     ...
;     if (r < IT_OUT) {
;         const int kb = r / 32, nb = r % 32, k0 = 64 * kb;
;         const float* gk = (k0 < 256) ? a.in[17] + (size_t)l * 256 + k0 : (k0 < 768 ? a.in[18] + (size_t)l * 512 + (k0 - 256) : a.in[26] + (size_t)l * 256 + (k0 - 768));
;         transpose_item(a.in[27] + (size_t)l * DM * DM, DM, (bf16*)(wl + WL_WOUT), DM, k0, 32 * nb, 32 * nb, gk, scr, lane); return; }
.LBB0_34:
	v_readlane_b32 s52, v250, 59
	s_lshl_b64 s[4:5], s[26:27], 22
	v_readlane_b32 s58, v251, 1
	v_readlane_b32 s59, v251, 2
	s_add_u32 s4, s58, s4
	s_addc_u32 s5, s59, s5
	s_lshl_b32 s27, s26, 9
	s_sub_i32 s27, s43, s27
	s_add_i32 s27, s27, 0xfffbe000
	s_and_b32 s27, s27, 0x3e0
	s_lshl_b32 s30, s27, 2
	v_or_b32_e32 v12, s16, v4
	s_add_u32 s4, s4, s30
	s_addc_u32 s5, s5, 0
	v_or_b32_e32 v26, 10, v12
	v_mov_b32_e32 v27, v7
	v_lshl_add_u64 v[14:15], s[4:5], 0, v[6:7]
	v_lshlrev_b64 v[26:27], 12, v[26:27]
	v_lshl_add_u64 v[28:29], v[14:15], 0, v[26:27]
	v_or_b32_e32 v26, 12, v12
	v_mov_b32_e32 v27, v7
	v_mov_b32_e32 v13, v7
	v_or_b32_e32 v22, 6, v12
	v_mov_b32_e32 v23, v7
	v_or_b32_e32 v24, 8, v12
	v_mov_b32_e32 v25, v7
	v_lshlrev_b64 v[26:27], 12, v[26:27]
	v_lshlrev_b64 v[16:17], 12, v[12:13]
	v_or_b32_e32 v18, 2, v12
	v_mov_b32_e32 v19, v7
	v_or_b32_e32 v20, 4, v12
	v_mov_b32_e32 v21, v7
	v_lshlrev_b64 v[22:23], 12, v[22:23]
	v_lshlrev_b64 v[24:25], 12, v[24:25]
	v_lshl_add_u64 v[56:57], v[14:15], 0, v[26:27]
	v_or_b32_e32 v26, 14, v12
	v_mov_b32_e32 v27, v7
	v_lshl_add_u64 v[16:17], v[14:15], 0, v[16:17]
	v_lshlrev_b64 v[18:19], 12, v[18:19]
	v_lshlrev_b64 v[20:21], 12, v[20:21]
	v_lshl_add_u64 v[22:23], v[14:15], 0, v[22:23]
	v_lshl_add_u64 v[24:25], v[14:15], 0, v[24:25]
	v_lshlrev_b64 v[26:27], 12, v[26:27]
	v_lshl_add_u64 v[18:19], v[14:15], 0, v[18:19]
	v_lshl_add_u64 v[20:21], v[14:15], 0, v[20:21]
	v_lshl_add_u64 v[58:59], v[14:15], 0, v[26:27]
	global_load_dword v68, v[16:17], off nt
	global_load_dword v67, v[18:19], off nt
	global_load_dword v26, v[20:21], off nt
	global_load_dword v27, v[22:23], off nt
	global_load_dword v65, v[24:25], off nt
	global_load_dword v66, v[28:29], off nt
	s_nop 0
	global_load_dword v24, v[56:57], off nt
	global_load_dword v25, v[58:59], off nt
	v_or_b32_e32 v22, 22, v12
	v_mov_b32_e32 v23, v7
	v_lshlrev_b64 v[22:23], 12, v[22:23]
	v_lshl_add_u64 v[28:29], v[14:15], 0, v[22:23]
	v_or_b32_e32 v22, 24, v12
	v_mov_b32_e32 v23, v7
	v_lshlrev_b64 v[22:23], 12, v[22:23]
	v_lshl_add_u64 v[56:57], v[14:15], 0, v[22:23]
	v_or_b32_e32 v22, 26, v12
	v_mov_b32_e32 v23, v7
	v_lshlrev_b64 v[22:23], 12, v[22:23]
	v_lshl_add_u64 v[58:59], v[14:15], 0, v[22:23]
	v_or_b32_e32 v22, 28, v12
	v_mov_b32_e32 v23, v7
	v_or_b32_e32 v16, 16, v12
	v_mov_b32_e32 v17, v7
	v_or_b32_e32 v20, 20, v12
	v_mov_b32_e32 v21, v7
	v_lshlrev_b64 v[22:23], 12, v[22:23]
	v_lshlrev_b64 v[16:17], 12, v[16:17]
	v_or_b32_e32 v18, 18, v12
	v_mov_b32_e32 v19, v7
	v_lshlrev_b64 v[20:21], 12, v[20:21]
	v_lshl_add_u64 v[70:71], v[14:15], 0, v[22:23]
	v_or_b32_e32 v22, 30, v12
	v_mov_b32_e32 v23, v7
	v_lshl_add_u64 v[16:17], v[14:15], 0, v[16:17]
	v_lshlrev_b64 v[18:19], 12, v[18:19]
	v_lshl_add_u64 v[20:21], v[14:15], 0, v[20:21]
	v_lshlrev_b64 v[22:23], 12, v[22:23]
	v_lshl_add_u64 v[18:19], v[14:15], 0, v[18:19]
	v_lshl_add_u64 v[72:73], v[14:15], 0, v[22:23]
	global_load_dword v63, v[16:17], off nt
	global_load_dword v64, v[18:19], off nt
	global_load_dword v22, v[20:21], off nt
	global_load_dword v23, v[28:29], off nt
	global_load_dword v61, v[56:57], off nt
	global_load_dword v62, v[58:59], off nt
	s_nop 0
	global_load_dword v20, v[70:71], off nt
	global_load_dword v21, v[72:73], off nt
	v_or_b32_e32 v58, 40, v12
	v_mov_b32_e32 v59, v7
	v_lshlrev_b64 v[58:59], 12, v[58:59]
	v_lshl_add_u64 v[70:71], v[14:15], 0, v[58:59]
	v_or_b32_e32 v58, 42, v12
	v_mov_b32_e32 v59, v7
	v_lshlrev_b64 v[58:59], 12, v[58:59]
	v_lshl_add_u64 v[72:73], v[14:15], 0, v[58:59]
	v_or_b32_e32 v58, 44, v12
	v_mov_b32_e32 v59, v7
	v_or_b32_e32 v16, 32, v12
	v_mov_b32_e32 v17, v7
	v_or_b32_e32 v18, 34, v12
	v_mov_b32_e32 v19, v7
	v_or_b32_e32 v28, 36, v12
	v_mov_b32_e32 v29, v7
	v_or_b32_e32 v56, 38, v12
	v_mov_b32_e32 v57, v7
	v_lshlrev_b64 v[58:59], 12, v[58:59]
	v_lshlrev_b64 v[16:17], 12, v[16:17]
	v_lshlrev_b64 v[18:19], 12, v[18:19]
	v_lshlrev_b64 v[28:29], 12, v[28:29]
	v_lshlrev_b64 v[56:57], 12, v[56:57]
	v_lshl_add_u64 v[74:75], v[14:15], 0, v[58:59]
	v_or_b32_e32 v58, 46, v12
	v_mov_b32_e32 v59, v7
	v_lshl_add_u64 v[16:17], v[14:15], 0, v[16:17]
	v_lshl_add_u64 v[18:19], v[14:15], 0, v[18:19]
	v_lshl_add_u64 v[28:29], v[14:15], 0, v[28:29]
	v_lshl_add_u64 v[56:57], v[14:15], 0, v[56:57]
	v_lshlrev_b64 v[58:59], 12, v[58:59]
	v_lshl_add_u64 v[76:77], v[14:15], 0, v[58:59]
	global_load_dword v59, v[16:17], off nt
	global_load_dword v60, v[18:19], off nt
	s_nop 0
	global_load_dword v18, v[28:29], off nt
	global_load_dword v19, v[56:57], off nt
	s_nop 0
	global_load_dword v57, v[70:71], off nt
	global_load_dword v58, v[72:73], off nt
	global_load_dword v16, v[74:75], off nt
	global_load_dword v17, v[76:77], off nt
	v_or_b32_e32 v28, 48, v12
	v_mov_b32_e32 v29, v7
	v_lshlrev_b64 v[28:29], 12, v[28:29]
	v_or_b32_e32 v70, 50, v12
	v_mov_b32_e32 v71, v7
	v_or_b32_e32 v72, 52, v12
	v_mov_b32_e32 v73, v7
	v_or_b32_e32 v74, 54, v12
	v_mov_b32_e32 v75, v7
	v_or_b32_e32 v76, 56, v12
	v_mov_b32_e32 v77, v7
	v_or_b32_e32 v78, 58, v12
	v_mov_b32_e32 v79, v7
	v_or_b32_e32 v80, 60, v12
	v_mov_b32_e32 v81, v7
	v_or_b32_e32 v12, 62, v12
	v_lshl_add_u64 v[28:29], v[14:15], 0, v[28:29]
	v_lshlrev_b64 v[70:71], 12, v[70:71]
	v_lshlrev_b64 v[72:73], 12, v[72:73]
	v_lshlrev_b64 v[74:75], 12, v[74:75]
	v_lshlrev_b64 v[76:77], 12, v[76:77]
	v_lshlrev_b64 v[78:79], 12, v[78:79]
	v_lshlrev_b64 v[80:81], 12, v[80:81]
	v_lshlrev_b64 v[12:13], 12, v[12:13]
	v_lshl_add_u64 v[70:71], v[14:15], 0, v[70:71]
	v_lshl_add_u64 v[72:73], v[14:15], 0, v[72:73]
	v_lshl_add_u64 v[74:75], v[14:15], 0, v[74:75]
	v_lshl_add_u64 v[76:77], v[14:15], 0, v[76:77]
	v_lshl_add_u64 v[78:79], v[14:15], 0, v[78:79]
	v_lshl_add_u64 v[80:81], v[14:15], 0, v[80:81]
	v_lshl_add_u64 v[82:83], v[14:15], 0, v[12:13]
	global_load_dword v55, v[28:29], off nt
	global_load_dword v56, v[70:71], off nt
	global_load_dword v14, v[72:73], off nt
	global_load_dword v15, v[74:75], off nt
	global_load_dword v9, v[76:77], off nt
	global_load_dword v11, v[78:79], off nt
	global_load_dword v12, v[80:81], off nt
	global_load_dword v13, v[82:83], off nt
	s_cmp_lg_u64 s[28:29], 0
	s_cselect_b64 s[30:31], -1, 0
	s_cmp_eq_u64 s[28:29], 0
	v_readlane_b32 s53, v250, 60
	v_readlane_b32 s54, v250, 61
	v_readlane_b32 s55, v250, 62
	v_readlane_b32 s56, v250, 63
	v_readlane_b32 s57, v251, 0
	v_readlane_b32 s60, v251, 3
	v_readlane_b32 s61, v251, 4
	v_readlane_b32 s62, v251, 5
	v_readlane_b32 s63, v251, 6
	v_readlane_b32 s64, v251, 7
	v_readlane_b32 s65, v251, 8
	v_readlane_b32 s66, v251, 9
	v_readlane_b32 s67, v251, 10
	s_cbranch_scc1 .LBB0_170
; __device__ __forceinline__ void transpose_item(const float* W, int N, bf16* WT, int K, int k0, int n0, int drow0, const float* gk, LAS float* scr, int lane) {
;     ...
;     for (int i = 0; i < 32; ++i) { const int kk = 2 * i + (lane >> 5); float v = wv[i]; if (gk) v *= gk[kk]; scr[kk * 33 + (lane & 31)] = v; }
	v_lshlrev_b32_e32 v29, 2, v4
	s_waitcnt vmcnt(32)
	global_load_dword v204, v29, s[28:29]
	global_load_dword v205, v29, s[28:29] offset:8
	global_load_dword v206, v29, s[28:29] offset:16
	global_load_dword v207, v29, s[28:29] offset:24
	global_load_dword v208, v29, s[28:29] offset:32
	global_load_dword v209, v29, s[28:29] offset:40
	global_load_dword v210, v29, s[28:29] offset:48
	global_load_dword v211, v29, s[28:29] offset:56
	global_load_dword v212, v29, s[28:29] offset:64
	global_load_dword v213, v29, s[28:29] offset:72
	global_load_dword v214, v29, s[28:29] offset:80
	global_load_dword v215, v29, s[28:29] offset:88
	global_load_dword v216, v29, s[28:29] offset:96
	global_load_dword v217, v29, s[28:29] offset:104
	global_load_dword v218, v29, s[28:29] offset:112
	global_load_dword v219, v29, s[28:29] offset:120
	global_load_dword v220, v29, s[28:29] offset:128
	global_load_dword v221, v29, s[28:29] offset:136
	global_load_dword v222, v29, s[28:29] offset:144
	global_load_dword v223, v29, s[28:29] offset:152
	global_load_dword v224, v29, s[28:29] offset:160
	global_load_dword v225, v29, s[28:29] offset:168
	global_load_dword v226, v29, s[28:29] offset:176
	global_load_dword v227, v29, s[28:29] offset:184
	global_load_dword v228, v29, s[28:29] offset:192
	global_load_dword v229, v29, s[28:29] offset:200
	global_load_dword v230, v29, s[28:29] offset:208
	global_load_dword v231, v29, s[28:29] offset:216
	global_load_dword v232, v29, s[28:29] offset:224
	global_load_dword v233, v29, s[28:29] offset:232
	global_load_dword v234, v29, s[28:29] offset:240
	s_waitcnt vmcnt(62)
	global_load_dword v235, v29, s[28:29] offset:248
	s_waitcnt vmcnt(0)
	v_mov_b32_e32 v69, v204
	v_mov_b32_e32 v70, v205
	v_mov_b32_e32 v28, v206
	s_nop 0
	v_mov_b32_e32 v29, v207
	v_add_u32_e32 v71, v3, v35
	s_waitcnt vmcnt(3)
	v_mul_f32_e32 v69, v68, v69
	s_waitcnt vmcnt(2)
	v_mul_f32_e32 v70, v67, v70
	ds_write_b32 v5, v69
	ds_write_b32 v71, v70
	s_waitcnt vmcnt(0)
	v_pk_mul_f32 v[28:29], v[26:27], v[28:29]
	s_cbranch_execnz .LBB0_37

; #define LAS __attribute__((address_space(3)))
; __device__ __forceinline__ unsigned pk2(float lo, float hi) { return pg8::cvt_pk_bf16(lo, hi); }
; __device__ __forceinline__ void lds_wait() { asm volatile("s_waitcnt lgkmcnt(0)" ::: "memory"); }
; __device__ __forceinline__ void transpose_item(const float* W, int N, bf16* WT, int K, int k0, int n0, int drow0, const float* gk, LAS float* scr, int lane) {
;     ...
;     const int c = lane & 7;
; #pragma unroll
;     for (int j = 0; j < 4; ++j) { const int n = (lane >> 3) + 8 * j; const LAS float* s = scr + (8 * c) * 33 + n;
;         u32x4 o; o.x = pk2(s[0 * 33], s[1 * 33]); o.y = pk2(s[2 * 33], s[3 * 33]); o.z = pk2(s[4 * 33], s[5 * 33]); o.w = pk2(s[6 * 33], s[7 * 33]);
;         *(u32x4*)(WT + (size_t)(drow0 + n) * K + k0 + 8 * c) = o; }
;     lds_wait();
.LBB0_58:
	s_waitcnt vmcnt(4)
	ds_write2_b32 v16, v14, v15 offset0:140 offset1:206
	s_lshl_b64 s[4:5], s[16:17], 1
	s_waitcnt lgkmcnt(0)
	s_add_u32 s4, s84, s4
	s_waitcnt vmcnt(0)
	ds_read2_b32 v[12:13], v31 offset1:33
	v_mov_b32_e32 v11, v7
	s_addc_u32 s5, s83, s5
	s_waitcnt lgkmcnt(0)
	v_cvt_pk_bf16_f32 v12, v12, v13
	ds_read2_b32 v[14:15], v31 offset0:66 offset1:99
	v_or_b32_e32 v9, s27, v30
	v_lshl_add_u64 v[20:21], s[4:5], 0, v[10:11]
	s_mov_b64 s[4:5], 0x1600000
	s_waitcnt lgkmcnt(0)
	v_cvt_pk_bf16_f32 v13, v14, v15
	ds_read2_b32 v[14:15], v31 offset0:132 offset1:165
	v_mov_b32_e32 v19, v7
	v_lshlrev_b32_e32 v18, 11, v9
	v_lshl_add_u64 v[20:21], v[20:21], 0, s[4:5]
	s_waitcnt lgkmcnt(0)
	v_cvt_pk_bf16_f32 v14, v14, v15
	ds_read2_b32 v[16:17], v31 offset0:198 offset1:231
	s_waitcnt lgkmcnt(0)
	v_cvt_pk_bf16_f32 v15, v16, v17
	v_lshl_add_u64 v[18:19], v[20:21], 0, v[18:19]
	ds_read2_b32 v[16:17], v31 offset0:8 offset1:41
	global_store_dwordx4 v[18:19], v[12:15], off sc1
	v_or_b32_e32 v9, s27, v32
	v_mov_b32_e32 v19, v7
	s_waitcnt lgkmcnt(0)
	v_cvt_pk_bf16_f32 v12, v16, v17
	ds_read2_b32 v[14:15], v31 offset0:74 offset1:107
	s_waitcnt lgkmcnt(0)
	v_cvt_pk_bf16_f32 v13, v14, v15
	ds_read2_b32 v[14:15], v31 offset0:140 offset1:173
	v_lshlrev_b32_e32 v18, 11, v9
	s_waitcnt lgkmcnt(0)
	v_cvt_pk_bf16_f32 v14, v14, v15
	ds_read2_b32 v[16:17], v31 offset0:206 offset1:239
	s_waitcnt lgkmcnt(0)
	v_cvt_pk_bf16_f32 v15, v16, v17
	v_lshl_add_u64 v[18:19], v[20:21], 0, v[18:19]
	ds_read2_b32 v[16:17], v31 offset0:16 offset1:49
	global_store_dwordx4 v[18:19], v[12:15], off sc1
	v_or_b32_e32 v9, s27, v33
	v_mov_b32_e32 v19, v7
	s_waitcnt lgkmcnt(0)
	v_cvt_pk_bf16_f32 v12, v16, v17
	ds_read2_b32 v[14:15], v31 offset0:82 offset1:115
	s_waitcnt lgkmcnt(0)
	v_cvt_pk_bf16_f32 v13, v14, v15
	ds_read2_b32 v[14:15], v31 offset0:148 offset1:181
	v_lshlrev_b32_e32 v18, 11, v9
	s_waitcnt lgkmcnt(0)
	v_cvt_pk_bf16_f32 v14, v14, v15
	ds_read2_b32 v[16:17], v31 offset0:214 offset1:247
	s_waitcnt lgkmcnt(0)
	v_cvt_pk_bf16_f32 v15, v16, v17
	v_lshl_add_u64 v[18:19], v[20:21], 0, v[18:19]
	ds_read2_b32 v[16:17], v31 offset0:24 offset1:57
	global_store_dwordx4 v[18:19], v[12:15], off sc1
	v_or_b32_e32 v9, s27, v34
	v_mov_b32_e32 v19, v7
	s_waitcnt lgkmcnt(0)
	v_cvt_pk_bf16_f32 v12, v16, v17
	ds_read2_b32 v[14:15], v31 offset0:90 offset1:123
	s_waitcnt lgkmcnt(0)
	v_cvt_pk_bf16_f32 v13, v14, v15
	ds_read2_b32 v[14:15], v31 offset0:156 offset1:189
	s_waitcnt lgkmcnt(0)
	v_cvt_pk_bf16_f32 v14, v14, v15
	ds_read2_b32 v[16:17], v31 offset0:222 offset1:255
	v_lshlrev_b32_e32 v18, 11, v9
	s_waitcnt lgkmcnt(0)
	v_cvt_pk_bf16_f32 v15, v16, v17
	v_lshl_add_u64 v[16:17], v[20:21], 0, v[18:19]
	global_store_dwordx4 v[16:17], v[12:15], off sc1
	s_waitcnt lgkmcnt(0)

; #define LAS __attribute__((address_space(3)))
; __device__ __forceinline__ void transpose_item(const float* W, int N, bf16* WT, int K, int k0, int n0, int drow0, const float* gk, LAS float* scr, int lane) {
;     float wv[32];
; #pragma unroll
;     for (int i = 0; i < 32; ++i) wv[i] = W[(size_t)(k0 + 2 * i + (lane >> 5)) * N + n0 + (lane & 31)];
; __device__ __forceinline__ void p0_weight_item(const Args& a, int l, int r, LAS float* scr, int lane) {
;     ...
;     if (r < IT_BIG) {
;         const int kb = r / 88, nb = r % 88, k0 = 64 * kb, n0 = 32 * nb; const int tile = n0 >> 8, c0 = n0 & 255;
;         int drow = n0;
;         if (tile >= 1 && tile <= 4) { const int hh = c0 >> 7, d0 = c0 & 127, bj = d0 >> 6, dd0 = d0 & 63; drow = tile * 256 + bj * 128 + hh * 64 + dd0; }
;         transpose_item(a.in[6] + (size_t)l * DM * IW, IW, (bf16*)(wl + WL_WIN), DM, k0, n0, drow, a.in[5] + (size_t)l * DM + k0, scr, lane); return; }
.LBB0_63:
	v_readlane_b32 s52, v250, 11
	s_lshl_b32 s5, s5, 6
	v_readlane_b32 s64, v250, 23
	v_readlane_b32 s65, v250, 24
	s_add_u32 s30, s64, s86
	v_readlane_b32 s62, v250, 21
	s_addc_u32 s31, s65, s85
	v_readlane_b32 s63, v250, 22
	s_add_u32 s28, s62, s24
	s_addc_u32 s29, s63, s25
	s_and_b32 s27, s5, 0xffc0
	s_lshl_b32 s5, s27, 2
	s_add_u32 s28, s28, s5
	s_addc_u32 s29, s29, 0
	s_lshl_b32 s4, s4, 2
	s_add_u32 s4, s30, s4
	v_or_b32_e32 v9, s27, v4
	s_addc_u32 s5, s31, 0
	v_lshl_add_u64 v[12:13], s[4:5], 0, v[6:7]
	v_mul_u32_u24_e32 v14, 0x2c00, v9
	v_mov_b32_e32 v15, v7
	v_lshl_add_u64 v[12:13], v[12:13], 0, v[14:15]
	v_add_co_u32_e32 v14, vcc, s93, v12
	v_readlane_b32 s12, v251, 20
	s_nop 0
	v_addc_co_u32_e32 v15, vcc, 0, v13, vcc
	v_add_co_u32_e32 v16, vcc, s94, v12
	v_readlane_b32 s13, v251, 21
	s_nop 0
	v_addc_co_u32_e32 v17, vcc, 0, v13, vcc
	v_add_co_u32_e32 v18, vcc, s95, v12
	v_readlane_b32 s53, v250, 12
	s_nop 0
	v_addc_co_u32_e32 v19, vcc, 0, v13, vcc
	v_add_co_u32_e32 v20, vcc, s96, v12
	v_readlane_b32 s54, v250, 13
	s_nop 0
	v_addc_co_u32_e32 v21, vcc, 0, v13, vcc
	v_add_co_u32_e32 v22, vcc, s97, v12
	v_readlane_b32 s55, v250, 14
	s_nop 0
	v_addc_co_u32_e32 v23, vcc, 0, v13, vcc
	v_add_co_u32_e32 v24, vcc, s51, v12
	v_readlane_b32 s56, v250, 15
	s_nop 0
	v_addc_co_u32_e32 v25, vcc, 0, v13, vcc
	v_add_co_u32_e32 v28, vcc, s2, v12
	v_readlane_b32 s57, v250, 16
	s_nop 0
	v_addc_co_u32_e32 v29, vcc, 0, v13, vcc
	global_load_dword v68, v[12:13], off nt
	global_load_dword v67, v[14:15], off offset:2048 nt
	global_load_dword v26, v[16:17], off nt
	global_load_dword v27, v[18:19], off offset:2048 nt
	global_load_dword v65, v[20:21], off nt
	global_load_dword v66, v[22:23], off offset:2048 nt
	s_nop 0
	global_load_dword v24, v[24:25], off nt
	s_nop 0
	global_load_dword v25, v[28:29], off offset:2048 nt
	v_add_co_u32_e32 v14, vcc, s6, v12
	v_readlane_b32 s58, v250, 17
	s_nop 0
	v_addc_co_u32_e32 v15, vcc, 0, v13, vcc
	v_add_co_u32_e32 v16, vcc, s7, v12
	v_readlane_b32 s59, v250, 18
	s_nop 0
	v_addc_co_u32_e32 v17, vcc, 0, v13, vcc
	v_add_co_u32_e32 v18, vcc, s20, v12
	v_readlane_b32 s60, v250, 19
	s_nop 0
	v_addc_co_u32_e32 v19, vcc, 0, v13, vcc
	v_add_co_u32_e32 v20, vcc, s21, v12
	v_readlane_b32 s61, v250, 20
	s_nop 0
	v_addc_co_u32_e32 v21, vcc, 0, v13, vcc
	v_add_co_u32_e32 v28, vcc, s23, v12
	v_readlane_b32 s66, v250, 25
	s_nop 0
	v_addc_co_u32_e32 v29, vcc, 0, v13, vcc
	v_add_co_u32_e32 v56, vcc, s36, v12
	v_readlane_b32 s67, v250, 26
	s_nop 0
	v_addc_co_u32_e32 v57, vcc, 0, v13, vcc
	v_add_co_u32_e32 v58, vcc, s37, v12
	s_nop 1
	v_addc_co_u32_e32 v59, vcc, 0, v13, vcc
	v_add_co_u32_e32 v70, vcc, s68, v12
	s_nop 1
	v_addc_co_u32_e32 v71, vcc, 0, v13, vcc
	global_load_dword v63, v[14:15], off nt
	global_load_dword v64, v[16:17], off offset:2048 nt
	global_load_dword v22, v[18:19], off nt
	global_load_dword v23, v[20:21], off offset:2048 nt
	global_load_dword v61, v[28:29], off nt
	global_load_dword v62, v[56:57], off offset:2048 nt
	s_nop 0
	global_load_dword v20, v[58:59], off nt
	global_load_dword v21, v[70:71], off offset:2048 nt
	v_add_co_u32_e32 v14, vcc, s69, v12
	s_nop 1
	v_addc_co_u32_e32 v15, vcc, 0, v13, vcc
	v_add_co_u32_e32 v16, vcc, s70, v12
	s_nop 1
	v_addc_co_u32_e32 v17, vcc, 0, v13, vcc
	v_add_co_u32_e32 v18, vcc, s71, v12
	s_nop 1
	v_addc_co_u32_e32 v19, vcc, 0, v13, vcc
	v_add_co_u32_e32 v28, vcc, s72, v12
	s_nop 1
	v_addc_co_u32_e32 v29, vcc, 0, v13, vcc
	v_add_co_u32_e32 v56, vcc, s73, v12
	s_nop 1
	v_addc_co_u32_e32 v57, vcc, 0, v13, vcc
	v_add_co_u32_e32 v70, vcc, s74, v12
	s_nop 1
	v_addc_co_u32_e32 v71, vcc, 0, v13, vcc
	v_add_co_u32_e32 v72, vcc, s75, v12
	s_nop 1
	v_addc_co_u32_e32 v73, vcc, 0, v13, vcc
	v_add_co_u32_e32 v74, vcc, s76, v12
	s_nop 1
	v_addc_co_u32_e32 v75, vcc, 0, v13, vcc
	global_load_dword v59, v[14:15], off nt
	global_load_dword v60, v[16:17], off offset:2048 nt
	s_nop 0
	global_load_dword v18, v[18:19], off nt
	s_nop 0
	global_load_dword v19, v[28:29], off offset:2048 nt
	global_load_dword v55, v[56:57], off nt
	s_nop 0
	global_load_dword v57, v[70:71], off offset:2048 nt
	global_load_dword v16, v[72:73], off nt
	global_load_dword v17, v[74:75], off offset:2048 nt
	v_add_co_u32_e32 v14, vcc, s77, v12
	s_nop 1
	v_addc_co_u32_e32 v15, vcc, 0, v13, vcc
	v_add_co_u32_e32 v28, vcc, s78, v12
	s_nop 1
	v_addc_co_u32_e32 v29, vcc, 0, v13, vcc
	v_add_co_u32_e32 v70, vcc, s79, v12
	s_nop 1
	v_addc_co_u32_e32 v71, vcc, 0, v13, vcc
	v_add_co_u32_e32 v72, vcc, s80, v12
	s_nop 1
	v_addc_co_u32_e32 v73, vcc, 0, v13, vcc
	v_add_co_u32_e32 v74, vcc, s81, v12
	s_nop 1
	v_addc_co_u32_e32 v75, vcc, 0, v13, vcc
	v_add_co_u32_e32 v76, vcc, 0x9f000, v12
	s_nop 1
	v_addc_co_u32_e32 v77, vcc, 0, v13, vcc
	v_add_co_u32_e32 v78, vcc, 0xa5000, v12
	s_nop 1
	v_addc_co_u32_e32 v79, vcc, 0, v13, vcc
	v_add_co_u32_e32 v80, vcc, 0xaa000, v12
	s_nop 1
	v_addc_co_u32_e32 v81, vcc, 0, v13, vcc
	global_load_dword v56, v[14:15], off nt
	global_load_dword v58, v[28:29], off offset:2048 nt
	s_nop 0
	global_load_dword v14, v[70:71], off nt
	global_load_dword v15, v[72:73], off offset:2048 nt
	global_load_dword v9, v[74:75], off nt
	global_load_dword v11, v[76:77], off offset:2048 nt
	global_load_dword v12, v[78:79], off nt
	global_load_dword v13, v[80:81], off offset:2048 nt
	v_cndmask_b32_e64 v28, 0, 1, s[12:13]
	v_cmp_ne_u32_e64 s[4:5], 1, v28
	s_andn2_b64 vcc, exec, s[12:13]
	s_cbranch_vccnz .LBB0_162
; __device__ __forceinline__ void transpose_item(const float* W, int N, bf16* WT, int K, int k0, int n0, int drow0, const float* gk, LAS float* scr, int lane) {
;     ...
; #pragma unroll
;     for (int i = 0; i < 32; ++i) { const int kk = 2 * i + (lane >> 5); float v = wv[i]; if (gk) v *= gk[kk]; scr[kk * 33 + (lane & 31)] = v; }
	v_lshlrev_b32_e32 v29, 2, v4
	s_waitcnt vmcnt(32)
	global_load_dword v204, v29, s[28:29]
	global_load_dword v205, v29, s[28:29] offset:8
	global_load_dword v206, v29, s[28:29] offset:16
	global_load_dword v207, v29, s[28:29] offset:24
	global_load_dword v208, v29, s[28:29] offset:32
	global_load_dword v209, v29, s[28:29] offset:40
	global_load_dword v210, v29, s[28:29] offset:48
	global_load_dword v211, v29, s[28:29] offset:56
	global_load_dword v212, v29, s[28:29] offset:64
	global_load_dword v213, v29, s[28:29] offset:72
	global_load_dword v214, v29, s[28:29] offset:80
	global_load_dword v215, v29, s[28:29] offset:88
	global_load_dword v216, v29, s[28:29] offset:96
	global_load_dword v217, v29, s[28:29] offset:104
	global_load_dword v218, v29, s[28:29] offset:112
	global_load_dword v219, v29, s[28:29] offset:120
	global_load_dword v220, v29, s[28:29] offset:128
	global_load_dword v221, v29, s[28:29] offset:136
	global_load_dword v222, v29, s[28:29] offset:144
	global_load_dword v223, v29, s[28:29] offset:152
	global_load_dword v224, v29, s[28:29] offset:160
	global_load_dword v225, v29, s[28:29] offset:168
	global_load_dword v226, v29, s[28:29] offset:176
	global_load_dword v227, v29, s[28:29] offset:184
	global_load_dword v228, v29, s[28:29] offset:192
	global_load_dword v229, v29, s[28:29] offset:200
	global_load_dword v230, v29, s[28:29] offset:208
	global_load_dword v231, v29, s[28:29] offset:216
	global_load_dword v232, v29, s[28:29] offset:224
	global_load_dword v233, v29, s[28:29] offset:232
	global_load_dword v234, v29, s[28:29] offset:240
	s_waitcnt vmcnt(62)
	global_load_dword v235, v29, s[28:29] offset:248
	s_waitcnt vmcnt(0)
	v_mov_b32_e32 v69, v204
	v_mov_b32_e32 v70, v205
	v_mov_b32_e32 v28, v206
	s_nop 0
	v_mov_b32_e32 v29, v207
	v_add_u32_e32 v71, v3, v35
	s_waitcnt vmcnt(3)
	v_mul_f32_e32 v69, v68, v69
	s_waitcnt vmcnt(2)
	v_mul_f32_e32 v70, v67, v70
	ds_write_b32 v5, v69
	ds_write_b32 v71, v70
	s_waitcnt vmcnt(0)
	v_pk_mul_f32 v[28:29], v[26:27], v[28:29]
	s_cbranch_execnz .LBB0_66

; #define LAS __attribute__((address_space(3)))
; __device__ __forceinline__ unsigned pk2(float lo, float hi) { return pg8::cvt_pk_bf16(lo, hi); }
; __device__ __forceinline__ void lds_wait() { asm volatile("s_waitcnt lgkmcnt(0)" ::: "memory"); }
; __device__ __forceinline__ void transpose_item(const float* W, int N, bf16* WT, int K, int k0, int n0, int drow0, const float* gk, LAS float* scr, int lane) {
;     ...
;     lds_wait();
;     const int c = lane & 7;
; #pragma unroll
;     for (int j = 0; j < 4; ++j) { const int n = (lane >> 3) + 8 * j; const LAS float* s = scr + (8 * c) * 33 + n;
;         u32x4 o; o.x = pk2(s[0 * 33], s[1 * 33]); o.y = pk2(s[2 * 33], s[3 * 33]); o.z = pk2(s[4 * 33], s[5 * 33]); o.w = pk2(s[6 * 33], s[7 * 33]);
;         *(u32x4*)(WT + (size_t)(drow0 + n) * K + k0 + 8 * c) = o; }
;     lds_wait();
.LBB0_87:
	s_waitcnt vmcnt(4)
	ds_write2_b32 v16, v14, v15 offset0:140 offset1:206
	s_waitcnt lgkmcnt(0)
	s_lshl_b32 s4, s27, 1
	s_waitcnt vmcnt(0)
	ds_read2_b32 v[12:13], v31 offset1:33
	s_add_u32 s4, s84, s4
	s_waitcnt lgkmcnt(0)
	v_cvt_pk_bf16_f32 v12, v12, v13
	ds_read2_b32 v[14:15], v31 offset0:66 offset1:99
	v_mov_b32_e32 v11, v7
	s_addc_u32 s5, s83, 0
	s_waitcnt lgkmcnt(0)
	v_cvt_pk_bf16_f32 v13, v14, v15
	ds_read2_b32 v[14:15], v31 offset0:132 offset1:165
	v_add_u32_e32 v16, s22, v30
	v_mov_b32_e32 v17, v7
	v_lshl_add_u64 v[20:21], s[4:5], 0, v[10:11]
	s_mov_b64 s[4:5], 0x1080000
	s_waitcnt lgkmcnt(0)
	v_cvt_pk_bf16_f32 v14, v14, v15
	ds_read2_b32 v[18:19], v31 offset0:198 offset1:231
	v_lshlrev_b64 v[16:17], 11, v[16:17]
	v_lshl_add_u64 v[20:21], v[20:21], 0, s[4:5]
	s_waitcnt lgkmcnt(0)
	v_cvt_pk_bf16_f32 v15, v18, v19
	ds_read2_b32 v[18:19], v31 offset0:8 offset1:41
	v_lshl_add_u64 v[16:17], v[20:21], 0, v[16:17]
	global_store_dwordx4 v[16:17], v[12:15], off sc1
	s_waitcnt lgkmcnt(0)
	s_nop 0
	v_cvt_pk_bf16_f32 v12, v18, v19
	ds_read2_b32 v[14:15], v31 offset0:74 offset1:107
	v_add_u32_e32 v18, s22, v32
	v_mov_b32_e32 v19, v7
	s_waitcnt lgkmcnt(0)
	v_cvt_pk_bf16_f32 v13, v14, v15
	ds_read2_b32 v[14:15], v31 offset0:140 offset1:173
	v_lshlrev_b64 v[18:19], 11, v[18:19]
	s_waitcnt lgkmcnt(0)
	v_cvt_pk_bf16_f32 v14, v14, v15
	ds_read2_b32 v[16:17], v31 offset0:206 offset1:239
	s_waitcnt lgkmcnt(0)
	v_cvt_pk_bf16_f32 v15, v16, v17
	v_lshl_add_u64 v[18:19], v[20:21], 0, v[18:19]
	ds_read2_b32 v[16:17], v31 offset0:16 offset1:49
	global_store_dwordx4 v[18:19], v[12:15], off sc1
	v_add_u32_e32 v18, s22, v33
	v_mov_b32_e32 v19, v7
	s_waitcnt lgkmcnt(0)
	v_cvt_pk_bf16_f32 v12, v16, v17
	ds_read2_b32 v[14:15], v31 offset0:82 offset1:115
	s_waitcnt lgkmcnt(0)
	v_cvt_pk_bf16_f32 v13, v14, v15
	ds_read2_b32 v[14:15], v31 offset0:148 offset1:181
	v_lshlrev_b64 v[18:19], 11, v[18:19]
	s_waitcnt lgkmcnt(0)
	v_cvt_pk_bf16_f32 v14, v14, v15
	ds_read2_b32 v[16:17], v31 offset0:214 offset1:247
	s_waitcnt lgkmcnt(0)
	v_cvt_pk_bf16_f32 v15, v16, v17
	v_lshl_add_u64 v[18:19], v[20:21], 0, v[18:19]
	ds_read2_b32 v[16:17], v31 offset0:24 offset1:57
	global_store_dwordx4 v[18:19], v[12:15], off sc1
	v_add_u32_e32 v18, s22, v34
	v_mov_b32_e32 v19, v7
	s_waitcnt lgkmcnt(0)
	v_cvt_pk_bf16_f32 v12, v16, v17
	ds_read2_b32 v[14:15], v31 offset0:90 offset1:123
	s_waitcnt lgkmcnt(0)
	v_cvt_pk_bf16_f32 v13, v14, v15
	ds_read2_b32 v[14:15], v31 offset0:156 offset1:189
	s_waitcnt lgkmcnt(0)
	v_cvt_pk_bf16_f32 v14, v14, v15
	ds_read2_b32 v[16:17], v31 offset0:222 offset1:255
	v_lshlrev_b64 v[18:19], 11, v[18:19]
	s_waitcnt lgkmcnt(0)
	v_cvt_pk_bf16_f32 v15, v16, v17
	v_lshl_add_u64 v[16:17], v[20:21], 0, v[18:19]
	global_store_dwordx4 v[16:17], v[12:15], off sc1
	s_waitcnt lgkmcnt(0)

; #define LAS __attribute__((address_space(3)))
; __device__ __forceinline__ void transpose_item(const float* W, int N, bf16* WT, int K, int k0, int n0, int drow0, const float* gk, LAS float* scr, int lane) {
;     float wv[32];
; #pragma unroll
;     for (int i = 0; i < 32; ++i) wv[i] = W[(size_t)(k0 + 2 * i + (lane >> 5)) * N + n0 + (lane & 31)];
; __device__ __forceinline__ void p0_weight_item(const Args& a, int l, int r, LAS float* scr, int lane) {
;     ...
;         if (r < IT_BIG) { const int kb = r / 32, nb = r % 32; const float* W = a.in[f ? 31 : 4] + (size_t)l * FF * DM;
;             transpose_item(W, DM, dn, FF, 64 * kb, 32 * nb, 32 * nb, nullptr, scr, lane); return; }
.LBB0_89:
	s_andn2_b64 vcc, exec, s[4:5]
	s_cbranch_vccnz .LBB0_91
	v_readlane_b32 s52, v250, 59
	v_readlane_b32 s66, v251, 9
	v_readlane_b32 s67, v251, 10
	s_add_u32 s22, s66, s86
	s_mul_i32 s4, s26, 0xffffaea0
	s_addc_u32 s27, s67, s85
	s_add_i32 s4, s45, s4
	s_addk_i32 s4, 0xdf00
	s_and_b32 s5, s4, 0x7fffffc0
	s_lshl_b32 s4, s26, 9
	s_sub_i32 s4, s43, s4
	s_add_i32 s4, s4, 0xfffdf000
	s_and_b32 s4, s4, 0x3e0
	s_lshl_b32 s28, s4, 2
	v_or_b32_e32 v12, s5, v4
	s_add_u32 s28, s22, s28
	s_addc_u32 s29, s27, 0
	v_mov_b32_e32 v13, v7
	v_or_b32_e32 v18, 2, v12
	v_mov_b32_e32 v19, v7
	v_or_b32_e32 v20, 4, v12
	v_mov_b32_e32 v21, v7
	v_or_b32_e32 v22, 6, v12
	v_mov_b32_e32 v23, v7
	v_or_b32_e32 v24, 8, v12
	v_mov_b32_e32 v25, v7
	v_or_b32_e32 v26, 10, v12
	v_mov_b32_e32 v27, v7
	v_or_b32_e32 v28, 12, v12
	v_mov_b32_e32 v29, v7
	v_or_b32_e32 v56, 14, v12
	v_mov_b32_e32 v57, v7
	v_lshl_add_u64 v[14:15], s[28:29], 0, v[6:7]
	v_lshlrev_b64 v[16:17], 12, v[12:13]
	v_lshlrev_b64 v[18:19], 12, v[18:19]
	v_lshlrev_b64 v[20:21], 12, v[20:21]
	v_lshlrev_b64 v[22:23], 12, v[22:23]
	v_lshlrev_b64 v[24:25], 12, v[24:25]
	v_lshlrev_b64 v[26:27], 12, v[26:27]
	v_lshlrev_b64 v[28:29], 12, v[28:29]
	v_lshlrev_b64 v[56:57], 12, v[56:57]
	v_lshl_add_u64 v[16:17], v[14:15], 0, v[16:17]
	v_lshl_add_u64 v[18:19], v[14:15], 0, v[18:19]
	v_lshl_add_u64 v[20:21], v[14:15], 0, v[20:21]
	v_lshl_add_u64 v[22:23], v[14:15], 0, v[22:23]
	v_lshl_add_u64 v[24:25], v[14:15], 0, v[24:25]
	v_lshl_add_u64 v[26:27], v[14:15], 0, v[26:27]
	v_lshl_add_u64 v[28:29], v[14:15], 0, v[28:29]
	v_lshl_add_u64 v[56:57], v[14:15], 0, v[56:57]
	global_load_dword v9, v[16:17], off nt
	global_load_dword v11, v[18:19], off nt
	global_load_dword v55, v[20:21], off nt
	global_load_dword v58, v[22:23], off nt
	global_load_dword v59, v[24:25], off nt
	global_load_dword v60, v[26:27], off nt
	global_load_dword v61, v[28:29], off nt
	global_load_dword v62, v[56:57], off nt
	v_or_b32_e32 v16, 16, v12
	v_mov_b32_e32 v17, v7
	v_or_b32_e32 v18, 18, v12
	v_mov_b32_e32 v19, v7
	v_or_b32_e32 v20, 20, v12
	v_mov_b32_e32 v21, v7
	v_or_b32_e32 v22, 22, v12
	v_mov_b32_e32 v23, v7
	v_or_b32_e32 v24, 24, v12
	v_mov_b32_e32 v25, v7
	v_or_b32_e32 v26, 26, v12
	v_mov_b32_e32 v27, v7
	v_or_b32_e32 v28, 28, v12
	v_mov_b32_e32 v29, v7
	v_or_b32_e32 v56, 30, v12
	v_mov_b32_e32 v57, v7
	v_lshlrev_b64 v[16:17], 12, v[16:17]
	v_lshlrev_b64 v[18:19], 12, v[18:19]
	v_lshlrev_b64 v[20:21], 12, v[20:21]
	v_lshlrev_b64 v[22:23], 12, v[22:23]
	v_lshlrev_b64 v[24:25], 12, v[24:25]
	v_lshlrev_b64 v[26:27], 12, v[26:27]
	v_lshlrev_b64 v[28:29], 12, v[28:29]
	v_lshlrev_b64 v[56:57], 12, v[56:57]
	v_lshl_add_u64 v[16:17], v[14:15], 0, v[16:17]
	v_lshl_add_u64 v[18:19], v[14:15], 0, v[18:19]
	v_lshl_add_u64 v[20:21], v[14:15], 0, v[20:21]
	v_lshl_add_u64 v[22:23], v[14:15], 0, v[22:23]
	v_lshl_add_u64 v[24:25], v[14:15], 0, v[24:25]
	v_lshl_add_u64 v[26:27], v[14:15], 0, v[26:27]
	v_lshl_add_u64 v[28:29], v[14:15], 0, v[28:29]
	v_lshl_add_u64 v[56:57], v[14:15], 0, v[56:57]
	global_load_dword v63, v[16:17], off nt
	global_load_dword v64, v[18:19], off nt
	global_load_dword v65, v[20:21], off nt
	global_load_dword v66, v[22:23], off nt
	global_load_dword v67, v[24:25], off nt
	global_load_dword v68, v[26:27], off nt
	global_load_dword v69, v[28:29], off nt
	global_load_dword v70, v[56:57], off nt
	v_or_b32_e32 v16, 32, v12
	v_mov_b32_e32 v17, v7
	v_or_b32_e32 v18, 34, v12
	v_mov_b32_e32 v19, v7
	v_or_b32_e32 v20, 36, v12
	v_mov_b32_e32 v21, v7
	v_or_b32_e32 v22, 38, v12
	v_mov_b32_e32 v23, v7
	v_or_b32_e32 v24, 40, v12
	v_mov_b32_e32 v25, v7
	v_or_b32_e32 v26, 42, v12
	v_mov_b32_e32 v27, v7
	v_or_b32_e32 v28, 44, v12
	v_mov_b32_e32 v29, v7
	v_or_b32_e32 v56, 46, v12
	v_mov_b32_e32 v57, v7
	v_lshlrev_b64 v[16:17], 12, v[16:17]
	v_lshlrev_b64 v[18:19], 12, v[18:19]
	v_lshlrev_b64 v[20:21], 12, v[20:21]
	v_lshlrev_b64 v[22:23], 12, v[22:23]
	v_lshlrev_b64 v[24:25], 12, v[24:25]
	v_lshlrev_b64 v[26:27], 12, v[26:27]
	v_lshlrev_b64 v[28:29], 12, v[28:29]
	v_lshlrev_b64 v[56:57], 12, v[56:57]
	v_lshl_add_u64 v[16:17], v[14:15], 0, v[16:17]
	v_lshl_add_u64 v[18:19], v[14:15], 0, v[18:19]
	v_lshl_add_u64 v[20:21], v[14:15], 0, v[20:21]
	v_lshl_add_u64 v[22:23], v[14:15], 0, v[22:23]
	v_lshl_add_u64 v[24:25], v[14:15], 0, v[24:25]
	v_lshl_add_u64 v[26:27], v[14:15], 0, v[26:27]
	v_lshl_add_u64 v[28:29], v[14:15], 0, v[28:29]
	v_lshl_add_u64 v[56:57], v[14:15], 0, v[56:57]
	global_load_dword v71, v[16:17], off nt
	global_load_dword v72, v[18:19], off nt
	global_load_dword v73, v[20:21], off nt
	global_load_dword v74, v[22:23], off nt
	global_load_dword v75, v[24:25], off nt
	global_load_dword v76, v[26:27], off nt
	global_load_dword v77, v[28:29], off nt
	s_nop 0
	global_load_dword v56, v[56:57], off nt
	v_or_b32_e32 v16, 48, v12
	v_mov_b32_e32 v17, v7
	v_or_b32_e32 v18, 50, v12
	v_mov_b32_e32 v19, v7
	v_or_b32_e32 v20, 52, v12
	v_mov_b32_e32 v21, v7
	v_or_b32_e32 v22, 54, v12
	v_or_b32_e32 v24, 56, v12
	v_or_b32_e32 v26, 58, v12
	v_or_b32_e32 v28, 60, v12
	v_or_b32_e32 v12, 62, v12
	v_lshlrev_b64 v[16:17], 12, v[16:17]
	v_lshlrev_b64 v[18:19], 12, v[18:19]
	v_lshlrev_b64 v[20:21], 12, v[20:21]
	v_mov_b32_e32 v23, v7
	v_mov_b32_e32 v25, v7
	v_mov_b32_e32 v27, v7
	v_mov_b32_e32 v29, v7
	v_lshlrev_b64 v[12:13], 12, v[12:13]
	v_lshl_add_u64 v[16:17], v[14:15], 0, v[16:17]
	v_lshl_add_u64 v[18:19], v[14:15], 0, v[18:19]
	v_lshl_add_u64 v[20:21], v[14:15], 0, v[20:21]
	v_lshlrev_b64 v[22:23], 12, v[22:23]
	v_lshlrev_b64 v[24:25], 12, v[24:25]
	v_lshlrev_b64 v[26:27], 12, v[26:27]
	v_lshlrev_b64 v[28:29], 12, v[28:29]
	v_lshl_add_u64 v[12:13], v[14:15], 0, v[12:13]
	v_lshl_add_u64 v[22:23], v[14:15], 0, v[22:23]
	v_lshl_add_u64 v[24:25], v[14:15], 0, v[24:25]
	v_lshl_add_u64 v[26:27], v[14:15], 0, v[26:27]
	v_lshl_add_u64 v[28:29], v[14:15], 0, v[28:29]
	global_load_dword v14, v[16:17], off nt
	global_load_dword v15, v[18:19], off nt
	s_nop 0
	global_load_dword v16, v[20:21], off nt
	global_load_dword v17, v[22:23], off nt
	global_load_dword v18, v[24:25], off nt
	global_load_dword v19, v[26:27], off nt
	s_nop 0
	global_load_dword v20, v[28:29], off nt
	s_nop 0
	global_load_dword v12, v[12:13], off nt
	s_waitcnt vmcnt(30)
; #define LAS __attribute__((address_space(3)))
; __device__ __forceinline__ unsigned pk2(float lo, float hi) { return pg8::cvt_pk_bf16(lo, hi); }
; __device__ __forceinline__ void lds_wait() { asm volatile("s_waitcnt lgkmcnt(0)" ::: "memory"); }
; __device__ __forceinline__ void transpose_item(const float* W, int N, bf16* WT, int K, int k0, int n0, int drow0, const float* gk, LAS float* scr, int lane) {
;     ...
; #pragma unroll
;     for (int i = 0; i < 32; ++i) { const int kk = 2 * i + (lane >> 5); float v = wv[i]; if (gk) v *= gk[kk]; scr[kk * 33 + (lane & 31)] = v; }
;     lds_wait();
;     const int c = lane & 7;
; #pragma unroll
;     for (int j = 0; j < 4; ++j) { const int n = (lane >> 3) + 8 * j; const LAS float* s = scr + (8 * c) * 33 + n;
;         u32x4 o; o.x = pk2(s[0 * 33], s[1 * 33]); o.y = pk2(s[2 * 33], s[3 * 33]); o.z = pk2(s[4 * 33], s[5 * 33]); o.w = pk2(s[6 * 33], s[7 * 33]);
;         *(u32x4*)(WT + (size_t)(drow0 + n) * K + k0 + 8 * c) = o; }
;     lds_wait();
	ds_write2_b32 v5, v9, v11 offset1:66
	s_waitcnt vmcnt(28)
	ds_write2_b32 v5, v55, v58 offset0:132 offset1:198
	s_waitcnt vmcnt(26)
	ds_write2_b32 v48, v59, v60 offset0:8 offset1:74
	s_waitcnt vmcnt(24)
	ds_write2_b32 v48, v61, v62 offset0:140 offset1:206
	s_waitcnt vmcnt(22)
	ds_write2_b32 v49, v63, v64 offset0:16 offset1:82
	s_waitcnt vmcnt(20)
	ds_write2_b32 v49, v65, v66 offset0:148 offset1:214
	s_waitcnt vmcnt(18)
	ds_write2_b32 v50, v67, v68 offset0:24 offset1:90
	s_waitcnt vmcnt(16)
	ds_write2_b32 v50, v69, v70 offset0:156 offset1:222
	s_waitcnt vmcnt(14)
	ds_write2_b32 v51, v71, v72 offset0:32 offset1:98
	s_waitcnt vmcnt(12)
	ds_write2_b32 v51, v73, v74 offset0:164 offset1:230
	s_waitcnt vmcnt(10)
	ds_write2_b32 v52, v75, v76 offset0:40 offset1:106
	s_waitcnt vmcnt(8)
	ds_write2_b32 v52, v77, v56 offset0:172 offset1:238
	s_waitcnt vmcnt(6)
	ds_write2_b32 v53, v14, v15 offset0:48 offset1:114
	s_waitcnt vmcnt(4)
	ds_write2_b32 v53, v16, v17 offset0:180 offset1:246
	s_waitcnt vmcnt(2)
	ds_write2_b32 v54, v18, v19 offset0:56 offset1:122
	s_waitcnt vmcnt(0)
	ds_write2_b32 v54, v20, v12 offset0:188 offset1:254
	s_lshl_b32 s5, s5, 1
	s_waitcnt lgkmcnt(0)
	s_add_u32 s28, s84, s5
	ds_read2_b32 v[12:13], v31 offset1:33
	s_addc_u32 s29, s83, 0
	v_mov_b32_e32 v11, v7
	v_or_b32_e32 v9, s4, v30
	s_waitcnt lgkmcnt(0)
	v_cvt_pk_bf16_f32 v12, v12, v13
	ds_read2_b32 v[14:15], v31 offset0:66 offset1:99
	v_lshl_add_u64 v[18:19], s[28:29], 0, v[10:11]
	s_mov_b64 s[28:29], 0x2300000
	v_mul_u32_u24_e32 v9, 0xb00, v9
	s_waitcnt lgkmcnt(0)
	v_cvt_pk_bf16_f32 v13, v14, v15
	ds_read2_b32 v[14:15], v31 offset0:132 offset1:165
	v_lshl_add_u64 v[18:19], v[18:19], 0, s[28:29]
	v_lshlrev_b32_e32 v20, 1, v9
	v_mov_b32_e32 v21, v7
	s_waitcnt lgkmcnt(0)
	v_cvt_pk_bf16_f32 v14, v14, v15
	ds_read2_b32 v[16:17], v31 offset0:198 offset1:231
	s_waitcnt lgkmcnt(0)
	v_cvt_pk_bf16_f32 v15, v16, v17
	v_lshl_add_u64 v[20:21], v[18:19], 0, v[20:21]
	v_or_b32_e32 v9, s4, v32
	ds_read2_b32 v[16:17], v31 offset0:8 offset1:41
	global_store_dwordx4 v[20:21], v[12:15], off sc1
	v_mul_u32_u24_e32 v9, 0xb00, v9
	v_lshlrev_b32_e32 v20, 1, v9
	s_waitcnt lgkmcnt(0)
	v_cvt_pk_bf16_f32 v12, v16, v17
	ds_read2_b32 v[14:15], v31 offset0:74 offset1:107
	s_waitcnt lgkmcnt(0)
	v_cvt_pk_bf16_f32 v13, v14, v15
	ds_read2_b32 v[14:15], v31 offset0:140 offset1:173
	v_mov_b32_e32 v21, v7
	s_waitcnt lgkmcnt(0)
	v_cvt_pk_bf16_f32 v14, v14, v15
	ds_read2_b32 v[16:17], v31 offset0:206 offset1:239
	s_waitcnt lgkmcnt(0)
	v_cvt_pk_bf16_f32 v15, v16, v17
	v_lshl_add_u64 v[20:21], v[18:19], 0, v[20:21]
	v_or_b32_e32 v9, s4, v33
	ds_read2_b32 v[16:17], v31 offset0:16 offset1:49
	global_store_dwordx4 v[20:21], v[12:15], off sc1
	v_mul_u32_u24_e32 v9, 0xb00, v9
	v_lshlrev_b32_e32 v20, 1, v9
	s_waitcnt lgkmcnt(0)
	v_cvt_pk_bf16_f32 v12, v16, v17
	ds_read2_b32 v[14:15], v31 offset0:82 offset1:115
	s_waitcnt lgkmcnt(0)
	v_cvt_pk_bf16_f32 v13, v14, v15
	ds_read2_b32 v[14:15], v31 offset0:148 offset1:181
	v_mov_b32_e32 v21, v7
	s_waitcnt lgkmcnt(0)
	v_cvt_pk_bf16_f32 v14, v14, v15
	ds_read2_b32 v[16:17], v31 offset0:214 offset1:247
	s_waitcnt lgkmcnt(0)
	v_cvt_pk_bf16_f32 v15, v16, v17
	v_lshl_add_u64 v[20:21], v[18:19], 0, v[20:21]
	ds_read2_b32 v[16:17], v31 offset0:24 offset1:57
	global_store_dwordx4 v[20:21], v[12:15], off sc1
	v_or_b32_e32 v9, s4, v34
	v_mul_u32_u24_e32 v9, 0xb00, v9
	s_waitcnt lgkmcnt(0)
	v_cvt_pk_bf16_f32 v12, v16, v17
	ds_read2_b32 v[14:15], v31 offset0:90 offset1:123
	s_waitcnt lgkmcnt(0)
	v_cvt_pk_bf16_f32 v13, v14, v15
	ds_read2_b32 v[14:15], v31 offset0:156 offset1:189
	s_waitcnt lgkmcnt(0)
	v_cvt_pk_bf16_f32 v14, v14, v15
	ds_read2_b32 v[16:17], v31 offset0:222 offset1:255
	s_waitcnt lgkmcnt(0)
	v_cvt_pk_bf16_f32 v15, v16, v17
	v_lshlrev_b32_e32 v16, 1, v9
	v_mov_b32_e32 v17, v7
	v_lshl_add_u64 v[16:17], v[18:19], 0, v[16:17]
	global_store_dwordx4 v[16:17], v[12:15], off sc1
	s_waitcnt lgkmcnt(0)
	v_readlane_b32 s53, v250, 60
	v_readlane_b32 s54, v250, 61
	v_readlane_b32 s55, v250, 62
	v_readlane_b32 s56, v250, 63
	v_readlane_b32 s57, v251, 0
	v_readlane_b32 s58, v251, 1
	v_readlane_b32 s59, v251, 2
	v_readlane_b32 s60, v251, 3
	v_readlane_b32 s61, v251, 4
	v_readlane_b32 s62, v251, 5
	v_readlane_b32 s63, v251, 6
	v_readlane_b32 s64, v251, 7
	v_readlane_b32 s65, v251, 8

; #define LAS __attribute__((address_space(3)))
; __device__ __forceinline__ void transpose_item(const float* W, int N, bf16* WT, int K, int k0, int n0, int drow0, const float* gk, LAS float* scr, int lane) {
;     float wv[32];
; #pragma unroll
;     for (int i = 0; i < 32; ++i) wv[i] = W[(size_t)(k0 + 2 * i + (lane >> 5)) * N + n0 + (lane & 31)];
; __device__ __forceinline__ void p0_weight_item(const Args& a, int l, int r, LAS float* scr, int lane) {
;     ...
;         if (r < 2 * IT_BIG) { const int up = r >= IT_BIG; const int it = r - up * IT_BIG; const int kb = it / 88, nb = it % 88, k0 = 64 * kb, n0 = 32 * nb;
;             const float* W = a.in[(f ? 29 : 2) + up] + (size_t)l * DM * FF;
;             transpose_item(W, FF, gu, DM, k0, n0, (n0 >> 7) * 256 + up * 128 + (n0 & 127), nrm + k0, scr, lane); return; }
.LBB0_92:
	s_andn2_b64 vcc, exec, s[4:5]
	s_cbranch_vccnz .LBB0_118
	v_readlane_b32 s52, v250, 59
	v_readlane_b32 s60, v251, 3
	v_readlane_b32 s61, v251, 4
	s_add_u32 s27, s60, s24
	s_addc_u32 s35, s61, s25
	s_cmpk_gt_u32 s88, 0x15ff
	s_cselect_b64 s[28:29], -1, 0
	s_and_b64 s[4:5], s[28:29], exec
	v_readlane_b32 s62, v251, 5
	v_readlane_b32 s63, v251, 6
	v_readlane_b32 s64, v251, 7
	v_readlane_b32 s65, v251, 8
	s_cselect_b32 s4, 0xfa80, 0
	s_cselect_b32 s5, s64, s62
	s_cselect_b32 s31, s65, s63
	s_sub_i32 s4, s4, s87
	s_add_i32 s4, s82, s4
	s_addk_i32 s4, 0xef80
	s_sext_i32_i16 s22, s4
	s_mulk_i32 s22, 0xba3
	s_lshr_b32 s30, s22, 31
	s_ashr_i32 s22, s22, 18
	s_add_i32 s30, s22, s30
	s_mul_i32 s22, s30, 0x58
	s_sub_i32 s4, s4, s22
	s_sext_i32_i16 s22, s4
	s_lshl_b32 s30, s30, 6
	s_lshl_b32 s34, s22, 5
	s_add_u32 s40, s5, s86
	s_addc_u32 s41, s31, s85
	s_ashr_i32 s31, s30, 31
	s_lshl_b64 s[4:5], s[30:31], 2
	s_add_u32 s38, s27, s4
	s_addc_u32 s39, s35, s5
	s_ashr_i32 s35, s34, 31
	s_lshl_b64 s[4:5], s[34:35], 2
	v_or_b32_e32 v9, s30, v4
	s_add_u32 s4, s40, s4
	s_addc_u32 s5, s41, s5
	v_mul_i32_i24_e32 v14, 0x2c00, v9
	v_lshl_add_u64 v[12:13], s[4:5], 0, v[6:7]
	v_ashrrev_i32_e32 v15, 31, v14
	v_lshl_add_u64 v[12:13], v[12:13], 0, v[14:15]
	v_add_co_u32_e32 v14, vcc, s93, v12
	v_readlane_b32 s53, v250, 60
	s_nop 0
	v_addc_co_u32_e32 v15, vcc, 0, v13, vcc
	v_add_co_u32_e32 v16, vcc, s94, v12
	v_readlane_b32 s54, v250, 61
	s_nop 0
	v_addc_co_u32_e32 v17, vcc, 0, v13, vcc
	v_add_co_u32_e32 v18, vcc, s95, v12
	v_readlane_b32 s55, v250, 62
	s_nop 0
	v_addc_co_u32_e32 v19, vcc, 0, v13, vcc
	v_add_co_u32_e32 v20, vcc, s96, v12
	v_readlane_b32 s56, v250, 63
	s_nop 0
	v_addc_co_u32_e32 v21, vcc, 0, v13, vcc
	v_add_co_u32_e32 v22, vcc, s97, v12
	v_readlane_b32 s57, v251, 0
	s_nop 0
	v_addc_co_u32_e32 v23, vcc, 0, v13, vcc
	v_add_co_u32_e32 v24, vcc, s51, v12
	v_readlane_b32 s58, v251, 1
	s_nop 0
	v_addc_co_u32_e32 v25, vcc, 0, v13, vcc
	v_add_co_u32_e32 v28, vcc, s2, v12
	v_readlane_b32 s59, v251, 2
	s_nop 0
	v_addc_co_u32_e32 v29, vcc, 0, v13, vcc
	global_load_dword v68, v[12:13], off nt
	global_load_dword v67, v[14:15], off offset:2048 nt
	global_load_dword v26, v[16:17], off nt
	global_load_dword v27, v[18:19], off offset:2048 nt
	global_load_dword v65, v[20:21], off nt
	global_load_dword v66, v[22:23], off offset:2048 nt
	s_nop 0
	global_load_dword v24, v[24:25], off nt
	s_nop 0
	global_load_dword v25, v[28:29], off offset:2048 nt
	v_add_co_u32_e32 v14, vcc, s6, v12
	v_readlane_b32 s66, v251, 9
	s_nop 0
	v_addc_co_u32_e32 v15, vcc, 0, v13, vcc
	v_add_co_u32_e32 v16, vcc, s7, v12
	v_readlane_b32 s67, v251, 10
	s_nop 0
	v_addc_co_u32_e32 v17, vcc, 0, v13, vcc
	v_add_co_u32_e32 v18, vcc, s20, v12
	s_nop 1
	v_addc_co_u32_e32 v19, vcc, 0, v13, vcc
	v_add_co_u32_e32 v20, vcc, s21, v12
	s_nop 1
	v_addc_co_u32_e32 v21, vcc, 0, v13, vcc
	v_add_co_u32_e32 v28, vcc, s23, v12
	s_nop 1
	v_addc_co_u32_e32 v29, vcc, 0, v13, vcc
	v_add_co_u32_e32 v56, vcc, s36, v12
	s_nop 1
	v_addc_co_u32_e32 v57, vcc, 0, v13, vcc
	v_add_co_u32_e32 v58, vcc, s37, v12
	s_nop 1
	v_addc_co_u32_e32 v59, vcc, 0, v13, vcc
	v_add_co_u32_e32 v70, vcc, s68, v12
	s_nop 1
	v_addc_co_u32_e32 v71, vcc, 0, v13, vcc
	global_load_dword v63, v[14:15], off nt
	global_load_dword v64, v[16:17], off offset:2048 nt
	global_load_dword v22, v[18:19], off nt
	global_load_dword v23, v[20:21], off offset:2048 nt
	global_load_dword v61, v[28:29], off nt
	global_load_dword v62, v[56:57], off offset:2048 nt
	s_nop 0
	global_load_dword v20, v[58:59], off nt
	global_load_dword v21, v[70:71], off offset:2048 nt
	v_add_co_u32_e32 v14, vcc, s69, v12
	s_nop 1
	v_addc_co_u32_e32 v15, vcc, 0, v13, vcc
	v_add_co_u32_e32 v16, vcc, s70, v12
	s_nop 1
	v_addc_co_u32_e32 v17, vcc, 0, v13, vcc
	v_add_co_u32_e32 v18, vcc, s71, v12
	s_nop 1
	v_addc_co_u32_e32 v19, vcc, 0, v13, vcc
	v_add_co_u32_e32 v28, vcc, s72, v12
	s_nop 1
	v_addc_co_u32_e32 v29, vcc, 0, v13, vcc
	v_add_co_u32_e32 v56, vcc, s73, v12
	s_nop 1
	v_addc_co_u32_e32 v57, vcc, 0, v13, vcc
	v_add_co_u32_e32 v70, vcc, s74, v12
	s_nop 1
	v_addc_co_u32_e32 v71, vcc, 0, v13, vcc
	v_add_co_u32_e32 v72, vcc, s75, v12
	s_nop 1
	v_addc_co_u32_e32 v73, vcc, 0, v13, vcc
	v_add_co_u32_e32 v74, vcc, s76, v12
	s_nop 1
	v_addc_co_u32_e32 v75, vcc, 0, v13, vcc
	global_load_dword v59, v[14:15], off nt
	global_load_dword v60, v[16:17], off offset:2048 nt
	s_nop 0
	global_load_dword v18, v[18:19], off nt
	s_nop 0
	global_load_dword v19, v[28:29], off offset:2048 nt
	global_load_dword v55, v[56:57], off nt
	s_nop 0
	global_load_dword v57, v[70:71], off offset:2048 nt
	global_load_dword v16, v[72:73], off nt
	global_load_dword v17, v[74:75], off offset:2048 nt
	v_add_co_u32_e32 v14, vcc, s77, v12
	s_nop 1
	v_addc_co_u32_e32 v15, vcc, 0, v13, vcc
	v_add_co_u32_e32 v28, vcc, s78, v12
	s_nop 1
	v_addc_co_u32_e32 v29, vcc, 0, v13, vcc
	v_add_co_u32_e32 v70, vcc, s79, v12
	s_nop 1
	v_addc_co_u32_e32 v71, vcc, 0, v13, vcc
	v_add_co_u32_e32 v72, vcc, s80, v12
	s_nop 1
	v_addc_co_u32_e32 v73, vcc, 0, v13, vcc
	v_add_co_u32_e32 v74, vcc, s81, v12
	s_nop 1
	v_addc_co_u32_e32 v75, vcc, 0, v13, vcc
	v_add_co_u32_e32 v76, vcc, 0x9f000, v12
	s_nop 1
	v_addc_co_u32_e32 v77, vcc, 0, v13, vcc
	v_add_co_u32_e32 v78, vcc, 0xa5000, v12
	s_nop 1
	v_addc_co_u32_e32 v79, vcc, 0, v13, vcc
	v_add_co_u32_e32 v80, vcc, 0xaa000, v12
	s_nop 1
	v_addc_co_u32_e32 v81, vcc, 0, v13, vcc
	global_load_dword v56, v[14:15], off nt
	global_load_dword v58, v[28:29], off offset:2048 nt
	s_nop 0
	global_load_dword v14, v[70:71], off nt
	global_load_dword v15, v[72:73], off offset:2048 nt
	global_load_dword v9, v[74:75], off nt
	global_load_dword v11, v[76:77], off offset:2048 nt
	global_load_dword v12, v[78:79], off nt
	global_load_dword v13, v[80:81], off offset:2048 nt
	v_cndmask_b32_e64 v28, 0, 1, s[8:9]
	v_cmp_ne_u32_e64 s[4:5], 1, v28
	s_andn2_b64 vcc, exec, s[8:9]
	s_cbranch_vccnz .LBB0_154
; __device__ __forceinline__ void transpose_item(const float* W, int N, bf16* WT, int K, int k0, int n0, int drow0, const float* gk, LAS float* scr, int lane) {
;     ...
; #pragma unroll
;     for (int i = 0; i < 32; ++i) { const int kk = 2 * i + (lane >> 5); float v = wv[i]; if (gk) v *= gk[kk]; scr[kk * 33 + (lane & 31)] = v; }
	v_lshlrev_b32_e32 v29, 2, v4
	s_waitcnt vmcnt(32)
	global_load_dword v204, v29, s[38:39]
	global_load_dword v205, v29, s[38:39] offset:8
	global_load_dword v206, v29, s[38:39] offset:16
	global_load_dword v207, v29, s[38:39] offset:24
	global_load_dword v208, v29, s[38:39] offset:32
	global_load_dword v209, v29, s[38:39] offset:40
	global_load_dword v210, v29, s[38:39] offset:48
	global_load_dword v211, v29, s[38:39] offset:56
	global_load_dword v212, v29, s[38:39] offset:64
	global_load_dword v213, v29, s[38:39] offset:72
	global_load_dword v214, v29, s[38:39] offset:80
	global_load_dword v215, v29, s[38:39] offset:88
	global_load_dword v216, v29, s[38:39] offset:96
	global_load_dword v217, v29, s[38:39] offset:104
	global_load_dword v218, v29, s[38:39] offset:112
	global_load_dword v219, v29, s[38:39] offset:120
	global_load_dword v220, v29, s[38:39] offset:128
	global_load_dword v221, v29, s[38:39] offset:136
	global_load_dword v222, v29, s[38:39] offset:144
	global_load_dword v223, v29, s[38:39] offset:152
	global_load_dword v224, v29, s[38:39] offset:160
	global_load_dword v225, v29, s[38:39] offset:168
	global_load_dword v226, v29, s[38:39] offset:176
	global_load_dword v227, v29, s[38:39] offset:184
	global_load_dword v228, v29, s[38:39] offset:192
	global_load_dword v229, v29, s[38:39] offset:200
	global_load_dword v230, v29, s[38:39] offset:208
	global_load_dword v231, v29, s[38:39] offset:216
	global_load_dword v232, v29, s[38:39] offset:224
	global_load_dword v233, v29, s[38:39] offset:232
	global_load_dword v234, v29, s[38:39] offset:240
	s_waitcnt vmcnt(62)
	global_load_dword v235, v29, s[38:39] offset:248
	s_waitcnt vmcnt(0)
	v_mov_b32_e32 v69, v204
	v_mov_b32_e32 v70, v205
	v_mov_b32_e32 v28, v206
	s_nop 0
	v_mov_b32_e32 v29, v207
	v_add_u32_e32 v71, v3, v35
	s_waitcnt vmcnt(3)
	v_mul_f32_e32 v69, v68, v69
	s_waitcnt vmcnt(2)
	v_mul_f32_e32 v70, v67, v70
	ds_write_b32 v5, v69
	ds_write_b32 v71, v70
	s_waitcnt vmcnt(0)
	v_pk_mul_f32 v[28:29], v[26:27], v[28:29]
	s_cbranch_execnz .LBB0_96

; #define LAS __attribute__((address_space(3)))
; __device__ __forceinline__ unsigned pk2(float lo, float hi) { return pg8::cvt_pk_bf16(lo, hi); }
; __device__ __forceinline__ void lds_wait() { asm volatile("s_waitcnt lgkmcnt(0)" ::: "memory"); }
; __device__ __forceinline__ void transpose_item(const float* W, int N, bf16* WT, int K, int k0, int n0, int drow0, const float* gk, LAS float* scr, int lane) {
;     ...
;     lds_wait();
;     const int c = lane & 7;
; #pragma unroll
;     for (int j = 0; j < 4; ++j) { const int n = (lane >> 3) + 8 * j; const LAS float* s = scr + (8 * c) * 33 + n;
;         u32x4 o; o.x = pk2(s[0 * 33], s[1 * 33]); o.y = pk2(s[2 * 33], s[3 * 33]); o.z = pk2(s[4 * 33], s[5 * 33]); o.w = pk2(s[6 * 33], s[7 * 33]);
;         *(u32x4*)(WT + (size_t)(drow0 + n) * K + k0 + 8 * c) = o; }
;     lds_wait();
.LBB0_117:
	s_lshl_b32 s4, s22, 6
	s_waitcnt vmcnt(4)
	ds_write2_b32 v16, v14, v15 offset0:140 offset1:206
	s_and_b32 s22, s4, 0xffffff00
	s_waitcnt lgkmcnt(0)
	s_and_b64 s[4:5], s[28:29], exec
	s_waitcnt vmcnt(0)
	ds_read2_b32 v[12:13], v31 offset1:33
	s_cselect_b32 s27, 0x80, 0
	s_waitcnt lgkmcnt(0)
	v_cvt_pk_bf16_f32 v12, v12, v13
	ds_read2_b32 v[14:15], v31 offset0:66 offset1:99
	s_and_b32 s28, s34, 0x60
	s_or_b32 s22, s22, s27
	s_waitcnt lgkmcnt(0)
	v_cvt_pk_bf16_f32 v13, v14, v15
	ds_read2_b32 v[14:15], v31 offset0:132 offset1:165
	s_lshl_b64 s[4:5], s[30:31], 1
	s_or_b32 s22, s22, s28
	s_waitcnt lgkmcnt(0)
	v_cvt_pk_bf16_f32 v14, v14, v15
	ds_read2_b32 v[16:17], v31 offset0:198 offset1:231
	s_add_u32 s4, s84, s4
	v_mov_b32_e32 v11, v7
	s_addc_u32 s5, s83, s5
	s_waitcnt lgkmcnt(0)
	v_cvt_pk_bf16_f32 v15, v16, v17
	v_or_b32_e32 v16, s22, v30
	v_lshl_add_u64 v[18:19], s[4:5], 0, v[10:11]
	s_mov_b64 s[4:5], 0x1800000
	v_ashrrev_i32_e32 v17, 31, v16
	v_lshl_add_u64 v[18:19], v[18:19], 0, s[4:5]
	v_lshlrev_b64 v[16:17], 11, v[16:17]
	ds_read2_b32 v[20:21], v31 offset0:8 offset1:41
	v_lshl_add_u64 v[16:17], v[18:19], 0, v[16:17]
	global_store_dwordx4 v[16:17], v[12:15], off sc1
	s_waitcnt lgkmcnt(0)
	s_nop 0
	v_cvt_pk_bf16_f32 v12, v20, v21
	v_or_b32_e32 v20, s22, v32
	v_ashrrev_i32_e32 v21, 31, v20
	ds_read2_b32 v[14:15], v31 offset0:74 offset1:107
	v_lshlrev_b64 v[20:21], 11, v[20:21]
	s_waitcnt lgkmcnt(0)
	v_cvt_pk_bf16_f32 v13, v14, v15
	ds_read2_b32 v[14:15], v31 offset0:140 offset1:173
	v_lshl_add_u64 v[20:21], v[18:19], 0, v[20:21]
	s_waitcnt lgkmcnt(0)
	v_cvt_pk_bf16_f32 v14, v14, v15
	ds_read2_b32 v[16:17], v31 offset0:206 offset1:239
	s_waitcnt lgkmcnt(0)
	v_cvt_pk_bf16_f32 v15, v16, v17
	global_store_dwordx4 v[20:21], v[12:15], off sc1
	v_or_b32_e32 v20, s22, v33
	ds_read2_b32 v[16:17], v31 offset0:16 offset1:49
	s_waitcnt lgkmcnt(0)
	v_cvt_pk_bf16_f32 v12, v16, v17
	ds_read2_b32 v[14:15], v31 offset0:82 offset1:115
	v_ashrrev_i32_e32 v21, 31, v20
	s_waitcnt lgkmcnt(0)
	v_cvt_pk_bf16_f32 v13, v14, v15
	ds_read2_b32 v[14:15], v31 offset0:148 offset1:181
	v_lshlrev_b64 v[20:21], 11, v[20:21]
	s_waitcnt lgkmcnt(0)
	v_cvt_pk_bf16_f32 v14, v14, v15
	ds_read2_b32 v[16:17], v31 offset0:214 offset1:247
	s_waitcnt lgkmcnt(0)
	v_cvt_pk_bf16_f32 v15, v16, v17
	v_lshl_add_u64 v[20:21], v[18:19], 0, v[20:21]
	ds_read2_b32 v[16:17], v31 offset0:24 offset1:57
	global_store_dwordx4 v[20:21], v[12:15], off sc1
	v_or_b32_e32 v20, s22, v34
	v_ashrrev_i32_e32 v21, 31, v20
	s_waitcnt lgkmcnt(0)
	v_cvt_pk_bf16_f32 v12, v16, v17
	ds_read2_b32 v[14:15], v31 offset0:90 offset1:123
	s_waitcnt lgkmcnt(0)
	v_cvt_pk_bf16_f32 v13, v14, v15
	ds_read2_b32 v[14:15], v31 offset0:156 offset1:189
	s_waitcnt lgkmcnt(0)
	v_cvt_pk_bf16_f32 v14, v14, v15
	ds_read2_b32 v[16:17], v31 offset0:222 offset1:255
	v_lshlrev_b64 v[20:21], 11, v[20:21]
	s_waitcnt lgkmcnt(0)
	v_cvt_pk_bf16_f32 v15, v16, v17
	v_lshl_add_u64 v[16:17], v[18:19], 0, v[20:21]
	global_store_dwordx4 v[16:17], v[12:15], off sc1
	s_waitcnt lgkmcnt(0)

; #define LAS __attribute__((address_space(3)))
; __device__ __forceinline__ void transpose_item(const float* W, int N, bf16* WT, int K, int k0, int n0, int drow0, const float* gk, LAS float* scr, int lane) {
;     float wv[32];
; #pragma unroll
;     for (int i = 0; i < 32; ++i) wv[i] = W[(size_t)(k0 + 2 * i + (lane >> 5)) * N + n0 + (lane & 31)];
; __device__ __forceinline__ void p0_weight_item(const Args& a, int l, int r, LAS float* scr, int lane) {
;     ...
;         if (r < IT_BIG) { const int kb = r / 32, nb = r % 32; const float* W = a.in[f ? 31 : 4] + (size_t)l * FF * DM;
;             transpose_item(W, DM, dn, FF, 64 * kb, 32 * nb, 32 * nb, nullptr, scr, lane); return; }
.LBB0_119:
	s_andn2_b64 vcc, exec, s[4:5]
	s_cbranch_vccnz .LBB0_121
	v_readlane_b32 s52, v250, 11
	v_readlane_b32 s60, v250, 19
	v_readlane_b32 s61, v250, 20
	s_add_u32 s22, s60, s86
	s_mul_i32 s4, s26, 0xffffaea0
	s_addc_u32 s27, s61, s85
	s_add_i32 s4, s45, s4
	s_and_b32 s5, s4, 0x7fffffc0
	s_lshl_b32 s4, s26, 9
	s_sub_i32 s4, s43, s4
	s_and_b32 s4, s4, 0x3e0
	s_lshl_b32 s26, s4, 2
	v_or_b32_e32 v12, s5, v4
	s_add_u32 s26, s22, s26
	s_addc_u32 s27, s27, 0
	v_mov_b32_e32 v13, v7
	v_or_b32_e32 v18, 2, v12
	v_mov_b32_e32 v19, v7
	v_or_b32_e32 v20, 4, v12
	v_mov_b32_e32 v21, v7
	v_or_b32_e32 v22, 6, v12
	v_mov_b32_e32 v23, v7
	v_or_b32_e32 v24, 8, v12
	v_mov_b32_e32 v25, v7
	v_or_b32_e32 v26, 10, v12
	v_mov_b32_e32 v27, v7
	v_or_b32_e32 v28, 12, v12
	v_mov_b32_e32 v29, v7
	v_or_b32_e32 v56, 14, v12
	v_mov_b32_e32 v57, v7
	v_lshl_add_u64 v[14:15], s[26:27], 0, v[6:7]
	v_lshlrev_b64 v[16:17], 12, v[12:13]
	v_lshlrev_b64 v[18:19], 12, v[18:19]
	v_lshlrev_b64 v[20:21], 12, v[20:21]
	v_lshlrev_b64 v[22:23], 12, v[22:23]
	v_lshlrev_b64 v[24:25], 12, v[24:25]
	v_lshlrev_b64 v[26:27], 12, v[26:27]
	v_lshlrev_b64 v[28:29], 12, v[28:29]
	v_lshlrev_b64 v[56:57], 12, v[56:57]
	v_lshl_add_u64 v[16:17], v[14:15], 0, v[16:17]
	v_lshl_add_u64 v[18:19], v[14:15], 0, v[18:19]
	v_lshl_add_u64 v[20:21], v[14:15], 0, v[20:21]
	v_lshl_add_u64 v[22:23], v[14:15], 0, v[22:23]
	v_lshl_add_u64 v[24:25], v[14:15], 0, v[24:25]
	v_lshl_add_u64 v[26:27], v[14:15], 0, v[26:27]
	v_lshl_add_u64 v[28:29], v[14:15], 0, v[28:29]
	v_lshl_add_u64 v[56:57], v[14:15], 0, v[56:57]
	global_load_dword v9, v[16:17], off nt
	global_load_dword v11, v[18:19], off nt
	global_load_dword v55, v[20:21], off nt
	global_load_dword v58, v[22:23], off nt
	global_load_dword v59, v[24:25], off nt
	global_load_dword v60, v[26:27], off nt
	global_load_dword v61, v[28:29], off nt
	global_load_dword v62, v[56:57], off nt
	v_or_b32_e32 v16, 16, v12
	v_mov_b32_e32 v17, v7
	v_or_b32_e32 v18, 18, v12
	v_mov_b32_e32 v19, v7
	v_or_b32_e32 v20, 20, v12
	v_mov_b32_e32 v21, v7
	v_or_b32_e32 v22, 22, v12
	v_mov_b32_e32 v23, v7
	v_or_b32_e32 v24, 24, v12
	v_mov_b32_e32 v25, v7
	v_or_b32_e32 v26, 26, v12
	v_mov_b32_e32 v27, v7
	v_or_b32_e32 v28, 28, v12
	v_mov_b32_e32 v29, v7
	v_or_b32_e32 v56, 30, v12
	v_mov_b32_e32 v57, v7
	v_lshlrev_b64 v[16:17], 12, v[16:17]
	v_lshlrev_b64 v[18:19], 12, v[18:19]
	v_lshlrev_b64 v[20:21], 12, v[20:21]
	v_lshlrev_b64 v[22:23], 12, v[22:23]
	v_lshlrev_b64 v[24:25], 12, v[24:25]
	v_lshlrev_b64 v[26:27], 12, v[26:27]
	v_lshlrev_b64 v[28:29], 12, v[28:29]
	v_lshlrev_b64 v[56:57], 12, v[56:57]
	v_lshl_add_u64 v[16:17], v[14:15], 0, v[16:17]
	v_lshl_add_u64 v[18:19], v[14:15], 0, v[18:19]
	v_lshl_add_u64 v[20:21], v[14:15], 0, v[20:21]
	v_lshl_add_u64 v[22:23], v[14:15], 0, v[22:23]
	v_lshl_add_u64 v[24:25], v[14:15], 0, v[24:25]
	v_lshl_add_u64 v[26:27], v[14:15], 0, v[26:27]
	v_lshl_add_u64 v[28:29], v[14:15], 0, v[28:29]
	v_lshl_add_u64 v[56:57], v[14:15], 0, v[56:57]
	global_load_dword v63, v[16:17], off nt
	global_load_dword v64, v[18:19], off nt
	global_load_dword v65, v[20:21], off nt
	global_load_dword v66, v[22:23], off nt
	global_load_dword v67, v[24:25], off nt
	global_load_dword v68, v[26:27], off nt
	global_load_dword v69, v[28:29], off nt
	global_load_dword v70, v[56:57], off nt
	v_or_b32_e32 v16, 32, v12
	v_mov_b32_e32 v17, v7
	v_or_b32_e32 v18, 34, v12
	v_mov_b32_e32 v19, v7
	v_or_b32_e32 v20, 36, v12
	v_mov_b32_e32 v21, v7
	v_or_b32_e32 v22, 38, v12
	v_mov_b32_e32 v23, v7
	v_or_b32_e32 v24, 40, v12
	v_mov_b32_e32 v25, v7
	v_or_b32_e32 v26, 42, v12
	v_mov_b32_e32 v27, v7
	v_or_b32_e32 v28, 44, v12
	v_mov_b32_e32 v29, v7
	v_or_b32_e32 v56, 46, v12
	v_mov_b32_e32 v57, v7
	v_lshlrev_b64 v[16:17], 12, v[16:17]
	v_lshlrev_b64 v[18:19], 12, v[18:19]
	v_lshlrev_b64 v[20:21], 12, v[20:21]
	v_lshlrev_b64 v[22:23], 12, v[22:23]
	v_lshlrev_b64 v[24:25], 12, v[24:25]
	v_lshlrev_b64 v[26:27], 12, v[26:27]
	v_lshlrev_b64 v[28:29], 12, v[28:29]
	v_lshlrev_b64 v[56:57], 12, v[56:57]
	v_lshl_add_u64 v[16:17], v[14:15], 0, v[16:17]
	v_lshl_add_u64 v[18:19], v[14:15], 0, v[18:19]
	v_lshl_add_u64 v[20:21], v[14:15], 0, v[20:21]
	v_lshl_add_u64 v[22:23], v[14:15], 0, v[22:23]
	v_lshl_add_u64 v[24:25], v[14:15], 0, v[24:25]
	v_lshl_add_u64 v[26:27], v[14:15], 0, v[26:27]
	v_lshl_add_u64 v[28:29], v[14:15], 0, v[28:29]
	v_lshl_add_u64 v[56:57], v[14:15], 0, v[56:57]
	global_load_dword v71, v[16:17], off nt
	global_load_dword v72, v[18:19], off nt
	global_load_dword v73, v[20:21], off nt
	global_load_dword v74, v[22:23], off nt
	global_load_dword v75, v[24:25], off nt
	global_load_dword v76, v[26:27], off nt
	global_load_dword v77, v[28:29], off nt
	s_nop 0
	global_load_dword v56, v[56:57], off nt
	v_or_b32_e32 v16, 48, v12
	v_mov_b32_e32 v17, v7
	v_or_b32_e32 v18, 50, v12
	v_mov_b32_e32 v19, v7
	v_or_b32_e32 v20, 52, v12
	v_mov_b32_e32 v21, v7
	v_or_b32_e32 v22, 54, v12
	v_or_b32_e32 v24, 56, v12
	v_or_b32_e32 v26, 58, v12
	v_or_b32_e32 v28, 60, v12
	v_or_b32_e32 v12, 62, v12
	v_lshlrev_b64 v[16:17], 12, v[16:17]
	v_lshlrev_b64 v[18:19], 12, v[18:19]
	v_lshlrev_b64 v[20:21], 12, v[20:21]
	v_mov_b32_e32 v23, v7
	v_mov_b32_e32 v25, v7
	v_mov_b32_e32 v27, v7
	v_mov_b32_e32 v29, v7
	v_lshlrev_b64 v[12:13], 12, v[12:13]
	v_lshl_add_u64 v[16:17], v[14:15], 0, v[16:17]
	v_lshl_add_u64 v[18:19], v[14:15], 0, v[18:19]
	v_lshl_add_u64 v[20:21], v[14:15], 0, v[20:21]
	v_lshlrev_b64 v[22:23], 12, v[22:23]
	v_lshlrev_b64 v[24:25], 12, v[24:25]
	v_lshlrev_b64 v[26:27], 12, v[26:27]
	v_lshlrev_b64 v[28:29], 12, v[28:29]
	v_lshl_add_u64 v[12:13], v[14:15], 0, v[12:13]
	v_lshl_add_u64 v[22:23], v[14:15], 0, v[22:23]
	v_lshl_add_u64 v[24:25], v[14:15], 0, v[24:25]
	v_lshl_add_u64 v[26:27], v[14:15], 0, v[26:27]
	v_lshl_add_u64 v[28:29], v[14:15], 0, v[28:29]
	global_load_dword v14, v[16:17], off nt
	global_load_dword v15, v[18:19], off nt
	s_nop 0
	global_load_dword v16, v[20:21], off nt
	global_load_dword v17, v[22:23], off nt
	global_load_dword v18, v[24:25], off nt
	global_load_dword v19, v[26:27], off nt
	s_nop 0
	global_load_dword v20, v[28:29], off nt
	s_nop 0
	global_load_dword v12, v[12:13], off nt
	s_waitcnt vmcnt(30)
; #define LAS __attribute__((address_space(3)))
; __device__ __forceinline__ unsigned pk2(float lo, float hi) { return pg8::cvt_pk_bf16(lo, hi); }
; __device__ __forceinline__ void lds_wait() { asm volatile("s_waitcnt lgkmcnt(0)" ::: "memory"); }
; __device__ __forceinline__ void transpose_item(const float* W, int N, bf16* WT, int K, int k0, int n0, int drow0, const float* gk, LAS float* scr, int lane) {
;     ...
; #pragma unroll
;     for (int i = 0; i < 32; ++i) { const int kk = 2 * i + (lane >> 5); float v = wv[i]; if (gk) v *= gk[kk]; scr[kk * 33 + (lane & 31)] = v; }
;     lds_wait();
;     const int c = lane & 7;
; #pragma unroll
;     for (int j = 0; j < 4; ++j) { const int n = (lane >> 3) + 8 * j; const LAS float* s = scr + (8 * c) * 33 + n;
;         u32x4 o; o.x = pk2(s[0 * 33], s[1 * 33]); o.y = pk2(s[2 * 33], s[3 * 33]); o.z = pk2(s[4 * 33], s[5 * 33]); o.w = pk2(s[6 * 33], s[7 * 33]);
;         *(u32x4*)(WT + (size_t)(drow0 + n) * K + k0 + 8 * c) = o; }
;     lds_wait();
	ds_write2_b32 v5, v9, v11 offset1:66
	s_waitcnt vmcnt(28)
	ds_write2_b32 v5, v55, v58 offset0:132 offset1:198
	s_waitcnt vmcnt(26)
	ds_write2_b32 v48, v59, v60 offset0:8 offset1:74
	s_waitcnt vmcnt(24)
	ds_write2_b32 v48, v61, v62 offset0:140 offset1:206
	s_waitcnt vmcnt(22)
	ds_write2_b32 v49, v63, v64 offset0:16 offset1:82
	s_waitcnt vmcnt(20)
	ds_write2_b32 v49, v65, v66 offset0:148 offset1:214
	s_waitcnt vmcnt(18)
	ds_write2_b32 v50, v67, v68 offset0:24 offset1:90
	s_waitcnt vmcnt(16)
	ds_write2_b32 v50, v69, v70 offset0:156 offset1:222
	s_waitcnt vmcnt(14)
	ds_write2_b32 v51, v71, v72 offset0:32 offset1:98
	s_waitcnt vmcnt(12)
	ds_write2_b32 v51, v73, v74 offset0:164 offset1:230
	s_waitcnt vmcnt(10)
	ds_write2_b32 v52, v75, v76 offset0:40 offset1:106
	s_waitcnt vmcnt(8)
	ds_write2_b32 v52, v77, v56 offset0:172 offset1:238
	s_waitcnt vmcnt(6)
	ds_write2_b32 v53, v14, v15 offset0:48 offset1:114
	s_waitcnt vmcnt(4)
	ds_write2_b32 v53, v16, v17 offset0:180 offset1:246
	s_waitcnt vmcnt(2)
	ds_write2_b32 v54, v18, v19 offset0:56 offset1:122
	s_waitcnt vmcnt(0)
	ds_write2_b32 v54, v20, v12 offset0:188 offset1:254
	s_lshl_b32 s5, s5, 1
	s_waitcnt lgkmcnt(0)
	s_add_u32 s26, s84, s5
	ds_read2_b32 v[12:13], v31 offset1:33
	s_addc_u32 s27, s83, 0
	v_mov_b32_e32 v11, v7
	v_or_b32_e32 v9, s4, v30
	s_waitcnt lgkmcnt(0)
	v_cvt_pk_bf16_f32 v12, v12, v13
	ds_read2_b32 v[14:15], v31 offset0:66 offset1:99
	v_lshl_add_u64 v[18:19], s[26:27], 0, v[10:11]
	s_mov_b64 s[26:27], 0xb00000
	v_mul_u32_u24_e32 v9, 0xb00, v9
	s_waitcnt lgkmcnt(0)
	v_cvt_pk_bf16_f32 v13, v14, v15
	ds_read2_b32 v[14:15], v31 offset0:132 offset1:165
	v_lshl_add_u64 v[18:19], v[18:19], 0, s[26:27]
	v_lshlrev_b32_e32 v20, 1, v9
	v_mov_b32_e32 v21, v7
	s_waitcnt lgkmcnt(0)
	v_cvt_pk_bf16_f32 v14, v14, v15
	ds_read2_b32 v[16:17], v31 offset0:198 offset1:231
	s_waitcnt lgkmcnt(0)
	v_cvt_pk_bf16_f32 v15, v16, v17
	v_lshl_add_u64 v[20:21], v[18:19], 0, v[20:21]
	v_or_b32_e32 v9, s4, v32
	ds_read2_b32 v[16:17], v31 offset0:8 offset1:41
	global_store_dwordx4 v[20:21], v[12:15], off sc1
	v_mul_u32_u24_e32 v9, 0xb00, v9
	v_lshlrev_b32_e32 v20, 1, v9
	s_waitcnt lgkmcnt(0)
	v_cvt_pk_bf16_f32 v12, v16, v17
	ds_read2_b32 v[14:15], v31 offset0:74 offset1:107
	s_waitcnt lgkmcnt(0)
	v_cvt_pk_bf16_f32 v13, v14, v15
	ds_read2_b32 v[14:15], v31 offset0:140 offset1:173
	v_mov_b32_e32 v21, v7
	s_waitcnt lgkmcnt(0)
	v_cvt_pk_bf16_f32 v14, v14, v15
	ds_read2_b32 v[16:17], v31 offset0:206 offset1:239
	s_waitcnt lgkmcnt(0)
	v_cvt_pk_bf16_f32 v15, v16, v17
	v_lshl_add_u64 v[20:21], v[18:19], 0, v[20:21]
	v_or_b32_e32 v9, s4, v33
	ds_read2_b32 v[16:17], v31 offset0:16 offset1:49
	global_store_dwordx4 v[20:21], v[12:15], off sc1
	v_mul_u32_u24_e32 v9, 0xb00, v9
	v_lshlrev_b32_e32 v20, 1, v9
	s_waitcnt lgkmcnt(0)
	v_cvt_pk_bf16_f32 v12, v16, v17
	ds_read2_b32 v[14:15], v31 offset0:82 offset1:115
	s_waitcnt lgkmcnt(0)
	v_cvt_pk_bf16_f32 v13, v14, v15
	ds_read2_b32 v[14:15], v31 offset0:148 offset1:181
	v_mov_b32_e32 v21, v7
	s_waitcnt lgkmcnt(0)
	v_cvt_pk_bf16_f32 v14, v14, v15
	ds_read2_b32 v[16:17], v31 offset0:214 offset1:247
	s_waitcnt lgkmcnt(0)
	v_cvt_pk_bf16_f32 v15, v16, v17
	v_lshl_add_u64 v[20:21], v[18:19], 0, v[20:21]
	ds_read2_b32 v[16:17], v31 offset0:24 offset1:57
	global_store_dwordx4 v[20:21], v[12:15], off sc1
	v_or_b32_e32 v9, s4, v34
	v_mul_u32_u24_e32 v9, 0xb00, v9
	s_waitcnt lgkmcnt(0)
	v_cvt_pk_bf16_f32 v12, v16, v17
	ds_read2_b32 v[14:15], v31 offset0:90 offset1:123
	s_waitcnt lgkmcnt(0)
	v_cvt_pk_bf16_f32 v13, v14, v15
	ds_read2_b32 v[14:15], v31 offset0:156 offset1:189
	s_waitcnt lgkmcnt(0)
	v_cvt_pk_bf16_f32 v14, v14, v15
	ds_read2_b32 v[16:17], v31 offset0:222 offset1:255
	s_waitcnt lgkmcnt(0)
	v_cvt_pk_bf16_f32 v15, v16, v17
	v_lshlrev_b32_e32 v16, 1, v9
	v_mov_b32_e32 v17, v7
	v_lshl_add_u64 v[16:17], v[18:19], 0, v[16:17]
	global_store_dwordx4 v[16:17], v[12:15], off sc1
	s_waitcnt lgkmcnt(0)
	v_readlane_b32 s53, v250, 12
	v_readlane_b32 s54, v250, 13
	v_readlane_b32 s55, v250, 14
	v_readlane_b32 s56, v250, 15
	v_readlane_b32 s57, v250, 16
	v_readlane_b32 s58, v250, 17
	v_readlane_b32 s59, v250, 18
	v_readlane_b32 s62, v250, 21
	v_readlane_b32 s63, v250, 22
	v_readlane_b32 s64, v250, 23
	v_readlane_b32 s65, v250, 24
	v_readlane_b32 s66, v250, 25
	v_readlane_b32 s67, v250, 26

; #define LAS __attribute__((address_space(3)))
; __device__ __forceinline__ void transpose_item(const float* W, int N, bf16* WT, int K, int k0, int n0, int drow0, const float* gk, LAS float* scr, int lane) {
;     float wv[32];
; #pragma unroll
;     for (int i = 0; i < 32; ++i) wv[i] = W[(size_t)(k0 + 2 * i + (lane >> 5)) * N + n0 + (lane & 31)];
; __device__ __forceinline__ void p0_weight_item(const Args& a, int l, int r, LAS float* scr, int lane) {
;     ...
;         if (r < 2 * IT_BIG) { const int up = r >= IT_BIG; const int it = r - up * IT_BIG; const int kb = it / 88, nb = it % 88, k0 = 64 * kb, n0 = 32 * nb;
;             const float* W = a.in[(f ? 29 : 2) + up] + (size_t)l * DM * FF;
;             transpose_item(W, FF, gu, DM, k0, n0, (n0 >> 7) * 256 + up * 128 + (n0 & 127), nrm + k0, scr, lane); return; }
.LBB0_122:
	s_andn2_b64 vcc, exec, s[4:5]
	s_cbranch_vccnz .LBB0_9
	v_readlane_b32 s52, v250, 11
	v_readlane_b32 s54, v250, 13
	v_readlane_b32 s55, v250, 14
	s_add_u32 s29, s54, s24
	s_addc_u32 s31, s55, s25
	s_cmpk_gt_i32 s88, 0x57f
	s_cselect_b64 s[24:25], -1, 0
	s_and_b64 s[4:5], s[24:25], exec
	v_readlane_b32 s56, v250, 15
	v_readlane_b32 s57, v250, 16
	v_readlane_b32 s58, v250, 17
	v_readlane_b32 s59, v250, 18
	s_cselect_b32 s4, 0xfa80, 0
	s_cselect_b32 s5, s59, s57
	s_cselect_b32 s27, s58, s56
	s_sub_i32 s4, s4, s87
	s_add_i32 s4, s82, s4
	s_sext_i32_i16 s22, s4
	s_mulk_i32 s22, 0xba3
	s_lshr_b32 s26, s22, 31
	s_ashr_i32 s22, s22, 18
	s_add_i32 s26, s22, s26
	s_mul_i32 s22, s26, 0x58
	s_sub_i32 s4, s4, s22
	s_sext_i32_i16 s22, s4
	s_lshl_b32 s26, s26, 6
	s_lshl_b32 s28, s22, 5
	s_add_u32 s34, s27, s86
	s_addc_u32 s35, s5, s85
	s_ashr_i32 s27, s26, 31
	s_lshl_b64 s[4:5], s[26:27], 2
	s_add_u32 s30, s29, s4
	s_addc_u32 s31, s31, s5
	s_ashr_i32 s29, s28, 31
	s_lshl_b64 s[4:5], s[28:29], 2
	v_or_b32_e32 v9, s26, v4
	s_add_u32 s4, s34, s4
	s_addc_u32 s5, s35, s5
	v_mul_i32_i24_e32 v14, 0x2c00, v9
	v_lshl_add_u64 v[12:13], s[4:5], 0, v[6:7]
	v_ashrrev_i32_e32 v15, 31, v14
	v_lshl_add_u64 v[12:13], v[12:13], 0, v[14:15]
	v_add_co_u32_e32 v14, vcc, s93, v12
	v_readlane_b32 s53, v250, 12
	s_nop 0
	v_addc_co_u32_e32 v15, vcc, 0, v13, vcc
	v_add_co_u32_e32 v16, vcc, s94, v12
	v_readlane_b32 s60, v250, 19
	s_nop 0
	v_addc_co_u32_e32 v17, vcc, 0, v13, vcc
	v_add_co_u32_e32 v18, vcc, s95, v12
	v_readlane_b32 s61, v250, 20
	s_nop 0
	v_addc_co_u32_e32 v19, vcc, 0, v13, vcc
	v_add_co_u32_e32 v20, vcc, s96, v12
	v_readlane_b32 s62, v250, 21
	s_nop 0
	v_addc_co_u32_e32 v21, vcc, 0, v13, vcc
	v_add_co_u32_e32 v22, vcc, s97, v12
	v_readlane_b32 s63, v250, 22
	s_nop 0
	v_addc_co_u32_e32 v23, vcc, 0, v13, vcc
	v_add_co_u32_e32 v24, vcc, s51, v12
	v_readlane_b32 s64, v250, 23
	s_nop 0
	v_addc_co_u32_e32 v25, vcc, 0, v13, vcc
	v_add_co_u32_e32 v28, vcc, s2, v12
	v_readlane_b32 s65, v250, 24
	s_nop 0
	v_addc_co_u32_e32 v29, vcc, 0, v13, vcc
	global_load_dword v68, v[12:13], off nt
	global_load_dword v69, v[14:15], off offset:2048 nt
	global_load_dword v26, v[16:17], off nt
	global_load_dword v27, v[18:19], off offset:2048 nt
	global_load_dword v66, v[20:21], off nt
	global_load_dword v67, v[22:23], off offset:2048 nt
	s_nop 0
	global_load_dword v24, v[24:25], off nt
	s_nop 0
	global_load_dword v25, v[28:29], off offset:2048 nt
	v_add_co_u32_e32 v14, vcc, s6, v12
	v_readlane_b32 s66, v250, 25
	s_nop 0
	v_addc_co_u32_e32 v15, vcc, 0, v13, vcc
	v_add_co_u32_e32 v16, vcc, s7, v12
	v_readlane_b32 s67, v250, 26
	s_nop 0
	v_addc_co_u32_e32 v17, vcc, 0, v13, vcc
	v_add_co_u32_e32 v18, vcc, s20, v12
	s_nop 1
	v_addc_co_u32_e32 v19, vcc, 0, v13, vcc
	v_add_co_u32_e32 v20, vcc, s21, v12
	s_nop 1
	v_addc_co_u32_e32 v21, vcc, 0, v13, vcc
	v_add_co_u32_e32 v28, vcc, s23, v12
	s_nop 1
	v_addc_co_u32_e32 v29, vcc, 0, v13, vcc
	v_add_co_u32_e32 v56, vcc, s36, v12
	s_nop 1
	v_addc_co_u32_e32 v57, vcc, 0, v13, vcc
	v_add_co_u32_e32 v58, vcc, s37, v12
	s_nop 1
	v_addc_co_u32_e32 v59, vcc, 0, v13, vcc
	v_add_co_u32_e32 v60, vcc, s68, v12
	s_nop 1
	v_addc_co_u32_e32 v61, vcc, 0, v13, vcc
	global_load_dword v64, v[14:15], off nt
	global_load_dword v65, v[16:17], off offset:2048 nt
	global_load_dword v22, v[18:19], off nt
	global_load_dword v23, v[20:21], off offset:2048 nt
	global_load_dword v62, v[28:29], off nt
	global_load_dword v63, v[56:57], off offset:2048 nt
	s_nop 0
	global_load_dword v20, v[58:59], off nt
	global_load_dword v21, v[60:61], off offset:2048 nt
	v_add_co_u32_e32 v14, vcc, s69, v12
	s_nop 1
	v_addc_co_u32_e32 v15, vcc, 0, v13, vcc
	v_add_co_u32_e32 v16, vcc, s70, v12
	s_nop 1
	v_addc_co_u32_e32 v17, vcc, 0, v13, vcc
	v_add_co_u32_e32 v18, vcc, s71, v12
	s_nop 1
	v_addc_co_u32_e32 v19, vcc, 0, v13, vcc
	v_add_co_u32_e32 v28, vcc, s72, v12
	s_nop 1
	v_addc_co_u32_e32 v29, vcc, 0, v13, vcc
	v_add_co_u32_e32 v56, vcc, s73, v12
	s_nop 1
	v_addc_co_u32_e32 v57, vcc, 0, v13, vcc
	v_add_co_u32_e32 v58, vcc, s74, v12
	s_nop 1
	v_addc_co_u32_e32 v59, vcc, 0, v13, vcc
	v_add_co_u32_e32 v70, vcc, s75, v12
	s_nop 1
	v_addc_co_u32_e32 v71, vcc, 0, v13, vcc
	v_add_co_u32_e32 v72, vcc, s76, v12
	s_nop 1
	v_addc_co_u32_e32 v73, vcc, 0, v13, vcc
	global_load_dword v60, v[14:15], off nt
	global_load_dword v61, v[16:17], off offset:2048 nt
	s_nop 0
	global_load_dword v18, v[18:19], off nt
	s_nop 0
	global_load_dword v19, v[28:29], off offset:2048 nt
	global_load_dword v55, v[56:57], off nt
	s_nop 0
	global_load_dword v56, v[58:59], off offset:2048 nt
	global_load_dword v14, v[70:71], off nt
	global_load_dword v15, v[72:73], off offset:2048 nt
	v_add_co_u32_e32 v16, vcc, s77, v12
	v_lshlrev_b32_e32 v57, 2, v4
	s_nop 0
	v_addc_co_u32_e32 v17, vcc, 0, v13, vcc
	v_add_co_u32_e32 v28, vcc, s78, v12
	s_nop 1
	v_addc_co_u32_e32 v29, vcc, 0, v13, vcc
	v_add_co_u32_e32 v70, vcc, s79, v12
	s_nop 1
	v_addc_co_u32_e32 v71, vcc, 0, v13, vcc
	v_add_co_u32_e32 v72, vcc, s80, v12
	s_nop 1
	v_addc_co_u32_e32 v73, vcc, 0, v13, vcc
	v_add_co_u32_e32 v74, vcc, s81, v12
	s_nop 1
	v_addc_co_u32_e32 v75, vcc, 0, v13, vcc
	v_add_co_u32_e32 v76, vcc, 0x9f000, v12
	s_nop 1
	v_addc_co_u32_e32 v77, vcc, 0, v13, vcc
	v_add_co_u32_e32 v78, vcc, 0xa5000, v12
	s_nop 1
	v_addc_co_u32_e32 v79, vcc, 0, v13, vcc
	v_add_co_u32_e32 v80, vcc, 0xaa000, v12
	s_nop 1
	v_addc_co_u32_e32 v81, vcc, 0, v13, vcc
	global_load_dword v58, v[16:17], off nt
	global_load_dword v59, v[28:29], off offset:2048 nt
	s_nop 0
	global_load_dword v16, v[70:71], off nt
	global_load_dword v17, v[72:73], off offset:2048 nt
	global_load_dword v9, v[74:75], off nt
	global_load_dword v11, v[76:77], off offset:2048 nt
	global_load_dword v12, v[78:79], off nt
	global_load_dword v13, v[80:81], off offset:2048 nt
	v_cndmask_b32_e64 v28, 0, 1, s[10:11]
	v_cmp_ne_u32_e64 s[4:5], 1, v28
	s_andn2_b64 vcc, exec, s[10:11]
	v_add_u32_e32 v70, v3, v35
	s_cbranch_vccnz .LBB0_146
; __device__ __forceinline__ void transpose_item(const float* W, int N, bf16* WT, int K, int k0, int n0, int drow0, const float* gk, LAS float* scr, int lane) {
;     ...
; #pragma unroll
;     for (int i = 0; i < 32; ++i) { const int kk = 2 * i + (lane >> 5); float v = wv[i]; if (gk) v *= gk[kk]; scr[kk * 33 + (lane & 31)] = v; }
	s_waitcnt vmcnt(32)
	global_load_dword v204, v57, s[30:31]
	global_load_dword v205, v57, s[30:31] offset:8
	global_load_dword v206, v57, s[30:31] offset:16
	global_load_dword v207, v57, s[30:31] offset:24
	global_load_dword v208, v57, s[30:31] offset:32
	global_load_dword v209, v57, s[30:31] offset:40
	global_load_dword v210, v57, s[30:31] offset:48
	global_load_dword v211, v57, s[30:31] offset:56
	global_load_dword v212, v57, s[30:31] offset:64
	global_load_dword v213, v57, s[30:31] offset:72
	global_load_dword v214, v57, s[30:31] offset:80
	global_load_dword v215, v57, s[30:31] offset:88
	global_load_dword v216, v57, s[30:31] offset:96
	global_load_dword v217, v57, s[30:31] offset:104
	global_load_dword v218, v57, s[30:31] offset:112
	global_load_dword v219, v57, s[30:31] offset:120
	global_load_dword v220, v57, s[30:31] offset:128
	global_load_dword v221, v57, s[30:31] offset:136
	global_load_dword v222, v57, s[30:31] offset:144
	global_load_dword v223, v57, s[30:31] offset:152
	global_load_dword v224, v57, s[30:31] offset:160
	global_load_dword v225, v57, s[30:31] offset:168
	global_load_dword v226, v57, s[30:31] offset:176
	global_load_dword v227, v57, s[30:31] offset:184
	global_load_dword v228, v57, s[30:31] offset:192
	global_load_dword v229, v57, s[30:31] offset:200
	global_load_dword v230, v57, s[30:31] offset:208
	global_load_dword v231, v57, s[30:31] offset:216
	global_load_dword v232, v57, s[30:31] offset:224
	global_load_dword v233, v57, s[30:31] offset:232
	global_load_dword v234, v57, s[30:31] offset:240
	s_waitcnt vmcnt(62)
	global_load_dword v235, v57, s[30:31] offset:248
	s_waitcnt vmcnt(0)
	v_mov_b32_e32 v71, v204
	v_mov_b32_e32 v72, v205
	v_mov_b32_e32 v28, v206
	v_mov_b32_e32 v29, v207
	s_waitcnt vmcnt(3)
	v_mul_f32_e32 v71, v68, v71
	s_waitcnt vmcnt(2)
	v_mul_f32_e32 v72, v69, v72
	ds_write_b32 v5, v71
	ds_write_b32 v70, v72
	s_waitcnt vmcnt(0)
	v_pk_mul_f32 v[28:29], v[26:27], v[28:29]
	s_cbranch_execnz .LBB0_126

; __device__ __forceinline__ unsigned pk2(float lo, float hi) { return pg8::cvt_pk_bf16(lo, hi); }
; __device__ __forceinline__ void p0_prologue(const Args& a, LAS unsigned char* lds, int tid, int lane, int wave, int G) {
;     ...
;     const float* x = a.in[0]; bf16* xb = (bf16*)(a.ws + WS_XB); float* ssq = (float*)(a.ws + WS_SSQ);
;     for (int m = gw; m < NTOK; m += NGW) {
;         const f32x4* xr = (const f32x4*)(x + (size_t)m * DM) + lane; u32x2* brow = (u32x2*)(xb + (size_t)m * DM) + lane;
;         float s = 0.f;
; #pragma unroll
;         for (int j = 0; j < 4; ++j) { const f32x4 v = xr[64 * j]; u32x2 w; w.x = pk2(v.x, v.y); w.y = pk2(v.z, v.w); brow[64 * j] = w; s += (v.x * v.x + v.y * v.y) + (v.z * v.z + v.w * v.w); }
;         s = wave_sum(s);
;         if (lane < 16) ssq[(size_t)m * 16 + lane] = (lane == 0) ? s : 0.f;
.LBB0_178:
	s_cmpk_gt_i32 s0, 0x3fff
	v_lshlrev_b32_e32 v6, 2, v2
	v_lshlrev_b32_e32 v8, 4, v2
	v_mbcnt_lo_u32_b32 v22, -1, 0
	s_cbranch_scc1 .LBB0_183
	s_ashr_i32 s1, s0, 31
	s_lshl_b64 s[8:9], s[0:1], 6
	v_mov_b32_e32 v7, 0
	v_lshl_add_u64 v[4:5], s[8:9], 0, v[6:7]
	s_mov_b64 s[8:9], 0x500000
	s_ashr_i32 s91, s90, 31
	s_lshl_b64 s[10:11], s[0:1], 11
	v_lshl_add_u64 v[4:5], v[4:5], 0, s[8:9]
	s_lshl_b64 s[8:9], s[90:91], 6
	v_lshl_or_b32 v10, v2, 3, s10
	v_mov_b32_e32 v11, s11
	s_lshl_b64 s[10:11], s[90:91], 11
	s_lshl_b64 s[22:23], s[0:1], 12
	v_readlane_b32 s40, v250, 11
	v_readlane_b32 s41, v250, 12
	s_add_u32 s22, s40, s22
	v_mov_b32_e32 v9, v7
	s_addc_u32 s23, s41, s23
	v_mbcnt_hi_u32_b32 v3, -1, v22
	v_lshl_add_u64 v[12:13], s[22:23], 0, v[8:9]
	s_mov_b64 s[22:23], 0xc00
	v_and_b32_e32 v7, 64, v3
	v_cmp_gt_u32_e64 s[6:7], 16, v2
	v_cmp_eq_u32_e64 s[4:5], 0, v2
	v_lshl_add_u64 v[12:13], v[12:13], 0, s[22:23]
	s_lshl_b64 s[22:23], s[90:91], 12
	v_add_u32_e32 v7, 64, v7
	v_xor_b32_e32 v9, 1, v3
	v_xor_b32_e32 v14, 2, v3
	v_xor_b32_e32 v15, 4, v3
	v_xor_b32_e32 v16, 8, v3
	v_xor_b32_e32 v17, 16, v3
	v_xor_b32_e32 v18, 32, v3
	v_readlane_b32 s42, v250, 13
	v_readlane_b32 s43, v250, 14
	v_readlane_b32 s44, v250, 15
	v_readlane_b32 s45, v250, 16
	v_readlane_b32 s46, v250, 17
	v_readlane_b32 s47, v250, 18
	v_readlane_b32 s48, v250, 19
	v_readlane_b32 s49, v250, 20
	v_readlane_b32 s50, v250, 21
	v_readlane_b32 s51, v250, 22
	v_readlane_b32 s52, v250, 23
	v_readlane_b32 s53, v250, 24
	v_readlane_b32 s54, v250, 25
	v_readlane_b32 s55, v250, 26
	global_load_dwordx4 v[24:27], v[12:13], off offset:-3072 nt
	global_load_dwordx4 v[28:31], v[12:13], off offset:-2048 nt
	global_load_dwordx4 v[32:35], v[12:13], off offset:-1024 nt
	global_load_dwordx4 v[36:39], v[12:13], off nt
	s_waitcnt vmcnt(0)
	s_branch .LBB0_181

; __device__ __forceinline__ unsigned pk2(float lo, float hi) { return pg8::cvt_pk_bf16(lo, hi); }
; __device__ __forceinline__ void p0_prologue(const Args& a, LAS unsigned char* lds, int tid, int lane, int wave, int G) {
;     ...
;     for (int m = gw; m < NTOK; m += NGW) {
;         const f32x4* xr = (const f32x4*)(x + (size_t)m * DM) + lane; u32x2* brow = (u32x2*)(xb + (size_t)m * DM) + lane;
;         float s = 0.f;
; #pragma unroll
;         for (int j = 0; j < 4; ++j) { const f32x4 v = xr[64 * j]; u32x2 w; w.x = pk2(v.x, v.y); w.y = pk2(v.z, v.w); brow[64 * j] = w; s += (v.x * v.x + v.y * v.y) + (v.z * v.z + v.w * v.w); }
.LBB0_181:
	s_add_i32 vcc_lo, s0, s90
	s_cmpk_gt_i32 vcc_lo, 0x3fff
	s_cbranch_scc1 .Lx_nopf
	v_lshl_add_u64 v[44:45], v[12:13], 0, s[22:23]
	global_load_dwordx4 v[48:51], v[44:45], off offset:-3072 nt
	global_load_dwordx4 v[52:55], v[44:45], off offset:-2048 nt
	global_load_dwordx4 v[56:59], v[44:45], off offset:-1024 nt
	global_load_dwordx4 v[60:63], v[44:45], off nt

; #define LAS __attribute__((address_space(3)))
; __device__ __forceinline__ unsigned pk2(float lo, float hi) { return pg8::cvt_pk_bf16(lo, hi); }
; __device__ __forceinline__ void lds_wait() { asm volatile("s_waitcnt lgkmcnt(0)" ::: "memory"); }
; __device__ __forceinline__ void transpose_item(const float* W, int N, bf16* WT, int K, int k0, int n0, int drow0, const float* gk, LAS float* scr, int lane) {
;     float wv[32];
; #pragma unroll
;     for (int i = 0; i < 32; ++i) wv[i] = W[(size_t)(k0 + 2 * i + (lane >> 5)) * N + n0 + (lane & 31)];
; #pragma unroll
;     for (int i = 0; i < 32; ++i) { const int kk = 2 * i + (lane >> 5); float v = wv[i]; if (gk) v *= gk[kk]; scr[kk * 33 + (lane & 31)] = v; }
;     lds_wait();
;     const int c = lane & 7;
; #pragma unroll
;     for (int j = 0; j < 4; ++j) { const int n = (lane >> 3) + 8 * j; const LAS float* s = scr + (8 * c) * 33 + n;
;         u32x4 o; o.x = pk2(s[0 * 33], s[1 * 33]); o.y = pk2(s[2 * 33], s[3 * 33]); o.z = pk2(s[4 * 33], s[5 * 33]); o.w = pk2(s[6 * 33], s[7 * 33]);
;         *(u32x4*)(WT + (size_t)(drow0 + n) * K + k0 + 8 * c) = o; }
;     lds_wait();
; __device__ __forceinline__ void p0_weight_item(const Args& a, int l, int r, LAS float* scr, int lane) {
;     ...
;     if (r < IT_OUT) {
;         const int kb = r / 32, nb = r % 32, k0 = 64 * kb;
;         const float* gk = (k0 < 256) ? a.in[17] + (size_t)l * 256 + k0 : (k0 < 768 ? a.in[18] + (size_t)l * 512 + (k0 - 256) : a.in[26] + (size_t)l * 256 + (k0 - 768));
;         transpose_item(a.in[27] + (size_t)l * DM * DM, DM, (bf16*)(wl + WL_WOUT), DM, k0, 32 * nb, 32 * nb, gk, scr, lane); return; }
;     r -= IT_OUT;
;     if (r < IT_GLU) { const int kb = r / 8, nb = r % 8; transpose_item(a.in[15] + (size_t)l * 65536, 256, (bf16*)(wl + WL_GLU), 256, 64 * kb, 32 * nb, 32 * nb, nullptr, scr, lane); return; }
;     r -= IT_GLU;
;     if (r < IT_LW) { const int blk = r >> 1, nb = r & 1; transpose_item(a.in[21] + (size_t)l * 16384 + blk * 4096, 64, (bf16*)(wl + WL_WA) + blk * 4096, 64, 0, 32 * nb, 32 * nb, nullptr, scr, lane); return; }
;     r -= IT_LW;
;     { const int blk = r >> 1, nb = r & 1; transpose_item(a.in[23] + (size_t)l * 16384 + blk * 4096, 64, (bf16*)(wl + WL_WX) + blk * 4096, 64, 0, 32 * nb, 32 * nb, nullptr, scr, lane); }
.LBB0_1031:
	s_add_i32 s39, s27, 0x2100
	s_cmpk_gt_i32 s39, 0xaff
	s_mov_b64 s[0:1], -1
	s_cbranch_scc0 .LBB0_1143
	s_cmpk_gt_u32 s39, 0x107f
	s_cbranch_scc0 .LBB0_1140
	s_cmpk_gt_u32 s39, 0x1b7f
	s_cbranch_scc0 .LBB0_1113
	s_add_i32 s0, s27, 0x1080
	s_cmpk_lt_u32 s0, 0x1080
	s_mov_b64 s[0:1], -1
	s_cbranch_scc1 .LBB0_1110
	s_cmpk_gt_u32 s39, 0x267f
	s_cbranch_scc0 .LBB0_1081
	s_cmpk_gt_u32 s27, 0x77f
	s_cbranch_scc0 .LBB0_1046
	s_cmpk_gt_u32 s27, 0x79f
	s_cbranch_scc0 .LBB0_1043
	s_add_i32 s0, s35, 0xfffba000
	s_and_b32 s4, s0, 32
	s_cmpk_gt_u32 s27, 0x7a7
	s_mov_b64 s[0:1], -1
	v_lshlrev_b32_e32 v34, 2, v4
	v_or_b32_e32 v39, s4, v5
	v_or_b32_e32 v38, s4, v53
	v_or_b32_e32 v37, s4, v54
	v_or_b32_e32 v36, s4, v55
	s_cbranch_scc0 .LBB0_1040
	s_and_b32 s0, s34, 0x7ffff000
	s_add_i32 s82, s0, 0xffc2c000
	s_lshl_b64 s[0:1], s[82:83], 2
	v_readlane_b32 s5, v253, 55
	s_add_u32 s0, s5, s0
	v_readlane_b32 s5, v253, 56
	s_addc_u32 s1, s5, s1
	s_lshl_b32 s5, s4, 2
	s_add_u32 s0, s0, s5
	s_addc_u32 s1, s1, 0
	v_lshlrev_b32_e32 v144, 2, v2
	v_lshl_add_u64 v[40:41], s[0:1], 0, v[144:145]
	v_mov_b32_e32 v35, v145
	v_lshl_add_u64 v[40:41], v[40:41], 0, v[34:35]
	s_movk_i32 s0, 0x1000
	global_load_dword v35, v[40:41], off nt
	global_load_dword v46, v[40:41], off offset:512 nt
	global_load_dword v47, v[40:41], off offset:1024 nt
	global_load_dword v48, v[40:41], off offset:1536 nt
	global_load_dword v49, v[40:41], off offset:2048 nt
	global_load_dword v50, v[40:41], off offset:2560 nt
	global_load_dword v51, v[40:41], off offset:3072 nt
	global_load_dword v69, v[40:41], off offset:3584 nt
	v_add_co_u32_e32 v42, vcc, s0, v40
	s_movk_i32 s0, 0x2000
	s_nop 0
	v_addc_co_u32_e32 v43, vcc, 0, v41, vcc
	v_add_co_u32_e32 v44, vcc, s0, v40
	s_movk_i32 s0, 0x3000
	s_nop 0
	v_addc_co_u32_e32 v45, vcc, 0, v41, vcc
	global_load_dword v70, v[44:45], off offset:-4096 nt
	global_load_dword v71, v[42:43], off offset:512 nt
	global_load_dword v72, v[42:43], off offset:1024 nt
	global_load_dword v73, v[42:43], off offset:1536 nt
	global_load_dword v74, v[42:43], off offset:2048 nt
	global_load_dword v75, v[42:43], off offset:2560 nt
	global_load_dword v76, v[42:43], off offset:3072 nt
	s_nop 0
	global_load_dword v42, v[42:43], off offset:3584 nt
	s_nop 0
	global_load_dword v43, v[44:45], off nt
	global_load_dword v77, v[44:45], off offset:512 nt
	global_load_dword v78, v[44:45], off offset:1024 nt
	global_load_dword v79, v[44:45], off offset:1536 nt
	global_load_dword v80, v[44:45], off offset:2048 nt
	global_load_dword v81, v[44:45], off offset:2560 nt
	global_load_dword v82, v[44:45], off offset:3072 nt
	s_nop 0
	global_load_dword v44, v[44:45], off offset:3584 nt
	v_add_co_u32_e32 v40, vcc, s0, v40
	v_lshlrev_b32_e32 v144, 7, v39
	s_nop 0
	v_addc_co_u32_e32 v41, vcc, 0, v41, vcc
	global_load_dword v45, v[40:41], off nt
	global_load_dword v83, v[40:41], off offset:512 nt
	global_load_dword v84, v[40:41], off offset:1024 nt
	global_load_dword v85, v[40:41], off offset:1536 nt
	global_load_dword v86, v[40:41], off offset:2048 nt
	global_load_dword v87, v[40:41], off offset:2560 nt
	global_load_dword v88, v[40:41], off offset:3072 nt
	s_nop 0
	global_load_dword v40, v[40:41], off offset:3584 nt
	s_mov_b64 s[0:1], 0
	s_waitcnt vmcnt(0)
	ds_write2_b32 v3, v35, v46 offset1:66
	ds_write2_b32 v3, v47, v48 offset0:132 offset1:198
	v_add_u32_e32 v35, 0x400, v3
	ds_write2_b32 v35, v49, v50 offset0:8 offset1:74
	ds_write2_b32 v35, v51, v69 offset0:140 offset1:206
	v_add_u32_e32 v35, 0x800, v3
	ds_write2_b32 v35, v70, v71 offset0:16 offset1:82
	ds_write2_b32 v35, v72, v73 offset0:148 offset1:214
	v_add_u32_e32 v35, 0xc00, v3
	ds_write2_b32 v35, v74, v75 offset0:24 offset1:90
	ds_write2_b32 v35, v76, v42 offset0:156 offset1:222
	v_add_u32_e32 v35, 0x1000, v3
	ds_write2_b32 v35, v43, v77 offset0:32 offset1:98
	ds_write2_b32 v35, v78, v79 offset0:164 offset1:230
	v_add_u32_e32 v35, 0x1400, v3
	ds_write2_b32 v35, v80, v81 offset0:40 offset1:106
	ds_write2_b32 v35, v82, v44 offset0:172 offset1:238
	v_add_u32_e32 v35, 0x1800, v3
	ds_write2_b32 v35, v45, v83 offset0:48 offset1:114
	ds_write2_b32 v35, v84, v85 offset0:180 offset1:246
	v_add_u32_e32 v35, 0x1c00, v3
	ds_write2_b32 v35, v86, v87 offset0:56 offset1:122
	ds_write2_b32 v35, v88, v40 offset0:188 offset1:254
	s_waitcnt lgkmcnt(0)
	ds_read2_b32 v[40:41], v52 offset1:33
	s_waitcnt lgkmcnt(0)
	v_cvt_pk_bf16_f32 v40, v40, v41
	ds_read2_b32 v[42:43], v52 offset0:66 offset1:99
	s_waitcnt lgkmcnt(0)
	v_cvt_pk_bf16_f32 v41, v42, v43
	ds_read2_b32 v[42:43], v52 offset0:132 offset1:165
	v_lshl_add_u64 v[44:45], s[82:83], 1, v[10:11]
	s_waitcnt lgkmcnt(0)
	v_cvt_pk_bf16_f32 v42, v42, v43
	ds_read2_b32 v[46:47], v52 offset0:198 offset1:231
	s_waitcnt lgkmcnt(0)
	v_cvt_pk_bf16_f32 v43, v46, v47
	v_lshl_add_u64 v[46:47], v[44:45], 0, v[144:145]
	global_store_dwordx4 v[46:47], v[40:43], off sc1
	ds_read2_b32 v[40:41], v52 offset0:8 offset1:41
	v_lshlrev_b32_e32 v144, 7, v38
	s_waitcnt lgkmcnt(0)
	v_cvt_pk_bf16_f32 v40, v40, v41
	ds_read2_b32 v[42:43], v52 offset0:74 offset1:107
	s_waitcnt lgkmcnt(0)
	v_cvt_pk_bf16_f32 v41, v42, v43
	ds_read2_b32 v[42:43], v52 offset0:140 offset1:173
	s_waitcnt lgkmcnt(0)
	v_cvt_pk_bf16_f32 v42, v42, v43
	ds_read2_b32 v[46:47], v52 offset0:206 offset1:239
	s_waitcnt lgkmcnt(0)
	v_cvt_pk_bf16_f32 v43, v46, v47
	v_lshl_add_u64 v[46:47], v[44:45], 0, v[144:145]
	global_store_dwordx4 v[46:47], v[40:43], off sc1
	ds_read2_b32 v[40:41], v52 offset0:16 offset1:49
	v_lshlrev_b32_e32 v144, 7, v37
	s_waitcnt lgkmcnt(0)
	v_cvt_pk_bf16_f32 v40, v40, v41
	ds_read2_b32 v[42:43], v52 offset0:82 offset1:115
	s_waitcnt lgkmcnt(0)
	v_cvt_pk_bf16_f32 v41, v42, v43
	ds_read2_b32 v[42:43], v52 offset0:148 offset1:181
	s_waitcnt lgkmcnt(0)
	v_cvt_pk_bf16_f32 v42, v42, v43
	ds_read2_b32 v[46:47], v52 offset0:214 offset1:247
	s_waitcnt lgkmcnt(0)
	v_cvt_pk_bf16_f32 v43, v46, v47
	v_lshl_add_u64 v[46:47], v[44:45], 0, v[144:145]
	global_store_dwordx4 v[46:47], v[40:43], off sc1
	ds_read2_b32 v[40:41], v52 offset0:24 offset1:57
	v_lshlrev_b32_e32 v144, 7, v36
	s_waitcnt lgkmcnt(0)
	v_cvt_pk_bf16_f32 v40, v40, v41
	ds_read2_b32 v[42:43], v52 offset0:90 offset1:123
	s_waitcnt lgkmcnt(0)
	v_cvt_pk_bf16_f32 v41, v42, v43
	ds_read2_b32 v[42:43], v52 offset0:156 offset1:189
	v_lshl_add_u64 v[44:45], v[44:45], 0, v[144:145]
	s_waitcnt lgkmcnt(0)
	v_cvt_pk_bf16_f32 v42, v42, v43
	ds_read2_b32 v[46:47], v52 offset0:222 offset1:255
	s_waitcnt lgkmcnt(0)
	v_cvt_pk_bf16_f32 v43, v46, v47
	global_store_dwordx4 v[44:45], v[40:43], off sc1
	s_waitcnt lgkmcnt(0)
; #define LAS __attribute__((address_space(3)))
; __device__ __forceinline__ unsigned pk2(float lo, float hi) { return pg8::cvt_pk_bf16(lo, hi); }
; __device__ __forceinline__ void lds_wait() { asm volatile("s_waitcnt lgkmcnt(0)" ::: "memory"); }
; __device__ __forceinline__ void transpose_item(const float* W, int N, bf16* WT, int K, int k0, int n0, int drow0, const float* gk, LAS float* scr, int lane) {
;     float wv[32];
; #pragma unroll
;     for (int i = 0; i < 32; ++i) wv[i] = W[(size_t)(k0 + 2 * i + (lane >> 5)) * N + n0 + (lane & 31)];
; #pragma unroll
;     for (int i = 0; i < 32; ++i) { const int kk = 2 * i + (lane >> 5); float v = wv[i]; if (gk) v *= gk[kk]; scr[kk * 33 + (lane & 31)] = v; }
;     lds_wait();
;     const int c = lane & 7;
; #pragma unroll
;     for (int j = 0; j < 4; ++j) { const int n = (lane >> 3) + 8 * j; const LAS float* s = scr + (8 * c) * 33 + n;
;         u32x4 o; o.x = pk2(s[0 * 33], s[1 * 33]); o.y = pk2(s[2 * 33], s[3 * 33]); o.z = pk2(s[4 * 33], s[5 * 33]); o.w = pk2(s[6 * 33], s[7 * 33]);
;         *(u32x4*)(WT + (size_t)(drow0 + n) * K + k0 + 8 * c) = o; }
;     lds_wait();
; __device__ __forceinline__ void p0_weight_item(const Args& a, int l, int r, LAS float* scr, int lane) {
;     ...
;     if (r < IT_LW) { const int blk = r >> 1, nb = r & 1; transpose_item(a.in[21] + (size_t)l * 16384 + blk * 4096, 64, (bf16*)(wl + WL_WA) + blk * 4096, 64, 0, 32 * nb, 32 * nb, nullptr, scr, lane); return; }
;     r -= IT_LW;
;     { const int blk = r >> 1, nb = r & 1; transpose_item(a.in[23] + (size_t)l * 16384 + blk * 4096, 64, (bf16*)(wl + WL_WX) + blk * 4096, 64, 0, 32 * nb, 32 * nb, nullptr, scr, lane); }
.LBB0_1040:
	s_andn2_b64 vcc, exec, s[0:1]
	s_cbranch_vccnz .LBB0_1042
	s_and_b32 s0, s34, 0x3ff000
	s_add_i32 s82, s0, 0xffc30000
	s_lshl_b64 s[0:1], s[82:83], 2
	v_readlane_b32 s5, v253, 59
	s_add_u32 s0, s5, s0
	v_readlane_b32 s5, v253, 60
	s_addc_u32 s1, s5, s1
	s_lshl_b32 s4, s4, 2
	s_add_u32 s0, s0, s4
	s_addc_u32 s1, s1, 0
	v_lshlrev_b32_e32 v144, 2, v2
	v_lshl_add_u64 v[40:41], s[0:1], 0, v[144:145]
	v_mov_b32_e32 v35, v145
	v_lshl_add_u64 v[34:35], v[40:41], 0, v[34:35]
	s_movk_i32 s0, 0x1000
	global_load_dword v44, v[34:35], off nt
	global_load_dword v45, v[34:35], off offset:512 nt
	global_load_dword v46, v[34:35], off offset:1024 nt
	global_load_dword v47, v[34:35], off offset:1536 nt
	global_load_dword v48, v[34:35], off offset:2048 nt
	global_load_dword v49, v[34:35], off offset:2560 nt
	global_load_dword v50, v[34:35], off offset:3072 nt
	global_load_dword v51, v[34:35], off offset:3584 nt
	v_add_co_u32_e32 v40, vcc, s0, v34
	s_movk_i32 s0, 0x2000
	s_nop 0
	v_addc_co_u32_e32 v41, vcc, 0, v35, vcc
	v_add_co_u32_e32 v42, vcc, s0, v34
	s_movk_i32 s0, 0x3000
	s_nop 0
	v_addc_co_u32_e32 v43, vcc, 0, v35, vcc
	global_load_dword v69, v[42:43], off offset:-4096 nt
	global_load_dword v70, v[40:41], off offset:512 nt
	global_load_dword v71, v[40:41], off offset:1024 nt
	global_load_dword v72, v[40:41], off offset:1536 nt
	global_load_dword v73, v[40:41], off offset:2048 nt
	global_load_dword v74, v[40:41], off offset:2560 nt
	global_load_dword v75, v[40:41], off offset:3072 nt
	s_nop 0
	global_load_dword v40, v[40:41], off offset:3584 nt
	s_nop 0
	global_load_dword v41, v[42:43], off nt
	global_load_dword v76, v[42:43], off offset:512 nt
	global_load_dword v77, v[42:43], off offset:1024 nt
	global_load_dword v78, v[42:43], off offset:1536 nt
	global_load_dword v79, v[42:43], off offset:2048 nt
	global_load_dword v80, v[42:43], off offset:2560 nt
	global_load_dword v81, v[42:43], off offset:3072 nt
	s_nop 0
	global_load_dword v42, v[42:43], off offset:3584 nt
	v_add_co_u32_e32 v34, vcc, s0, v34
	v_lshlrev_b32_e32 v144, 7, v39
	s_nop 0
	v_addc_co_u32_e32 v35, vcc, 0, v35, vcc
	global_load_dword v43, v[34:35], off nt
	global_load_dword v82, v[34:35], off offset:512 nt
	global_load_dword v83, v[34:35], off offset:1024 nt
	global_load_dword v84, v[34:35], off offset:1536 nt
	global_load_dword v85, v[34:35], off offset:2048 nt
	global_load_dword v86, v[34:35], off offset:2560 nt
	global_load_dword v87, v[34:35], off offset:3072 nt
	s_nop 0
	global_load_dword v34, v[34:35], off offset:3584 nt
	v_add_u32_e32 v35, 0x400, v3
	s_waitcnt vmcnt(0)
	ds_write2_b32 v3, v44, v45 offset1:66
	ds_write2_b32 v3, v46, v47 offset0:132 offset1:198
	ds_write2_b32 v35, v48, v49 offset0:8 offset1:74
	ds_write2_b32 v35, v50, v51 offset0:140 offset1:206
	v_add_u32_e32 v35, 0x800, v3
	ds_write2_b32 v35, v69, v70 offset0:16 offset1:82
	ds_write2_b32 v35, v71, v72 offset0:148 offset1:214
	v_add_u32_e32 v35, 0xc00, v3
	ds_write2_b32 v35, v73, v74 offset0:24 offset1:90
	ds_write2_b32 v35, v75, v40 offset0:156 offset1:222
	v_add_u32_e32 v35, 0x1000, v3
	ds_write2_b32 v35, v41, v76 offset0:32 offset1:98
	ds_write2_b32 v35, v77, v78 offset0:164 offset1:230
	v_add_u32_e32 v35, 0x1400, v3
	ds_write2_b32 v35, v79, v80 offset0:40 offset1:106
	ds_write2_b32 v35, v81, v42 offset0:172 offset1:238
	v_add_u32_e32 v35, 0x1800, v3
	ds_write2_b32 v35, v43, v82 offset0:48 offset1:114
	ds_write2_b32 v35, v83, v84 offset0:180 offset1:246
	v_add_u32_e32 v35, 0x1c00, v3
	ds_write2_b32 v35, v85, v86 offset0:56 offset1:122
	ds_write2_b32 v35, v87, v34 offset0:188 offset1:254
	s_waitcnt lgkmcnt(0)
	ds_read2_b32 v[40:41], v52 offset1:33
	s_waitcnt lgkmcnt(0)
	v_cvt_pk_bf16_f32 v40, v40, v41
	ds_read2_b32 v[42:43], v52 offset0:66 offset1:99
	s_waitcnt lgkmcnt(0)
	v_cvt_pk_bf16_f32 v41, v42, v43
	ds_read2_b32 v[42:43], v52 offset0:132 offset1:165
	v_lshl_add_u64 v[34:35], s[82:83], 1, v[12:13]
	s_waitcnt lgkmcnt(0)
	v_cvt_pk_bf16_f32 v42, v42, v43
	ds_read2_b32 v[44:45], v52 offset0:198 offset1:231
	s_waitcnt lgkmcnt(0)
	v_cvt_pk_bf16_f32 v43, v44, v45
	v_lshl_add_u64 v[44:45], v[34:35], 0, v[144:145]
	global_store_dwordx4 v[44:45], v[40:43], off sc1
	ds_read2_b32 v[40:41], v52 offset0:8 offset1:41
	v_lshlrev_b32_e32 v144, 7, v38
	s_waitcnt lgkmcnt(0)
	v_cvt_pk_bf16_f32 v40, v40, v41
	ds_read2_b32 v[42:43], v52 offset0:74 offset1:107
	s_waitcnt lgkmcnt(0)
	v_cvt_pk_bf16_f32 v41, v42, v43
	ds_read2_b32 v[42:43], v52 offset0:140 offset1:173
	v_lshl_add_u64 v[38:39], v[34:35], 0, v[144:145]
	s_waitcnt lgkmcnt(0)
	v_cvt_pk_bf16_f32 v42, v42, v43
	ds_read2_b32 v[44:45], v52 offset0:206 offset1:239
	s_waitcnt lgkmcnt(0)
	v_cvt_pk_bf16_f32 v43, v44, v45
	global_store_dwordx4 v[38:39], v[40:43], off sc1
	ds_read2_b32 v[38:39], v52 offset0:16 offset1:49
	s_waitcnt lgkmcnt(0)
	v_cvt_pk_bf16_f32 v38, v38, v39
	ds_read2_b32 v[40:41], v52 offset0:82 offset1:115
	s_waitcnt lgkmcnt(0)
	v_cvt_pk_bf16_f32 v39, v40, v41
	ds_read2_b32 v[40:41], v52 offset0:148 offset1:181
	s_waitcnt lgkmcnt(0)
	v_cvt_pk_bf16_f32 v40, v40, v41
	ds_read2_b32 v[42:43], v52 offset0:214 offset1:247
	v_lshlrev_b32_e32 v144, 7, v37
	s_waitcnt lgkmcnt(0)
	v_cvt_pk_bf16_f32 v41, v42, v43
	v_lshl_add_u64 v[42:43], v[34:35], 0, v[144:145]
	global_store_dwordx4 v[42:43], v[38:41], off sc1
	ds_read2_b32 v[38:39], v52 offset0:24 offset1:57
	v_lshlrev_b32_e32 v144, 7, v36
	s_waitcnt lgkmcnt(0)
	v_cvt_pk_bf16_f32 v38, v38, v39
	ds_read2_b32 v[40:41], v52 offset0:90 offset1:123
	s_waitcnt lgkmcnt(0)
	v_cvt_pk_bf16_f32 v39, v40, v41
	ds_read2_b32 v[40:41], v52 offset0:156 offset1:189
	v_lshl_add_u64 v[34:35], v[34:35], 0, v[144:145]
	s_waitcnt lgkmcnt(0)
	v_cvt_pk_bf16_f32 v40, v40, v41
	ds_read2_b32 v[42:43], v52 offset0:222 offset1:255
	s_waitcnt lgkmcnt(0)
	v_cvt_pk_bf16_f32 v41, v42, v43
	global_store_dwordx4 v[34:35], v[38:41], off sc1
	s_waitcnt lgkmcnt(0)

; #define LAS __attribute__((address_space(3)))
; __device__ __forceinline__ void transpose_item(const float* W, int N, bf16* WT, int K, int k0, int n0, int drow0, const float* gk, LAS float* scr, int lane) {
;     float wv[32];
; #pragma unroll
;     for (int i = 0; i < 32; ++i) wv[i] = W[(size_t)(k0 + 2 * i + (lane >> 5)) * N + n0 + (lane & 31)];
; __device__ __forceinline__ void p0_weight_item(const Args& a, int l, int r, LAS float* scr, int lane) {
;     ...
;     if (r < IT_GLU) { const int kb = r / 8, nb = r % 8; transpose_item(a.in[15] + (size_t)l * 65536, 256, (bf16*)(wl + WL_GLU), 256, 64 * kb, 32 * nb, 32 * nb, nullptr, scr, lane); return; }
.LBB0_1043:
	s_andn2_b64 vcc, exec, s[0:1]
	s_cbranch_vccnz .LBB0_1045
	s_and_b32 s0, s38, 0x3fc0
	s_add_i32 s1, s35, 0xfffba000
	s_addk_i32 s0, 0xc400
	s_and_b32 s4, s1, 0xe0
	v_or_b32_e32 v144, s0, v0
	s_lshl_b32 s82, s4, 2
	v_lshl_add_u64 v[34:35], v[14:15], 0, s[82:83]
	v_lshlrev_b64 v[36:37], 10, v[144:145]
	v_lshl_add_u64 v[36:37], v[34:35], 0, v[36:37]
	global_load_dword v38, v[36:37], off nt
	v_or_b32_e32 v36, 2, v144
	v_mov_b32_e32 v37, v145
	v_lshlrev_b64 v[36:37], 10, v[36:37]
	v_lshl_add_u64 v[36:37], v[34:35], 0, v[36:37]
	global_load_dword v39, v[36:37], off nt
	v_or_b32_e32 v36, 4, v144
	v_mov_b32_e32 v37, v145
	v_lshlrev_b64 v[36:37], 10, v[36:37]
	v_lshl_add_u64 v[36:37], v[34:35], 0, v[36:37]
	global_load_dword v40, v[36:37], off nt
	v_or_b32_e32 v36, 6, v144
	v_mov_b32_e32 v37, v145
	v_lshlrev_b64 v[36:37], 10, v[36:37]
	v_lshl_add_u64 v[36:37], v[34:35], 0, v[36:37]
	global_load_dword v41, v[36:37], off nt
	v_or_b32_e32 v36, 8, v144
	v_mov_b32_e32 v37, v145
	v_lshlrev_b64 v[36:37], 10, v[36:37]
	v_lshl_add_u64 v[36:37], v[34:35], 0, v[36:37]
	global_load_dword v42, v[36:37], off nt
	v_or_b32_e32 v36, 10, v144
	v_mov_b32_e32 v37, v145
	v_lshlrev_b64 v[36:37], 10, v[36:37]
	v_lshl_add_u64 v[36:37], v[34:35], 0, v[36:37]
	global_load_dword v43, v[36:37], off nt
	v_or_b32_e32 v36, 12, v144
	v_mov_b32_e32 v37, v145
	v_lshlrev_b64 v[36:37], 10, v[36:37]
	v_lshl_add_u64 v[36:37], v[34:35], 0, v[36:37]
	global_load_dword v44, v[36:37], off nt
	v_or_b32_e32 v36, 14, v144
	v_mov_b32_e32 v37, v145
	v_lshlrev_b64 v[36:37], 10, v[36:37]
	v_lshl_add_u64 v[36:37], v[34:35], 0, v[36:37]
	global_load_dword v45, v[36:37], off nt
	v_or_b32_e32 v36, 16, v144
	v_mov_b32_e32 v37, v145
	v_lshlrev_b64 v[36:37], 10, v[36:37]
	v_lshl_add_u64 v[36:37], v[34:35], 0, v[36:37]
	global_load_dword v46, v[36:37], off nt
	v_or_b32_e32 v36, 18, v144
	v_mov_b32_e32 v37, v145
	v_lshlrev_b64 v[36:37], 10, v[36:37]
	v_lshl_add_u64 v[36:37], v[34:35], 0, v[36:37]
	global_load_dword v47, v[36:37], off nt
	v_or_b32_e32 v36, 20, v144
	v_mov_b32_e32 v37, v145
	v_lshlrev_b64 v[36:37], 10, v[36:37]
	v_lshl_add_u64 v[36:37], v[34:35], 0, v[36:37]
	global_load_dword v48, v[36:37], off nt
	v_or_b32_e32 v36, 22, v144
	v_mov_b32_e32 v37, v145
	v_lshlrev_b64 v[36:37], 10, v[36:37]
	v_lshl_add_u64 v[36:37], v[34:35], 0, v[36:37]
	global_load_dword v49, v[36:37], off nt
	v_or_b32_e32 v36, 24, v144
	v_mov_b32_e32 v37, v145
	v_lshlrev_b64 v[36:37], 10, v[36:37]
	v_lshl_add_u64 v[36:37], v[34:35], 0, v[36:37]
	global_load_dword v50, v[36:37], off nt
	v_or_b32_e32 v36, 26, v144
	v_mov_b32_e32 v37, v145
	v_lshlrev_b64 v[36:37], 10, v[36:37]
	v_lshl_add_u64 v[36:37], v[34:35], 0, v[36:37]
	global_load_dword v51, v[36:37], off nt
	v_or_b32_e32 v36, 28, v144
	v_mov_b32_e32 v37, v145
	v_lshlrev_b64 v[36:37], 10, v[36:37]
	v_lshl_add_u64 v[36:37], v[34:35], 0, v[36:37]
	global_load_dword v69, v[36:37], off nt
	v_or_b32_e32 v36, 30, v144
	v_mov_b32_e32 v37, v145
	v_lshlrev_b64 v[36:37], 10, v[36:37]
	v_lshl_add_u64 v[36:37], v[34:35], 0, v[36:37]
	global_load_dword v70, v[36:37], off nt
	v_or_b32_e32 v36, 32, v144
	v_mov_b32_e32 v37, v145
	v_lshlrev_b64 v[36:37], 10, v[36:37]
	v_lshl_add_u64 v[36:37], v[34:35], 0, v[36:37]
	global_load_dword v71, v[36:37], off nt
	v_or_b32_e32 v36, 34, v144
	v_mov_b32_e32 v37, v145
	v_lshlrev_b64 v[36:37], 10, v[36:37]
	v_lshl_add_u64 v[36:37], v[34:35], 0, v[36:37]
	global_load_dword v72, v[36:37], off nt
	v_or_b32_e32 v36, 36, v144
	v_mov_b32_e32 v37, v145
	v_lshlrev_b64 v[36:37], 10, v[36:37]
	v_lshl_add_u64 v[36:37], v[34:35], 0, v[36:37]
	global_load_dword v73, v[36:37], off nt
	v_or_b32_e32 v36, 38, v144
	v_mov_b32_e32 v37, v145
	v_lshlrev_b64 v[36:37], 10, v[36:37]
	v_lshl_add_u64 v[36:37], v[34:35], 0, v[36:37]
	global_load_dword v74, v[36:37], off nt
	v_or_b32_e32 v36, 40, v144
	v_mov_b32_e32 v37, v145
	v_lshlrev_b64 v[36:37], 10, v[36:37]
	v_lshl_add_u64 v[36:37], v[34:35], 0, v[36:37]
	global_load_dword v75, v[36:37], off nt
	v_or_b32_e32 v36, 42, v144
	v_mov_b32_e32 v37, v145
	v_lshlrev_b64 v[36:37], 10, v[36:37]
	v_lshl_add_u64 v[36:37], v[34:35], 0, v[36:37]
	global_load_dword v76, v[36:37], off nt
	v_or_b32_e32 v36, 44, v144
	v_mov_b32_e32 v37, v145
	v_lshlrev_b64 v[36:37], 10, v[36:37]
	v_lshl_add_u64 v[36:37], v[34:35], 0, v[36:37]
	global_load_dword v77, v[36:37], off nt
	v_or_b32_e32 v36, 46, v144
	v_mov_b32_e32 v37, v145
	v_lshlrev_b64 v[36:37], 10, v[36:37]
	v_lshl_add_u64 v[36:37], v[34:35], 0, v[36:37]
	global_load_dword v78, v[36:37], off nt
	v_or_b32_e32 v36, 48, v144
	v_mov_b32_e32 v37, v145
	v_lshlrev_b64 v[36:37], 10, v[36:37]
	v_lshl_add_u64 v[36:37], v[34:35], 0, v[36:37]
	global_load_dword v79, v[36:37], off nt
	v_or_b32_e32 v36, 50, v144
	v_mov_b32_e32 v37, v145
	v_lshlrev_b64 v[36:37], 10, v[36:37]
	v_lshl_add_u64 v[36:37], v[34:35], 0, v[36:37]
	global_load_dword v80, v[36:37], off nt
	v_or_b32_e32 v36, 52, v144
	v_mov_b32_e32 v37, v145
	v_lshlrev_b64 v[36:37], 10, v[36:37]
	v_lshl_add_u64 v[36:37], v[34:35], 0, v[36:37]
	global_load_dword v81, v[36:37], off nt
	v_or_b32_e32 v36, 54, v144
	v_mov_b32_e32 v37, v145
	v_lshlrev_b64 v[36:37], 10, v[36:37]
	v_lshl_add_u64 v[36:37], v[34:35], 0, v[36:37]
	global_load_dword v82, v[36:37], off nt
	v_or_b32_e32 v36, 56, v144
	v_mov_b32_e32 v37, v145
	v_lshlrev_b64 v[36:37], 10, v[36:37]
	v_lshl_add_u64 v[36:37], v[34:35], 0, v[36:37]
	global_load_dword v83, v[36:37], off nt
	v_or_b32_e32 v36, 58, v144
	v_mov_b32_e32 v37, v145
	v_lshlrev_b64 v[36:37], 10, v[36:37]
	v_lshl_add_u64 v[36:37], v[34:35], 0, v[36:37]
	global_load_dword v84, v[36:37], off nt
	v_or_b32_e32 v36, 60, v144
	v_mov_b32_e32 v37, v145
	v_lshlrev_b64 v[36:37], 10, v[36:37]
	v_lshl_add_u64 v[36:37], v[34:35], 0, v[36:37]
	v_or_b32_e32 v144, 62, v144
	global_load_dword v85, v[36:37], off nt
	v_lshlrev_b64 v[36:37], 10, v[144:145]
	v_lshl_add_u64 v[34:35], v[34:35], 0, v[36:37]
	global_load_dword v34, v[34:35], off nt
	v_add_u32_e32 v35, 0x400, v3
	s_waitcnt vmcnt(0)
; #define LAS __attribute__((address_space(3)))
; __device__ __forceinline__ unsigned pk2(float lo, float hi) { return pg8::cvt_pk_bf16(lo, hi); }
; __device__ __forceinline__ void lds_wait() { asm volatile("s_waitcnt lgkmcnt(0)" ::: "memory"); }
; __device__ __forceinline__ void transpose_item(const float* W, int N, bf16* WT, int K, int k0, int n0, int drow0, const float* gk, LAS float* scr, int lane) {
;     ...
; #pragma unroll
;     for (int i = 0; i < 32; ++i) { const int kk = 2 * i + (lane >> 5); float v = wv[i]; if (gk) v *= gk[kk]; scr[kk * 33 + (lane & 31)] = v; }
;     lds_wait();
;     const int c = lane & 7;
; #pragma unroll
;     for (int j = 0; j < 4; ++j) { const int n = (lane >> 3) + 8 * j; const LAS float* s = scr + (8 * c) * 33 + n;
;         u32x4 o; o.x = pk2(s[0 * 33], s[1 * 33]); o.y = pk2(s[2 * 33], s[3 * 33]); o.z = pk2(s[4 * 33], s[5 * 33]); o.w = pk2(s[6 * 33], s[7 * 33]);
;         *(u32x4*)(WT + (size_t)(drow0 + n) * K + k0 + 8 * c) = o; }
;     lds_wait();
	ds_write2_b32 v3, v38, v39 offset1:66
	ds_write2_b32 v3, v40, v41 offset0:132 offset1:198
	ds_write2_b32 v35, v42, v43 offset0:8 offset1:74
	ds_write2_b32 v35, v44, v45 offset0:140 offset1:206
	v_add_u32_e32 v35, 0x800, v3
	ds_write2_b32 v35, v46, v47 offset0:16 offset1:82
	ds_write2_b32 v35, v48, v49 offset0:148 offset1:214
	v_add_u32_e32 v35, 0xc00, v3
	ds_write2_b32 v35, v50, v51 offset0:24 offset1:90
	ds_write2_b32 v35, v69, v70 offset0:156 offset1:222
	v_add_u32_e32 v35, 0x1000, v3
	ds_write2_b32 v35, v71, v72 offset0:32 offset1:98
	ds_write2_b32 v35, v73, v74 offset0:164 offset1:230
	v_add_u32_e32 v35, 0x1400, v3
	ds_write2_b32 v35, v75, v76 offset0:40 offset1:106
	ds_write2_b32 v35, v77, v78 offset0:172 offset1:238
	v_add_u32_e32 v35, 0x1800, v3
	ds_write2_b32 v35, v79, v80 offset0:48 offset1:114
	ds_write2_b32 v35, v81, v82 offset0:180 offset1:246
	v_add_u32_e32 v35, 0x1c00, v3
	ds_write2_b32 v35, v83, v84 offset0:56 offset1:122
	ds_write2_b32 v35, v85, v34 offset0:188 offset1:254
	s_waitcnt lgkmcnt(0)
	ds_read2_b32 v[34:35], v52 offset1:33
	s_waitcnt lgkmcnt(0)
	v_cvt_pk_bf16_f32 v34, v34, v35
	ds_read2_b32 v[36:37], v52 offset0:66 offset1:99
	s_waitcnt lgkmcnt(0)
	v_cvt_pk_bf16_f32 v35, v36, v37
	ds_read2_b32 v[36:37], v52 offset0:132 offset1:165
	s_waitcnt lgkmcnt(0)
	v_cvt_pk_bf16_f32 v36, v36, v37
	ds_read2_b32 v[40:41], v52 offset0:198 offset1:231
	s_mov_b32 s1, s83
	s_waitcnt lgkmcnt(0)
	v_cvt_pk_bf16_f32 v37, v40, v41
	v_or_b32_e32 v40, s4, v5
	v_lshl_add_u64 v[38:39], s[0:1], 1, v[16:17]
	v_lshlrev_b32_e32 v144, 9, v40
	v_lshl_add_u64 v[40:41], v[38:39], 0, v[144:145]
	global_store_dwordx4 v[40:41], v[34:37], off sc1
	ds_read2_b32 v[34:35], v52 offset0:8 offset1:41
	s_waitcnt lgkmcnt(0)
	v_cvt_pk_bf16_f32 v34, v34, v35
	ds_read2_b32 v[36:37], v52 offset0:74 offset1:107
	s_waitcnt lgkmcnt(0)
	v_cvt_pk_bf16_f32 v35, v36, v37
	ds_read2_b32 v[36:37], v52 offset0:140 offset1:173
	s_waitcnt lgkmcnt(0)
	v_cvt_pk_bf16_f32 v36, v36, v37
	ds_read2_b32 v[40:41], v52 offset0:206 offset1:239
	s_waitcnt lgkmcnt(0)
	v_cvt_pk_bf16_f32 v37, v40, v41
	v_or_b32_e32 v40, s4, v53
	v_lshlrev_b32_e32 v144, 9, v40
	v_lshl_add_u64 v[40:41], v[38:39], 0, v[144:145]
	global_store_dwordx4 v[40:41], v[34:37], off sc1
	ds_read2_b32 v[34:35], v52 offset0:16 offset1:49
	s_waitcnt lgkmcnt(0)
	v_cvt_pk_bf16_f32 v34, v34, v35
	ds_read2_b32 v[36:37], v52 offset0:82 offset1:115
	s_waitcnt lgkmcnt(0)
	v_cvt_pk_bf16_f32 v35, v36, v37
	ds_read2_b32 v[36:37], v52 offset0:148 offset1:181
	s_waitcnt lgkmcnt(0)
	v_cvt_pk_bf16_f32 v36, v36, v37
	ds_read2_b32 v[40:41], v52 offset0:214 offset1:247
	s_waitcnt lgkmcnt(0)
	v_cvt_pk_bf16_f32 v37, v40, v41
	v_or_b32_e32 v40, s4, v54
	v_lshlrev_b32_e32 v144, 9, v40
	v_lshl_add_u64 v[40:41], v[38:39], 0, v[144:145]
	global_store_dwordx4 v[40:41], v[34:37], off sc1
	ds_read2_b32 v[34:35], v52 offset0:24 offset1:57
	s_waitcnt lgkmcnt(0)
	v_cvt_pk_bf16_f32 v34, v34, v35
	ds_read2_b32 v[36:37], v52 offset0:90 offset1:123
	s_waitcnt lgkmcnt(0)
	v_cvt_pk_bf16_f32 v35, v36, v37
	ds_read2_b32 v[36:37], v52 offset0:156 offset1:189
	s_waitcnt lgkmcnt(0)
	v_cvt_pk_bf16_f32 v36, v36, v37
	ds_read2_b32 v[40:41], v52 offset0:222 offset1:255
	s_waitcnt lgkmcnt(0)
	v_cvt_pk_bf16_f32 v37, v40, v41
	v_or_b32_e32 v40, s4, v55
	v_lshlrev_b32_e32 v144, 9, v40
	v_lshl_add_u64 v[38:39], v[38:39], 0, v[144:145]
	global_store_dwordx4 v[38:39], v[34:37], off sc1
	s_waitcnt lgkmcnt(0)

; #define LAS __attribute__((address_space(3)))
; __device__ __forceinline__ void transpose_item(const float* W, int N, bf16* WT, int K, int k0, int n0, int drow0, const float* gk, LAS float* scr, int lane) {
;     float wv[32];
; #pragma unroll
;     for (int i = 0; i < 32; ++i) wv[i] = W[(size_t)(k0 + 2 * i + (lane >> 5)) * N + n0 + (lane & 31)];
; __device__ __forceinline__ void p0_weight_item(const Args& a, int l, int r, LAS float* scr, int lane) {
;     ...
;     if (r < IT_OUT) {
;         const int kb = r / 32, nb = r % 32, k0 = 64 * kb;
;         const float* gk = (k0 < 256) ? a.in[17] + (size_t)l * 256 + k0 : (k0 < 768 ? a.in[18] + (size_t)l * 512 + (k0 - 256) : a.in[26] + (size_t)l * 256 + (k0 - 768));
;         transpose_item(a.in[27] + (size_t)l * DM * DM, DM, (bf16*)(wl + WL_WOUT), DM, k0, 32 * nb, 32 * nb, gk, scr, lane); return; }
.LBB0_1055:
	s_add_i32 s0, s35, 0xfffba000
	s_and_b32 s28, s0, 0x3e0
	v_or_b32_e32 v144, s4, v0
	s_lshl_b32 s82, s28, 2
	v_lshl_add_u64 v[50:51], v[18:19], 0, s[82:83]
	v_lshlrev_b64 v[34:35], 12, v[144:145]
	v_lshl_add_u64 v[34:35], v[50:51], 0, v[34:35]
	global_load_dword v83, v[34:35], off nt
	v_or_b32_e32 v34, 2, v144
	v_mov_b32_e32 v35, v145
	v_lshlrev_b64 v[34:35], 12, v[34:35]
	v_lshl_add_u64 v[34:35], v[50:51], 0, v[34:35]
	global_load_dword v84, v[34:35], off nt
	v_or_b32_e32 v34, 4, v144
	v_mov_b32_e32 v35, v145
	v_lshlrev_b64 v[34:35], 12, v[34:35]
	v_lshl_add_u64 v[34:35], v[50:51], 0, v[34:35]
	global_load_dword v48, v[34:35], off nt
	v_or_b32_e32 v34, 6, v144
	v_mov_b32_e32 v35, v145
	v_lshlrev_b64 v[34:35], 12, v[34:35]
	v_lshl_add_u64 v[34:35], v[50:51], 0, v[34:35]
	global_load_dword v49, v[34:35], off nt
	v_or_b32_e32 v34, 8, v144
	v_mov_b32_e32 v35, v145
	v_lshlrev_b64 v[34:35], 12, v[34:35]
	v_lshl_add_u64 v[34:35], v[50:51], 0, v[34:35]
	global_load_dword v81, v[34:35], off nt
	v_or_b32_e32 v34, 10, v144
	v_mov_b32_e32 v35, v145
	v_lshlrev_b64 v[34:35], 12, v[34:35]
	v_lshl_add_u64 v[34:35], v[50:51], 0, v[34:35]
	global_load_dword v82, v[34:35], off nt
	v_or_b32_e32 v34, 12, v144
	v_mov_b32_e32 v35, v145
	v_lshlrev_b64 v[34:35], 12, v[34:35]
	v_lshl_add_u64 v[34:35], v[50:51], 0, v[34:35]
	global_load_dword v46, v[34:35], off nt
	v_or_b32_e32 v34, 14, v144
	v_mov_b32_e32 v35, v145
	v_lshlrev_b64 v[34:35], 12, v[34:35]
	v_lshl_add_u64 v[34:35], v[50:51], 0, v[34:35]
	global_load_dword v47, v[34:35], off nt
	v_or_b32_e32 v34, 16, v144
	v_mov_b32_e32 v35, v145
	v_lshlrev_b64 v[34:35], 12, v[34:35]
	v_lshl_add_u64 v[34:35], v[50:51], 0, v[34:35]
	global_load_dword v79, v[34:35], off nt
	v_or_b32_e32 v34, 18, v144
	v_mov_b32_e32 v35, v145
	v_lshlrev_b64 v[34:35], 12, v[34:35]
	v_lshl_add_u64 v[34:35], v[50:51], 0, v[34:35]
	global_load_dword v80, v[34:35], off nt
	v_or_b32_e32 v34, 20, v144
	v_mov_b32_e32 v35, v145
	v_lshlrev_b64 v[34:35], 12, v[34:35]
	v_lshl_add_u64 v[34:35], v[50:51], 0, v[34:35]
	global_load_dword v44, v[34:35], off nt
	v_or_b32_e32 v34, 22, v144
	v_mov_b32_e32 v35, v145
	v_lshlrev_b64 v[34:35], 12, v[34:35]
	v_lshl_add_u64 v[34:35], v[50:51], 0, v[34:35]
	global_load_dword v45, v[34:35], off nt
	v_or_b32_e32 v34, 24, v144
	v_mov_b32_e32 v35, v145
	v_lshlrev_b64 v[34:35], 12, v[34:35]
	v_lshl_add_u64 v[34:35], v[50:51], 0, v[34:35]
	global_load_dword v77, v[34:35], off nt
	v_or_b32_e32 v34, 26, v144
	v_mov_b32_e32 v35, v145
	v_lshlrev_b64 v[34:35], 12, v[34:35]
	v_lshl_add_u64 v[34:35], v[50:51], 0, v[34:35]
	global_load_dword v78, v[34:35], off nt
	v_or_b32_e32 v34, 28, v144
	v_mov_b32_e32 v35, v145
	v_lshlrev_b64 v[34:35], 12, v[34:35]
	v_lshl_add_u64 v[34:35], v[50:51], 0, v[34:35]
	global_load_dword v42, v[34:35], off nt
	v_or_b32_e32 v34, 30, v144
	v_mov_b32_e32 v35, v145
	v_lshlrev_b64 v[34:35], 12, v[34:35]
	v_lshl_add_u64 v[34:35], v[50:51], 0, v[34:35]
	global_load_dword v43, v[34:35], off nt
	v_or_b32_e32 v34, 32, v144
	v_mov_b32_e32 v35, v145
	v_lshlrev_b64 v[34:35], 12, v[34:35]
	v_lshl_add_u64 v[34:35], v[50:51], 0, v[34:35]
	global_load_dword v75, v[34:35], off nt
	v_or_b32_e32 v34, 34, v144
	v_mov_b32_e32 v35, v145
	v_lshlrev_b64 v[34:35], 12, v[34:35]
	v_lshl_add_u64 v[34:35], v[50:51], 0, v[34:35]
	global_load_dword v76, v[34:35], off nt
	v_or_b32_e32 v34, 36, v144
	v_mov_b32_e32 v35, v145
	v_lshlrev_b64 v[34:35], 12, v[34:35]
	v_lshl_add_u64 v[34:35], v[50:51], 0, v[34:35]
	global_load_dword v40, v[34:35], off nt
	v_or_b32_e32 v34, 38, v144
	v_mov_b32_e32 v35, v145
	v_lshlrev_b64 v[34:35], 12, v[34:35]
	v_lshl_add_u64 v[34:35], v[50:51], 0, v[34:35]
	global_load_dword v41, v[34:35], off nt
	v_or_b32_e32 v34, 40, v144
	v_mov_b32_e32 v35, v145
	v_lshlrev_b64 v[34:35], 12, v[34:35]
	v_lshl_add_u64 v[34:35], v[50:51], 0, v[34:35]
	global_load_dword v73, v[34:35], off nt
	v_or_b32_e32 v34, 42, v144
	v_mov_b32_e32 v35, v145
	v_lshlrev_b64 v[34:35], 12, v[34:35]
	v_lshl_add_u64 v[34:35], v[50:51], 0, v[34:35]
	global_load_dword v74, v[34:35], off nt
	v_or_b32_e32 v34, 44, v144
	v_mov_b32_e32 v35, v145
	v_lshlrev_b64 v[34:35], 12, v[34:35]
	v_lshl_add_u64 v[34:35], v[50:51], 0, v[34:35]
	global_load_dword v38, v[34:35], off nt
	v_or_b32_e32 v34, 46, v144
	v_mov_b32_e32 v35, v145
	v_lshlrev_b64 v[34:35], 12, v[34:35]
	v_lshl_add_u64 v[34:35], v[50:51], 0, v[34:35]
	global_load_dword v39, v[34:35], off nt
	v_or_b32_e32 v34, 48, v144
	v_mov_b32_e32 v35, v145
	v_lshlrev_b64 v[34:35], 12, v[34:35]
	v_lshl_add_u64 v[34:35], v[50:51], 0, v[34:35]
	global_load_dword v71, v[34:35], off nt
	v_or_b32_e32 v34, 50, v144
	v_mov_b32_e32 v35, v145
	v_lshlrev_b64 v[34:35], 12, v[34:35]
	v_lshl_add_u64 v[34:35], v[50:51], 0, v[34:35]
	global_load_dword v72, v[34:35], off nt
	v_or_b32_e32 v34, 52, v144
	v_mov_b32_e32 v35, v145
	v_lshlrev_b64 v[34:35], 12, v[34:35]
	v_lshl_add_u64 v[34:35], v[50:51], 0, v[34:35]
	global_load_dword v36, v[34:35], off nt
	v_or_b32_e32 v34, 54, v144
	v_mov_b32_e32 v35, v145
	v_lshlrev_b64 v[34:35], 12, v[34:35]
	v_lshl_add_u64 v[34:35], v[50:51], 0, v[34:35]
	global_load_dword v37, v[34:35], off nt
	v_or_b32_e32 v34, 56, v144
	v_mov_b32_e32 v35, v145
	v_lshlrev_b64 v[34:35], 12, v[34:35]
	v_lshl_add_u64 v[34:35], v[50:51], 0, v[34:35]
	global_load_dword v69, v[34:35], off nt
	v_or_b32_e32 v34, 58, v144
	v_mov_b32_e32 v35, v145
	v_lshlrev_b64 v[34:35], 12, v[34:35]
	v_lshl_add_u64 v[34:35], v[50:51], 0, v[34:35]
	global_load_dword v70, v[34:35], off nt
	v_or_b32_e32 v34, 60, v144
	v_mov_b32_e32 v35, v145
	v_or_b32_e32 v144, 62, v144
	v_lshlrev_b64 v[34:35], 12, v[34:35]
	v_lshlrev_b64 v[86:87], 12, v[144:145]
	v_lshl_add_u64 v[34:35], v[50:51], 0, v[34:35]
	v_lshl_add_u64 v[50:51], v[50:51], 0, v[86:87]
	global_load_dword v34, v[34:35], off nt
	s_cmp_lg_u64 s[6:7], 0
	global_load_dword v35, v[50:51], off nt
	s_cselect_b64 s[0:1], -1, 0
	s_cmp_eq_u64 s[6:7], 0
	s_cbranch_scc1 .LBB0_1191
; __device__ __forceinline__ void transpose_item(const float* W, int N, bf16* WT, int K, int k0, int n0, int drow0, const float* gk, LAS float* scr, int lane) {
;     ...
; #pragma unroll
;     for (int i = 0; i < 32; ++i) { const int kk = 2 * i + (lane >> 5); float v = wv[i]; if (gk) v *= gk[kk]; scr[kk * 33 + (lane & 31)] = v; }
	v_lshlrev_b32_e32 v51, 2, v0
	s_waitcnt vmcnt(32)
	global_load_dword v204, v51, s[6:7]
	global_load_dword v205, v51, s[6:7] offset:8
	global_load_dword v206, v51, s[6:7] offset:16
	global_load_dword v207, v51, s[6:7] offset:24
	global_load_dword v208, v51, s[6:7] offset:32
	global_load_dword v209, v51, s[6:7] offset:40
	global_load_dword v210, v51, s[6:7] offset:48
	global_load_dword v211, v51, s[6:7] offset:56
	global_load_dword v212, v51, s[6:7] offset:64
	global_load_dword v213, v51, s[6:7] offset:72
	global_load_dword v214, v51, s[6:7] offset:80
	global_load_dword v215, v51, s[6:7] offset:88
	global_load_dword v216, v51, s[6:7] offset:96
	global_load_dword v217, v51, s[6:7] offset:104
	global_load_dword v218, v51, s[6:7] offset:112
	global_load_dword v219, v51, s[6:7] offset:120
	global_load_dword v220, v51, s[6:7] offset:128
	global_load_dword v221, v51, s[6:7] offset:136
	global_load_dword v222, v51, s[6:7] offset:144
	global_load_dword v223, v51, s[6:7] offset:152
	global_load_dword v224, v51, s[6:7] offset:160
	global_load_dword v225, v51, s[6:7] offset:168
	global_load_dword v226, v51, s[6:7] offset:176
	global_load_dword v227, v51, s[6:7] offset:184
	global_load_dword v228, v51, s[6:7] offset:192
	global_load_dword v229, v51, s[6:7] offset:200
	global_load_dword v230, v51, s[6:7] offset:208
	global_load_dword v231, v51, s[6:7] offset:216
	global_load_dword v232, v51, s[6:7] offset:224
	global_load_dword v233, v51, s[6:7] offset:232
	global_load_dword v234, v51, s[6:7] offset:240
	s_waitcnt vmcnt(62)
	global_load_dword v235, v51, s[6:7] offset:248
	s_waitcnt vmcnt(0)
	v_mov_b32_e32 v50, v204
	v_mov_b32_e32 v85, v205
	s_waitcnt vmcnt(0)
	v_mul_f32_e32 v50, v83, v50
	v_mul_f32_e32 v85, v84, v85
	ds_write_b32 v3, v50
	v_add_u32_e32 v50, v1, v56
	ds_write_b32 v50, v85
	v_mov_b32_e32 v50, v206
	s_nop 0
	v_mov_b32_e32 v51, v207
	s_waitcnt vmcnt(0)
	v_pk_mul_f32 v[50:51], v[48:49], v[50:51]
	s_cbranch_execnz .LBB0_1058

; #define LAS __attribute__((address_space(3)))
; __device__ __forceinline__ unsigned pk2(float lo, float hi) { return pg8::cvt_pk_bf16(lo, hi); }
; __device__ __forceinline__ void lds_wait() { asm volatile("s_waitcnt lgkmcnt(0)" ::: "memory"); }
; __device__ __forceinline__ void transpose_item(const float* W, int N, bf16* WT, int K, int k0, int n0, int drow0, const float* gk, LAS float* scr, int lane) {
;     ...
;     lds_wait();
;     const int c = lane & 7;
; #pragma unroll
;     for (int j = 0; j < 4; ++j) { const int n = (lane >> 3) + 8 * j; const LAS float* s = scr + (8 * c) * 33 + n;
;         u32x4 o; o.x = pk2(s[0 * 33], s[1 * 33]); o.y = pk2(s[2 * 33], s[3 * 33]); o.z = pk2(s[4 * 33], s[5 * 33]); o.w = pk2(s[6 * 33], s[7 * 33]);
;         *(u32x4*)(WT + (size_t)(drow0 + n) * K + k0 + 8 * c) = o; }
;     lds_wait();
.LBB0_1079:
	ds_write2_b32 v38, v36, v37 offset0:140 offset1:206
	s_waitcnt lgkmcnt(0)
	ds_read2_b32 v[34:35], v52 offset1:33
	s_waitcnt lgkmcnt(0)
	v_cvt_pk_bf16_f32 v34, v34, v35
	ds_read2_b32 v[36:37], v52 offset0:66 offset1:99
	s_waitcnt lgkmcnt(0)
	v_cvt_pk_bf16_f32 v35, v36, v37
	ds_read2_b32 v[36:37], v52 offset0:132 offset1:165
	s_waitcnt lgkmcnt(0)
	v_cvt_pk_bf16_f32 v36, v36, v37
	ds_read2_b32 v[40:41], v52 offset0:198 offset1:231
	s_mov_b32 s5, s83
	s_waitcnt lgkmcnt(0)
	v_cvt_pk_bf16_f32 v37, v40, v41
	v_or_b32_e32 v40, s28, v5
	v_lshl_add_u64 v[38:39], s[4:5], 1, v[20:21]
	v_lshlrev_b32_e32 v144, 11, v40
	v_lshl_add_u64 v[40:41], v[38:39], 0, v[144:145]
	global_store_dwordx4 v[40:41], v[34:37], off sc1
	ds_read2_b32 v[34:35], v52 offset0:8 offset1:41
	s_waitcnt lgkmcnt(0)
	v_cvt_pk_bf16_f32 v34, v34, v35
	ds_read2_b32 v[36:37], v52 offset0:74 offset1:107
	s_waitcnt lgkmcnt(0)
	v_cvt_pk_bf16_f32 v35, v36, v37
	ds_read2_b32 v[36:37], v52 offset0:140 offset1:173
	s_waitcnt lgkmcnt(0)
	v_cvt_pk_bf16_f32 v36, v36, v37
	ds_read2_b32 v[40:41], v52 offset0:206 offset1:239
	s_waitcnt lgkmcnt(0)
	v_cvt_pk_bf16_f32 v37, v40, v41
	v_or_b32_e32 v40, s28, v53
	v_lshlrev_b32_e32 v144, 11, v40
	v_lshl_add_u64 v[40:41], v[38:39], 0, v[144:145]
	global_store_dwordx4 v[40:41], v[34:37], off sc1
	ds_read2_b32 v[34:35], v52 offset0:16 offset1:49
	s_waitcnt lgkmcnt(0)
	v_cvt_pk_bf16_f32 v34, v34, v35
	ds_read2_b32 v[36:37], v52 offset0:82 offset1:115
	s_waitcnt lgkmcnt(0)
	v_cvt_pk_bf16_f32 v35, v36, v37
	ds_read2_b32 v[36:37], v52 offset0:148 offset1:181
	s_waitcnt lgkmcnt(0)
	v_cvt_pk_bf16_f32 v36, v36, v37
	ds_read2_b32 v[40:41], v52 offset0:214 offset1:247
	s_waitcnt lgkmcnt(0)
	v_cvt_pk_bf16_f32 v37, v40, v41
	v_or_b32_e32 v40, s28, v54
	v_lshlrev_b32_e32 v144, 11, v40
	v_lshl_add_u64 v[40:41], v[38:39], 0, v[144:145]
	global_store_dwordx4 v[40:41], v[34:37], off sc1
	ds_read2_b32 v[34:35], v52 offset0:24 offset1:57
	s_waitcnt lgkmcnt(0)
	v_cvt_pk_bf16_f32 v34, v34, v35
	ds_read2_b32 v[36:37], v52 offset0:90 offset1:123
	s_waitcnt lgkmcnt(0)
	v_cvt_pk_bf16_f32 v35, v36, v37
	ds_read2_b32 v[36:37], v52 offset0:156 offset1:189
	s_waitcnt lgkmcnt(0)
	v_cvt_pk_bf16_f32 v36, v36, v37
	ds_read2_b32 v[40:41], v52 offset0:222 offset1:255
	s_waitcnt lgkmcnt(0)
	v_cvt_pk_bf16_f32 v37, v40, v41
	v_or_b32_e32 v40, s28, v55
	v_lshlrev_b32_e32 v144, 11, v40
	v_lshl_add_u64 v[38:39], v[38:39], 0, v[144:145]
	global_store_dwordx4 v[38:39], v[34:37], off sc1
	s_waitcnt lgkmcnt(0)

; #define LAS __attribute__((address_space(3)))
; __device__ __forceinline__ void transpose_item(const float* W, int N, bf16* WT, int K, int k0, int n0, int drow0, const float* gk, LAS float* scr, int lane) {
;     float wv[32];
; #pragma unroll
;     for (int i = 0; i < 32; ++i) wv[i] = W[(size_t)(k0 + 2 * i + (lane >> 5)) * N + n0 + (lane & 31)];
; __device__ __forceinline__ void p0_weight_item(const Args& a, int l, int r, LAS float* scr, int lane) {
;     ...
;         if (r < 2 * IT_BIG) { const int up = r >= IT_BIG; const int it = r - up * IT_BIG; const int kb = it / 88, nb = it % 88, k0 = 64 * kb, n0 = 32 * nb;
;             const float* W = a.in[(f ? 29 : 2) + up] + (size_t)l * DM * FF;
;             transpose_item(W, FF, gu, DM, k0, n0, (n0 >> 7) * 256 + up * 128 + (n0 & 127), nrm + k0, scr, lane); return; }
.LBB0_1084:
	s_lshl_b32 s1, s1, 6
	s_and_b32 s7, s1, 0xffc0
	s_lshl_b32 s1, s7, 2
	v_readlane_b32 s4, v254, 19
	s_add_u32 s4, s4, s1
	v_readlane_b32 s1, v254, 20
	s_addc_u32 s5, s1, 0
	v_or_b32_e32 v36, s7, v0
	s_lshl_b32 s82, s0, 2
	v_lshl_add_u64 v[34:35], v[22:23], 0, s[82:83]
	v_mul_u32_u24_e32 v144, 0x2c00, v36
	v_lshl_add_u64 v[50:51], v[34:35], 0, v[144:145]
	s_movk_i32 s0, 0x5000
	v_add_co_u32_e32 v34, vcc, s0, v50
	s_mov_b32 s0, 0xb000
	s_nop 0
	v_addc_co_u32_e32 v35, vcc, 0, v51, vcc
	global_load_dword v84, v[34:35], off offset:2048 nt
	v_add_co_u32_e32 v34, vcc, s0, v50
	s_mov_b32 s0, 0x10000
	s_nop 0
	v_addc_co_u32_e32 v35, vcc, 0, v51, vcc
	global_load_dword v83, v[50:51], off nt
	global_load_dword v48, v[34:35], off nt
	v_add_co_u32_e32 v34, vcc, s0, v50
	s_mov_b32 s0, 0x16000
	s_nop 0
	v_addc_co_u32_e32 v35, vcc, 0, v51, vcc
	global_load_dword v49, v[34:35], off offset:2048 nt
	v_add_co_u32_e32 v34, vcc, s0, v50
	s_mov_b32 s0, 0x1b000
	s_nop 0
	v_addc_co_u32_e32 v35, vcc, 0, v51, vcc
	global_load_dword v81, v[34:35], off nt
	v_add_co_u32_e32 v34, vcc, s0, v50
	s_mov_b32 s0, 0x21000
	s_nop 0
	v_addc_co_u32_e32 v35, vcc, 0, v51, vcc
	global_load_dword v82, v[34:35], off offset:2048 nt
	v_add_co_u32_e32 v34, vcc, s0, v50
	s_mov_b32 s0, 0x26000
	s_nop 0
	v_addc_co_u32_e32 v35, vcc, 0, v51, vcc
	global_load_dword v46, v[34:35], off nt
	v_add_co_u32_e32 v34, vcc, s0, v50
	s_mov_b32 s0, 0x2c000
	s_nop 0
	v_addc_co_u32_e32 v35, vcc, 0, v51, vcc
	global_load_dword v47, v[34:35], off offset:2048 nt
	v_add_co_u32_e32 v34, vcc, s0, v50
	s_mov_b32 s0, 0x31000
	s_nop 0
	v_addc_co_u32_e32 v35, vcc, 0, v51, vcc
	global_load_dword v79, v[34:35], off nt
	v_add_co_u32_e32 v34, vcc, s0, v50
	s_mov_b32 s0, 0x37000
	s_nop 0
	v_addc_co_u32_e32 v35, vcc, 0, v51, vcc
	global_load_dword v80, v[34:35], off offset:2048 nt
	v_add_co_u32_e32 v34, vcc, s0, v50
	s_mov_b32 s0, 0x3c000
	s_nop 0
	v_addc_co_u32_e32 v35, vcc, 0, v51, vcc
	global_load_dword v44, v[34:35], off nt
	v_add_co_u32_e32 v34, vcc, s0, v50
	s_mov_b32 s0, 0x42000
	s_nop 0
	v_addc_co_u32_e32 v35, vcc, 0, v51, vcc
	global_load_dword v45, v[34:35], off offset:2048 nt
	v_add_co_u32_e32 v34, vcc, s0, v50
	s_mov_b32 s0, 0x47000
	s_nop 0
	v_addc_co_u32_e32 v35, vcc, 0, v51, vcc
	global_load_dword v77, v[34:35], off nt
	v_add_co_u32_e32 v34, vcc, s0, v50
	s_mov_b32 s0, 0x4d000
	s_nop 0
	v_addc_co_u32_e32 v35, vcc, 0, v51, vcc
	global_load_dword v78, v[34:35], off offset:2048 nt
	v_add_co_u32_e32 v34, vcc, s0, v50
	s_mov_b32 s0, 0x52000
	s_nop 0
	v_addc_co_u32_e32 v35, vcc, 0, v51, vcc
	global_load_dword v42, v[34:35], off nt
	v_add_co_u32_e32 v34, vcc, s0, v50
	s_mov_b32 s0, 0x58000
	s_nop 0
	v_addc_co_u32_e32 v35, vcc, 0, v51, vcc
	global_load_dword v43, v[34:35], off offset:2048 nt
	v_add_co_u32_e32 v34, vcc, s0, v50
	s_mov_b32 s0, 0x5d000
	s_nop 0
	v_addc_co_u32_e32 v35, vcc, 0, v51, vcc
	global_load_dword v75, v[34:35], off nt
	v_add_co_u32_e32 v34, vcc, s0, v50
	s_mov_b32 s0, 0x63000
	s_nop 0
	v_addc_co_u32_e32 v35, vcc, 0, v51, vcc
	global_load_dword v76, v[34:35], off offset:2048 nt
	v_add_co_u32_e32 v34, vcc, s0, v50
	s_mov_b32 s0, 0x68000
	s_nop 0
	v_addc_co_u32_e32 v35, vcc, 0, v51, vcc
	global_load_dword v40, v[34:35], off nt
	v_add_co_u32_e32 v34, vcc, s0, v50
	s_mov_b32 s0, 0x6e000
	s_nop 0
	v_addc_co_u32_e32 v35, vcc, 0, v51, vcc
	global_load_dword v41, v[34:35], off offset:2048 nt
	v_add_co_u32_e32 v34, vcc, s0, v50
	s_mov_b32 s0, 0x73000
	s_nop 0
	v_addc_co_u32_e32 v35, vcc, 0, v51, vcc
	global_load_dword v73, v[34:35], off nt
	v_add_co_u32_e32 v34, vcc, s0, v50
	s_mov_b32 s0, 0x79000
	s_nop 0
	v_addc_co_u32_e32 v35, vcc, 0, v51, vcc
	global_load_dword v74, v[34:35], off offset:2048 nt
	v_add_co_u32_e32 v34, vcc, s0, v50
	s_mov_b32 s0, 0x7e000
	s_nop 0
	v_addc_co_u32_e32 v35, vcc, 0, v51, vcc
	global_load_dword v38, v[34:35], off nt
	v_add_co_u32_e32 v34, vcc, s0, v50
	s_mov_b32 s0, 0x84000
	s_nop 0
	v_addc_co_u32_e32 v35, vcc, 0, v51, vcc
	global_load_dword v39, v[34:35], off offset:2048 nt
	v_add_co_u32_e32 v34, vcc, s0, v50
	s_mov_b32 s0, 0x89000
	s_nop 0
	v_addc_co_u32_e32 v35, vcc, 0, v51, vcc
	global_load_dword v71, v[34:35], off nt
	v_add_co_u32_e32 v34, vcc, s0, v50
	s_mov_b32 s0, 0x8f000
	s_nop 0
	v_addc_co_u32_e32 v35, vcc, 0, v51, vcc
	global_load_dword v72, v[34:35], off offset:2048 nt
	v_add_co_u32_e32 v34, vcc, s0, v50
	s_mov_b32 s0, 0x94000
	s_nop 0
	v_addc_co_u32_e32 v35, vcc, 0, v51, vcc
	global_load_dword v36, v[34:35], off nt
	v_add_co_u32_e32 v34, vcc, s0, v50
	s_mov_b32 s0, 0x9a000
	s_nop 0
	v_addc_co_u32_e32 v35, vcc, 0, v51, vcc
	global_load_dword v37, v[34:35], off offset:2048 nt
	v_add_co_u32_e32 v34, vcc, s0, v50
	v_readlane_b32 s0, v251, 38
	s_nop 0
	v_addc_co_u32_e32 v35, vcc, 0, v51, vcc
	global_load_dword v69, v[34:35], off nt
	v_add_co_u32_e32 v34, vcc, 0x9f000, v50
	v_readlane_b32 s1, v251, 39
	s_nop 0
	v_addc_co_u32_e32 v35, vcc, 0, v51, vcc
	global_load_dword v70, v[34:35], off offset:2048 nt
	v_add_co_u32_e32 v34, vcc, 0xa5000, v50
	s_nop 1
	v_addc_co_u32_e32 v35, vcc, 0, v51, vcc
	v_add_co_u32_e32 v50, vcc, 0xaa000, v50
	global_load_dword v34, v[34:35], off nt
	s_nop 0
	v_addc_co_u32_e32 v51, vcc, 0, v51, vcc
	global_load_dword v35, v[50:51], off offset:2048 nt
	v_cndmask_b32_e64 v50, 0, 1, s[0:1]
	v_cmp_ne_u32_e64 s[36:37], 1, v50
	s_andn2_b64 vcc, exec, s[0:1]
	s_cbranch_vccnz .LBB0_1183
; __device__ __forceinline__ void transpose_item(const float* W, int N, bf16* WT, int K, int k0, int n0, int drow0, const float* gk, LAS float* scr, int lane) {
;     ...
; #pragma unroll
;     for (int i = 0; i < 32; ++i) { const int kk = 2 * i + (lane >> 5); float v = wv[i]; if (gk) v *= gk[kk]; scr[kk * 33 + (lane & 31)] = v; }
	v_lshlrev_b32_e32 v51, 2, v0
	s_waitcnt vmcnt(32)
	global_load_dword v204, v51, s[4:5]
	global_load_dword v205, v51, s[4:5] offset:8
	global_load_dword v206, v51, s[4:5] offset:16
	global_load_dword v207, v51, s[4:5] offset:24
	global_load_dword v208, v51, s[4:5] offset:32
	global_load_dword v209, v51, s[4:5] offset:40
	global_load_dword v210, v51, s[4:5] offset:48
	global_load_dword v211, v51, s[4:5] offset:56
	global_load_dword v212, v51, s[4:5] offset:64
	global_load_dword v213, v51, s[4:5] offset:72
	global_load_dword v214, v51, s[4:5] offset:80
	global_load_dword v215, v51, s[4:5] offset:88
	global_load_dword v216, v51, s[4:5] offset:96
	global_load_dword v217, v51, s[4:5] offset:104
	global_load_dword v218, v51, s[4:5] offset:112
	global_load_dword v219, v51, s[4:5] offset:120
	global_load_dword v220, v51, s[4:5] offset:128
	global_load_dword v221, v51, s[4:5] offset:136
	global_load_dword v222, v51, s[4:5] offset:144
	global_load_dword v223, v51, s[4:5] offset:152
	global_load_dword v224, v51, s[4:5] offset:160
	global_load_dword v225, v51, s[4:5] offset:168
	global_load_dword v226, v51, s[4:5] offset:176
	global_load_dword v227, v51, s[4:5] offset:184
	global_load_dword v228, v51, s[4:5] offset:192
	global_load_dword v229, v51, s[4:5] offset:200
	global_load_dword v230, v51, s[4:5] offset:208
	global_load_dword v231, v51, s[4:5] offset:216
	global_load_dword v232, v51, s[4:5] offset:224
	global_load_dword v233, v51, s[4:5] offset:232
	global_load_dword v234, v51, s[4:5] offset:240
	s_waitcnt vmcnt(62)
	global_load_dword v235, v51, s[4:5] offset:248
	s_waitcnt vmcnt(0)
	v_mov_b32_e32 v50, v204
	v_mov_b32_e32 v85, v205
	s_waitcnt vmcnt(0)
	v_mul_f32_e32 v50, v83, v50
	v_mul_f32_e32 v85, v84, v85
	ds_write_b32 v3, v50
	v_add_u32_e32 v50, v1, v56
	ds_write_b32 v50, v85
	v_mov_b32_e32 v50, v206
	s_nop 0
	v_mov_b32_e32 v51, v207
	s_waitcnt vmcnt(0)
	v_pk_mul_f32 v[50:51], v[48:49], v[50:51]
	s_cbranch_execnz .LBB0_1087

; #define LAS __attribute__((address_space(3)))
; __device__ __forceinline__ unsigned pk2(float lo, float hi) { return pg8::cvt_pk_bf16(lo, hi); }
; __device__ __forceinline__ void lds_wait() { asm volatile("s_waitcnt lgkmcnt(0)" ::: "memory"); }
; __device__ __forceinline__ void transpose_item(const float* W, int N, bf16* WT, int K, int k0, int n0, int drow0, const float* gk, LAS float* scr, int lane) {
;     ...
;     lds_wait();
;     const int c = lane & 7;
; #pragma unroll
;     for (int j = 0; j < 4; ++j) { const int n = (lane >> 3) + 8 * j; const LAS float* s = scr + (8 * c) * 33 + n;
;         u32x4 o; o.x = pk2(s[0 * 33], s[1 * 33]); o.y = pk2(s[2 * 33], s[3 * 33]); o.z = pk2(s[4 * 33], s[5 * 33]); o.w = pk2(s[6 * 33], s[7 * 33]);
;         *(u32x4*)(WT + (size_t)(drow0 + n) * K + k0 + 8 * c) = o; }
;     lds_wait();
.LBB0_1108:
	ds_write2_b32 v38, v36, v37 offset0:140 offset1:206
	s_waitcnt lgkmcnt(0)
	ds_read2_b32 v[34:35], v52 offset1:33
	s_waitcnt lgkmcnt(0)
	v_cvt_pk_bf16_f32 v34, v34, v35
	ds_read2_b32 v[36:37], v52 offset0:66 offset1:99
	s_waitcnt lgkmcnt(0)
	v_cvt_pk_bf16_f32 v35, v36, v37
	ds_read2_b32 v[36:37], v52 offset0:132 offset1:165
	s_lshl_b32 s82, s7, 1
	s_waitcnt lgkmcnt(0)
	v_cvt_pk_bf16_f32 v36, v36, v37
	ds_read2_b32 v[40:41], v52 offset0:198 offset1:231
	v_add_u32_e32 v144, s6, v5
	v_lshl_add_u64 v[38:39], v[24:25], 0, s[82:83]
	s_waitcnt lgkmcnt(0)
	v_cvt_pk_bf16_f32 v37, v40, v41
	v_lshlrev_b64 v[40:41], 11, v[144:145]
	v_lshl_add_u64 v[40:41], v[38:39], 0, v[40:41]
	global_store_dwordx4 v[40:41], v[34:37], off sc1
	ds_read2_b32 v[34:35], v52 offset0:8 offset1:41
	v_add_u32_e32 v144, s6, v53
	s_waitcnt lgkmcnt(0)
	v_cvt_pk_bf16_f32 v34, v34, v35
	ds_read2_b32 v[36:37], v52 offset0:74 offset1:107
	s_waitcnt lgkmcnt(0)
	v_cvt_pk_bf16_f32 v35, v36, v37
	ds_read2_b32 v[36:37], v52 offset0:140 offset1:173
	s_waitcnt lgkmcnt(0)
	v_cvt_pk_bf16_f32 v36, v36, v37
	ds_read2_b32 v[40:41], v52 offset0:206 offset1:239
	s_waitcnt lgkmcnt(0)
	v_cvt_pk_bf16_f32 v37, v40, v41
	v_lshlrev_b64 v[40:41], 11, v[144:145]
	v_lshl_add_u64 v[40:41], v[38:39], 0, v[40:41]
	global_store_dwordx4 v[40:41], v[34:37], off sc1
	ds_read2_b32 v[34:35], v52 offset0:16 offset1:49
	v_add_u32_e32 v144, s6, v54
	s_waitcnt lgkmcnt(0)
	v_cvt_pk_bf16_f32 v34, v34, v35
	ds_read2_b32 v[36:37], v52 offset0:82 offset1:115
	s_waitcnt lgkmcnt(0)
	v_cvt_pk_bf16_f32 v35, v36, v37
	ds_read2_b32 v[36:37], v52 offset0:148 offset1:181
	s_waitcnt lgkmcnt(0)
	v_cvt_pk_bf16_f32 v36, v36, v37
	ds_read2_b32 v[40:41], v52 offset0:214 offset1:247
	s_waitcnt lgkmcnt(0)
	v_cvt_pk_bf16_f32 v37, v40, v41
	v_lshlrev_b64 v[40:41], 11, v[144:145]
	v_lshl_add_u64 v[40:41], v[38:39], 0, v[40:41]
	global_store_dwordx4 v[40:41], v[34:37], off sc1
	ds_read2_b32 v[34:35], v52 offset0:24 offset1:57
	v_add_u32_e32 v144, s6, v55
	s_waitcnt lgkmcnt(0)
	v_cvt_pk_bf16_f32 v34, v34, v35
	ds_read2_b32 v[36:37], v52 offset0:90 offset1:123
	s_waitcnt lgkmcnt(0)
	v_cvt_pk_bf16_f32 v35, v36, v37
	ds_read2_b32 v[36:37], v52 offset0:156 offset1:189
	s_waitcnt lgkmcnt(0)
	v_cvt_pk_bf16_f32 v36, v36, v37
	ds_read2_b32 v[40:41], v52 offset0:222 offset1:255
	s_waitcnt lgkmcnt(0)
	v_cvt_pk_bf16_f32 v37, v40, v41
	v_lshlrev_b64 v[40:41], 11, v[144:145]
	v_lshl_add_u64 v[38:39], v[38:39], 0, v[40:41]
	global_store_dwordx4 v[38:39], v[34:37], off sc1
	s_waitcnt lgkmcnt(0)

; #define LAS __attribute__((address_space(3)))
; __device__ __forceinline__ void transpose_item(const float* W, int N, bf16* WT, int K, int k0, int n0, int drow0, const float* gk, LAS float* scr, int lane) {
;     float wv[32];
; #pragma unroll
;     for (int i = 0; i < 32; ++i) wv[i] = W[(size_t)(k0 + 2 * i + (lane >> 5)) * N + n0 + (lane & 31)];
; __device__ __forceinline__ void p0_weight_item(const Args& a, int l, int r, LAS float* scr, int lane) {
;     ...
;         if (r < IT_BIG) { const int kb = r / 32, nb = r % 32; const float* W = a.in[f ? 31 : 4] + (size_t)l * FF * DM;
;             transpose_item(W, DM, dn, FF, 64 * kb, 32 * nb, 32 * nb, nullptr, scr, lane); return; }
.LBB0_1110:
	s_andn2_b64 vcc, exec, s[0:1]
	s_cbranch_vccnz .LBB0_1112
	s_add_i32 s0, s35, 0xfffdb000
	s_and_b32 s1, s26, 0x7fffffc0
	s_and_b32 s0, s0, 0x3e0
	v_or_b32_e32 v144, s1, v0
	s_lshl_b32 s82, s0, 2
	v_lshl_add_u64 v[34:35], v[26:27], 0, s[82:83]
	v_lshlrev_b64 v[36:37], 12, v[144:145]
	v_lshl_add_u64 v[36:37], v[34:35], 0, v[36:37]
	global_load_dword v38, v[36:37], off nt
	v_or_b32_e32 v36, 2, v144
	v_mov_b32_e32 v37, v145
	v_lshlrev_b64 v[36:37], 12, v[36:37]
	v_lshl_add_u64 v[36:37], v[34:35], 0, v[36:37]
	global_load_dword v39, v[36:37], off nt
	v_or_b32_e32 v36, 4, v144
	v_mov_b32_e32 v37, v145
	v_lshlrev_b64 v[36:37], 12, v[36:37]
	v_lshl_add_u64 v[36:37], v[34:35], 0, v[36:37]
	global_load_dword v40, v[36:37], off nt
	v_or_b32_e32 v36, 6, v144
	v_mov_b32_e32 v37, v145
	v_lshlrev_b64 v[36:37], 12, v[36:37]
	v_lshl_add_u64 v[36:37], v[34:35], 0, v[36:37]
	global_load_dword v41, v[36:37], off nt
	v_or_b32_e32 v36, 8, v144
	v_mov_b32_e32 v37, v145
	v_lshlrev_b64 v[36:37], 12, v[36:37]
	v_lshl_add_u64 v[36:37], v[34:35], 0, v[36:37]
	global_load_dword v42, v[36:37], off nt
	v_or_b32_e32 v36, 10, v144
	v_mov_b32_e32 v37, v145
	v_lshlrev_b64 v[36:37], 12, v[36:37]
	v_lshl_add_u64 v[36:37], v[34:35], 0, v[36:37]
	global_load_dword v43, v[36:37], off nt
	v_or_b32_e32 v36, 12, v144
	v_mov_b32_e32 v37, v145
	v_lshlrev_b64 v[36:37], 12, v[36:37]
	v_lshl_add_u64 v[36:37], v[34:35], 0, v[36:37]
	global_load_dword v44, v[36:37], off nt
	v_or_b32_e32 v36, 14, v144
	v_mov_b32_e32 v37, v145
	v_lshlrev_b64 v[36:37], 12, v[36:37]
	v_lshl_add_u64 v[36:37], v[34:35], 0, v[36:37]
	global_load_dword v45, v[36:37], off nt
	v_or_b32_e32 v36, 16, v144
	v_mov_b32_e32 v37, v145
	v_lshlrev_b64 v[36:37], 12, v[36:37]
	v_lshl_add_u64 v[36:37], v[34:35], 0, v[36:37]
	global_load_dword v46, v[36:37], off nt
	v_or_b32_e32 v36, 18, v144
	v_mov_b32_e32 v37, v145
	v_lshlrev_b64 v[36:37], 12, v[36:37]
	v_lshl_add_u64 v[36:37], v[34:35], 0, v[36:37]
	global_load_dword v47, v[36:37], off nt
	v_or_b32_e32 v36, 20, v144
	v_mov_b32_e32 v37, v145
	v_lshlrev_b64 v[36:37], 12, v[36:37]
	v_lshl_add_u64 v[36:37], v[34:35], 0, v[36:37]
	global_load_dword v48, v[36:37], off nt
	v_or_b32_e32 v36, 22, v144
	v_mov_b32_e32 v37, v145
	v_lshlrev_b64 v[36:37], 12, v[36:37]
	v_lshl_add_u64 v[36:37], v[34:35], 0, v[36:37]
	global_load_dword v49, v[36:37], off nt
	v_or_b32_e32 v36, 24, v144
	v_mov_b32_e32 v37, v145
	v_lshlrev_b64 v[36:37], 12, v[36:37]
	v_lshl_add_u64 v[36:37], v[34:35], 0, v[36:37]
	global_load_dword v50, v[36:37], off nt
	v_or_b32_e32 v36, 26, v144
	v_mov_b32_e32 v37, v145
	v_lshlrev_b64 v[36:37], 12, v[36:37]
	v_lshl_add_u64 v[36:37], v[34:35], 0, v[36:37]
	global_load_dword v51, v[36:37], off nt
	v_or_b32_e32 v36, 28, v144
	v_mov_b32_e32 v37, v145
	v_lshlrev_b64 v[36:37], 12, v[36:37]
	v_lshl_add_u64 v[36:37], v[34:35], 0, v[36:37]
	global_load_dword v69, v[36:37], off nt
	v_or_b32_e32 v36, 30, v144
	v_mov_b32_e32 v37, v145
	v_lshlrev_b64 v[36:37], 12, v[36:37]
	v_lshl_add_u64 v[36:37], v[34:35], 0, v[36:37]
	global_load_dword v70, v[36:37], off nt
	v_or_b32_e32 v36, 32, v144
	v_mov_b32_e32 v37, v145
	v_lshlrev_b64 v[36:37], 12, v[36:37]
	v_lshl_add_u64 v[36:37], v[34:35], 0, v[36:37]
	global_load_dword v71, v[36:37], off nt
	v_or_b32_e32 v36, 34, v144
	v_mov_b32_e32 v37, v145
	v_lshlrev_b64 v[36:37], 12, v[36:37]
	v_lshl_add_u64 v[36:37], v[34:35], 0, v[36:37]
	global_load_dword v72, v[36:37], off nt
	v_or_b32_e32 v36, 36, v144
	v_mov_b32_e32 v37, v145
	v_lshlrev_b64 v[36:37], 12, v[36:37]
	v_lshl_add_u64 v[36:37], v[34:35], 0, v[36:37]
	global_load_dword v73, v[36:37], off nt
	v_or_b32_e32 v36, 38, v144
	v_mov_b32_e32 v37, v145
	v_lshlrev_b64 v[36:37], 12, v[36:37]
	v_lshl_add_u64 v[36:37], v[34:35], 0, v[36:37]
	global_load_dword v74, v[36:37], off nt
	v_or_b32_e32 v36, 40, v144
	v_mov_b32_e32 v37, v145
	v_lshlrev_b64 v[36:37], 12, v[36:37]
	v_lshl_add_u64 v[36:37], v[34:35], 0, v[36:37]
	global_load_dword v75, v[36:37], off nt
	v_or_b32_e32 v36, 42, v144
	v_mov_b32_e32 v37, v145
	v_lshlrev_b64 v[36:37], 12, v[36:37]
	v_lshl_add_u64 v[36:37], v[34:35], 0, v[36:37]
	global_load_dword v76, v[36:37], off nt
	v_or_b32_e32 v36, 44, v144
	v_mov_b32_e32 v37, v145
	v_lshlrev_b64 v[36:37], 12, v[36:37]
	v_lshl_add_u64 v[36:37], v[34:35], 0, v[36:37]
	global_load_dword v77, v[36:37], off nt
	v_or_b32_e32 v36, 46, v144
	v_mov_b32_e32 v37, v145
	v_lshlrev_b64 v[36:37], 12, v[36:37]
	v_lshl_add_u64 v[36:37], v[34:35], 0, v[36:37]
	global_load_dword v78, v[36:37], off nt
	v_or_b32_e32 v36, 48, v144
	v_mov_b32_e32 v37, v145
	v_lshlrev_b64 v[36:37], 12, v[36:37]
	v_lshl_add_u64 v[36:37], v[34:35], 0, v[36:37]
	global_load_dword v79, v[36:37], off nt
	v_or_b32_e32 v36, 50, v144
	v_mov_b32_e32 v37, v145
	v_lshlrev_b64 v[36:37], 12, v[36:37]
	v_lshl_add_u64 v[36:37], v[34:35], 0, v[36:37]
	global_load_dword v80, v[36:37], off nt
	v_or_b32_e32 v36, 52, v144
	v_mov_b32_e32 v37, v145
	v_lshlrev_b64 v[36:37], 12, v[36:37]
	v_lshl_add_u64 v[36:37], v[34:35], 0, v[36:37]
	global_load_dword v81, v[36:37], off nt
	v_or_b32_e32 v36, 54, v144
	v_mov_b32_e32 v37, v145
	v_lshlrev_b64 v[36:37], 12, v[36:37]
	v_lshl_add_u64 v[36:37], v[34:35], 0, v[36:37]
	global_load_dword v82, v[36:37], off nt
	v_or_b32_e32 v36, 56, v144
	v_mov_b32_e32 v37, v145
	v_lshlrev_b64 v[36:37], 12, v[36:37]
	v_lshl_add_u64 v[36:37], v[34:35], 0, v[36:37]
	global_load_dword v83, v[36:37], off nt
	v_or_b32_e32 v36, 58, v144
	v_mov_b32_e32 v37, v145
	v_lshlrev_b64 v[36:37], 12, v[36:37]
	v_lshl_add_u64 v[36:37], v[34:35], 0, v[36:37]
	global_load_dword v84, v[36:37], off nt
	v_or_b32_e32 v36, 60, v144
	v_mov_b32_e32 v37, v145
	v_lshlrev_b64 v[36:37], 12, v[36:37]
	v_lshl_add_u64 v[36:37], v[34:35], 0, v[36:37]
	v_or_b32_e32 v144, 62, v144
	global_load_dword v85, v[36:37], off nt
	v_lshlrev_b64 v[36:37], 12, v[144:145]
	v_lshl_add_u64 v[34:35], v[34:35], 0, v[36:37]
	global_load_dword v34, v[34:35], off nt
	v_add_u32_e32 v35, 0x400, v3
	s_waitcnt vmcnt(0)
; #define LAS __attribute__((address_space(3)))
; __device__ __forceinline__ unsigned pk2(float lo, float hi) { return pg8::cvt_pk_bf16(lo, hi); }
; __device__ __forceinline__ void lds_wait() { asm volatile("s_waitcnt lgkmcnt(0)" ::: "memory"); }
; __device__ __forceinline__ void transpose_item(const float* W, int N, bf16* WT, int K, int k0, int n0, int drow0, const float* gk, LAS float* scr, int lane) {
;     ...
; #pragma unroll
;     for (int i = 0; i < 32; ++i) { const int kk = 2 * i + (lane >> 5); float v = wv[i]; if (gk) v *= gk[kk]; scr[kk * 33 + (lane & 31)] = v; }
;     lds_wait();
;     const int c = lane & 7;
; #pragma unroll
;     for (int j = 0; j < 4; ++j) { const int n = (lane >> 3) + 8 * j; const LAS float* s = scr + (8 * c) * 33 + n;
;         u32x4 o; o.x = pk2(s[0 * 33], s[1 * 33]); o.y = pk2(s[2 * 33], s[3 * 33]); o.z = pk2(s[4 * 33], s[5 * 33]); o.w = pk2(s[6 * 33], s[7 * 33]);
;         *(u32x4*)(WT + (size_t)(drow0 + n) * K + k0 + 8 * c) = o; }
;     lds_wait();
	ds_write2_b32 v3, v38, v39 offset1:66
	ds_write2_b32 v3, v40, v41 offset0:132 offset1:198
	ds_write2_b32 v35, v42, v43 offset0:8 offset1:74
	ds_write2_b32 v35, v44, v45 offset0:140 offset1:206
	v_add_u32_e32 v35, 0x800, v3
	ds_write2_b32 v35, v46, v47 offset0:16 offset1:82
	ds_write2_b32 v35, v48, v49 offset0:148 offset1:214
	v_add_u32_e32 v35, 0xc00, v3
	ds_write2_b32 v35, v50, v51 offset0:24 offset1:90
	ds_write2_b32 v35, v69, v70 offset0:156 offset1:222
	v_add_u32_e32 v35, 0x1000, v3
	ds_write2_b32 v35, v71, v72 offset0:32 offset1:98
	ds_write2_b32 v35, v73, v74 offset0:164 offset1:230
	v_add_u32_e32 v35, 0x1400, v3
	ds_write2_b32 v35, v75, v76 offset0:40 offset1:106
	ds_write2_b32 v35, v77, v78 offset0:172 offset1:238
	v_add_u32_e32 v35, 0x1800, v3
	ds_write2_b32 v35, v79, v80 offset0:48 offset1:114
	ds_write2_b32 v35, v81, v82 offset0:180 offset1:246
	v_add_u32_e32 v35, 0x1c00, v3
	ds_write2_b32 v35, v83, v84 offset0:56 offset1:122
	ds_write2_b32 v35, v85, v34 offset0:188 offset1:254
	s_waitcnt lgkmcnt(0)
	ds_read2_b32 v[34:35], v52 offset1:33
	s_waitcnt lgkmcnt(0)
	v_cvt_pk_bf16_f32 v34, v34, v35
	ds_read2_b32 v[36:37], v52 offset0:66 offset1:99
	s_waitcnt lgkmcnt(0)
	v_cvt_pk_bf16_f32 v35, v36, v37
	ds_read2_b32 v[36:37], v52 offset0:132 offset1:165
	s_waitcnt lgkmcnt(0)
	v_cvt_pk_bf16_f32 v36, v36, v37
	ds_read2_b32 v[40:41], v52 offset0:198 offset1:231
	s_waitcnt lgkmcnt(0)
	v_cvt_pk_bf16_f32 v37, v40, v41
	v_or_b32_e32 v40, s0, v5
	s_lshl_b32 s82, s1, 1
	v_mul_u32_u24_e32 v40, 0xb00, v40
	v_lshl_add_u64 v[38:39], v[28:29], 0, s[82:83]
	v_lshlrev_b32_e32 v144, 1, v40
	v_lshl_add_u64 v[40:41], v[38:39], 0, v[144:145]
	global_store_dwordx4 v[40:41], v[34:37], off sc1
	ds_read2_b32 v[34:35], v52 offset0:8 offset1:41
	s_waitcnt lgkmcnt(0)
	v_cvt_pk_bf16_f32 v34, v34, v35
	ds_read2_b32 v[36:37], v52 offset0:74 offset1:107
	s_waitcnt lgkmcnt(0)
	v_cvt_pk_bf16_f32 v35, v36, v37
	ds_read2_b32 v[36:37], v52 offset0:140 offset1:173
	s_waitcnt lgkmcnt(0)
	v_cvt_pk_bf16_f32 v36, v36, v37
	ds_read2_b32 v[40:41], v52 offset0:206 offset1:239
	s_waitcnt lgkmcnt(0)
	v_cvt_pk_bf16_f32 v37, v40, v41
	v_or_b32_e32 v40, s0, v53
	v_mul_u32_u24_e32 v40, 0xb00, v40
	v_lshlrev_b32_e32 v144, 1, v40
	v_lshl_add_u64 v[40:41], v[38:39], 0, v[144:145]
	global_store_dwordx4 v[40:41], v[34:37], off sc1
	ds_read2_b32 v[34:35], v52 offset0:16 offset1:49
	s_waitcnt lgkmcnt(0)
	v_cvt_pk_bf16_f32 v34, v34, v35
	ds_read2_b32 v[36:37], v52 offset0:82 offset1:115
	s_waitcnt lgkmcnt(0)
	v_cvt_pk_bf16_f32 v35, v36, v37
	ds_read2_b32 v[36:37], v52 offset0:148 offset1:181
	s_waitcnt lgkmcnt(0)
	v_cvt_pk_bf16_f32 v36, v36, v37
	ds_read2_b32 v[40:41], v52 offset0:214 offset1:247
	s_waitcnt lgkmcnt(0)
	v_cvt_pk_bf16_f32 v37, v40, v41
	v_or_b32_e32 v40, s0, v54
	v_mul_u32_u24_e32 v40, 0xb00, v40
	v_lshlrev_b32_e32 v144, 1, v40
	v_lshl_add_u64 v[40:41], v[38:39], 0, v[144:145]
	global_store_dwordx4 v[40:41], v[34:37], off sc1
	ds_read2_b32 v[34:35], v52 offset0:24 offset1:57
	s_waitcnt lgkmcnt(0)
	v_cvt_pk_bf16_f32 v34, v34, v35
	ds_read2_b32 v[36:37], v52 offset0:90 offset1:123
	s_waitcnt lgkmcnt(0)
	v_cvt_pk_bf16_f32 v35, v36, v37
	ds_read2_b32 v[36:37], v52 offset0:156 offset1:189
	s_waitcnt lgkmcnt(0)
	v_cvt_pk_bf16_f32 v36, v36, v37
	ds_read2_b32 v[40:41], v52 offset0:222 offset1:255
	s_waitcnt lgkmcnt(0)
	v_cvt_pk_bf16_f32 v37, v40, v41
	v_or_b32_e32 v40, s0, v55
	v_mul_u32_u24_e32 v40, 0xb00, v40
	v_lshlrev_b32_e32 v144, 1, v40
	v_lshl_add_u64 v[38:39], v[38:39], 0, v[144:145]
	global_store_dwordx4 v[38:39], v[34:37], off sc1
	s_waitcnt lgkmcnt(0)

; __device__ __forceinline__ void transpose_item(const float* W, int N, bf16* WT, int K, int k0, int n0, int drow0, const float* gk, LAS float* scr, int lane) {
;     float wv[32];
; #pragma unroll
;     for (int i = 0; i < 32; ++i) wv[i] = W[(size_t)(k0 + 2 * i + (lane >> 5)) * N + n0 + (lane & 31)];
; __device__ __forceinline__ void p0_weight_item(const Args& a, int l, int r, LAS float* scr, int lane) {
;     ...
;         if (r < 2 * IT_BIG) { const int up = r >= IT_BIG; const int it = r - up * IT_BIG; const int kb = it / 88, nb = it % 88, k0 = 64 * kb, n0 = 32 * nb;
;             const float* W = a.in[(f ? 29 : 2) + up] + (size_t)l * DM * FF;
;             transpose_item(W, FF, gu, DM, k0, n0, (n0 >> 7) * 256 + up * 128 + (n0 & 127), nrm + k0, scr, lane); return; }
.LBB0_1113:
	s_andn2_b64 vcc, exec, s[0:1]
	s_cbranch_vccnz .LBB0_1139
	s_cmpk_gt_u32 s39, 0x15ff
	v_readlane_b32 s40, v250, 59
	s_cselect_b64 s[4:5], -1, 0
	v_readlane_b32 s41, v250, 60
	v_readlane_b32 s42, v250, 61
	v_readlane_b32 s43, v250, 62
	v_readlane_b32 s44, v250, 63
	v_readlane_b32 s45, v251, 0
	v_readlane_b32 s46, v251, 1
	v_readlane_b32 s47, v251, 2
	v_readlane_b32 s48, v251, 3
	v_readlane_b32 s49, v251, 4
	v_readlane_b32 s50, v251, 5
	v_readlane_b32 s51, v251, 6
	s_and_b64 s[0:1], s[4:5], exec
	v_readlane_b32 s52, v251, 7
	v_readlane_b32 s53, v251, 8
	v_readlane_b32 s54, v251, 9
	v_readlane_b32 s55, v251, 10
	s_mov_b64 s[40:41], s[44:45]
	s_cselect_b32 s0, 0xfa80, 0
	s_mov_b64 s[42:43], s[46:47]
	s_mov_b64 s[44:45], s[48:49]
	s_mov_b64 s[46:47], s[50:51]
	s_mov_b64 s[48:49], s[52:53]
	s_cselect_b32 s1, s49, s47
	s_cselect_b32 s7, s48, s46
	s_add_i32 s0, s0, s27
	s_addk_i32 s0, 0x1080
	s_sext_i32_i16 s6, s0
	s_mulk_i32 s6, 0xba3
	s_lshr_b32 s24, s6, 31
	s_ashr_i32 s6, s6, 18
	s_add_i32 s6, s6, s24
	s_mul_i32 s24, s6, 0x58
	s_sub_i32 s0, s0, s24
	s_sext_i32_i16 s24, s0
	s_lshl_b32 s28, s6, 6
	s_lshl_b32 s6, s24, 5
	s_add_u32 s25, s7, s81
	s_addc_u32 s36, s1, s80
	s_ashr_i32 s29, s28, 31
	s_lshl_b64 s[0:1], s[28:29], 2
	v_readlane_b32 s7, v254, 27
	s_add_u32 s30, s7, s0
	v_readlane_b32 s0, v254, 28
	s_addc_u32 s31, s0, s1
	s_ashr_i32 s7, s6, 31
	s_lshl_b64 s[0:1], s[6:7], 2
	v_or_b32_e32 v36, s28, v0
	s_add_u32 s0, s25, s0
	s_addc_u32 s1, s36, s1
	v_lshlrev_b32_e32 v144, 2, v2
	v_mul_i32_i24_e32 v36, 0x2c00, v36
	v_lshl_add_u64 v[34:35], s[0:1], 0, v[144:145]
	v_ashrrev_i32_e32 v37, 31, v36
	v_lshl_add_u64 v[50:51], v[34:35], 0, v[36:37]
	s_movk_i32 s0, 0x5000
	v_add_co_u32_e32 v34, vcc, s0, v50
	s_mov_b32 s0, 0xb000
	s_nop 0
	v_addc_co_u32_e32 v35, vcc, 0, v51, vcc
	global_load_dword v84, v[34:35], off offset:2048 nt
	v_add_co_u32_e32 v34, vcc, s0, v50
	s_mov_b32 s0, 0x10000
	s_nop 0
	v_addc_co_u32_e32 v35, vcc, 0, v51, vcc
	global_load_dword v83, v[50:51], off nt
	global_load_dword v48, v[34:35], off nt
	v_add_co_u32_e32 v34, vcc, s0, v50
	s_mov_b32 s0, 0x16000
	s_nop 0
	v_addc_co_u32_e32 v35, vcc, 0, v51, vcc
	global_load_dword v49, v[34:35], off offset:2048 nt
	v_add_co_u32_e32 v34, vcc, s0, v50
	s_mov_b32 s0, 0x1b000
	s_nop 0
	v_addc_co_u32_e32 v35, vcc, 0, v51, vcc
	global_load_dword v81, v[34:35], off nt
	v_add_co_u32_e32 v34, vcc, s0, v50
	s_mov_b32 s0, 0x21000
	s_nop 0
	v_addc_co_u32_e32 v35, vcc, 0, v51, vcc
	global_load_dword v82, v[34:35], off offset:2048 nt
	v_add_co_u32_e32 v34, vcc, s0, v50
	s_mov_b32 s0, 0x26000
	s_nop 0
	v_addc_co_u32_e32 v35, vcc, 0, v51, vcc
	global_load_dword v46, v[34:35], off nt
	v_add_co_u32_e32 v34, vcc, s0, v50
	s_mov_b32 s0, 0x2c000
	s_nop 0
	v_addc_co_u32_e32 v35, vcc, 0, v51, vcc
	global_load_dword v47, v[34:35], off offset:2048 nt
	v_add_co_u32_e32 v34, vcc, s0, v50
	s_mov_b32 s0, 0x31000
	s_nop 0
	v_addc_co_u32_e32 v35, vcc, 0, v51, vcc
	global_load_dword v79, v[34:35], off nt
	v_add_co_u32_e32 v34, vcc, s0, v50
	s_mov_b32 s0, 0x37000
	s_nop 0
	v_addc_co_u32_e32 v35, vcc, 0, v51, vcc
	global_load_dword v80, v[34:35], off offset:2048 nt
	v_add_co_u32_e32 v34, vcc, s0, v50
	s_mov_b32 s0, 0x3c000
	s_nop 0
	v_addc_co_u32_e32 v35, vcc, 0, v51, vcc
	global_load_dword v44, v[34:35], off nt
	v_add_co_u32_e32 v34, vcc, s0, v50
	s_mov_b32 s0, 0x42000
	s_nop 0
	v_addc_co_u32_e32 v35, vcc, 0, v51, vcc
	global_load_dword v45, v[34:35], off offset:2048 nt
	v_add_co_u32_e32 v34, vcc, s0, v50
	s_mov_b32 s0, 0x47000
	s_nop 0
	v_addc_co_u32_e32 v35, vcc, 0, v51, vcc
	global_load_dword v77, v[34:35], off nt
	v_add_co_u32_e32 v34, vcc, s0, v50
	s_mov_b32 s0, 0x4d000
	s_nop 0
	v_addc_co_u32_e32 v35, vcc, 0, v51, vcc
	global_load_dword v78, v[34:35], off offset:2048 nt
	v_add_co_u32_e32 v34, vcc, s0, v50
	s_mov_b32 s0, 0x52000
	s_nop 0
	v_addc_co_u32_e32 v35, vcc, 0, v51, vcc
	global_load_dword v42, v[34:35], off nt
	v_add_co_u32_e32 v34, vcc, s0, v50
	s_mov_b32 s0, 0x58000
	s_nop 0
	v_addc_co_u32_e32 v35, vcc, 0, v51, vcc
	global_load_dword v43, v[34:35], off offset:2048 nt
	v_add_co_u32_e32 v34, vcc, s0, v50
	s_mov_b32 s0, 0x5d000
	s_nop 0
	v_addc_co_u32_e32 v35, vcc, 0, v51, vcc
	global_load_dword v75, v[34:35], off nt
	v_add_co_u32_e32 v34, vcc, s0, v50
	s_mov_b32 s0, 0x63000
	s_nop 0
	v_addc_co_u32_e32 v35, vcc, 0, v51, vcc
	global_load_dword v76, v[34:35], off offset:2048 nt
	v_add_co_u32_e32 v34, vcc, s0, v50
	s_mov_b32 s0, 0x68000
	s_nop 0
	v_addc_co_u32_e32 v35, vcc, 0, v51, vcc
	global_load_dword v40, v[34:35], off nt
	v_add_co_u32_e32 v34, vcc, s0, v50
	s_mov_b32 s0, 0x6e000
	s_nop 0
	v_addc_co_u32_e32 v35, vcc, 0, v51, vcc
	global_load_dword v41, v[34:35], off offset:2048 nt
	v_add_co_u32_e32 v34, vcc, s0, v50
	s_mov_b32 s0, 0x73000
	s_nop 0
	v_addc_co_u32_e32 v35, vcc, 0, v51, vcc
	global_load_dword v73, v[34:35], off nt
	v_add_co_u32_e32 v34, vcc, s0, v50
	s_mov_b32 s0, 0x79000
	s_nop 0
	v_addc_co_u32_e32 v35, vcc, 0, v51, vcc
	global_load_dword v74, v[34:35], off offset:2048 nt
	v_add_co_u32_e32 v34, vcc, s0, v50
	s_mov_b32 s0, 0x7e000
	s_nop 0
	v_addc_co_u32_e32 v35, vcc, 0, v51, vcc
	global_load_dword v38, v[34:35], off nt
	v_add_co_u32_e32 v34, vcc, s0, v50
	s_mov_b32 s0, 0x84000
	s_nop 0
	v_addc_co_u32_e32 v35, vcc, 0, v51, vcc
	global_load_dword v39, v[34:35], off offset:2048 nt
	v_add_co_u32_e32 v34, vcc, s0, v50
	s_mov_b32 s0, 0x89000
	s_nop 0
	v_addc_co_u32_e32 v35, vcc, 0, v51, vcc
	global_load_dword v71, v[34:35], off nt
	v_add_co_u32_e32 v34, vcc, s0, v50
	s_mov_b32 s0, 0x8f000
	s_nop 0
	v_addc_co_u32_e32 v35, vcc, 0, v51, vcc
	global_load_dword v72, v[34:35], off offset:2048 nt
	v_add_co_u32_e32 v34, vcc, s0, v50
	s_mov_b32 s0, 0x94000
	s_nop 0
	v_addc_co_u32_e32 v35, vcc, 0, v51, vcc
	global_load_dword v36, v[34:35], off nt
	v_add_co_u32_e32 v34, vcc, s0, v50
	s_mov_b32 s0, 0x9a000
	s_nop 0
	v_addc_co_u32_e32 v35, vcc, 0, v51, vcc
	global_load_dword v37, v[34:35], off offset:2048 nt
	v_add_co_u32_e32 v34, vcc, s0, v50
	v_readlane_b32 s0, v251, 40
	s_nop 0
	v_addc_co_u32_e32 v35, vcc, 0, v51, vcc
	global_load_dword v69, v[34:35], off nt
	v_add_co_u32_e32 v34, vcc, 0x9f000, v50
	v_readlane_b32 s1, v251, 41
	s_nop 0
	v_addc_co_u32_e32 v35, vcc, 0, v51, vcc
	global_load_dword v70, v[34:35], off offset:2048 nt
	v_add_co_u32_e32 v34, vcc, 0xa5000, v50
	s_mov_b64 s[50:51], s[54:55]
	s_nop 0
	v_addc_co_u32_e32 v35, vcc, 0, v51, vcc
	v_add_co_u32_e32 v50, vcc, 0xaa000, v50
	global_load_dword v34, v[34:35], off nt
	s_nop 0
	v_addc_co_u32_e32 v51, vcc, 0, v51, vcc
	global_load_dword v35, v[50:51], off offset:2048 nt
	v_cndmask_b32_e64 v50, 0, 1, s[0:1]
	v_cmp_ne_u32_e64 s[36:37], 1, v50
	s_andn2_b64 vcc, exec, s[0:1]
	s_cbranch_vccnz .LBB0_1175
; __device__ __forceinline__ void transpose_item(const float* W, int N, bf16* WT, int K, int k0, int n0, int drow0, const float* gk, LAS float* scr, int lane) {
;     ...
;     for (int i = 0; i < 32; ++i) wv[i] = W[(size_t)(k0 + 2 * i + (lane >> 5)) * N + n0 + (lane & 31)];
; #pragma unroll
;     for (int i = 0; i < 32; ++i) { const int kk = 2 * i + (lane >> 5); float v = wv[i]; if (gk) v *= gk[kk]; scr[kk * 33 + (lane & 31)] = v; }
	v_lshlrev_b32_e32 v51, 2, v0
	s_waitcnt vmcnt(32)
	global_load_dword v204, v51, s[30:31]
	global_load_dword v205, v51, s[30:31] offset:8
	global_load_dword v206, v51, s[30:31] offset:16
	global_load_dword v207, v51, s[30:31] offset:24
	global_load_dword v208, v51, s[30:31] offset:32
	global_load_dword v209, v51, s[30:31] offset:40
	global_load_dword v210, v51, s[30:31] offset:48
	global_load_dword v211, v51, s[30:31] offset:56
	global_load_dword v212, v51, s[30:31] offset:64
	global_load_dword v213, v51, s[30:31] offset:72
	global_load_dword v214, v51, s[30:31] offset:80
	global_load_dword v215, v51, s[30:31] offset:88
	global_load_dword v216, v51, s[30:31] offset:96
	global_load_dword v217, v51, s[30:31] offset:104
	global_load_dword v218, v51, s[30:31] offset:112
	global_load_dword v219, v51, s[30:31] offset:120
	global_load_dword v220, v51, s[30:31] offset:128
	global_load_dword v221, v51, s[30:31] offset:136
	global_load_dword v222, v51, s[30:31] offset:144
	global_load_dword v223, v51, s[30:31] offset:152
	global_load_dword v224, v51, s[30:31] offset:160
	global_load_dword v225, v51, s[30:31] offset:168
	global_load_dword v226, v51, s[30:31] offset:176
	global_load_dword v227, v51, s[30:31] offset:184
	global_load_dword v228, v51, s[30:31] offset:192
	global_load_dword v229, v51, s[30:31] offset:200
	global_load_dword v230, v51, s[30:31] offset:208
	global_load_dword v231, v51, s[30:31] offset:216
	global_load_dword v232, v51, s[30:31] offset:224
	global_load_dword v233, v51, s[30:31] offset:232
	global_load_dword v234, v51, s[30:31] offset:240
	s_waitcnt vmcnt(62)
	global_load_dword v235, v51, s[30:31] offset:248
	s_waitcnt vmcnt(0)
	v_mov_b32_e32 v50, v204
	v_mov_b32_e32 v85, v205
	s_waitcnt vmcnt(0)
	v_mul_f32_e32 v50, v83, v50
	v_mul_f32_e32 v85, v84, v85
	ds_write_b32 v3, v50
	v_add_u32_e32 v50, v1, v56
	ds_write_b32 v50, v85
	v_mov_b32_e32 v50, v206
	s_nop 0
	v_mov_b32_e32 v51, v207
	s_waitcnt vmcnt(0)
	v_pk_mul_f32 v[50:51], v[48:49], v[50:51]
	s_cbranch_execnz .LBB0_1117

; #define LAS __attribute__((address_space(3)))
; __device__ __forceinline__ unsigned pk2(float lo, float hi) { return pg8::cvt_pk_bf16(lo, hi); }
; __device__ __forceinline__ void transpose_item(const float* W, int N, bf16* WT, int K, int k0, int n0, int drow0, const float* gk, LAS float* scr, int lane) {
;     ...
;     const int c = lane & 7;
; #pragma unroll
;     for (int j = 0; j < 4; ++j) { const int n = (lane >> 3) + 8 * j; const LAS float* s = scr + (8 * c) * 33 + n;
;         u32x4 o; o.x = pk2(s[0 * 33], s[1 * 33]); o.y = pk2(s[2 * 33], s[3 * 33]); o.z = pk2(s[4 * 33], s[5 * 33]); o.w = pk2(s[6 * 33], s[7 * 33]);
;         *(u32x4*)(WT + (size_t)(drow0 + n) * K + k0 + 8 * c) = o; }
.LBB0_1138:
	s_lshl_b32 s0, s24, 6
	s_and_b32 s7, s0, 0xffffff00
	s_and_b64 s[0:1], s[4:5], exec
	s_cselect_b32 s0, 0x80, 0
	s_and_b32 s1, s6, 0x60
	s_or_b32 s0, s7, s0
	ds_write2_b32 v38, v36, v37 offset0:140 offset1:206
	s_or_b32 s0, s0, s1
	s_waitcnt lgkmcnt(0)
	v_or_b32_e32 v42, s0, v5
	ds_read2_b32 v[34:35], v52 offset1:33
	v_ashrrev_i32_e32 v43, 31, v42
	s_waitcnt lgkmcnt(0)
	v_cvt_pk_bf16_f32 v34, v34, v35
	ds_read2_b32 v[36:37], v52 offset0:66 offset1:99
	v_lshl_add_u64 v[38:39], s[28:29], 1, v[30:31]
	v_lshlrev_b64 v[42:43], 11, v[42:43]
	s_waitcnt lgkmcnt(0)
	v_cvt_pk_bf16_f32 v35, v36, v37
	ds_read2_b32 v[36:37], v52 offset0:132 offset1:165
	v_lshl_add_u64 v[42:43], v[38:39], 0, v[42:43]
	s_waitcnt lgkmcnt(0)
	v_cvt_pk_bf16_f32 v36, v36, v37
	ds_read2_b32 v[40:41], v52 offset0:198 offset1:231
	s_waitcnt lgkmcnt(0)
	v_cvt_pk_bf16_f32 v37, v40, v41
	global_store_dwordx4 v[42:43], v[34:37], off sc1
	v_or_b32_e32 v42, s0, v53
	v_ashrrev_i32_e32 v43, 31, v42
	ds_read2_b32 v[40:41], v52 offset0:8 offset1:41
	s_waitcnt lgkmcnt(0)
	v_cvt_pk_bf16_f32 v34, v40, v41
	ds_read2_b32 v[36:37], v52 offset0:74 offset1:107
	v_lshlrev_b64 v[42:43], 11, v[42:43]
	s_waitcnt lgkmcnt(0)
	v_cvt_pk_bf16_f32 v35, v36, v37
	ds_read2_b32 v[36:37], v52 offset0:140 offset1:173
	v_lshl_add_u64 v[42:43], v[38:39], 0, v[42:43]
	s_waitcnt lgkmcnt(0)
	v_cvt_pk_bf16_f32 v36, v36, v37
	ds_read2_b32 v[40:41], v52 offset0:206 offset1:239
	s_waitcnt lgkmcnt(0)
	v_cvt_pk_bf16_f32 v37, v40, v41
	global_store_dwordx4 v[42:43], v[34:37], off sc1
	v_or_b32_e32 v42, s0, v54
	v_ashrrev_i32_e32 v43, 31, v42
	ds_read2_b32 v[40:41], v52 offset0:16 offset1:49
	s_waitcnt lgkmcnt(0)
	v_cvt_pk_bf16_f32 v34, v40, v41
	ds_read2_b32 v[36:37], v52 offset0:82 offset1:115
	v_lshlrev_b64 v[42:43], 11, v[42:43]
	s_waitcnt lgkmcnt(0)
	v_cvt_pk_bf16_f32 v35, v36, v37
	ds_read2_b32 v[36:37], v52 offset0:148 offset1:181
	v_lshl_add_u64 v[42:43], v[38:39], 0, v[42:43]
	s_waitcnt lgkmcnt(0)
	v_cvt_pk_bf16_f32 v36, v36, v37
	ds_read2_b32 v[40:41], v52 offset0:214 offset1:247
	s_waitcnt lgkmcnt(0)
	v_cvt_pk_bf16_f32 v37, v40, v41
	global_store_dwordx4 v[42:43], v[34:37], off sc1
	v_or_b32_e32 v42, s0, v55
	v_ashrrev_i32_e32 v43, 31, v42
	ds_read2_b32 v[40:41], v52 offset0:24 offset1:57
	s_waitcnt lgkmcnt(0)
	v_cvt_pk_bf16_f32 v34, v40, v41
	ds_read2_b32 v[36:37], v52 offset0:90 offset1:123
	v_lshlrev_b64 v[42:43], 11, v[42:43]
	s_waitcnt lgkmcnt(0)
	v_cvt_pk_bf16_f32 v35, v36, v37
	ds_read2_b32 v[36:37], v52 offset0:156 offset1:189
	v_lshl_add_u64 v[38:39], v[38:39], 0, v[42:43]
	s_waitcnt lgkmcnt(0)
	v_cvt_pk_bf16_f32 v36, v36, v37
	ds_read2_b32 v[40:41], v52 offset0:222 offset1:255
	s_waitcnt lgkmcnt(0)
	v_cvt_pk_bf16_f32 v37, v40, v41
	global_store_dwordx4 v[38:39], v[34:37], off sc1
	s_waitcnt lgkmcnt(0)

; __device__ __forceinline__ void transpose_item(const float* W, int N, bf16* WT, int K, int k0, int n0, int drow0, const float* gk, LAS float* scr, int lane) {
;     float wv[32];
; #pragma unroll
;     for (int i = 0; i < 32; ++i) wv[i] = W[(size_t)(k0 + 2 * i + (lane >> 5)) * N + n0 + (lane & 31)];
; __device__ __forceinline__ void p0_weight_item(const Args& a, int l, int r, LAS float* scr, int lane) {
;     ...
;         if (r < IT_BIG) { const int kb = r / 32, nb = r % 32; const float* W = a.in[f ? 31 : 4] + (size_t)l * FF * DM;
;             transpose_item(W, DM, dn, FF, 64 * kb, 32 * nb, 32 * nb, nullptr, scr, lane); return; }
.LBB0_1140:
	s_andn2_b64 vcc, exec, s[0:1]
	s_cbranch_vccnz .LBB0_1142
	s_add_i32 s0, s26, 0x2100
	s_and_b32 s1, s0, 0x7fffffc0
	s_add_i32 s0, s35, 0xffffc000
	s_and_b32 s0, s0, 0x3e0
	v_or_b32_e32 v144, s1, v0
	s_lshl_b32 s82, s0, 2
	v_lshl_add_u64 v[34:35], v[32:33], 0, s[82:83]
	v_lshlrev_b64 v[36:37], 12, v[144:145]
	v_lshl_add_u64 v[36:37], v[34:35], 0, v[36:37]
	global_load_dword v38, v[36:37], off nt
	v_or_b32_e32 v36, 2, v144
	v_mov_b32_e32 v37, v145
	v_lshlrev_b64 v[36:37], 12, v[36:37]
	v_lshl_add_u64 v[36:37], v[34:35], 0, v[36:37]
	global_load_dword v39, v[36:37], off nt
	v_or_b32_e32 v36, 4, v144
	v_mov_b32_e32 v37, v145
	v_lshlrev_b64 v[36:37], 12, v[36:37]
	v_lshl_add_u64 v[36:37], v[34:35], 0, v[36:37]
	global_load_dword v40, v[36:37], off nt
	v_or_b32_e32 v36, 6, v144
	v_mov_b32_e32 v37, v145
	v_lshlrev_b64 v[36:37], 12, v[36:37]
	v_lshl_add_u64 v[36:37], v[34:35], 0, v[36:37]
	global_load_dword v41, v[36:37], off nt
	v_or_b32_e32 v36, 8, v144
	v_mov_b32_e32 v37, v145
	v_lshlrev_b64 v[36:37], 12, v[36:37]
	v_lshl_add_u64 v[36:37], v[34:35], 0, v[36:37]
	global_load_dword v42, v[36:37], off nt
	v_or_b32_e32 v36, 10, v144
	v_mov_b32_e32 v37, v145
	v_lshlrev_b64 v[36:37], 12, v[36:37]
	v_lshl_add_u64 v[36:37], v[34:35], 0, v[36:37]
	global_load_dword v43, v[36:37], off nt
	v_or_b32_e32 v36, 12, v144
	v_mov_b32_e32 v37, v145
	v_lshlrev_b64 v[36:37], 12, v[36:37]
	v_lshl_add_u64 v[36:37], v[34:35], 0, v[36:37]
	global_load_dword v44, v[36:37], off nt
	v_or_b32_e32 v36, 14, v144
	v_mov_b32_e32 v37, v145
	v_lshlrev_b64 v[36:37], 12, v[36:37]
	v_lshl_add_u64 v[36:37], v[34:35], 0, v[36:37]
	global_load_dword v45, v[36:37], off nt
	v_or_b32_e32 v36, 16, v144
	v_mov_b32_e32 v37, v145
	v_lshlrev_b64 v[36:37], 12, v[36:37]
	v_lshl_add_u64 v[36:37], v[34:35], 0, v[36:37]
	global_load_dword v46, v[36:37], off nt
	v_or_b32_e32 v36, 18, v144
	v_mov_b32_e32 v37, v145
	v_lshlrev_b64 v[36:37], 12, v[36:37]
	v_lshl_add_u64 v[36:37], v[34:35], 0, v[36:37]
	global_load_dword v47, v[36:37], off nt
	v_or_b32_e32 v36, 20, v144
	v_mov_b32_e32 v37, v145
	v_lshlrev_b64 v[36:37], 12, v[36:37]
	v_lshl_add_u64 v[36:37], v[34:35], 0, v[36:37]
	global_load_dword v48, v[36:37], off nt
	v_or_b32_e32 v36, 22, v144
	v_mov_b32_e32 v37, v145
	v_lshlrev_b64 v[36:37], 12, v[36:37]
	v_lshl_add_u64 v[36:37], v[34:35], 0, v[36:37]
	global_load_dword v49, v[36:37], off nt
	v_or_b32_e32 v36, 24, v144
	v_mov_b32_e32 v37, v145
	v_lshlrev_b64 v[36:37], 12, v[36:37]
	v_lshl_add_u64 v[36:37], v[34:35], 0, v[36:37]
	global_load_dword v50, v[36:37], off nt
	v_or_b32_e32 v36, 26, v144
	v_mov_b32_e32 v37, v145
	v_lshlrev_b64 v[36:37], 12, v[36:37]
	v_lshl_add_u64 v[36:37], v[34:35], 0, v[36:37]
	global_load_dword v51, v[36:37], off nt
	v_or_b32_e32 v36, 28, v144
	v_mov_b32_e32 v37, v145
	v_lshlrev_b64 v[36:37], 12, v[36:37]
	v_lshl_add_u64 v[36:37], v[34:35], 0, v[36:37]
	global_load_dword v69, v[36:37], off nt
	v_or_b32_e32 v36, 30, v144
	v_mov_b32_e32 v37, v145
	v_lshlrev_b64 v[36:37], 12, v[36:37]
	v_lshl_add_u64 v[36:37], v[34:35], 0, v[36:37]
	global_load_dword v70, v[36:37], off nt
	v_or_b32_e32 v36, 32, v144
	v_mov_b32_e32 v37, v145
	v_lshlrev_b64 v[36:37], 12, v[36:37]
	v_lshl_add_u64 v[36:37], v[34:35], 0, v[36:37]
	global_load_dword v71, v[36:37], off nt
	v_or_b32_e32 v36, 34, v144
	v_mov_b32_e32 v37, v145
	v_lshlrev_b64 v[36:37], 12, v[36:37]
	v_lshl_add_u64 v[36:37], v[34:35], 0, v[36:37]
	global_load_dword v72, v[36:37], off nt
	v_or_b32_e32 v36, 36, v144
	v_mov_b32_e32 v37, v145
	v_lshlrev_b64 v[36:37], 12, v[36:37]
	v_lshl_add_u64 v[36:37], v[34:35], 0, v[36:37]
	global_load_dword v73, v[36:37], off nt
	v_or_b32_e32 v36, 38, v144
	v_mov_b32_e32 v37, v145
	v_lshlrev_b64 v[36:37], 12, v[36:37]
	v_lshl_add_u64 v[36:37], v[34:35], 0, v[36:37]
	global_load_dword v74, v[36:37], off nt
	v_or_b32_e32 v36, 40, v144
	v_mov_b32_e32 v37, v145
	v_lshlrev_b64 v[36:37], 12, v[36:37]
	v_lshl_add_u64 v[36:37], v[34:35], 0, v[36:37]
	global_load_dword v75, v[36:37], off nt
	v_or_b32_e32 v36, 42, v144
	v_mov_b32_e32 v37, v145
	v_lshlrev_b64 v[36:37], 12, v[36:37]
	v_lshl_add_u64 v[36:37], v[34:35], 0, v[36:37]
	global_load_dword v76, v[36:37], off nt
	v_or_b32_e32 v36, 44, v144
	v_mov_b32_e32 v37, v145
	v_lshlrev_b64 v[36:37], 12, v[36:37]
	v_lshl_add_u64 v[36:37], v[34:35], 0, v[36:37]
	global_load_dword v77, v[36:37], off nt
	v_or_b32_e32 v36, 46, v144
	v_mov_b32_e32 v37, v145
	v_lshlrev_b64 v[36:37], 12, v[36:37]
	v_lshl_add_u64 v[36:37], v[34:35], 0, v[36:37]
	global_load_dword v78, v[36:37], off nt
	v_or_b32_e32 v36, 48, v144
	v_mov_b32_e32 v37, v145
	v_lshlrev_b64 v[36:37], 12, v[36:37]
	v_lshl_add_u64 v[36:37], v[34:35], 0, v[36:37]
	global_load_dword v79, v[36:37], off nt
	v_or_b32_e32 v36, 50, v144
	v_mov_b32_e32 v37, v145
	v_lshlrev_b64 v[36:37], 12, v[36:37]
	v_lshl_add_u64 v[36:37], v[34:35], 0, v[36:37]
	global_load_dword v80, v[36:37], off nt
	v_or_b32_e32 v36, 52, v144
	v_mov_b32_e32 v37, v145
	v_lshlrev_b64 v[36:37], 12, v[36:37]
	v_lshl_add_u64 v[36:37], v[34:35], 0, v[36:37]
	global_load_dword v81, v[36:37], off nt
	v_or_b32_e32 v36, 54, v144
	v_mov_b32_e32 v37, v145
	v_lshlrev_b64 v[36:37], 12, v[36:37]
	v_lshl_add_u64 v[36:37], v[34:35], 0, v[36:37]
	global_load_dword v82, v[36:37], off nt
	v_or_b32_e32 v36, 56, v144
	v_mov_b32_e32 v37, v145
	v_lshlrev_b64 v[36:37], 12, v[36:37]
	v_lshl_add_u64 v[36:37], v[34:35], 0, v[36:37]
	global_load_dword v83, v[36:37], off nt
	v_or_b32_e32 v36, 58, v144
	v_mov_b32_e32 v37, v145
	v_lshlrev_b64 v[36:37], 12, v[36:37]
	v_lshl_add_u64 v[36:37], v[34:35], 0, v[36:37]
	global_load_dword v84, v[36:37], off nt
	v_or_b32_e32 v36, 60, v144
	v_mov_b32_e32 v37, v145
	v_lshlrev_b64 v[36:37], 12, v[36:37]
	v_lshl_add_u64 v[36:37], v[34:35], 0, v[36:37]
	v_or_b32_e32 v144, 62, v144
	global_load_dword v85, v[36:37], off nt
	v_lshlrev_b64 v[36:37], 12, v[144:145]
	v_lshl_add_u64 v[34:35], v[34:35], 0, v[36:37]
	global_load_dword v34, v[34:35], off nt
	v_add_u32_e32 v35, 0x400, v3
	s_waitcnt vmcnt(0)
; #define LAS __attribute__((address_space(3)))
; __device__ __forceinline__ unsigned pk2(float lo, float hi) { return pg8::cvt_pk_bf16(lo, hi); }
; __device__ __forceinline__ void lds_wait() { asm volatile("s_waitcnt lgkmcnt(0)" ::: "memory"); }
; __device__ __forceinline__ void transpose_item(const float* W, int N, bf16* WT, int K, int k0, int n0, int drow0, const float* gk, LAS float* scr, int lane) {
;     ...
;     for (int i = 0; i < 32; ++i) { const int kk = 2 * i + (lane >> 5); float v = wv[i]; if (gk) v *= gk[kk]; scr[kk * 33 + (lane & 31)] = v; }
;     lds_wait();
;     const int c = lane & 7;
; #pragma unroll
;     for (int j = 0; j < 4; ++j) { const int n = (lane >> 3) + 8 * j; const LAS float* s = scr + (8 * c) * 33 + n;
;         u32x4 o; o.x = pk2(s[0 * 33], s[1 * 33]); o.y = pk2(s[2 * 33], s[3 * 33]); o.z = pk2(s[4 * 33], s[5 * 33]); o.w = pk2(s[6 * 33], s[7 * 33]);
;         *(u32x4*)(WT + (size_t)(drow0 + n) * K + k0 + 8 * c) = o; }
	ds_write2_b32 v3, v38, v39 offset1:66
	ds_write2_b32 v3, v40, v41 offset0:132 offset1:198
	ds_write2_b32 v35, v42, v43 offset0:8 offset1:74
	ds_write2_b32 v35, v44, v45 offset0:140 offset1:206
	v_add_u32_e32 v35, 0x800, v3
	ds_write2_b32 v35, v46, v47 offset0:16 offset1:82
	ds_write2_b32 v35, v48, v49 offset0:148 offset1:214
	v_add_u32_e32 v35, 0xc00, v3
	ds_write2_b32 v35, v50, v51 offset0:24 offset1:90
	ds_write2_b32 v35, v69, v70 offset0:156 offset1:222
	v_add_u32_e32 v35, 0x1000, v3
	ds_write2_b32 v35, v71, v72 offset0:32 offset1:98
	ds_write2_b32 v35, v73, v74 offset0:164 offset1:230
	v_add_u32_e32 v35, 0x1400, v3
	ds_write2_b32 v35, v75, v76 offset0:40 offset1:106
	ds_write2_b32 v35, v77, v78 offset0:172 offset1:238
	v_add_u32_e32 v35, 0x1800, v3
	ds_write2_b32 v35, v79, v80 offset0:48 offset1:114
	ds_write2_b32 v35, v81, v82 offset0:180 offset1:246
	v_add_u32_e32 v35, 0x1c00, v3
	ds_write2_b32 v35, v83, v84 offset0:56 offset1:122
	ds_write2_b32 v35, v85, v34 offset0:188 offset1:254
	s_waitcnt lgkmcnt(0)
	ds_read2_b32 v[34:35], v52 offset1:33
	s_waitcnt lgkmcnt(0)
	v_cvt_pk_bf16_f32 v34, v34, v35
	ds_read2_b32 v[36:37], v52 offset0:66 offset1:99
	s_waitcnt lgkmcnt(0)
	v_cvt_pk_bf16_f32 v35, v36, v37
	ds_read2_b32 v[36:37], v52 offset0:132 offset1:165
	s_waitcnt lgkmcnt(0)
	v_cvt_pk_bf16_f32 v36, v36, v37
	ds_read2_b32 v[40:41], v52 offset0:198 offset1:231
	s_waitcnt lgkmcnt(0)
	v_cvt_pk_bf16_f32 v37, v40, v41
	v_or_b32_e32 v40, s0, v5
	s_lshl_b32 s82, s1, 1
	v_mul_u32_u24_e32 v40, 0xb00, v40
	v_lshl_add_u64 v[38:39], v[6:7], 0, s[82:83]
	v_lshlrev_b32_e32 v144, 1, v40
	v_lshl_add_u64 v[40:41], v[38:39], 0, v[144:145]
	global_store_dwordx4 v[40:41], v[34:37], off sc1
	ds_read2_b32 v[34:35], v52 offset0:8 offset1:41
	s_waitcnt lgkmcnt(0)
	v_cvt_pk_bf16_f32 v34, v34, v35
	ds_read2_b32 v[36:37], v52 offset0:74 offset1:107
	s_waitcnt lgkmcnt(0)
	v_cvt_pk_bf16_f32 v35, v36, v37
	ds_read2_b32 v[36:37], v52 offset0:140 offset1:173
	s_waitcnt lgkmcnt(0)
	v_cvt_pk_bf16_f32 v36, v36, v37
	ds_read2_b32 v[40:41], v52 offset0:206 offset1:239
	s_waitcnt lgkmcnt(0)
	v_cvt_pk_bf16_f32 v37, v40, v41
	v_or_b32_e32 v40, s0, v53
	v_mul_u32_u24_e32 v40, 0xb00, v40
	v_lshlrev_b32_e32 v144, 1, v40
	v_lshl_add_u64 v[40:41], v[38:39], 0, v[144:145]
	global_store_dwordx4 v[40:41], v[34:37], off sc1
	ds_read2_b32 v[34:35], v52 offset0:16 offset1:49
	s_waitcnt lgkmcnt(0)
	v_cvt_pk_bf16_f32 v34, v34, v35
	ds_read2_b32 v[36:37], v52 offset0:82 offset1:115
	s_waitcnt lgkmcnt(0)
	v_cvt_pk_bf16_f32 v35, v36, v37
	ds_read2_b32 v[36:37], v52 offset0:148 offset1:181
	s_waitcnt lgkmcnt(0)
	v_cvt_pk_bf16_f32 v36, v36, v37
	ds_read2_b32 v[40:41], v52 offset0:214 offset1:247
	s_waitcnt lgkmcnt(0)
	v_cvt_pk_bf16_f32 v37, v40, v41
	v_or_b32_e32 v40, s0, v54
	v_mul_u32_u24_e32 v40, 0xb00, v40
	v_lshlrev_b32_e32 v144, 1, v40
	v_lshl_add_u64 v[40:41], v[38:39], 0, v[144:145]
	global_store_dwordx4 v[40:41], v[34:37], off sc1
	ds_read2_b32 v[34:35], v52 offset0:24 offset1:57
	s_waitcnt lgkmcnt(0)
	v_cvt_pk_bf16_f32 v34, v34, v35
	ds_read2_b32 v[36:37], v52 offset0:90 offset1:123
	s_waitcnt lgkmcnt(0)
	v_cvt_pk_bf16_f32 v35, v36, v37
	ds_read2_b32 v[36:37], v52 offset0:156 offset1:189
	s_waitcnt lgkmcnt(0)
	v_cvt_pk_bf16_f32 v36, v36, v37
	ds_read2_b32 v[40:41], v52 offset0:222 offset1:255
	s_waitcnt lgkmcnt(0)
	v_cvt_pk_bf16_f32 v37, v40, v41
	v_or_b32_e32 v40, s0, v55
	v_mul_u32_u24_e32 v40, 0xb00, v40
	v_lshlrev_b32_e32 v144, 1, v40
	v_lshl_add_u64 v[38:39], v[38:39], 0, v[144:145]
	global_store_dwordx4 v[38:39], v[34:37], off sc1
	s_waitcnt lgkmcnt(0)

; __device__ __forceinline__ void transpose_item(const float* W, int N, bf16* WT, int K, int k0, int n0, int drow0, const float* gk, LAS float* scr, int lane) {
;     float wv[32];
; #pragma unroll
;     for (int i = 0; i < 32; ++i) wv[i] = W[(size_t)(k0 + 2 * i + (lane >> 5)) * N + n0 + (lane & 31)];
; __device__ __forceinline__ void p0_weight_item(const Args& a, int l, int r, LAS float* scr, int lane) {
;     ...
;         if (r < 2 * IT_BIG) { const int up = r >= IT_BIG; const int it = r - up * IT_BIG; const int kb = it / 88, nb = it % 88, k0 = 64 * kb, n0 = 32 * nb;
;             const float* W = a.in[(f ? 29 : 2) + up] + (size_t)l * DM * FF;
;             transpose_item(W, FF, gu, DM, k0, n0, (n0 >> 7) * 256 + up * 128 + (n0 & 127), nrm + k0, scr, lane); return; }
.LBB0_1143:
	s_andn2_b64 vcc, exec, s[0:1]
	s_cbranch_vccnz .LBB0_1030
	s_cmpk_gt_i32 s39, 0x57f
	s_cselect_b64 s[4:5], -1, 0
	s_and_b64 s[0:1], s[4:5], exec
	v_readlane_b32 s40, v250, 11
	s_cselect_b32 s0, 0xfffffa80, 0
	v_readlane_b32 s44, v250, 15
	v_readlane_b32 s45, v250, 16
	v_readlane_b32 s46, v250, 17
	v_readlane_b32 s47, v250, 18
	s_cselect_b32 s1, s47, s45
	s_cselect_b32 s7, s46, s44
	s_add_i32 s0, s0, s27
	s_addk_i32 s0, 0x2100
	s_mul_hi_i32 s6, s0, 0x2e8ba2e9
	s_lshr_b32 s24, s6, 31
	s_ashr_i32 s6, s6, 4
	s_add_i32 s6, s6, s24
	s_mul_i32 s24, s6, 0x58
	s_sub_i32 s24, s0, s24
	s_lshl_b32 s28, s6, 6
	s_lshl_b32 s6, s24, 5
	s_add_u32 s25, s7, s81
	s_addc_u32 s36, s1, s80
	s_ashr_i32 s29, s28, 31
	s_lshl_b64 s[0:1], s[28:29], 2
	v_readlane_b32 s7, v254, 31
	s_add_u32 s30, s7, s0
	v_readlane_b32 s0, v254, 32
	s_addc_u32 s31, s0, s1
	s_ashr_i32 s7, s6, 31
	s_lshl_b64 s[0:1], s[6:7], 2
	s_add_u32 s0, s25, s0
	s_addc_u32 s1, s36, s1
	v_lshlrev_b32_e32 v144, 2, v2
	v_or_b32_e32 v75, s28, v0
	v_lshl_add_u64 v[50:51], s[0:1], 0, v[144:145]
	v_mad_i64_i32 v[34:35], s[0:1], v75, s85, v[50:51]
	global_load_dword v84, v[34:35], off nt
	v_or_b32_e32 v34, 2, v75
	v_mad_i64_i32 v[34:35], s[0:1], v34, s85, v[50:51]
	global_load_dword v85, v[34:35], off nt
	v_or_b32_e32 v34, 4, v75
	v_mad_i64_i32 v[34:35], s[0:1], v34, s85, v[50:51]
	global_load_dword v48, v[34:35], off nt
	v_or_b32_e32 v34, 6, v75
	v_mad_i64_i32 v[34:35], s[0:1], v34, s85, v[50:51]
	global_load_dword v49, v[34:35], off nt
	v_or_b32_e32 v34, 8, v75
	v_mad_i64_i32 v[34:35], s[0:1], v34, s85, v[50:51]
	global_load_dword v82, v[34:35], off nt
	v_or_b32_e32 v34, 10, v75
	v_mad_i64_i32 v[34:35], s[0:1], v34, s85, v[50:51]
	global_load_dword v83, v[34:35], off nt
	v_or_b32_e32 v34, 12, v75
	v_mad_i64_i32 v[34:35], s[0:1], v34, s85, v[50:51]
	global_load_dword v46, v[34:35], off nt
	v_or_b32_e32 v34, 14, v75
	v_mad_i64_i32 v[34:35], s[0:1], v34, s85, v[50:51]
	global_load_dword v47, v[34:35], off nt
	v_or_b32_e32 v34, 16, v75
	v_mad_i64_i32 v[34:35], s[0:1], v34, s85, v[50:51]
	global_load_dword v80, v[34:35], off nt
	v_or_b32_e32 v34, 18, v75
	v_mad_i64_i32 v[34:35], s[0:1], v34, s85, v[50:51]
	global_load_dword v81, v[34:35], off nt
	v_or_b32_e32 v34, 20, v75
	v_mad_i64_i32 v[34:35], s[0:1], v34, s85, v[50:51]
	global_load_dword v44, v[34:35], off nt
	v_or_b32_e32 v34, 22, v75
	v_mad_i64_i32 v[34:35], s[0:1], v34, s85, v[50:51]
	global_load_dword v45, v[34:35], off nt
	v_or_b32_e32 v34, 24, v75
	v_mad_i64_i32 v[34:35], s[0:1], v34, s85, v[50:51]
	global_load_dword v78, v[34:35], off nt
	v_or_b32_e32 v34, 26, v75
	v_mad_i64_i32 v[34:35], s[0:1], v34, s85, v[50:51]
	global_load_dword v79, v[34:35], off nt
	v_or_b32_e32 v34, 28, v75
	v_mad_i64_i32 v[34:35], s[0:1], v34, s85, v[50:51]
	global_load_dword v42, v[34:35], off nt
	v_or_b32_e32 v34, 30, v75
	v_mad_i64_i32 v[34:35], s[0:1], v34, s85, v[50:51]
	global_load_dword v43, v[34:35], off nt
	v_or_b32_e32 v34, 32, v75
	v_mad_i64_i32 v[34:35], s[0:1], v34, s85, v[50:51]
	global_load_dword v76, v[34:35], off nt
	v_or_b32_e32 v34, 34, v75
	v_mad_i64_i32 v[34:35], s[0:1], v34, s85, v[50:51]
	global_load_dword v77, v[34:35], off nt
	v_or_b32_e32 v34, 36, v75
	v_mad_i64_i32 v[34:35], s[0:1], v34, s85, v[50:51]
	global_load_dword v40, v[34:35], off nt
	v_or_b32_e32 v34, 38, v75
	v_mad_i64_i32 v[34:35], s[0:1], v34, s85, v[50:51]
	global_load_dword v41, v[34:35], off nt
	v_or_b32_e32 v34, 40, v75
	v_mad_i64_i32 v[34:35], s[0:1], v34, s85, v[50:51]
	global_load_dword v73, v[34:35], off nt
	v_or_b32_e32 v34, 42, v75
	v_mad_i64_i32 v[34:35], s[0:1], v34, s85, v[50:51]
	global_load_dword v74, v[34:35], off nt
	v_or_b32_e32 v34, 44, v75
	v_mad_i64_i32 v[34:35], s[0:1], v34, s85, v[50:51]
	global_load_dword v38, v[34:35], off nt
	v_or_b32_e32 v34, 46, v75
	v_mad_i64_i32 v[34:35], s[0:1], v34, s85, v[50:51]
	global_load_dword v39, v[34:35], off nt
	v_or_b32_e32 v34, 48, v75
	v_mad_i64_i32 v[34:35], s[0:1], v34, s85, v[50:51]
	global_load_dword v71, v[34:35], off nt
	v_or_b32_e32 v34, 50, v75
	v_mad_i64_i32 v[34:35], s[0:1], v34, s85, v[50:51]
	global_load_dword v72, v[34:35], off nt
	v_or_b32_e32 v34, 52, v75
	v_mad_i64_i32 v[34:35], s[0:1], v34, s85, v[50:51]
	global_load_dword v36, v[34:35], off nt
	v_or_b32_e32 v34, 54, v75
	v_mad_i64_i32 v[34:35], s[0:1], v34, s85, v[50:51]
	global_load_dword v37, v[34:35], off nt
	v_or_b32_e32 v34, 56, v75
	v_mad_i64_i32 v[34:35], s[0:1], v34, s85, v[50:51]
	global_load_dword v69, v[34:35], off nt
	v_or_b32_e32 v34, 58, v75
	v_mad_i64_i32 v[34:35], s[0:1], v34, s85, v[50:51]
	global_load_dword v70, v[34:35], off nt
	v_or_b32_e32 v34, 60, v75
	v_mad_i64_i32 v[34:35], s[0:1], v34, s85, v[50:51]
	global_load_dword v34, v[34:35], off nt
	v_or_b32_e32 v35, 62, v75
	v_mad_i64_i32 v[50:51], s[0:1], v35, s85, v[50:51]
	global_load_dword v35, v[50:51], off nt
	v_cndmask_b32_e64 v50, 0, 1, s[90:91]
	v_cmp_ne_u32_e64 s[36:37], 1, v50
	s_andn2_b64 vcc, exec, s[90:91]
	v_add_u32_e32 v86, v1, v56
	v_lshlrev_b32_e32 v75, 2, v0
	v_readlane_b32 s41, v250, 12
	v_readlane_b32 s42, v250, 13
	v_readlane_b32 s43, v250, 14
	v_readlane_b32 s48, v250, 19
	v_readlane_b32 s49, v250, 20
	v_readlane_b32 s50, v250, 21
	v_readlane_b32 s51, v250, 22
	v_readlane_b32 s52, v250, 23
	v_readlane_b32 s53, v250, 24
	v_readlane_b32 s54, v250, 25
	v_readlane_b32 s55, v250, 26
	s_cbranch_vccnz .LBB0_1167
; __device__ __forceinline__ void transpose_item(const float* W, int N, bf16* WT, int K, int k0, int n0, int drow0, const float* gk, LAS float* scr, int lane) {
;     ...
;     for (int i = 0; i < 32; ++i) wv[i] = W[(size_t)(k0 + 2 * i + (lane >> 5)) * N + n0 + (lane & 31)];
; #pragma unroll
;     for (int i = 0; i < 32; ++i) { const int kk = 2 * i + (lane >> 5); float v = wv[i]; if (gk) v *= gk[kk]; scr[kk * 33 + (lane & 31)] = v; }
	s_waitcnt vmcnt(32)
	global_load_dword v204, v75, s[30:31]
	global_load_dword v205, v75, s[30:31] offset:8
	global_load_dword v206, v75, s[30:31] offset:16
	global_load_dword v207, v75, s[30:31] offset:24
	global_load_dword v208, v75, s[30:31] offset:32
	global_load_dword v209, v75, s[30:31] offset:40
	global_load_dword v210, v75, s[30:31] offset:48
	global_load_dword v211, v75, s[30:31] offset:56
	global_load_dword v212, v75, s[30:31] offset:64
	global_load_dword v213, v75, s[30:31] offset:72
	global_load_dword v214, v75, s[30:31] offset:80
	global_load_dword v215, v75, s[30:31] offset:88
	global_load_dword v216, v75, s[30:31] offset:96
	global_load_dword v217, v75, s[30:31] offset:104
	global_load_dword v218, v75, s[30:31] offset:112
	global_load_dword v219, v75, s[30:31] offset:120
	global_load_dword v220, v75, s[30:31] offset:128
	global_load_dword v221, v75, s[30:31] offset:136
	global_load_dword v222, v75, s[30:31] offset:144
	global_load_dword v223, v75, s[30:31] offset:152
	global_load_dword v224, v75, s[30:31] offset:160
	global_load_dword v225, v75, s[30:31] offset:168
	global_load_dword v226, v75, s[30:31] offset:176
	global_load_dword v227, v75, s[30:31] offset:184
	global_load_dword v228, v75, s[30:31] offset:192
	global_load_dword v229, v75, s[30:31] offset:200
	global_load_dword v230, v75, s[30:31] offset:208
	global_load_dword v231, v75, s[30:31] offset:216
	global_load_dword v232, v75, s[30:31] offset:224
	global_load_dword v233, v75, s[30:31] offset:232
	global_load_dword v234, v75, s[30:31] offset:240
	s_waitcnt vmcnt(62)
	global_load_dword v235, v75, s[30:31] offset:248
	s_waitcnt vmcnt(0)
	v_mov_b32_e32 v50, v204
	v_mov_b32_e32 v51, v205
	s_waitcnt vmcnt(0)
	v_mul_f32_e32 v50, v84, v50
	v_mul_f32_e32 v51, v85, v51
	ds_write_b32 v3, v50
	ds_write_b32 v86, v51
	v_mov_b32_e32 v50, v206
	v_mov_b32_e32 v51, v207
	s_waitcnt vmcnt(0)
	v_pk_mul_f32 v[50:51], v[48:49], v[50:51]
	s_cbranch_execnz .LBB0_1147

; #define LAS __attribute__((address_space(3)))
; __device__ __forceinline__ unsigned pk2(float lo, float hi) { return pg8::cvt_pk_bf16(lo, hi); }
; __device__ __forceinline__ void lds_wait() { asm volatile("s_waitcnt lgkmcnt(0)" ::: "memory"); }
; __device__ __forceinline__ void transpose_item(const float* W, int N, bf16* WT, int K, int k0, int n0, int drow0, const float* gk, LAS float* scr, int lane) {
;     float wv[32];
; #pragma unroll
;     for (int i = 0; i < 32; ++i) wv[i] = W[(size_t)(k0 + 2 * i + (lane >> 5)) * N + n0 + (lane & 31)];
; #pragma unroll
;     for (int i = 0; i < 32; ++i) { const int kk = 2 * i + (lane >> 5); float v = wv[i]; if (gk) v *= gk[kk]; scr[kk * 33 + (lane & 31)] = v; }
;     lds_wait();
;     const int c = lane & 7;
; #pragma unroll
;     for (int j = 0; j < 4; ++j) { const int n = (lane >> 3) + 8 * j; const LAS float* s = scr + (8 * c) * 33 + n;
;         u32x4 o; o.x = pk2(s[0 * 33], s[1 * 33]); o.y = pk2(s[2 * 33], s[3 * 33]); o.z = pk2(s[4 * 33], s[5 * 33]); o.w = pk2(s[6 * 33], s[7 * 33]);
;         *(u32x4*)(WT + (size_t)(drow0 + n) * K + k0 + 8 * c) = o; }
; __device__ __forceinline__ void p0_weight_item(const Args& a, int l, int r, LAS float* scr, int lane) {
;     ...
;     if (r < IT_GLU) { const int kb = r / 8, nb = r % 8; transpose_item(a.in[15] + (size_t)l * 65536, 256, (bf16*)(wl + WL_GLU), 256, 64 * kb, 32 * nb, 32 * nb, nullptr, scr, lane); return; }
;     r -= IT_GLU;
;     if (r < IT_LW) { const int blk = r >> 1, nb = r & 1; transpose_item(a.in[21] + (size_t)l * 16384 + blk * 4096, 64, (bf16*)(wl + WL_WA) + blk * 4096, 64, 0, 32 * nb, 32 * nb, nullptr, scr, lane); return; }
;     r -= IT_LW;
;     { const int blk = r >> 1, nb = r & 1; transpose_item(a.in[23] + (size_t)l * 16384 + blk * 4096, 64, (bf16*)(wl + WL_WX) + blk * 4096, 64, 0, 32 * nb, 32 * nb, nullptr, scr, lane); }
.LBB0_1662:
	s_add_i32 s39, s27, 0x2100
	s_cmpk_gt_i32 s39, 0xaff
	s_mov_b64 s[0:1], -1
	s_cbranch_scc0 .LBB0_1774
	s_cmpk_gt_u32 s39, 0x107f
	s_cbranch_scc0 .LBB0_1771
	s_cmpk_gt_u32 s39, 0x1b7f
	s_cbranch_scc0 .LBB0_1744
	s_add_i32 s0, s27, 0x1080
	s_cmpk_lt_u32 s0, 0x1080
	s_mov_b64 s[0:1], -1
	s_cbranch_scc1 .LBB0_1741
	s_cmpk_gt_u32 s39, 0x267f
	s_cbranch_scc0 .LBB0_1712
	s_cmpk_gt_u32 s27, 0x77f
	s_cbranch_scc0 .LBB0_1677
	s_cmpk_gt_u32 s27, 0x79f
	s_cbranch_scc0 .LBB0_1674
	s_add_i32 s0, s35, 0xfffb6000
	s_and_b32 s4, s0, 32
	s_cmpk_gt_u32 s27, 0x7a7
	s_mov_b64 s[0:1], -1
	v_lshlrev_b32_e32 v34, 2, v4
	v_or_b32_e32 v39, s4, v5
	v_or_b32_e32 v38, s4, v53
	v_or_b32_e32 v37, s4, v54
	v_or_b32_e32 v36, s4, v55
	s_cbranch_scc0 .LBB0_1671
	s_and_b32 s0, s34, 0x7ffff000
	s_add_i32 s82, s0, 0xffc2c000
	s_lshl_b64 s[0:1], s[82:83], 2
	v_readlane_b32 s5, v253, 55
	s_add_u32 s0, s5, s0
	v_readlane_b32 s5, v253, 56
	s_addc_u32 s1, s5, s1
	s_lshl_b32 s5, s4, 2
	s_add_u32 s0, s0, s5
	s_addc_u32 s1, s1, 0
	v_lshlrev_b32_e32 v144, 2, v2
	v_lshl_add_u64 v[40:41], s[0:1], 0, v[144:145]
	v_mov_b32_e32 v35, v145
	v_lshl_add_u64 v[40:41], v[40:41], 0, v[34:35]
	s_movk_i32 s0, 0x1000
	global_load_dword v35, v[40:41], off nt
	global_load_dword v46, v[40:41], off offset:512 nt
	global_load_dword v47, v[40:41], off offset:1024 nt
	global_load_dword v48, v[40:41], off offset:1536 nt
	global_load_dword v49, v[40:41], off offset:2048 nt
	global_load_dword v50, v[40:41], off offset:2560 nt
	global_load_dword v51, v[40:41], off offset:3072 nt
	global_load_dword v69, v[40:41], off offset:3584 nt
	v_add_co_u32_e32 v42, vcc, s0, v40
	s_movk_i32 s0, 0x2000
	s_nop 0
	v_addc_co_u32_e32 v43, vcc, 0, v41, vcc
	v_add_co_u32_e32 v44, vcc, s0, v40
	s_movk_i32 s0, 0x3000
	s_nop 0
	v_addc_co_u32_e32 v45, vcc, 0, v41, vcc
	global_load_dword v70, v[44:45], off offset:-4096 nt
	global_load_dword v71, v[42:43], off offset:512 nt
	global_load_dword v72, v[42:43], off offset:1024 nt
	global_load_dword v73, v[42:43], off offset:1536 nt
	global_load_dword v74, v[42:43], off offset:2048 nt
	global_load_dword v75, v[42:43], off offset:2560 nt
	global_load_dword v76, v[42:43], off offset:3072 nt
	s_nop 0
	global_load_dword v42, v[42:43], off offset:3584 nt
	s_nop 0
	global_load_dword v43, v[44:45], off nt
	global_load_dword v77, v[44:45], off offset:512 nt
	global_load_dword v78, v[44:45], off offset:1024 nt
	global_load_dword v79, v[44:45], off offset:1536 nt
	global_load_dword v80, v[44:45], off offset:2048 nt
	global_load_dword v81, v[44:45], off offset:2560 nt
	global_load_dword v82, v[44:45], off offset:3072 nt
	s_nop 0
	global_load_dword v44, v[44:45], off offset:3584 nt
	v_add_co_u32_e32 v40, vcc, s0, v40
	v_lshlrev_b32_e32 v144, 7, v39
	s_nop 0
	v_addc_co_u32_e32 v41, vcc, 0, v41, vcc
	global_load_dword v45, v[40:41], off nt
	global_load_dword v83, v[40:41], off offset:512 nt
	global_load_dword v84, v[40:41], off offset:1024 nt
	global_load_dword v85, v[40:41], off offset:1536 nt
	global_load_dword v86, v[40:41], off offset:2048 nt
	global_load_dword v87, v[40:41], off offset:2560 nt
	global_load_dword v88, v[40:41], off offset:3072 nt
	s_nop 0
	global_load_dword v40, v[40:41], off offset:3584 nt
	s_mov_b64 s[0:1], 0
	s_waitcnt vmcnt(0)
	ds_write2_b32 v3, v35, v46 offset1:66
	ds_write2_b32 v3, v47, v48 offset0:132 offset1:198
	v_add_u32_e32 v35, 0x400, v3
	ds_write2_b32 v35, v49, v50 offset0:8 offset1:74
	ds_write2_b32 v35, v51, v69 offset0:140 offset1:206
	v_add_u32_e32 v35, 0x800, v3
	ds_write2_b32 v35, v70, v71 offset0:16 offset1:82
	ds_write2_b32 v35, v72, v73 offset0:148 offset1:214
	v_add_u32_e32 v35, 0xc00, v3
	ds_write2_b32 v35, v74, v75 offset0:24 offset1:90
	ds_write2_b32 v35, v76, v42 offset0:156 offset1:222
	v_add_u32_e32 v35, 0x1000, v3
	ds_write2_b32 v35, v43, v77 offset0:32 offset1:98
	ds_write2_b32 v35, v78, v79 offset0:164 offset1:230
	v_add_u32_e32 v35, 0x1400, v3
	ds_write2_b32 v35, v80, v81 offset0:40 offset1:106
	ds_write2_b32 v35, v82, v44 offset0:172 offset1:238
	v_add_u32_e32 v35, 0x1800, v3
	ds_write2_b32 v35, v45, v83 offset0:48 offset1:114
	ds_write2_b32 v35, v84, v85 offset0:180 offset1:246
	v_add_u32_e32 v35, 0x1c00, v3
	ds_write2_b32 v35, v86, v87 offset0:56 offset1:122
	ds_write2_b32 v35, v88, v40 offset0:188 offset1:254
	s_waitcnt lgkmcnt(0)
	ds_read2_b32 v[40:41], v52 offset1:33
	s_waitcnt lgkmcnt(0)
	v_cvt_pk_bf16_f32 v40, v40, v41
	ds_read2_b32 v[42:43], v52 offset0:66 offset1:99
	s_waitcnt lgkmcnt(0)
	v_cvt_pk_bf16_f32 v41, v42, v43
	ds_read2_b32 v[42:43], v52 offset0:132 offset1:165
	v_lshl_add_u64 v[44:45], s[82:83], 1, v[10:11]
	s_waitcnt lgkmcnt(0)
	v_cvt_pk_bf16_f32 v42, v42, v43
	ds_read2_b32 v[46:47], v52 offset0:198 offset1:231
	s_waitcnt lgkmcnt(0)
	v_cvt_pk_bf16_f32 v43, v46, v47
	v_lshl_add_u64 v[46:47], v[44:45], 0, v[144:145]
	global_store_dwordx4 v[46:47], v[40:43], off sc1
	ds_read2_b32 v[40:41], v52 offset0:8 offset1:41
	v_lshlrev_b32_e32 v144, 7, v38
	s_waitcnt lgkmcnt(0)
	v_cvt_pk_bf16_f32 v40, v40, v41
	ds_read2_b32 v[42:43], v52 offset0:74 offset1:107
	s_waitcnt lgkmcnt(0)
	v_cvt_pk_bf16_f32 v41, v42, v43
	ds_read2_b32 v[42:43], v52 offset0:140 offset1:173
	s_waitcnt lgkmcnt(0)
	v_cvt_pk_bf16_f32 v42, v42, v43
	ds_read2_b32 v[46:47], v52 offset0:206 offset1:239
	s_waitcnt lgkmcnt(0)
	v_cvt_pk_bf16_f32 v43, v46, v47
	v_lshl_add_u64 v[46:47], v[44:45], 0, v[144:145]
	global_store_dwordx4 v[46:47], v[40:43], off sc1
	ds_read2_b32 v[40:41], v52 offset0:16 offset1:49
	v_lshlrev_b32_e32 v144, 7, v37
	s_waitcnt lgkmcnt(0)
	v_cvt_pk_bf16_f32 v40, v40, v41
	ds_read2_b32 v[42:43], v52 offset0:82 offset1:115
	s_waitcnt lgkmcnt(0)
	v_cvt_pk_bf16_f32 v41, v42, v43
	ds_read2_b32 v[42:43], v52 offset0:148 offset1:181
	s_waitcnt lgkmcnt(0)
	v_cvt_pk_bf16_f32 v42, v42, v43
	ds_read2_b32 v[46:47], v52 offset0:214 offset1:247
	s_waitcnt lgkmcnt(0)
	v_cvt_pk_bf16_f32 v43, v46, v47
	v_lshl_add_u64 v[46:47], v[44:45], 0, v[144:145]
	global_store_dwordx4 v[46:47], v[40:43], off sc1
	ds_read2_b32 v[40:41], v52 offset0:24 offset1:57
	v_lshlrev_b32_e32 v144, 7, v36
	s_waitcnt lgkmcnt(0)
	v_cvt_pk_bf16_f32 v40, v40, v41
	ds_read2_b32 v[42:43], v52 offset0:90 offset1:123
	s_waitcnt lgkmcnt(0)
	v_cvt_pk_bf16_f32 v41, v42, v43
	ds_read2_b32 v[42:43], v52 offset0:156 offset1:189
	v_lshl_add_u64 v[44:45], v[44:45], 0, v[144:145]
	s_waitcnt lgkmcnt(0)
	v_cvt_pk_bf16_f32 v42, v42, v43
	ds_read2_b32 v[46:47], v52 offset0:222 offset1:255
	s_waitcnt lgkmcnt(0)
	v_cvt_pk_bf16_f32 v43, v46, v47
	global_store_dwordx4 v[44:45], v[40:43], off sc1
	s_waitcnt lgkmcnt(0)

; __device__ __forceinline__ void transpose_item(const float* W, int N, bf16* WT, int K, int k0, int n0, int drow0, const float* gk, LAS float* scr, int lane) {
;     float wv[32];
; #pragma unroll
;     for (int i = 0; i < 32; ++i) wv[i] = W[(size_t)(k0 + 2 * i + (lane >> 5)) * N + n0 + (lane & 31)];
; __device__ __forceinline__ void p0_weight_item(const Args& a, int l, int r, LAS float* scr, int lane) {
;     ...
;     if (r < IT_GLU) { const int kb = r / 8, nb = r % 8; transpose_item(a.in[15] + (size_t)l * 65536, 256, (bf16*)(wl + WL_GLU), 256, 64 * kb, 32 * nb, 32 * nb, nullptr, scr, lane); return; }
;     r -= IT_GLU;
;     if (r < IT_LW) { const int blk = r >> 1, nb = r & 1; transpose_item(a.in[21] + (size_t)l * 16384 + blk * 4096, 64, (bf16*)(wl + WL_WA) + blk * 4096, 64, 0, 32 * nb, 32 * nb, nullptr, scr, lane); return; }
.LBB0_1674:
	s_andn2_b64 vcc, exec, s[0:1]
	s_cbranch_vccnz .LBB0_1676
	s_and_b32 s0, s38, 0x3fc0
	s_add_i32 s1, s35, 0xfffb6000
	s_addk_i32 s0, 0xc400
	s_and_b32 s4, s1, 0xe0
	v_or_b32_e32 v144, s0, v0
	s_lshl_b32 s82, s4, 2
	v_lshl_add_u64 v[34:35], v[14:15], 0, s[82:83]
	v_lshlrev_b64 v[36:37], 10, v[144:145]
	v_lshl_add_u64 v[36:37], v[34:35], 0, v[36:37]
	global_load_dword v38, v[36:37], off nt
	v_or_b32_e32 v36, 2, v144
	v_mov_b32_e32 v37, v145
	v_lshlrev_b64 v[36:37], 10, v[36:37]
	v_lshl_add_u64 v[36:37], v[34:35], 0, v[36:37]
	global_load_dword v39, v[36:37], off nt
	v_or_b32_e32 v36, 4, v144
	v_mov_b32_e32 v37, v145
	v_lshlrev_b64 v[36:37], 10, v[36:37]
	v_lshl_add_u64 v[36:37], v[34:35], 0, v[36:37]
	global_load_dword v40, v[36:37], off nt
	v_or_b32_e32 v36, 6, v144
	v_mov_b32_e32 v37, v145
	v_lshlrev_b64 v[36:37], 10, v[36:37]
	v_lshl_add_u64 v[36:37], v[34:35], 0, v[36:37]
	global_load_dword v41, v[36:37], off nt
	v_or_b32_e32 v36, 8, v144
	v_mov_b32_e32 v37, v145
	v_lshlrev_b64 v[36:37], 10, v[36:37]
	v_lshl_add_u64 v[36:37], v[34:35], 0, v[36:37]
	global_load_dword v42, v[36:37], off nt
	v_or_b32_e32 v36, 10, v144
	v_mov_b32_e32 v37, v145
	v_lshlrev_b64 v[36:37], 10, v[36:37]
	v_lshl_add_u64 v[36:37], v[34:35], 0, v[36:37]
	global_load_dword v43, v[36:37], off nt
	v_or_b32_e32 v36, 12, v144
	v_mov_b32_e32 v37, v145
	v_lshlrev_b64 v[36:37], 10, v[36:37]
	v_lshl_add_u64 v[36:37], v[34:35], 0, v[36:37]
	global_load_dword v44, v[36:37], off nt
	v_or_b32_e32 v36, 14, v144
	v_mov_b32_e32 v37, v145
	v_lshlrev_b64 v[36:37], 10, v[36:37]
	v_lshl_add_u64 v[36:37], v[34:35], 0, v[36:37]
	global_load_dword v45, v[36:37], off nt
	v_or_b32_e32 v36, 16, v144
	v_mov_b32_e32 v37, v145
	v_lshlrev_b64 v[36:37], 10, v[36:37]
	v_lshl_add_u64 v[36:37], v[34:35], 0, v[36:37]
	global_load_dword v46, v[36:37], off nt
	v_or_b32_e32 v36, 18, v144
	v_mov_b32_e32 v37, v145
	v_lshlrev_b64 v[36:37], 10, v[36:37]
	v_lshl_add_u64 v[36:37], v[34:35], 0, v[36:37]
	global_load_dword v47, v[36:37], off nt
	v_or_b32_e32 v36, 20, v144
	v_mov_b32_e32 v37, v145
	v_lshlrev_b64 v[36:37], 10, v[36:37]
	v_lshl_add_u64 v[36:37], v[34:35], 0, v[36:37]
	global_load_dword v48, v[36:37], off nt
	v_or_b32_e32 v36, 22, v144
	v_mov_b32_e32 v37, v145
	v_lshlrev_b64 v[36:37], 10, v[36:37]
	v_lshl_add_u64 v[36:37], v[34:35], 0, v[36:37]
	global_load_dword v49, v[36:37], off nt
	v_or_b32_e32 v36, 24, v144
	v_mov_b32_e32 v37, v145
	v_lshlrev_b64 v[36:37], 10, v[36:37]
	v_lshl_add_u64 v[36:37], v[34:35], 0, v[36:37]
	global_load_dword v50, v[36:37], off nt
	v_or_b32_e32 v36, 26, v144
	v_mov_b32_e32 v37, v145
	v_lshlrev_b64 v[36:37], 10, v[36:37]
	v_lshl_add_u64 v[36:37], v[34:35], 0, v[36:37]
	global_load_dword v51, v[36:37], off nt
	v_or_b32_e32 v36, 28, v144
	v_mov_b32_e32 v37, v145
	v_lshlrev_b64 v[36:37], 10, v[36:37]
	v_lshl_add_u64 v[36:37], v[34:35], 0, v[36:37]
	global_load_dword v69, v[36:37], off nt
	v_or_b32_e32 v36, 30, v144
	v_mov_b32_e32 v37, v145
	v_lshlrev_b64 v[36:37], 10, v[36:37]
	v_lshl_add_u64 v[36:37], v[34:35], 0, v[36:37]
	global_load_dword v70, v[36:37], off nt
	v_or_b32_e32 v36, 32, v144
	v_mov_b32_e32 v37, v145
	v_lshlrev_b64 v[36:37], 10, v[36:37]
	v_lshl_add_u64 v[36:37], v[34:35], 0, v[36:37]
	global_load_dword v71, v[36:37], off nt
	v_or_b32_e32 v36, 34, v144
	v_mov_b32_e32 v37, v145
	v_lshlrev_b64 v[36:37], 10, v[36:37]
	v_lshl_add_u64 v[36:37], v[34:35], 0, v[36:37]
	global_load_dword v72, v[36:37], off nt
	v_or_b32_e32 v36, 36, v144
	v_mov_b32_e32 v37, v145
	v_lshlrev_b64 v[36:37], 10, v[36:37]
	v_lshl_add_u64 v[36:37], v[34:35], 0, v[36:37]
	global_load_dword v73, v[36:37], off nt
	v_or_b32_e32 v36, 38, v144
	v_mov_b32_e32 v37, v145
	v_lshlrev_b64 v[36:37], 10, v[36:37]
	v_lshl_add_u64 v[36:37], v[34:35], 0, v[36:37]
	global_load_dword v74, v[36:37], off nt
	v_or_b32_e32 v36, 40, v144
	v_mov_b32_e32 v37, v145
	v_lshlrev_b64 v[36:37], 10, v[36:37]
	v_lshl_add_u64 v[36:37], v[34:35], 0, v[36:37]
	global_load_dword v75, v[36:37], off nt
	v_or_b32_e32 v36, 42, v144
	v_mov_b32_e32 v37, v145
	v_lshlrev_b64 v[36:37], 10, v[36:37]
	v_lshl_add_u64 v[36:37], v[34:35], 0, v[36:37]
	global_load_dword v76, v[36:37], off nt
	v_or_b32_e32 v36, 44, v144
	v_mov_b32_e32 v37, v145
	v_lshlrev_b64 v[36:37], 10, v[36:37]
	v_lshl_add_u64 v[36:37], v[34:35], 0, v[36:37]
	global_load_dword v77, v[36:37], off nt
	v_or_b32_e32 v36, 46, v144
	v_mov_b32_e32 v37, v145
	v_lshlrev_b64 v[36:37], 10, v[36:37]
	v_lshl_add_u64 v[36:37], v[34:35], 0, v[36:37]
	global_load_dword v78, v[36:37], off nt
	v_or_b32_e32 v36, 48, v144
	v_mov_b32_e32 v37, v145
	v_lshlrev_b64 v[36:37], 10, v[36:37]
	v_lshl_add_u64 v[36:37], v[34:35], 0, v[36:37]
	global_load_dword v79, v[36:37], off nt
	v_or_b32_e32 v36, 50, v144
	v_mov_b32_e32 v37, v145
	v_lshlrev_b64 v[36:37], 10, v[36:37]
	v_lshl_add_u64 v[36:37], v[34:35], 0, v[36:37]
	global_load_dword v80, v[36:37], off nt
	v_or_b32_e32 v36, 52, v144
	v_mov_b32_e32 v37, v145
	v_lshlrev_b64 v[36:37], 10, v[36:37]
	v_lshl_add_u64 v[36:37], v[34:35], 0, v[36:37]
	global_load_dword v81, v[36:37], off nt
	v_or_b32_e32 v36, 54, v144
	v_mov_b32_e32 v37, v145
	v_lshlrev_b64 v[36:37], 10, v[36:37]
	v_lshl_add_u64 v[36:37], v[34:35], 0, v[36:37]
	global_load_dword v82, v[36:37], off nt
	v_or_b32_e32 v36, 56, v144
	v_mov_b32_e32 v37, v145
	v_lshlrev_b64 v[36:37], 10, v[36:37]
	v_lshl_add_u64 v[36:37], v[34:35], 0, v[36:37]
	global_load_dword v83, v[36:37], off nt
	v_or_b32_e32 v36, 58, v144
	v_mov_b32_e32 v37, v145
	v_lshlrev_b64 v[36:37], 10, v[36:37]
	v_lshl_add_u64 v[36:37], v[34:35], 0, v[36:37]
	global_load_dword v84, v[36:37], off nt
	v_or_b32_e32 v36, 60, v144
	v_mov_b32_e32 v37, v145
	v_lshlrev_b64 v[36:37], 10, v[36:37]
	v_lshl_add_u64 v[36:37], v[34:35], 0, v[36:37]
	v_or_b32_e32 v144, 62, v144
	global_load_dword v85, v[36:37], off nt
	v_lshlrev_b64 v[36:37], 10, v[144:145]
	v_lshl_add_u64 v[34:35], v[34:35], 0, v[36:37]
	global_load_dword v34, v[34:35], off nt
	v_add_u32_e32 v35, 0x400, v3
	s_waitcnt vmcnt(0)
; #define LAS __attribute__((address_space(3)))
; __device__ __forceinline__ unsigned pk2(float lo, float hi) { return pg8::cvt_pk_bf16(lo, hi); }
; __device__ __forceinline__ void lds_wait() { asm volatile("s_waitcnt lgkmcnt(0)" ::: "memory"); }
; __device__ __forceinline__ void transpose_item(const float* W, int N, bf16* WT, int K, int k0, int n0, int drow0, const float* gk, LAS float* scr, int lane) {
;     ...
;     for (int i = 0; i < 32; ++i) { const int kk = 2 * i + (lane >> 5); float v = wv[i]; if (gk) v *= gk[kk]; scr[kk * 33 + (lane & 31)] = v; }
;     lds_wait();
;     const int c = lane & 7;
; #pragma unroll
;     for (int j = 0; j < 4; ++j) { const int n = (lane >> 3) + 8 * j; const LAS float* s = scr + (8 * c) * 33 + n;
;         u32x4 o; o.x = pk2(s[0 * 33], s[1 * 33]); o.y = pk2(s[2 * 33], s[3 * 33]); o.z = pk2(s[4 * 33], s[5 * 33]); o.w = pk2(s[6 * 33], s[7 * 33]);
;         *(u32x4*)(WT + (size_t)(drow0 + n) * K + k0 + 8 * c) = o; }
	ds_write2_b32 v3, v38, v39 offset1:66
	ds_write2_b32 v3, v40, v41 offset0:132 offset1:198
	ds_write2_b32 v35, v42, v43 offset0:8 offset1:74
	ds_write2_b32 v35, v44, v45 offset0:140 offset1:206
	v_add_u32_e32 v35, 0x800, v3
	ds_write2_b32 v35, v46, v47 offset0:16 offset1:82
	ds_write2_b32 v35, v48, v49 offset0:148 offset1:214
	v_add_u32_e32 v35, 0xc00, v3
	ds_write2_b32 v35, v50, v51 offset0:24 offset1:90
	ds_write2_b32 v35, v69, v70 offset0:156 offset1:222
	v_add_u32_e32 v35, 0x1000, v3
	ds_write2_b32 v35, v71, v72 offset0:32 offset1:98
	ds_write2_b32 v35, v73, v74 offset0:164 offset1:230
	v_add_u32_e32 v35, 0x1400, v3
	ds_write2_b32 v35, v75, v76 offset0:40 offset1:106
	ds_write2_b32 v35, v77, v78 offset0:172 offset1:238
	v_add_u32_e32 v35, 0x1800, v3
	ds_write2_b32 v35, v79, v80 offset0:48 offset1:114
	ds_write2_b32 v35, v81, v82 offset0:180 offset1:246
	v_add_u32_e32 v35, 0x1c00, v3
	ds_write2_b32 v35, v83, v84 offset0:56 offset1:122
	ds_write2_b32 v35, v85, v34 offset0:188 offset1:254
	s_waitcnt lgkmcnt(0)
	ds_read2_b32 v[34:35], v52 offset1:33
	s_waitcnt lgkmcnt(0)
	v_cvt_pk_bf16_f32 v34, v34, v35
	ds_read2_b32 v[36:37], v52 offset0:66 offset1:99
	s_waitcnt lgkmcnt(0)
	v_cvt_pk_bf16_f32 v35, v36, v37
	ds_read2_b32 v[36:37], v52 offset0:132 offset1:165
	s_waitcnt lgkmcnt(0)
	v_cvt_pk_bf16_f32 v36, v36, v37
	ds_read2_b32 v[40:41], v52 offset0:198 offset1:231
	s_mov_b32 s1, s83
	s_waitcnt lgkmcnt(0)
	v_cvt_pk_bf16_f32 v37, v40, v41
	v_or_b32_e32 v40, s4, v5
	v_lshl_add_u64 v[38:39], s[0:1], 1, v[16:17]
	v_lshlrev_b32_e32 v144, 9, v40
	v_lshl_add_u64 v[40:41], v[38:39], 0, v[144:145]
	global_store_dwordx4 v[40:41], v[34:37], off sc1
	ds_read2_b32 v[34:35], v52 offset0:8 offset1:41
	s_waitcnt lgkmcnt(0)
	v_cvt_pk_bf16_f32 v34, v34, v35
	ds_read2_b32 v[36:37], v52 offset0:74 offset1:107
	s_waitcnt lgkmcnt(0)
	v_cvt_pk_bf16_f32 v35, v36, v37
	ds_read2_b32 v[36:37], v52 offset0:140 offset1:173
	s_waitcnt lgkmcnt(0)
	v_cvt_pk_bf16_f32 v36, v36, v37
	ds_read2_b32 v[40:41], v52 offset0:206 offset1:239
	s_waitcnt lgkmcnt(0)
	v_cvt_pk_bf16_f32 v37, v40, v41
	v_or_b32_e32 v40, s4, v53
	v_lshlrev_b32_e32 v144, 9, v40
	v_lshl_add_u64 v[40:41], v[38:39], 0, v[144:145]
	global_store_dwordx4 v[40:41], v[34:37], off sc1
	ds_read2_b32 v[34:35], v52 offset0:16 offset1:49
	s_waitcnt lgkmcnt(0)
	v_cvt_pk_bf16_f32 v34, v34, v35
	ds_read2_b32 v[36:37], v52 offset0:82 offset1:115
	s_waitcnt lgkmcnt(0)
	v_cvt_pk_bf16_f32 v35, v36, v37
	ds_read2_b32 v[36:37], v52 offset0:148 offset1:181
	s_waitcnt lgkmcnt(0)
	v_cvt_pk_bf16_f32 v36, v36, v37
	ds_read2_b32 v[40:41], v52 offset0:214 offset1:247
	s_waitcnt lgkmcnt(0)
	v_cvt_pk_bf16_f32 v37, v40, v41
	v_or_b32_e32 v40, s4, v54
	v_lshlrev_b32_e32 v144, 9, v40
	v_lshl_add_u64 v[40:41], v[38:39], 0, v[144:145]
	global_store_dwordx4 v[40:41], v[34:37], off sc1
	ds_read2_b32 v[34:35], v52 offset0:24 offset1:57
	s_waitcnt lgkmcnt(0)
	v_cvt_pk_bf16_f32 v34, v34, v35
	ds_read2_b32 v[36:37], v52 offset0:90 offset1:123
	s_waitcnt lgkmcnt(0)
	v_cvt_pk_bf16_f32 v35, v36, v37
	ds_read2_b32 v[36:37], v52 offset0:156 offset1:189
	s_waitcnt lgkmcnt(0)
	v_cvt_pk_bf16_f32 v36, v36, v37
	ds_read2_b32 v[40:41], v52 offset0:222 offset1:255
	s_waitcnt lgkmcnt(0)
	v_cvt_pk_bf16_f32 v37, v40, v41
	v_or_b32_e32 v40, s4, v55
	v_lshlrev_b32_e32 v144, 9, v40
	v_lshl_add_u64 v[38:39], v[38:39], 0, v[144:145]
	global_store_dwordx4 v[38:39], v[34:37], off sc1
	s_waitcnt lgkmcnt(0)

; __device__ __forceinline__ void transpose_item(const float* W, int N, bf16* WT, int K, int k0, int n0, int drow0, const float* gk, LAS float* scr, int lane) {
;     float wv[32];
; #pragma unroll
;     for (int i = 0; i < 32; ++i) wv[i] = W[(size_t)(k0 + 2 * i + (lane >> 5)) * N + n0 + (lane & 31)];
; __device__ __forceinline__ void p0_weight_item(const Args& a, int l, int r, LAS float* scr, int lane) {
;     ...
;     if (r < IT_OUT) {
;         const int kb = r / 32, nb = r % 32, k0 = 64 * kb;
;         const float* gk = (k0 < 256) ? a.in[17] + (size_t)l * 256 + k0 : (k0 < 768 ? a.in[18] + (size_t)l * 512 + (k0 - 256) : a.in[26] + (size_t)l * 256 + (k0 - 768));
;         transpose_item(a.in[27] + (size_t)l * DM * DM, DM, (bf16*)(wl + WL_WOUT), DM, k0, 32 * nb, 32 * nb, gk, scr, lane); return; }
.LBB0_1686:
	s_add_i32 s0, s35, 0xfffb6000
	s_and_b32 s28, s0, 0x3e0
	v_or_b32_e32 v144, s4, v0
	s_lshl_b32 s82, s28, 2
	v_lshl_add_u64 v[50:51], v[18:19], 0, s[82:83]
	v_lshlrev_b64 v[34:35], 12, v[144:145]
	v_lshl_add_u64 v[34:35], v[50:51], 0, v[34:35]
	global_load_dword v83, v[34:35], off nt
	v_or_b32_e32 v34, 2, v144
	v_mov_b32_e32 v35, v145
	v_lshlrev_b64 v[34:35], 12, v[34:35]
	v_lshl_add_u64 v[34:35], v[50:51], 0, v[34:35]
	global_load_dword v84, v[34:35], off nt
	v_or_b32_e32 v34, 4, v144
	v_mov_b32_e32 v35, v145
	v_lshlrev_b64 v[34:35], 12, v[34:35]
	v_lshl_add_u64 v[34:35], v[50:51], 0, v[34:35]
	global_load_dword v48, v[34:35], off nt
	v_or_b32_e32 v34, 6, v144
	v_mov_b32_e32 v35, v145
	v_lshlrev_b64 v[34:35], 12, v[34:35]
	v_lshl_add_u64 v[34:35], v[50:51], 0, v[34:35]
	global_load_dword v49, v[34:35], off nt
	v_or_b32_e32 v34, 8, v144
	v_mov_b32_e32 v35, v145
	v_lshlrev_b64 v[34:35], 12, v[34:35]
	v_lshl_add_u64 v[34:35], v[50:51], 0, v[34:35]
	global_load_dword v81, v[34:35], off nt
	v_or_b32_e32 v34, 10, v144
	v_mov_b32_e32 v35, v145
	v_lshlrev_b64 v[34:35], 12, v[34:35]
	v_lshl_add_u64 v[34:35], v[50:51], 0, v[34:35]
	global_load_dword v82, v[34:35], off nt
	v_or_b32_e32 v34, 12, v144
	v_mov_b32_e32 v35, v145
	v_lshlrev_b64 v[34:35], 12, v[34:35]
	v_lshl_add_u64 v[34:35], v[50:51], 0, v[34:35]
	global_load_dword v46, v[34:35], off nt
	v_or_b32_e32 v34, 14, v144
	v_mov_b32_e32 v35, v145
	v_lshlrev_b64 v[34:35], 12, v[34:35]
	v_lshl_add_u64 v[34:35], v[50:51], 0, v[34:35]
	global_load_dword v47, v[34:35], off nt
	v_or_b32_e32 v34, 16, v144
	v_mov_b32_e32 v35, v145
	v_lshlrev_b64 v[34:35], 12, v[34:35]
	v_lshl_add_u64 v[34:35], v[50:51], 0, v[34:35]
	global_load_dword v79, v[34:35], off nt
	v_or_b32_e32 v34, 18, v144
	v_mov_b32_e32 v35, v145
	v_lshlrev_b64 v[34:35], 12, v[34:35]
	v_lshl_add_u64 v[34:35], v[50:51], 0, v[34:35]
	global_load_dword v80, v[34:35], off nt
	v_or_b32_e32 v34, 20, v144
	v_mov_b32_e32 v35, v145
	v_lshlrev_b64 v[34:35], 12, v[34:35]
	v_lshl_add_u64 v[34:35], v[50:51], 0, v[34:35]
	global_load_dword v44, v[34:35], off nt
	v_or_b32_e32 v34, 22, v144
	v_mov_b32_e32 v35, v145
	v_lshlrev_b64 v[34:35], 12, v[34:35]
	v_lshl_add_u64 v[34:35], v[50:51], 0, v[34:35]
	global_load_dword v45, v[34:35], off nt
	v_or_b32_e32 v34, 24, v144
	v_mov_b32_e32 v35, v145
	v_lshlrev_b64 v[34:35], 12, v[34:35]
	v_lshl_add_u64 v[34:35], v[50:51], 0, v[34:35]
	global_load_dword v77, v[34:35], off nt
	v_or_b32_e32 v34, 26, v144
	v_mov_b32_e32 v35, v145
	v_lshlrev_b64 v[34:35], 12, v[34:35]
	v_lshl_add_u64 v[34:35], v[50:51], 0, v[34:35]
	global_load_dword v78, v[34:35], off nt
	v_or_b32_e32 v34, 28, v144
	v_mov_b32_e32 v35, v145
	v_lshlrev_b64 v[34:35], 12, v[34:35]
	v_lshl_add_u64 v[34:35], v[50:51], 0, v[34:35]
	global_load_dword v42, v[34:35], off nt
	v_or_b32_e32 v34, 30, v144
	v_mov_b32_e32 v35, v145
	v_lshlrev_b64 v[34:35], 12, v[34:35]
	v_lshl_add_u64 v[34:35], v[50:51], 0, v[34:35]
	global_load_dword v43, v[34:35], off nt
	v_or_b32_e32 v34, 32, v144
	v_mov_b32_e32 v35, v145
	v_lshlrev_b64 v[34:35], 12, v[34:35]
	v_lshl_add_u64 v[34:35], v[50:51], 0, v[34:35]
	global_load_dword v75, v[34:35], off nt
	v_or_b32_e32 v34, 34, v144
	v_mov_b32_e32 v35, v145
	v_lshlrev_b64 v[34:35], 12, v[34:35]
	v_lshl_add_u64 v[34:35], v[50:51], 0, v[34:35]
	global_load_dword v76, v[34:35], off nt
	v_or_b32_e32 v34, 36, v144
	v_mov_b32_e32 v35, v145
	v_lshlrev_b64 v[34:35], 12, v[34:35]
	v_lshl_add_u64 v[34:35], v[50:51], 0, v[34:35]
	global_load_dword v40, v[34:35], off nt
	v_or_b32_e32 v34, 38, v144
	v_mov_b32_e32 v35, v145
	v_lshlrev_b64 v[34:35], 12, v[34:35]
	v_lshl_add_u64 v[34:35], v[50:51], 0, v[34:35]
	global_load_dword v41, v[34:35], off nt
	v_or_b32_e32 v34, 40, v144
	v_mov_b32_e32 v35, v145
	v_lshlrev_b64 v[34:35], 12, v[34:35]
	v_lshl_add_u64 v[34:35], v[50:51], 0, v[34:35]
	global_load_dword v73, v[34:35], off nt
	v_or_b32_e32 v34, 42, v144
	v_mov_b32_e32 v35, v145
	v_lshlrev_b64 v[34:35], 12, v[34:35]
	v_lshl_add_u64 v[34:35], v[50:51], 0, v[34:35]
	global_load_dword v74, v[34:35], off nt
	v_or_b32_e32 v34, 44, v144
	v_mov_b32_e32 v35, v145
	v_lshlrev_b64 v[34:35], 12, v[34:35]
	v_lshl_add_u64 v[34:35], v[50:51], 0, v[34:35]
	global_load_dword v38, v[34:35], off nt
	v_or_b32_e32 v34, 46, v144
	v_mov_b32_e32 v35, v145
	v_lshlrev_b64 v[34:35], 12, v[34:35]
	v_lshl_add_u64 v[34:35], v[50:51], 0, v[34:35]
	global_load_dword v39, v[34:35], off nt
	v_or_b32_e32 v34, 48, v144
	v_mov_b32_e32 v35, v145
	v_lshlrev_b64 v[34:35], 12, v[34:35]
	v_lshl_add_u64 v[34:35], v[50:51], 0, v[34:35]
	global_load_dword v71, v[34:35], off nt
	v_or_b32_e32 v34, 50, v144
	v_mov_b32_e32 v35, v145
	v_lshlrev_b64 v[34:35], 12, v[34:35]
	v_lshl_add_u64 v[34:35], v[50:51], 0, v[34:35]
	global_load_dword v72, v[34:35], off nt
	v_or_b32_e32 v34, 52, v144
	v_mov_b32_e32 v35, v145
	v_lshlrev_b64 v[34:35], 12, v[34:35]
	v_lshl_add_u64 v[34:35], v[50:51], 0, v[34:35]
	global_load_dword v36, v[34:35], off nt
	v_or_b32_e32 v34, 54, v144
	v_mov_b32_e32 v35, v145
	v_lshlrev_b64 v[34:35], 12, v[34:35]
	v_lshl_add_u64 v[34:35], v[50:51], 0, v[34:35]
	global_load_dword v37, v[34:35], off nt
	v_or_b32_e32 v34, 56, v144
	v_mov_b32_e32 v35, v145
	v_lshlrev_b64 v[34:35], 12, v[34:35]
	v_lshl_add_u64 v[34:35], v[50:51], 0, v[34:35]
	global_load_dword v69, v[34:35], off nt
	v_or_b32_e32 v34, 58, v144
	v_mov_b32_e32 v35, v145
	v_lshlrev_b64 v[34:35], 12, v[34:35]
	v_lshl_add_u64 v[34:35], v[50:51], 0, v[34:35]
	global_load_dword v70, v[34:35], off nt
	v_or_b32_e32 v34, 60, v144
	v_mov_b32_e32 v35, v145
	v_or_b32_e32 v144, 62, v144
	v_lshlrev_b64 v[34:35], 12, v[34:35]
	v_lshlrev_b64 v[86:87], 12, v[144:145]
	v_lshl_add_u64 v[34:35], v[50:51], 0, v[34:35]
	v_lshl_add_u64 v[50:51], v[50:51], 0, v[86:87]
	global_load_dword v34, v[34:35], off nt
	s_cmp_lg_u64 s[6:7], 0
	global_load_dword v35, v[50:51], off nt
	s_cselect_b64 s[0:1], -1, 0
	s_cmp_eq_u64 s[6:7], 0
	s_cbranch_scc1 .LBB0_1822
; __device__ __forceinline__ void transpose_item(const float* W, int N, bf16* WT, int K, int k0, int n0, int drow0, const float* gk, LAS float* scr, int lane) {
;     ...
;     for (int i = 0; i < 32; ++i) wv[i] = W[(size_t)(k0 + 2 * i + (lane >> 5)) * N + n0 + (lane & 31)];
; #pragma unroll
;     for (int i = 0; i < 32; ++i) { const int kk = 2 * i + (lane >> 5); float v = wv[i]; if (gk) v *= gk[kk]; scr[kk * 33 + (lane & 31)] = v; }
	v_lshlrev_b32_e32 v51, 2, v0
	s_waitcnt vmcnt(32)
	global_load_dword v204, v51, s[6:7]
	global_load_dword v205, v51, s[6:7] offset:8
	global_load_dword v206, v51, s[6:7] offset:16
	global_load_dword v207, v51, s[6:7] offset:24
	global_load_dword v208, v51, s[6:7] offset:32
	global_load_dword v209, v51, s[6:7] offset:40
	global_load_dword v210, v51, s[6:7] offset:48
	global_load_dword v211, v51, s[6:7] offset:56
	global_load_dword v212, v51, s[6:7] offset:64
	global_load_dword v213, v51, s[6:7] offset:72
	global_load_dword v214, v51, s[6:7] offset:80
	global_load_dword v215, v51, s[6:7] offset:88
	global_load_dword v216, v51, s[6:7] offset:96
	global_load_dword v217, v51, s[6:7] offset:104
	global_load_dword v218, v51, s[6:7] offset:112
	global_load_dword v219, v51, s[6:7] offset:120
	global_load_dword v220, v51, s[6:7] offset:128
	global_load_dword v221, v51, s[6:7] offset:136
	global_load_dword v222, v51, s[6:7] offset:144
	global_load_dword v223, v51, s[6:7] offset:152
	global_load_dword v224, v51, s[6:7] offset:160
	global_load_dword v225, v51, s[6:7] offset:168
	global_load_dword v226, v51, s[6:7] offset:176
	global_load_dword v227, v51, s[6:7] offset:184
	global_load_dword v228, v51, s[6:7] offset:192
	global_load_dword v229, v51, s[6:7] offset:200
	global_load_dword v230, v51, s[6:7] offset:208
	global_load_dword v231, v51, s[6:7] offset:216
	global_load_dword v232, v51, s[6:7] offset:224
	global_load_dword v233, v51, s[6:7] offset:232
	global_load_dword v234, v51, s[6:7] offset:240
	s_waitcnt vmcnt(62)
	global_load_dword v235, v51, s[6:7] offset:248
	s_waitcnt vmcnt(0)
	v_mov_b32_e32 v50, v204
	v_mov_b32_e32 v85, v205
	s_waitcnt vmcnt(0)
	v_mul_f32_e32 v50, v83, v50
	v_mul_f32_e32 v85, v84, v85
	ds_write_b32 v3, v50
	v_add_u32_e32 v50, v1, v56
	ds_write_b32 v50, v85
	v_mov_b32_e32 v50, v206
	s_nop 0
	v_mov_b32_e32 v51, v207
	s_waitcnt vmcnt(0)
	v_pk_mul_f32 v[50:51], v[48:49], v[50:51]
	s_cbranch_execnz .LBB0_1689

; __device__ __forceinline__ void transpose_item(const float* W, int N, bf16* WT, int K, int k0, int n0, int drow0, const float* gk, LAS float* scr, int lane) {
;     float wv[32];
; #pragma unroll
;     for (int i = 0; i < 32; ++i) wv[i] = W[(size_t)(k0 + 2 * i + (lane >> 5)) * N + n0 + (lane & 31)];
; __device__ __forceinline__ void p0_weight_item(const Args& a, int l, int r, LAS float* scr, int lane) {
;     ...
;         if (r < IT_BIG) { const int kb = r / 32, nb = r % 32; const float* W = a.in[f ? 31 : 4] + (size_t)l * FF * DM;
;             transpose_item(W, DM, dn, FF, 64 * kb, 32 * nb, 32 * nb, nullptr, scr, lane); return; }
.LBB0_1741:
	s_andn2_b64 vcc, exec, s[0:1]
	s_cbranch_vccnz .LBB0_1743
	s_add_i32 s0, s35, 0xfffd7000
	s_and_b32 s1, s26, 0x7fffffc0
	s_and_b32 s0, s0, 0x3e0
	v_or_b32_e32 v144, s1, v0
	s_lshl_b32 s82, s0, 2
	v_lshl_add_u64 v[34:35], v[26:27], 0, s[82:83]
	v_lshlrev_b64 v[36:37], 12, v[144:145]
	v_lshl_add_u64 v[36:37], v[34:35], 0, v[36:37]
	global_load_dword v38, v[36:37], off nt
	v_or_b32_e32 v36, 2, v144
	v_mov_b32_e32 v37, v145
	v_lshlrev_b64 v[36:37], 12, v[36:37]
	v_lshl_add_u64 v[36:37], v[34:35], 0, v[36:37]
	global_load_dword v39, v[36:37], off nt
	v_or_b32_e32 v36, 4, v144
	v_mov_b32_e32 v37, v145
	v_lshlrev_b64 v[36:37], 12, v[36:37]
	v_lshl_add_u64 v[36:37], v[34:35], 0, v[36:37]
	global_load_dword v40, v[36:37], off nt
	v_or_b32_e32 v36, 6, v144
	v_mov_b32_e32 v37, v145
	v_lshlrev_b64 v[36:37], 12, v[36:37]
	v_lshl_add_u64 v[36:37], v[34:35], 0, v[36:37]
	global_load_dword v41, v[36:37], off nt
	v_or_b32_e32 v36, 8, v144
	v_mov_b32_e32 v37, v145
	v_lshlrev_b64 v[36:37], 12, v[36:37]
	v_lshl_add_u64 v[36:37], v[34:35], 0, v[36:37]
	global_load_dword v42, v[36:37], off nt
	v_or_b32_e32 v36, 10, v144
	v_mov_b32_e32 v37, v145
	v_lshlrev_b64 v[36:37], 12, v[36:37]
	v_lshl_add_u64 v[36:37], v[34:35], 0, v[36:37]
	global_load_dword v43, v[36:37], off nt
	v_or_b32_e32 v36, 12, v144
	v_mov_b32_e32 v37, v145
	v_lshlrev_b64 v[36:37], 12, v[36:37]
	v_lshl_add_u64 v[36:37], v[34:35], 0, v[36:37]
	global_load_dword v44, v[36:37], off nt
	v_or_b32_e32 v36, 14, v144
	v_mov_b32_e32 v37, v145
	v_lshlrev_b64 v[36:37], 12, v[36:37]
	v_lshl_add_u64 v[36:37], v[34:35], 0, v[36:37]
	global_load_dword v45, v[36:37], off nt
	v_or_b32_e32 v36, 16, v144
	v_mov_b32_e32 v37, v145
	v_lshlrev_b64 v[36:37], 12, v[36:37]
	v_lshl_add_u64 v[36:37], v[34:35], 0, v[36:37]
	global_load_dword v46, v[36:37], off nt
	v_or_b32_e32 v36, 18, v144
	v_mov_b32_e32 v37, v145
	v_lshlrev_b64 v[36:37], 12, v[36:37]
	v_lshl_add_u64 v[36:37], v[34:35], 0, v[36:37]
	global_load_dword v47, v[36:37], off nt
	v_or_b32_e32 v36, 20, v144
	v_mov_b32_e32 v37, v145
	v_lshlrev_b64 v[36:37], 12, v[36:37]
	v_lshl_add_u64 v[36:37], v[34:35], 0, v[36:37]
	global_load_dword v48, v[36:37], off nt
	v_or_b32_e32 v36, 22, v144
	v_mov_b32_e32 v37, v145
	v_lshlrev_b64 v[36:37], 12, v[36:37]
	v_lshl_add_u64 v[36:37], v[34:35], 0, v[36:37]
	global_load_dword v49, v[36:37], off nt
	v_or_b32_e32 v36, 24, v144
	v_mov_b32_e32 v37, v145
	v_lshlrev_b64 v[36:37], 12, v[36:37]
	v_lshl_add_u64 v[36:37], v[34:35], 0, v[36:37]
	global_load_dword v50, v[36:37], off nt
	v_or_b32_e32 v36, 26, v144
	v_mov_b32_e32 v37, v145
	v_lshlrev_b64 v[36:37], 12, v[36:37]
	v_lshl_add_u64 v[36:37], v[34:35], 0, v[36:37]
	global_load_dword v51, v[36:37], off nt
	v_or_b32_e32 v36, 28, v144
	v_mov_b32_e32 v37, v145
	v_lshlrev_b64 v[36:37], 12, v[36:37]
	v_lshl_add_u64 v[36:37], v[34:35], 0, v[36:37]
	global_load_dword v69, v[36:37], off nt
	v_or_b32_e32 v36, 30, v144
	v_mov_b32_e32 v37, v145
	v_lshlrev_b64 v[36:37], 12, v[36:37]
	v_lshl_add_u64 v[36:37], v[34:35], 0, v[36:37]
	global_load_dword v70, v[36:37], off nt
	v_or_b32_e32 v36, 32, v144
	v_mov_b32_e32 v37, v145
	v_lshlrev_b64 v[36:37], 12, v[36:37]
	v_lshl_add_u64 v[36:37], v[34:35], 0, v[36:37]
	global_load_dword v71, v[36:37], off nt
	v_or_b32_e32 v36, 34, v144
	v_mov_b32_e32 v37, v145
	v_lshlrev_b64 v[36:37], 12, v[36:37]
	v_lshl_add_u64 v[36:37], v[34:35], 0, v[36:37]
	global_load_dword v72, v[36:37], off nt
	v_or_b32_e32 v36, 36, v144
	v_mov_b32_e32 v37, v145
	v_lshlrev_b64 v[36:37], 12, v[36:37]
	v_lshl_add_u64 v[36:37], v[34:35], 0, v[36:37]
	global_load_dword v73, v[36:37], off nt
	v_or_b32_e32 v36, 38, v144
	v_mov_b32_e32 v37, v145
	v_lshlrev_b64 v[36:37], 12, v[36:37]
	v_lshl_add_u64 v[36:37], v[34:35], 0, v[36:37]
	global_load_dword v74, v[36:37], off nt
	v_or_b32_e32 v36, 40, v144
	v_mov_b32_e32 v37, v145
	v_lshlrev_b64 v[36:37], 12, v[36:37]
	v_lshl_add_u64 v[36:37], v[34:35], 0, v[36:37]
	global_load_dword v75, v[36:37], off nt
	v_or_b32_e32 v36, 42, v144
	v_mov_b32_e32 v37, v145
	v_lshlrev_b64 v[36:37], 12, v[36:37]
	v_lshl_add_u64 v[36:37], v[34:35], 0, v[36:37]
	global_load_dword v76, v[36:37], off nt
	v_or_b32_e32 v36, 44, v144
	v_mov_b32_e32 v37, v145
	v_lshlrev_b64 v[36:37], 12, v[36:37]
	v_lshl_add_u64 v[36:37], v[34:35], 0, v[36:37]
	global_load_dword v77, v[36:37], off nt
	v_or_b32_e32 v36, 46, v144
	v_mov_b32_e32 v37, v145
	v_lshlrev_b64 v[36:37], 12, v[36:37]
	v_lshl_add_u64 v[36:37], v[34:35], 0, v[36:37]
	global_load_dword v78, v[36:37], off nt
	v_or_b32_e32 v36, 48, v144
	v_mov_b32_e32 v37, v145
	v_lshlrev_b64 v[36:37], 12, v[36:37]
	v_lshl_add_u64 v[36:37], v[34:35], 0, v[36:37]
	global_load_dword v79, v[36:37], off nt
	v_or_b32_e32 v36, 50, v144
	v_mov_b32_e32 v37, v145
	v_lshlrev_b64 v[36:37], 12, v[36:37]
	v_lshl_add_u64 v[36:37], v[34:35], 0, v[36:37]
	global_load_dword v80, v[36:37], off nt
	v_or_b32_e32 v36, 52, v144
	v_mov_b32_e32 v37, v145
	v_lshlrev_b64 v[36:37], 12, v[36:37]
	v_lshl_add_u64 v[36:37], v[34:35], 0, v[36:37]
	global_load_dword v81, v[36:37], off nt
	v_or_b32_e32 v36, 54, v144
	v_mov_b32_e32 v37, v145
	v_lshlrev_b64 v[36:37], 12, v[36:37]
	v_lshl_add_u64 v[36:37], v[34:35], 0, v[36:37]
	global_load_dword v82, v[36:37], off nt
	v_or_b32_e32 v36, 56, v144
	v_mov_b32_e32 v37, v145
	v_lshlrev_b64 v[36:37], 12, v[36:37]
	v_lshl_add_u64 v[36:37], v[34:35], 0, v[36:37]
	global_load_dword v83, v[36:37], off nt
	v_or_b32_e32 v36, 58, v144
	v_mov_b32_e32 v37, v145
	v_lshlrev_b64 v[36:37], 12, v[36:37]
	v_lshl_add_u64 v[36:37], v[34:35], 0, v[36:37]
	global_load_dword v84, v[36:37], off nt
	v_or_b32_e32 v36, 60, v144
	v_mov_b32_e32 v37, v145
	v_lshlrev_b64 v[36:37], 12, v[36:37]
	v_lshl_add_u64 v[36:37], v[34:35], 0, v[36:37]
	v_or_b32_e32 v144, 62, v144
	global_load_dword v85, v[36:37], off nt
	v_lshlrev_b64 v[36:37], 12, v[144:145]
	v_lshl_add_u64 v[34:35], v[34:35], 0, v[36:37]
	global_load_dword v34, v[34:35], off nt
	v_add_u32_e32 v35, 0x400, v3
	s_waitcnt vmcnt(0)
; #define LAS __attribute__((address_space(3)))
; __device__ __forceinline__ unsigned pk2(float lo, float hi) { return pg8::cvt_pk_bf16(lo, hi); }
; __device__ __forceinline__ void lds_wait() { asm volatile("s_waitcnt lgkmcnt(0)" ::: "memory"); }
; __device__ __forceinline__ void transpose_item(const float* W, int N, bf16* WT, int K, int k0, int n0, int drow0, const float* gk, LAS float* scr, int lane) {
;     ...
;     for (int i = 0; i < 32; ++i) { const int kk = 2 * i + (lane >> 5); float v = wv[i]; if (gk) v *= gk[kk]; scr[kk * 33 + (lane & 31)] = v; }
;     lds_wait();
;     const int c = lane & 7;
; #pragma unroll
;     for (int j = 0; j < 4; ++j) { const int n = (lane >> 3) + 8 * j; const LAS float* s = scr + (8 * c) * 33 + n;
;         u32x4 o; o.x = pk2(s[0 * 33], s[1 * 33]); o.y = pk2(s[2 * 33], s[3 * 33]); o.z = pk2(s[4 * 33], s[5 * 33]); o.w = pk2(s[6 * 33], s[7 * 33]);
;         *(u32x4*)(WT + (size_t)(drow0 + n) * K + k0 + 8 * c) = o; }
	ds_write2_b32 v3, v38, v39 offset1:66
	ds_write2_b32 v3, v40, v41 offset0:132 offset1:198
	ds_write2_b32 v35, v42, v43 offset0:8 offset1:74
	ds_write2_b32 v35, v44, v45 offset0:140 offset1:206
	v_add_u32_e32 v35, 0x800, v3
	ds_write2_b32 v35, v46, v47 offset0:16 offset1:82
	ds_write2_b32 v35, v48, v49 offset0:148 offset1:214
	v_add_u32_e32 v35, 0xc00, v3
	ds_write2_b32 v35, v50, v51 offset0:24 offset1:90
	ds_write2_b32 v35, v69, v70 offset0:156 offset1:222
	v_add_u32_e32 v35, 0x1000, v3
	ds_write2_b32 v35, v71, v72 offset0:32 offset1:98
	ds_write2_b32 v35, v73, v74 offset0:164 offset1:230
	v_add_u32_e32 v35, 0x1400, v3
	ds_write2_b32 v35, v75, v76 offset0:40 offset1:106
	ds_write2_b32 v35, v77, v78 offset0:172 offset1:238
	v_add_u32_e32 v35, 0x1800, v3
	ds_write2_b32 v35, v79, v80 offset0:48 offset1:114
	ds_write2_b32 v35, v81, v82 offset0:180 offset1:246
	v_add_u32_e32 v35, 0x1c00, v3
	ds_write2_b32 v35, v83, v84 offset0:56 offset1:122
	ds_write2_b32 v35, v85, v34 offset0:188 offset1:254
	s_waitcnt lgkmcnt(0)
	ds_read2_b32 v[34:35], v52 offset1:33
	s_waitcnt lgkmcnt(0)
	v_cvt_pk_bf16_f32 v34, v34, v35
	ds_read2_b32 v[36:37], v52 offset0:66 offset1:99
	s_waitcnt lgkmcnt(0)
	v_cvt_pk_bf16_f32 v35, v36, v37
	ds_read2_b32 v[36:37], v52 offset0:132 offset1:165
	s_waitcnt lgkmcnt(0)
	v_cvt_pk_bf16_f32 v36, v36, v37
	ds_read2_b32 v[40:41], v52 offset0:198 offset1:231
	s_waitcnt lgkmcnt(0)
	v_cvt_pk_bf16_f32 v37, v40, v41
	v_or_b32_e32 v40, s0, v5
	s_lshl_b32 s82, s1, 1
	v_mul_u32_u24_e32 v40, 0xb00, v40
	v_lshl_add_u64 v[38:39], v[28:29], 0, s[82:83]
	v_lshlrev_b32_e32 v144, 1, v40
	v_lshl_add_u64 v[40:41], v[38:39], 0, v[144:145]
	global_store_dwordx4 v[40:41], v[34:37], off sc1
	ds_read2_b32 v[34:35], v52 offset0:8 offset1:41
	s_waitcnt lgkmcnt(0)
	v_cvt_pk_bf16_f32 v34, v34, v35
	ds_read2_b32 v[36:37], v52 offset0:74 offset1:107
	s_waitcnt lgkmcnt(0)
	v_cvt_pk_bf16_f32 v35, v36, v37
	ds_read2_b32 v[36:37], v52 offset0:140 offset1:173
	s_waitcnt lgkmcnt(0)
	v_cvt_pk_bf16_f32 v36, v36, v37
	ds_read2_b32 v[40:41], v52 offset0:206 offset1:239
	s_waitcnt lgkmcnt(0)
	v_cvt_pk_bf16_f32 v37, v40, v41
	v_or_b32_e32 v40, s0, v53
	v_mul_u32_u24_e32 v40, 0xb00, v40
	v_lshlrev_b32_e32 v144, 1, v40
	v_lshl_add_u64 v[40:41], v[38:39], 0, v[144:145]
	global_store_dwordx4 v[40:41], v[34:37], off sc1
	ds_read2_b32 v[34:35], v52 offset0:16 offset1:49
	s_waitcnt lgkmcnt(0)
	v_cvt_pk_bf16_f32 v34, v34, v35
	ds_read2_b32 v[36:37], v52 offset0:82 offset1:115
	s_waitcnt lgkmcnt(0)
	v_cvt_pk_bf16_f32 v35, v36, v37
	ds_read2_b32 v[36:37], v52 offset0:148 offset1:181
	s_waitcnt lgkmcnt(0)
	v_cvt_pk_bf16_f32 v36, v36, v37
	ds_read2_b32 v[40:41], v52 offset0:214 offset1:247
	s_waitcnt lgkmcnt(0)
	v_cvt_pk_bf16_f32 v37, v40, v41
	v_or_b32_e32 v40, s0, v54
	v_mul_u32_u24_e32 v40, 0xb00, v40
	v_lshlrev_b32_e32 v144, 1, v40
	v_lshl_add_u64 v[40:41], v[38:39], 0, v[144:145]
	global_store_dwordx4 v[40:41], v[34:37], off sc1
	ds_read2_b32 v[34:35], v52 offset0:24 offset1:57
	s_waitcnt lgkmcnt(0)
	v_cvt_pk_bf16_f32 v34, v34, v35
	ds_read2_b32 v[36:37], v52 offset0:90 offset1:123
	s_waitcnt lgkmcnt(0)
	v_cvt_pk_bf16_f32 v35, v36, v37
	ds_read2_b32 v[36:37], v52 offset0:156 offset1:189
	s_waitcnt lgkmcnt(0)
	v_cvt_pk_bf16_f32 v36, v36, v37
	ds_read2_b32 v[40:41], v52 offset0:222 offset1:255
	s_waitcnt lgkmcnt(0)
	v_cvt_pk_bf16_f32 v37, v40, v41
	v_or_b32_e32 v40, s0, v55
	v_mul_u32_u24_e32 v40, 0xb00, v40
	v_lshlrev_b32_e32 v144, 1, v40
	v_lshl_add_u64 v[38:39], v[38:39], 0, v[144:145]
	global_store_dwordx4 v[38:39], v[34:37], off sc1
	s_waitcnt lgkmcnt(0)

; __device__ __forceinline__ void transpose_item(const float* W, int N, bf16* WT, int K, int k0, int n0, int drow0, const float* gk, LAS float* scr, int lane) {
;     float wv[32];
; #pragma unroll
;     for (int i = 0; i < 32; ++i) wv[i] = W[(size_t)(k0 + 2 * i + (lane >> 5)) * N + n0 + (lane & 31)];
; __device__ __forceinline__ void p0_weight_item(const Args& a, int l, int r, LAS float* scr, int lane) {
;     ...
;         if (r < IT_BIG) { const int kb = r / 32, nb = r % 32; const float* W = a.in[f ? 31 : 4] + (size_t)l * FF * DM;
;             transpose_item(W, DM, dn, FF, 64 * kb, 32 * nb, 32 * nb, nullptr, scr, lane); return; }
.LBB0_1771:
	s_andn2_b64 vcc, exec, s[0:1]
	s_cbranch_vccnz .LBB0_1773
	s_add_i32 s0, s26, 0x2100
	s_and_b32 s1, s0, 0x7fffffc0
	s_add_i32 s0, s35, 0xffff8000
	s_and_b32 s0, s0, 0x3e0
	v_or_b32_e32 v144, s1, v0
	s_lshl_b32 s82, s0, 2
	v_lshl_add_u64 v[34:35], v[32:33], 0, s[82:83]
	v_lshlrev_b64 v[36:37], 12, v[144:145]
	v_lshl_add_u64 v[36:37], v[34:35], 0, v[36:37]
	global_load_dword v38, v[36:37], off nt
	v_or_b32_e32 v36, 2, v144
	v_mov_b32_e32 v37, v145
	v_lshlrev_b64 v[36:37], 12, v[36:37]
	v_lshl_add_u64 v[36:37], v[34:35], 0, v[36:37]
	global_load_dword v39, v[36:37], off nt
	v_or_b32_e32 v36, 4, v144
	v_mov_b32_e32 v37, v145
	v_lshlrev_b64 v[36:37], 12, v[36:37]
	v_lshl_add_u64 v[36:37], v[34:35], 0, v[36:37]
	global_load_dword v40, v[36:37], off nt
	v_or_b32_e32 v36, 6, v144
	v_mov_b32_e32 v37, v145
	v_lshlrev_b64 v[36:37], 12, v[36:37]
	v_lshl_add_u64 v[36:37], v[34:35], 0, v[36:37]
	global_load_dword v41, v[36:37], off nt
	v_or_b32_e32 v36, 8, v144
	v_mov_b32_e32 v37, v145
	v_lshlrev_b64 v[36:37], 12, v[36:37]
	v_lshl_add_u64 v[36:37], v[34:35], 0, v[36:37]
	global_load_dword v42, v[36:37], off nt
	v_or_b32_e32 v36, 10, v144
	v_mov_b32_e32 v37, v145
	v_lshlrev_b64 v[36:37], 12, v[36:37]
	v_lshl_add_u64 v[36:37], v[34:35], 0, v[36:37]
	global_load_dword v43, v[36:37], off nt
	v_or_b32_e32 v36, 12, v144
	v_mov_b32_e32 v37, v145
	v_lshlrev_b64 v[36:37], 12, v[36:37]
	v_lshl_add_u64 v[36:37], v[34:35], 0, v[36:37]
	global_load_dword v44, v[36:37], off nt
	v_or_b32_e32 v36, 14, v144
	v_mov_b32_e32 v37, v145
	v_lshlrev_b64 v[36:37], 12, v[36:37]
	v_lshl_add_u64 v[36:37], v[34:35], 0, v[36:37]
	global_load_dword v45, v[36:37], off nt
	v_or_b32_e32 v36, 16, v144
	v_mov_b32_e32 v37, v145
	v_lshlrev_b64 v[36:37], 12, v[36:37]
	v_lshl_add_u64 v[36:37], v[34:35], 0, v[36:37]
	global_load_dword v46, v[36:37], off nt
	v_or_b32_e32 v36, 18, v144
	v_mov_b32_e32 v37, v145
	v_lshlrev_b64 v[36:37], 12, v[36:37]
	v_lshl_add_u64 v[36:37], v[34:35], 0, v[36:37]
	global_load_dword v47, v[36:37], off nt
	v_or_b32_e32 v36, 20, v144
	v_mov_b32_e32 v37, v145
	v_lshlrev_b64 v[36:37], 12, v[36:37]
	v_lshl_add_u64 v[36:37], v[34:35], 0, v[36:37]
	global_load_dword v48, v[36:37], off nt
	v_or_b32_e32 v36, 22, v144
	v_mov_b32_e32 v37, v145
	v_lshlrev_b64 v[36:37], 12, v[36:37]
	v_lshl_add_u64 v[36:37], v[34:35], 0, v[36:37]
	global_load_dword v49, v[36:37], off nt
	v_or_b32_e32 v36, 24, v144
	v_mov_b32_e32 v37, v145
	v_lshlrev_b64 v[36:37], 12, v[36:37]
	v_lshl_add_u64 v[36:37], v[34:35], 0, v[36:37]
	global_load_dword v50, v[36:37], off nt
	v_or_b32_e32 v36, 26, v144
	v_mov_b32_e32 v37, v145
	v_lshlrev_b64 v[36:37], 12, v[36:37]
	v_lshl_add_u64 v[36:37], v[34:35], 0, v[36:37]
	global_load_dword v51, v[36:37], off nt
	v_or_b32_e32 v36, 28, v144
	v_mov_b32_e32 v37, v145
	v_lshlrev_b64 v[36:37], 12, v[36:37]
	v_lshl_add_u64 v[36:37], v[34:35], 0, v[36:37]
	global_load_dword v69, v[36:37], off nt
	v_or_b32_e32 v36, 30, v144
	v_mov_b32_e32 v37, v145
	v_lshlrev_b64 v[36:37], 12, v[36:37]
	v_lshl_add_u64 v[36:37], v[34:35], 0, v[36:37]
	global_load_dword v70, v[36:37], off nt
	v_or_b32_e32 v36, 32, v144
	v_mov_b32_e32 v37, v145
	v_lshlrev_b64 v[36:37], 12, v[36:37]
	v_lshl_add_u64 v[36:37], v[34:35], 0, v[36:37]
	global_load_dword v71, v[36:37], off nt
	v_or_b32_e32 v36, 34, v144
	v_mov_b32_e32 v37, v145
	v_lshlrev_b64 v[36:37], 12, v[36:37]
	v_lshl_add_u64 v[36:37], v[34:35], 0, v[36:37]
	global_load_dword v72, v[36:37], off nt
	v_or_b32_e32 v36, 36, v144
	v_mov_b32_e32 v37, v145
	v_lshlrev_b64 v[36:37], 12, v[36:37]
	v_lshl_add_u64 v[36:37], v[34:35], 0, v[36:37]
	global_load_dword v73, v[36:37], off nt
	v_or_b32_e32 v36, 38, v144
	v_mov_b32_e32 v37, v145
	v_lshlrev_b64 v[36:37], 12, v[36:37]
	v_lshl_add_u64 v[36:37], v[34:35], 0, v[36:37]
	global_load_dword v74, v[36:37], off nt
	v_or_b32_e32 v36, 40, v144
	v_mov_b32_e32 v37, v145
	v_lshlrev_b64 v[36:37], 12, v[36:37]
	v_lshl_add_u64 v[36:37], v[34:35], 0, v[36:37]
	global_load_dword v75, v[36:37], off nt
	v_or_b32_e32 v36, 42, v144
	v_mov_b32_e32 v37, v145
	v_lshlrev_b64 v[36:37], 12, v[36:37]
	v_lshl_add_u64 v[36:37], v[34:35], 0, v[36:37]
	global_load_dword v76, v[36:37], off nt
	v_or_b32_e32 v36, 44, v144
	v_mov_b32_e32 v37, v145
	v_lshlrev_b64 v[36:37], 12, v[36:37]
	v_lshl_add_u64 v[36:37], v[34:35], 0, v[36:37]
	global_load_dword v77, v[36:37], off nt
	v_or_b32_e32 v36, 46, v144
	v_mov_b32_e32 v37, v145
	v_lshlrev_b64 v[36:37], 12, v[36:37]
	v_lshl_add_u64 v[36:37], v[34:35], 0, v[36:37]
	global_load_dword v78, v[36:37], off nt
	v_or_b32_e32 v36, 48, v144
	v_mov_b32_e32 v37, v145
	v_lshlrev_b64 v[36:37], 12, v[36:37]
	v_lshl_add_u64 v[36:37], v[34:35], 0, v[36:37]
	global_load_dword v79, v[36:37], off nt
	v_or_b32_e32 v36, 50, v144
	v_mov_b32_e32 v37, v145
	v_lshlrev_b64 v[36:37], 12, v[36:37]
	v_lshl_add_u64 v[36:37], v[34:35], 0, v[36:37]
	global_load_dword v80, v[36:37], off nt
	v_or_b32_e32 v36, 52, v144
	v_mov_b32_e32 v37, v145
	v_lshlrev_b64 v[36:37], 12, v[36:37]
	v_lshl_add_u64 v[36:37], v[34:35], 0, v[36:37]
	global_load_dword v81, v[36:37], off nt
	v_or_b32_e32 v36, 54, v144
	v_mov_b32_e32 v37, v145
	v_lshlrev_b64 v[36:37], 12, v[36:37]
	v_lshl_add_u64 v[36:37], v[34:35], 0, v[36:37]
	global_load_dword v82, v[36:37], off nt
	v_or_b32_e32 v36, 56, v144
	v_mov_b32_e32 v37, v145
	v_lshlrev_b64 v[36:37], 12, v[36:37]
	v_lshl_add_u64 v[36:37], v[34:35], 0, v[36:37]
	global_load_dword v83, v[36:37], off nt
	v_or_b32_e32 v36, 58, v144
	v_mov_b32_e32 v37, v145
	v_lshlrev_b64 v[36:37], 12, v[36:37]
	v_lshl_add_u64 v[36:37], v[34:35], 0, v[36:37]
	global_load_dword v84, v[36:37], off nt
	v_or_b32_e32 v36, 60, v144
	v_mov_b32_e32 v37, v145
	v_lshlrev_b64 v[36:37], 12, v[36:37]
	v_lshl_add_u64 v[36:37], v[34:35], 0, v[36:37]
	v_or_b32_e32 v144, 62, v144
	global_load_dword v85, v[36:37], off nt
	v_lshlrev_b64 v[36:37], 12, v[144:145]
	v_lshl_add_u64 v[34:35], v[34:35], 0, v[36:37]
	global_load_dword v34, v[34:35], off nt
	v_add_u32_e32 v35, 0x400, v3
	s_waitcnt vmcnt(0)
; #define LAS __attribute__((address_space(3)))
; __device__ __forceinline__ unsigned pk2(float lo, float hi) { return pg8::cvt_pk_bf16(lo, hi); }
; __device__ __forceinline__ void lds_wait() { asm volatile("s_waitcnt lgkmcnt(0)" ::: "memory"); }
; __device__ __forceinline__ void transpose_item(const float* W, int N, bf16* WT, int K, int k0, int n0, int drow0, const float* gk, LAS float* scr, int lane) {
;     ...
;     for (int i = 0; i < 32; ++i) { const int kk = 2 * i + (lane >> 5); float v = wv[i]; if (gk) v *= gk[kk]; scr[kk * 33 + (lane & 31)] = v; }
;     lds_wait();
;     const int c = lane & 7;
; #pragma unroll
;     for (int j = 0; j < 4; ++j) { const int n = (lane >> 3) + 8 * j; const LAS float* s = scr + (8 * c) * 33 + n;
;         u32x4 o; o.x = pk2(s[0 * 33], s[1 * 33]); o.y = pk2(s[2 * 33], s[3 * 33]); o.z = pk2(s[4 * 33], s[5 * 33]); o.w = pk2(s[6 * 33], s[7 * 33]);
;         *(u32x4*)(WT + (size_t)(drow0 + n) * K + k0 + 8 * c) = o; }
	ds_write2_b32 v3, v38, v39 offset1:66
	ds_write2_b32 v3, v40, v41 offset0:132 offset1:198
	ds_write2_b32 v35, v42, v43 offset0:8 offset1:74
	ds_write2_b32 v35, v44, v45 offset0:140 offset1:206
	v_add_u32_e32 v35, 0x800, v3
	ds_write2_b32 v35, v46, v47 offset0:16 offset1:82
	ds_write2_b32 v35, v48, v49 offset0:148 offset1:214
	v_add_u32_e32 v35, 0xc00, v3
	ds_write2_b32 v35, v50, v51 offset0:24 offset1:90
	ds_write2_b32 v35, v69, v70 offset0:156 offset1:222
	v_add_u32_e32 v35, 0x1000, v3
	ds_write2_b32 v35, v71, v72 offset0:32 offset1:98
	ds_write2_b32 v35, v73, v74 offset0:164 offset1:230
	v_add_u32_e32 v35, 0x1400, v3
	ds_write2_b32 v35, v75, v76 offset0:40 offset1:106
	ds_write2_b32 v35, v77, v78 offset0:172 offset1:238
	v_add_u32_e32 v35, 0x1800, v3
	ds_write2_b32 v35, v79, v80 offset0:48 offset1:114
	ds_write2_b32 v35, v81, v82 offset0:180 offset1:246
	v_add_u32_e32 v35, 0x1c00, v3
	ds_write2_b32 v35, v83, v84 offset0:56 offset1:122
	ds_write2_b32 v35, v85, v34 offset0:188 offset1:254
	s_waitcnt lgkmcnt(0)
	ds_read2_b32 v[34:35], v52 offset1:33
	s_waitcnt lgkmcnt(0)
	v_cvt_pk_bf16_f32 v34, v34, v35
	ds_read2_b32 v[36:37], v52 offset0:66 offset1:99
	s_waitcnt lgkmcnt(0)
	v_cvt_pk_bf16_f32 v35, v36, v37
	ds_read2_b32 v[36:37], v52 offset0:132 offset1:165
	s_waitcnt lgkmcnt(0)
	v_cvt_pk_bf16_f32 v36, v36, v37
	ds_read2_b32 v[40:41], v52 offset0:198 offset1:231
	s_waitcnt lgkmcnt(0)
	v_cvt_pk_bf16_f32 v37, v40, v41
	v_or_b32_e32 v40, s0, v5
	s_lshl_b32 s82, s1, 1
	v_mul_u32_u24_e32 v40, 0xb00, v40
	v_lshl_add_u64 v[38:39], v[6:7], 0, s[82:83]
	v_lshlrev_b32_e32 v144, 1, v40
	v_lshl_add_u64 v[40:41], v[38:39], 0, v[144:145]
	global_store_dwordx4 v[40:41], v[34:37], off sc1
	ds_read2_b32 v[34:35], v52 offset0:8 offset1:41
	s_waitcnt lgkmcnt(0)
	v_cvt_pk_bf16_f32 v34, v34, v35
	ds_read2_b32 v[36:37], v52 offset0:74 offset1:107
	s_waitcnt lgkmcnt(0)
	v_cvt_pk_bf16_f32 v35, v36, v37
	ds_read2_b32 v[36:37], v52 offset0:140 offset1:173
	s_waitcnt lgkmcnt(0)
	v_cvt_pk_bf16_f32 v36, v36, v37
	ds_read2_b32 v[40:41], v52 offset0:206 offset1:239
	s_waitcnt lgkmcnt(0)
	v_cvt_pk_bf16_f32 v37, v40, v41
	v_or_b32_e32 v40, s0, v53
	v_mul_u32_u24_e32 v40, 0xb00, v40
	v_lshlrev_b32_e32 v144, 1, v40
	v_lshl_add_u64 v[40:41], v[38:39], 0, v[144:145]
	global_store_dwordx4 v[40:41], v[34:37], off sc1
	ds_read2_b32 v[34:35], v52 offset0:16 offset1:49
	s_waitcnt lgkmcnt(0)
	v_cvt_pk_bf16_f32 v34, v34, v35
	ds_read2_b32 v[36:37], v52 offset0:82 offset1:115
	s_waitcnt lgkmcnt(0)
	v_cvt_pk_bf16_f32 v35, v36, v37
	ds_read2_b32 v[36:37], v52 offset0:148 offset1:181
	s_waitcnt lgkmcnt(0)
	v_cvt_pk_bf16_f32 v36, v36, v37
	ds_read2_b32 v[40:41], v52 offset0:214 offset1:247
	s_waitcnt lgkmcnt(0)
	v_cvt_pk_bf16_f32 v37, v40, v41
	v_or_b32_e32 v40, s0, v54
	v_mul_u32_u24_e32 v40, 0xb00, v40
	v_lshlrev_b32_e32 v144, 1, v40
	v_lshl_add_u64 v[40:41], v[38:39], 0, v[144:145]
	global_store_dwordx4 v[40:41], v[34:37], off sc1
	ds_read2_b32 v[34:35], v52 offset0:24 offset1:57
	s_waitcnt lgkmcnt(0)
	v_cvt_pk_bf16_f32 v34, v34, v35
	ds_read2_b32 v[36:37], v52 offset0:90 offset1:123
	s_waitcnt lgkmcnt(0)
	v_cvt_pk_bf16_f32 v35, v36, v37
	ds_read2_b32 v[36:37], v52 offset0:156 offset1:189
	s_waitcnt lgkmcnt(0)
	v_cvt_pk_bf16_f32 v36, v36, v37
	ds_read2_b32 v[40:41], v52 offset0:222 offset1:255
	s_waitcnt lgkmcnt(0)
	v_cvt_pk_bf16_f32 v37, v40, v41
	v_or_b32_e32 v40, s0, v55
	v_mul_u32_u24_e32 v40, 0xb00, v40
	v_lshlrev_b32_e32 v144, 1, v40
	v_lshl_add_u64 v[38:39], v[38:39], 0, v[144:145]
	global_store_dwordx4 v[38:39], v[34:37], off sc1
	s_waitcnt lgkmcnt(0)

; __global__ void __launch_bounds__(NTHR, 2) fwd_kernel(Args a) {
;     ...
;     { PH_IDS
;         const int gw = blockIdx.x * NWAVE + wave, NGW = G * NWAVE; const float* fn = a.in[32];
;         for (int m = gw; m < NTOK; m += NGW) {
;             const u32x2* xr = (const u32x2*)(XB + (size_t)m * DM) + lane; f32x4* orow = (f32x4*)(a.out + (size_t)m * DM) + lane; f32x4 v[4]; float s = 0.f;
; #pragma unroll
;             for (int j = 0; j < 4; ++j) { const u32x2 r = xr[64 * j]; v[j] = (f32x4){__uint_as_float(r.x << 16), __uint_as_float(r.x & 0xffff0000u), __uint_as_float(r.y << 16), __uint_as_float(r.y & 0xffff0000u)};
;                 s += (v[j].x * v[j].x + v[j].y * v[j].y) + (v[j].z * v[j].z + v[j].w * v[j].w); }
;             const float rstd = rsqrtf(wave_sum(s) * (1.0f / DM) + EPS);
; #pragma unroll
;             for (int j = 0; j < 4; ++j) { const f32x4 gn = *((const f32x4*)fn + lane + 64 * j); orow[64 * j] = v[j] * rstd * gn; }
;         }
.LBB0_1976:
	s_add_i32 s0, s0, s6
	v_lshl_add_u64 v[2:3], v[2:3], 0, s[2:3]
	s_cmpk_gt_i32 s0, 0x3fff
	global_load_dwordx2 v[120:121], v[2:3], off
	global_load_dwordx2 v[122:123], v[2:3], off offset:512
	global_load_dwordx2 v[124:125], v[2:3], off offset:1024
	global_load_dwordx2 v[126:127], v[2:3], off offset:1536
	v_lshlrev_b32_e32 v26, 16, v18
	v_and_b32_e32 v27, 0xffff0000, v18
	v_lshlrev_b32_e32 v18, 16, v19
	v_and_b32_e32 v19, 0xffff0000, v19
	v_lshlrev_b32_e32 v29, 16, v21
	v_lshlrev_b32_e32 v28, 16, v20
	v_and_b32_e32 v21, 0xffff0000, v21
	v_and_b32_e32 v20, 0xffff0000, v20
	v_and_b32_e32 v31, 0xffff0000, v22
	v_lshlrev_b32_e32 v33, 16, v24
	v_and_b32_e32 v35, 0xffff0000, v24
	v_mul_f32_e32 v32, v19, v19
	v_mul_f32_e32 v34, v27, v27
	v_lshlrev_b32_e32 v30, 16, v22
	v_lshlrev_b32_e32 v22, 16, v23
	v_and_b32_e32 v23, 0xffff0000, v23
	v_pk_mul_f32 v[36:37], v[20:21], v[20:21]
	v_mov_b32_e32 v39, v33
	v_mul_f32_e32 v38, v31, v31
	v_pk_fma_f32 v[42:43], v[18:19], v[18:19], v[32:33] op_sel_hi:[1,1,0]
	v_pk_fma_f32 v[44:45], v[26:27], v[26:27], v[34:35] op_sel_hi:[1,1,0]
	v_lshlrev_b32_e32 v24, 16, v25
	v_and_b32_e32 v25, 0xffff0000, v25
	v_mul_f32_e32 v40, v23, v23
	v_pk_fma_f32 v[36:37], v[28:29], v[28:29], v[36:37]
	v_pk_fma_f32 v[46:47], v[30:31], v[30:31], v[38:39] op_sel_hi:[1,1,0]
	v_mov_b32_e32 v32, v44
	v_mov_b32_e32 v38, v42
	v_mul_f32_e32 v13, v35, v35
	v_mul_f32_e32 v48, v24, v24
	v_mul_f32_e32 v49, v25, v25
	v_pk_fma_f32 v[40:41], v[22:23], v[22:23], v[40:41] op_sel_hi:[1,1,0]
	v_pk_add_f32 v[42:43], v[44:45], v[42:43]
	v_pk_add_f32 v[36:37], v[36:37], v[36:37] op_sel:[0,1] op_sel_hi:[1,0]
	v_pk_mul_f32 v[38:39], v[32:33], v[38:39]
	v_mov_b32_e32 v47, v48
	v_mov_b32_e32 v41, v49
	v_mov_b32_e32 v37, v13
	v_mov_b32_e32 v43, v39
	v_pk_add_f32 v[40:41], v[46:47], v[40:41]
	v_pk_add_f32 v[36:37], v[42:43], v[36:37]
	v_mov_b32_e32 v34, v33
	v_pk_add_f32 v[36:37], v[36:37], v[40:41]
	s_nop 0
	v_add_f32_e32 v13, v36, v37
	ds_bpermute_b32 v32, v6, v13
	s_waitcnt lgkmcnt(0)
	v_add_f32_e32 v13, v13, v32
	ds_bpermute_b32 v32, v7, v13
	s_waitcnt lgkmcnt(0)
	v_add_f32_e32 v13, v13, v32
	ds_bpermute_b32 v32, v8, v13
	s_waitcnt lgkmcnt(0)
	v_add_f32_e32 v13, v13, v32
	ds_bpermute_b32 v32, v9, v13
	s_waitcnt lgkmcnt(0)
	v_add_f32_e32 v13, v13, v32
	ds_bpermute_b32 v32, v10, v13
	s_waitcnt lgkmcnt(0)
	v_add_f32_e32 v13, v13, v32
	ds_bpermute_b32 v32, v11, v13
	s_waitcnt lgkmcnt(0)
	v_add_f32_e32 v13, v13, v32
	v_fmamk_f32 v13, v13, 0x3a800000, v12
	v_mul_f32_e32 v32, 0x4b800000, v13
	v_cmp_gt_f32_e32 vcc, s1, v13
	s_nop 1
	v_cndmask_b32_e32 v13, v13, v32, vcc
	v_rsq_f32_e32 v13, v13
	s_nop 0
	v_mul_f32_e32 v32, 0x45800000, v13
	v_cndmask_b32_e32 v32, v13, v32, vcc
	v_pk_mul_f32 v[26:27], v[32:33], v[26:27] op_sel_hi:[0,1]
	v_pk_mul_f32 v[18:19], v[32:33], v[18:19] op_sel_hi:[0,1]
	v_pk_mul_f32 v[16:17], v[102:103], v[18:19]
	v_pk_mul_f32 v[14:15], v[100:101], v[26:27]
	global_store_dwordx4 v[4:5], v[14:17], off offset:-3072 nt
	v_mov_b32_e32 v18, v29
	v_mov_b32_e32 v19, v21
	v_mov_b32_e32 v29, v20
	v_pk_mul_f32 v[18:19], v[32:33], v[18:19] op_sel_hi:[0,1]
	v_pk_mul_f32 v[20:21], v[32:33], v[28:29] op_sel_hi:[0,1]
	v_pk_mul_f32 v[128:129], v[104:105], v[20:21]
	v_pk_mul_f32 v[130:131], v[106:107], v[18:19]
	global_store_dwordx4 v[4:5], v[128:131], off offset:-2048 nt
	v_pk_mul_f32 v[18:19], v[32:33], v[22:23] op_sel_hi:[0,1]
	v_pk_mul_f32 v[20:21], v[32:33], v[30:31] op_sel_hi:[0,1]
	v_pk_mul_f32 v[132:133], v[108:109], v[20:21]
	v_pk_mul_f32 v[134:135], v[110:111], v[18:19]
	global_store_dwordx4 v[4:5], v[132:135], off offset:-1024 nt
	v_pk_mul_f32 v[18:19], v[32:33], v[24:25] op_sel_hi:[0,1]
	v_pk_mul_f32 v[20:21], v[32:33], v[34:35] op_sel_hi:[0,1]
	v_pk_mul_f32 v[136:137], v[112:113], v[20:21]
	v_pk_mul_f32 v[138:139], v[114:115], v[18:19]
	global_store_dwordx4 v[4:5], v[136:139], off nt
	v_lshl_add_u64 v[4:5], v[4:5], 0, s[4:5]
	s_waitcnt vmcnt(4)
	v_mov_b32_e32 v18, v120
	v_mov_b32_e32 v19, v121
	v_mov_b32_e32 v20, v122
	v_mov_b32_e32 v21, v123
	v_mov_b32_e32 v22, v124
	v_mov_b32_e32 v23, v125
	v_mov_b32_e32 v24, v126
	v_mov_b32_e32 v25, v127
	s_cbranch_scc0 .LBB0_1976
